# K-loop LDS-DMA rebalance: move 2 of 6 pieces from 2nd load segment to 3rd (4+4), wait recount vmcnt(6)
# speedup vs baseline: 1.0815x; 1.0068x over previous
.LBB0_410:
	ds_read_b128 v[154:157], v149
	ds_read_b128 v[158:161], v149 offset:1024
	ds_read_b128 v[162:165], v149 offset:2048
	ds_read_b128 v[166:169], v149 offset:3072
	ds_read_b128 v[170:173], v150
	ds_read_b128 v[174:177], v150 offset:1024
	ds_read_b128 v[178:181], v150 offset:2048
	ds_read_b128 v[182:185], v150 offset:3072
	s_add_u32 s30, s28, 0xfffc0080
	s_addc_u32 s31, s29, -1
	s_cmp_eq_u32 s71, 12
	s_cselect_b32 s35, s21, s31
	s_cselect_b32 s34, s61, s30
	s_cselect_b32 s31, s19, s70
	s_cselect_b32 s30, s62, s63
	v_lshl_add_u64 v[144:145], s[28:29], 0, v[136:137]
	s_add_i32 m0, s27, 0xc000
	ds_read_b128 v[186:189], v151
	ds_read_b128 v[190:193], v151 offset:1024
	ds_read_b128 v[196:199], v151 offset:2048
	ds_read_b128 v[200:203], v151 offset:3072
	ds_read_b128 v[204:207], v151 offset:4096
	ds_read_b128 v[208:211], v151 offset:5120
	ds_read_b128 v[212:215], v151 offset:6144
	ds_read_b128 v[216:219], v151 offset:7168
	global_load_lds_dwordx4 v[144:145], off
	v_lshl_add_u64 v[144:145], s[28:29], 0, v[138:139]
	s_add_i32 m0, s27, 0xe000
	s_nop 0
	global_load_lds_dwordx4 v[144:145], off
	s_waitcnt vmcnt(8)
	s_waitcnt lgkmcnt(0)
	s_barrier
	s_setprio 1
	s_waitcnt lgkmcnt(0)
	v_mfma_f32_16x16x32_bf16 v[116:119], v[154:157], v[186:189], v[116:119]
	v_mfma_f32_16x16x32_bf16 v[112:115], v[162:165], v[186:189], v[112:115]
	v_mfma_f32_16x16x32_bf16 v[100:103], v[154:157], v[196:199], v[100:103]
	v_mfma_f32_16x16x32_bf16 v[96:99], v[162:165], v[196:199], v[96:99]
	v_mfma_f32_16x16x32_bf16 v[84:87], v[154:157], v[204:207], v[84:87]
	v_mfma_f32_16x16x32_bf16 v[80:83], v[162:165], v[204:207], v[80:83]
	v_mfma_f32_16x16x32_bf16 v[68:71], v[154:157], v[212:215], v[68:71]
	v_mfma_f32_16x16x32_bf16 v[64:67], v[162:165], v[212:215], v[64:67]
	v_mfma_f32_16x16x32_bf16 v[116:119], v[158:161], v[190:193], v[116:119]
	v_mfma_f32_16x16x32_bf16 v[112:115], v[166:169], v[190:193], v[112:115]
	v_mfma_f32_16x16x32_bf16 v[100:103], v[158:161], v[200:203], v[100:103]
	v_mfma_f32_16x16x32_bf16 v[96:99], v[166:169], v[200:203], v[96:99]
	v_mfma_f32_16x16x32_bf16 v[84:87], v[158:161], v[208:211], v[84:87]
	v_mfma_f32_16x16x32_bf16 v[80:83], v[166:169], v[208:211], v[80:83]
	v_mfma_f32_16x16x32_bf16 v[68:71], v[158:161], v[216:219], v[68:71]
	v_mfma_f32_16x16x32_bf16 v[64:67], v[166:169], v[216:219], v[64:67]
	s_setprio 0
	s_setprio 1
	v_mfma_f32_16x16x32_bf16 v[124:127], v[170:173], v[186:189], v[124:127]
	v_mfma_f32_16x16x32_bf16 v[120:123], v[178:181], v[186:189], v[120:123]
	v_mfma_f32_16x16x32_bf16 v[108:111], v[170:173], v[196:199], v[108:111]
	v_mfma_f32_16x16x32_bf16 v[104:107], v[178:181], v[196:199], v[104:107]
	v_mfma_f32_16x16x32_bf16 v[92:95], v[170:173], v[204:207], v[92:95]
	v_mfma_f32_16x16x32_bf16 v[88:91], v[178:181], v[204:207], v[88:91]
	v_mfma_f32_16x16x32_bf16 v[76:79], v[170:173], v[212:215], v[76:79]
	v_mfma_f32_16x16x32_bf16 v[72:75], v[178:181], v[212:215], v[72:75]
	v_mfma_f32_16x16x32_bf16 v[124:127], v[174:177], v[190:193], v[124:127]
	v_mfma_f32_16x16x32_bf16 v[120:123], v[182:185], v[190:193], v[120:123]
	v_mfma_f32_16x16x32_bf16 v[108:111], v[174:177], v[200:203], v[108:111]
	v_mfma_f32_16x16x32_bf16 v[104:107], v[182:185], v[200:203], v[104:107]
	v_mfma_f32_16x16x32_bf16 v[92:95], v[174:177], v[208:211], v[92:95]
	v_mfma_f32_16x16x32_bf16 v[88:91], v[182:185], v[208:211], v[88:91]
	v_mfma_f32_16x16x32_bf16 v[76:79], v[174:177], v[216:219], v[76:79]
	v_mfma_f32_16x16x32_bf16 v[72:75], v[182:185], v[216:219], v[72:75]
	s_setprio 0
	s_barrier
	s_add_i32 s72, s54, s41
	v_lshl_add_u64 v[144:145], s[30:31], 0, v[132:133]
	s_mov_b32 m0, s72
	ds_read_b128 v[186:189], v151 offset:16384
	ds_read_b128 v[190:193], v151 offset:17408
	ds_read_b128 v[196:199], v151 offset:18432
	ds_read_b128 v[200:203], v151 offset:19456
	ds_read_b128 v[204:207], v151 offset:20480
	ds_read_b128 v[208:211], v151 offset:21504
	ds_read_b128 v[212:215], v151 offset:22528
	ds_read_b128 v[216:219], v151 offset:23552
	global_load_lds_dwordx4 v[144:145], off
	s_add_i32 m0, s72, 0x2000
	s_add_u32 s72, s30, 0x40000
	v_lshl_add_u64 v[220:221], s[30:31], 0, v[128:129]
	s_addc_u32 s73, s31, 0
	s_add_i32 s77, s55, s41
	global_load_lds_dwordx4 v[220:221], off
	v_lshl_add_u64 v[222:223], s[72:73], 0, v[132:133]
	s_mov_b32 m0, s77
	v_lshl_add_u64 v[224:225], s[34:35], 0, v[130:131]
	global_load_lds_dwordx4 v[222:223], off
	v_lshl_add_u64 v[222:223], s[72:73], 0, v[128:129]
	s_add_i32 m0, s77, 0x2000
	s_nop 0
	global_load_lds_dwordx4 v[222:223], off
	v_lshl_add_u64 v[222:223], s[34:35], 0, v[134:135]
	s_waitcnt vmcnt(6)
	s_waitcnt lgkmcnt(0)
	s_barrier
	s_setprio 1
	s_waitcnt lgkmcnt(0)
	v_mfma_f32_16x16x32_bf16 v[52:55], v[154:157], v[186:189], v[52:55]
	v_mfma_f32_16x16x32_bf16 v[48:51], v[162:165], v[186:189], v[48:51]
	v_mfma_f32_16x16x32_bf16 v[36:39], v[154:157], v[196:199], v[36:39]
	v_mfma_f32_16x16x32_bf16 v[32:35], v[162:165], v[196:199], v[32:35]
	v_mfma_f32_16x16x32_bf16 v[20:23], v[154:157], v[204:207], v[20:23]
	v_mfma_f32_16x16x32_bf16 v[16:19], v[162:165], v[204:207], v[16:19]
	v_mfma_f32_16x16x32_bf16 v[4:7], v[154:157], v[212:215], v[4:7]
	v_mfma_f32_16x16x32_bf16 v[0:3], v[162:165], v[212:215], v[0:3]
	v_mfma_f32_16x16x32_bf16 v[52:55], v[158:161], v[190:193], v[52:55]
	v_mfma_f32_16x16x32_bf16 v[48:51], v[166:169], v[190:193], v[48:51]
	v_mfma_f32_16x16x32_bf16 v[36:39], v[158:161], v[200:203], v[36:39]
	v_mfma_f32_16x16x32_bf16 v[32:35], v[166:169], v[200:203], v[32:35]
	v_mfma_f32_16x16x32_bf16 v[20:23], v[158:161], v[208:211], v[20:23]
	v_mfma_f32_16x16x32_bf16 v[16:19], v[166:169], v[208:211], v[16:19]
	v_mfma_f32_16x16x32_bf16 v[4:7], v[158:161], v[216:219], v[4:7]
	v_mfma_f32_16x16x32_bf16 v[0:3], v[166:169], v[216:219], v[0:3]
	s_setprio 0
	s_setprio 1
	v_mfma_f32_16x16x32_bf16 v[60:63], v[170:173], v[186:189], v[60:63]
	v_mfma_f32_16x16x32_bf16 v[56:59], v[178:181], v[186:189], v[56:59]
	v_mfma_f32_16x16x32_bf16 v[44:47], v[170:173], v[196:199], v[44:47]
	v_mfma_f32_16x16x32_bf16 v[40:43], v[178:181], v[196:199], v[40:43]
	v_mfma_f32_16x16x32_bf16 v[28:31], v[170:173], v[204:207], v[28:31]
	v_mfma_f32_16x16x32_bf16 v[24:27], v[178:181], v[204:207], v[24:27]
	v_mfma_f32_16x16x32_bf16 v[12:15], v[170:173], v[212:215], v[12:15]
	v_mfma_f32_16x16x32_bf16 v[8:11], v[178:181], v[212:215], v[8:11]
	v_mfma_f32_16x16x32_bf16 v[60:63], v[174:177], v[190:193], v[60:63]
	v_mfma_f32_16x16x32_bf16 v[56:59], v[182:185], v[190:193], v[56:59]
	v_mfma_f32_16x16x32_bf16 v[44:47], v[174:177], v[200:203], v[44:47]
	v_mfma_f32_16x16x32_bf16 v[40:43], v[182:185], v[200:203], v[40:43]
	v_mfma_f32_16x16x32_bf16 v[28:31], v[174:177], v[208:211], v[28:31]
	v_mfma_f32_16x16x32_bf16 v[24:27], v[182:185], v[208:211], v[24:27]
	v_mfma_f32_16x16x32_bf16 v[12:15], v[174:177], v[216:219], v[12:15]
	v_mfma_f32_16x16x32_bf16 v[8:11], v[182:185], v[216:219], v[8:11]
	s_setprio 0
	s_barrier
	s_add_i32 s72, 0, 0x18000
	v_add_u32_e32 v153, s72, v147
	s_add_i32 s73, 0, 0x1c000
	ds_read_b128 v[154:157], v153
	ds_read_b128 v[158:161], v153 offset:1024
	ds_read_b128 v[162:165], v153 offset:2048
	ds_read_b128 v[166:169], v153 offset:3072
	v_add_u32_e32 v153, s73, v147
	ds_read_b128 v[170:173], v153
	ds_read_b128 v[174:177], v153 offset:1024
	ds_read_b128 v[178:181], v153 offset:2048
	ds_read_b128 v[182:185], v153 offset:3072
	s_add_u32 s34, s34, 0x40000
	s_addc_u32 s35, s35, 0
	v_lshl_add_u64 v[226:227], s[34:35], 0, v[134:135]
	ds_read_b128 v[186:189], v151 offset:32768
	ds_read_b128 v[190:193], v151 offset:33792
	ds_read_b128 v[196:199], v151 offset:34816
	ds_read_b128 v[200:203], v151 offset:35840
	ds_read_b128 v[204:207], v151 offset:36864
	ds_read_b128 v[208:211], v151 offset:37888
	ds_read_b128 v[212:215], v151 offset:38912
	ds_read_b128 v[216:219], v151 offset:39936
	s_mov_b32 m0, s27
	s_nop 0
	global_load_lds_dwordx4 v[222:223], off
	s_mov_b32 m0, s43
	s_nop 0
	global_load_lds_dwordx4 v[224:225], off
	s_mov_b32 m0, s44
	s_nop 0
	global_load_lds_dwordx4 v[226:227], off
	v_lshl_add_u64 v[226:227], s[34:35], 0, v[130:131]
	s_mov_b32 m0, s45
	s_nop 0
	global_load_lds_dwordx4 v[226:227], off
	s_waitcnt vmcnt(8)
	s_waitcnt lgkmcnt(0)
	s_barrier
	s_setprio 1
	s_waitcnt lgkmcnt(0)
	v_mfma_f32_16x16x32_bf16 v[116:119], v[154:157], v[186:189], v[116:119]
	v_mfma_f32_16x16x32_bf16 v[112:115], v[162:165], v[186:189], v[112:115]
	v_mfma_f32_16x16x32_bf16 v[100:103], v[154:157], v[196:199], v[100:103]
	v_mfma_f32_16x16x32_bf16 v[96:99], v[162:165], v[196:199], v[96:99]
	v_mfma_f32_16x16x32_bf16 v[84:87], v[154:157], v[204:207], v[84:87]
	v_mfma_f32_16x16x32_bf16 v[80:83], v[162:165], v[204:207], v[80:83]
	v_mfma_f32_16x16x32_bf16 v[68:71], v[154:157], v[212:215], v[68:71]
	v_mfma_f32_16x16x32_bf16 v[64:67], v[162:165], v[212:215], v[64:67]
	v_mfma_f32_16x16x32_bf16 v[116:119], v[158:161], v[190:193], v[116:119]
	v_mfma_f32_16x16x32_bf16 v[112:115], v[166:169], v[190:193], v[112:115]
	v_mfma_f32_16x16x32_bf16 v[100:103], v[158:161], v[200:203], v[100:103]
	v_mfma_f32_16x16x32_bf16 v[96:99], v[166:169], v[200:203], v[96:99]
	v_mfma_f32_16x16x32_bf16 v[84:87], v[158:161], v[208:211], v[84:87]
	v_mfma_f32_16x16x32_bf16 v[80:83], v[166:169], v[208:211], v[80:83]
	v_mfma_f32_16x16x32_bf16 v[68:71], v[158:161], v[216:219], v[68:71]
	v_mfma_f32_16x16x32_bf16 v[64:67], v[166:169], v[216:219], v[64:67]
	s_setprio 0
	s_setprio 1
	v_mfma_f32_16x16x32_bf16 v[124:127], v[170:173], v[186:189], v[124:127]
	v_mfma_f32_16x16x32_bf16 v[120:123], v[178:181], v[186:189], v[120:123]
	v_mfma_f32_16x16x32_bf16 v[108:111], v[170:173], v[196:199], v[108:111]
	v_mfma_f32_16x16x32_bf16 v[104:107], v[178:181], v[196:199], v[104:107]
	v_mfma_f32_16x16x32_bf16 v[92:95], v[170:173], v[204:207], v[92:95]
	v_mfma_f32_16x16x32_bf16 v[88:91], v[178:181], v[204:207], v[88:91]
	v_mfma_f32_16x16x32_bf16 v[76:79], v[170:173], v[212:215], v[76:79]
	v_mfma_f32_16x16x32_bf16 v[72:75], v[178:181], v[212:215], v[72:75]
	v_mfma_f32_16x16x32_bf16 v[124:127], v[174:177], v[190:193], v[124:127]
	v_mfma_f32_16x16x32_bf16 v[120:123], v[182:185], v[190:193], v[120:123]
	v_mfma_f32_16x16x32_bf16 v[108:111], v[174:177], v[200:203], v[108:111]
	v_mfma_f32_16x16x32_bf16 v[104:107], v[182:185], v[200:203], v[104:107]
	v_mfma_f32_16x16x32_bf16 v[92:95], v[174:177], v[208:211], v[92:95]
	v_mfma_f32_16x16x32_bf16 v[88:91], v[182:185], v[208:211], v[88:91]
	v_mfma_f32_16x16x32_bf16 v[76:79], v[174:177], v[216:219], v[76:79]
	v_mfma_f32_16x16x32_bf16 v[72:75], v[182:185], v[216:219], v[72:75]
	s_setprio 0
	s_barrier
	s_add_i32 s34, s72, s41
	v_lshl_add_u64 v[144:145], v[144:145], 0, s[12:13]
	s_mov_b32 m0, s34
	ds_read_b128 v[186:189], v151 offset:49152
	ds_read_b128 v[190:193], v151 offset:50176
	ds_read_b128 v[196:199], v151 offset:51200
	ds_read_b128 v[200:203], v151 offset:52224
	ds_read_b128 v[204:207], v151 offset:53248
	ds_read_b128 v[208:211], v151 offset:54272
	ds_read_b128 v[212:215], v151 offset:55296
	ds_read_b128 v[216:219], v151 offset:56320
	global_load_lds_dwordx4 v[144:145], off
	s_add_i32 m0, s34, 0x2000
	s_add_u32 s30, s30, 0x40080
	v_lshl_add_u64 v[144:145], v[220:221], 0, s[12:13]
	s_addc_u32 s31, s31, 0
	s_add_i32 s34, s73, s41
	global_load_lds_dwordx4 v[144:145], off
	v_lshl_add_u64 v[144:145], s[30:31], 0, v[132:133]
	s_mov_b32 m0, s34
	s_nop 0
	global_load_lds_dwordx4 v[144:145], off
	v_lshl_add_u64 v[144:145], s[30:31], 0, v[128:129]
	s_add_i32 m0, s34, 0x2000
	s_nop 0
	global_load_lds_dwordx4 v[144:145], off
	v_lshl_add_u64 v[144:145], v[222:223], 0, s[12:13]
	s_mov_b32 m0, s51
	s_nop 0
	global_load_lds_dwordx4 v[144:145], off
	v_lshl_add_u64 v[144:145], v[224:225], 0, s[12:13]
	s_mov_b32 m0, s52
	s_nop 0
	global_load_lds_dwordx4 v[144:145], off
	s_waitcnt vmcnt(8)
	s_waitcnt lgkmcnt(0)
	s_barrier
	s_setprio 1
	s_waitcnt lgkmcnt(0)
	v_mfma_f32_16x16x32_bf16 v[52:55], v[154:157], v[186:189], v[52:55]
	v_mfma_f32_16x16x32_bf16 v[48:51], v[162:165], v[186:189], v[48:51]
	v_mfma_f32_16x16x32_bf16 v[36:39], v[154:157], v[196:199], v[36:39]
	v_mfma_f32_16x16x32_bf16 v[32:35], v[162:165], v[196:199], v[32:35]
	v_mfma_f32_16x16x32_bf16 v[20:23], v[154:157], v[204:207], v[20:23]
	v_mfma_f32_16x16x32_bf16 v[16:19], v[162:165], v[204:207], v[16:19]
	v_mfma_f32_16x16x32_bf16 v[4:7], v[154:157], v[212:215], v[4:7]
	v_mfma_f32_16x16x32_bf16 v[0:3], v[162:165], v[212:215], v[0:3]
	v_mfma_f32_16x16x32_bf16 v[52:55], v[158:161], v[190:193], v[52:55]
	v_mfma_f32_16x16x32_bf16 v[48:51], v[166:169], v[190:193], v[48:51]
	v_mfma_f32_16x16x32_bf16 v[36:39], v[158:161], v[200:203], v[36:39]
	v_mfma_f32_16x16x32_bf16 v[32:35], v[166:169], v[200:203], v[32:35]
	v_mfma_f32_16x16x32_bf16 v[20:23], v[158:161], v[208:211], v[20:23]
	v_mfma_f32_16x16x32_bf16 v[16:19], v[166:169], v[208:211], v[16:19]
	v_mfma_f32_16x16x32_bf16 v[4:7], v[158:161], v[216:219], v[4:7]
	v_mfma_f32_16x16x32_bf16 v[0:3], v[166:169], v[216:219], v[0:3]
	s_setprio 0
	s_setprio 1
	v_mfma_f32_16x16x32_bf16 v[60:63], v[170:173], v[186:189], v[60:63]
	v_mfma_f32_16x16x32_bf16 v[56:59], v[178:181], v[186:189], v[56:59]
	v_mfma_f32_16x16x32_bf16 v[44:47], v[170:173], v[196:199], v[44:47]
	v_mfma_f32_16x16x32_bf16 v[40:43], v[178:181], v[196:199], v[40:43]
	v_mfma_f32_16x16x32_bf16 v[28:31], v[170:173], v[204:207], v[28:31]
	v_mfma_f32_16x16x32_bf16 v[24:27], v[178:181], v[204:207], v[24:27]
	v_mfma_f32_16x16x32_bf16 v[12:15], v[170:173], v[212:215], v[12:15]
	v_mfma_f32_16x16x32_bf16 v[8:11], v[178:181], v[212:215], v[8:11]
	v_mfma_f32_16x16x32_bf16 v[60:63], v[174:177], v[190:193], v[60:63]
	v_mfma_f32_16x16x32_bf16 v[56:59], v[182:185], v[190:193], v[56:59]
	v_mfma_f32_16x16x32_bf16 v[44:47], v[174:177], v[200:203], v[44:47]
	v_mfma_f32_16x16x32_bf16 v[40:43], v[182:185], v[200:203], v[40:43]
	v_mfma_f32_16x16x32_bf16 v[28:31], v[174:177], v[208:211], v[28:31]
	v_mfma_f32_16x16x32_bf16 v[24:27], v[182:185], v[208:211], v[24:27]
	v_mfma_f32_16x16x32_bf16 v[12:15], v[174:177], v[216:219], v[12:15]
	v_mfma_f32_16x16x32_bf16 v[8:11], v[182:185], v[216:219], v[8:11]
	s_setprio 0
	s_barrier
	s_add_i32 s71, s71, 2
	s_add_u32 s28, s28, 0x100
	s_addc_u32 s29, s29, 0
	s_add_u32 s63, s63, 0x100
	s_addc_u32 s70, s70, 0
	s_cmp_gt_u32 s71, 13
	s_cbranch_scc0 .LBB0_410
	s_and_b64 vcc, exec, s[16:17]
	s_cbranch_vccz .LBB0_413
	s_barrier

.LBB0_532:
	ds_read_b128 v[146:149], v155
	ds_read_b128 v[160:163], v155 offset:1024
	ds_read_b128 v[164:167], v155 offset:2048
	ds_read_b128 v[168:171], v155 offset:3072
	ds_read_b128 v[172:175], v156
	ds_read_b128 v[176:179], v156 offset:1024
	ds_read_b128 v[180:183], v156 offset:2048
	ds_read_b128 v[184:187], v156 offset:3072
	s_add_u32 s30, s28, 0x100
	s_addc_u32 s31, s29, 0
	s_cmp_eq_u32 s77, 40
	s_cselect_b32 s37, s1, s31
	s_cselect_b32 s36, s0, s30
	s_cselect_b32 s35, s27, s73
	s_cselect_b32 s34, s26, s72
	v_lshl_add_u64 v[150:151], s[28:29], 0, v[138:139]
	s_add_i32 m0, s44, 0xc000
	ds_read_b128 v[188:191], v157
	ds_read_b128 v[196:199], v157 offset:1024
	ds_read_b128 v[200:203], v157 offset:2048
	ds_read_b128 v[204:207], v157 offset:3072
	ds_read_b128 v[208:211], v157 offset:4096
	ds_read_b128 v[212:215], v157 offset:5120
	ds_read_b128 v[216:219], v157 offset:6144
	ds_read_b128 v[220:223], v157 offset:7168
	global_load_lds_dwordx4 v[150:151], off
	v_lshl_add_u64 v[150:151], s[28:29], 0, v[140:141]
	s_add_i32 m0, s44, 0xe000
	s_nop 0
	global_load_lds_dwordx4 v[150:151], off
	s_waitcnt vmcnt(8)
	s_waitcnt lgkmcnt(0)
	s_barrier
	s_setprio 1
	s_waitcnt lgkmcnt(0)
	v_mfma_f32_16x16x32_bf16 v[124:127], v[146:149], v[188:191], v[124:127]
	v_mfma_f32_16x16x32_bf16 v[120:123], v[164:167], v[188:191], v[120:123]
	v_mfma_f32_16x16x32_bf16 v[108:111], v[146:149], v[200:203], v[108:111]
	v_mfma_f32_16x16x32_bf16 v[104:107], v[164:167], v[200:203], v[104:107]
	v_mfma_f32_16x16x32_bf16 v[92:95], v[146:149], v[208:211], v[92:95]
	v_mfma_f32_16x16x32_bf16 v[88:91], v[164:167], v[208:211], v[88:91]
	v_mfma_f32_16x16x32_bf16 v[76:79], v[146:149], v[216:219], v[76:79]
	v_mfma_f32_16x16x32_bf16 v[72:75], v[164:167], v[216:219], v[72:75]
	v_mfma_f32_16x16x32_bf16 v[124:127], v[160:163], v[196:199], v[124:127]
	v_mfma_f32_16x16x32_bf16 v[120:123], v[168:171], v[196:199], v[120:123]
	v_mfma_f32_16x16x32_bf16 v[108:111], v[160:163], v[204:207], v[108:111]
	v_mfma_f32_16x16x32_bf16 v[104:107], v[168:171], v[204:207], v[104:107]
	v_mfma_f32_16x16x32_bf16 v[92:95], v[160:163], v[212:215], v[92:95]
	v_mfma_f32_16x16x32_bf16 v[88:91], v[168:171], v[212:215], v[88:91]
	v_mfma_f32_16x16x32_bf16 v[76:79], v[160:163], v[220:223], v[76:79]
	v_mfma_f32_16x16x32_bf16 v[72:75], v[168:171], v[220:223], v[72:75]
	s_setprio 0
	s_setprio 1
	v_mfma_f32_16x16x32_bf16 v[116:119], v[172:175], v[188:191], v[116:119]
	v_mfma_f32_16x16x32_bf16 v[112:115], v[180:183], v[188:191], v[112:115]
	v_mfma_f32_16x16x32_bf16 v[100:103], v[172:175], v[200:203], v[100:103]
	v_mfma_f32_16x16x32_bf16 v[96:99], v[180:183], v[200:203], v[96:99]
	v_mfma_f32_16x16x32_bf16 v[84:87], v[172:175], v[208:211], v[84:87]
	v_mfma_f32_16x16x32_bf16 v[80:83], v[180:183], v[208:211], v[80:83]
	v_mfma_f32_16x16x32_bf16 v[68:71], v[172:175], v[216:219], v[68:71]
	v_mfma_f32_16x16x32_bf16 v[64:67], v[180:183], v[216:219], v[64:67]
	v_mfma_f32_16x16x32_bf16 v[116:119], v[176:179], v[196:199], v[116:119]
	v_mfma_f32_16x16x32_bf16 v[112:115], v[184:187], v[196:199], v[112:115]
	v_mfma_f32_16x16x32_bf16 v[100:103], v[176:179], v[204:207], v[100:103]
	v_mfma_f32_16x16x32_bf16 v[96:99], v[184:187], v[204:207], v[96:99]
	v_mfma_f32_16x16x32_bf16 v[84:87], v[176:179], v[212:215], v[84:87]
	v_mfma_f32_16x16x32_bf16 v[80:83], v[184:187], v[212:215], v[80:83]
	v_mfma_f32_16x16x32_bf16 v[68:71], v[176:179], v[220:223], v[68:71]
	v_mfma_f32_16x16x32_bf16 v[64:67], v[184:187], v[220:223], v[64:67]
	s_setprio 0
	s_barrier
	s_add_i32 s28, s60, s43
	v_lshl_add_u64 v[150:151], s[34:35], 0, v[132:133]
	s_mov_b32 m0, s28
	ds_read_b128 v[188:191], v157 offset:16384
	ds_read_b128 v[196:199], v157 offset:17408
	ds_read_b128 v[200:203], v157 offset:18432
	ds_read_b128 v[204:207], v157 offset:19456
	ds_read_b128 v[208:211], v157 offset:20480
	ds_read_b128 v[212:215], v157 offset:21504
	ds_read_b128 v[216:219], v157 offset:22528
	ds_read_b128 v[220:223], v157 offset:23552
	global_load_lds_dwordx4 v[150:151], off
	s_add_i32 m0, s28, 0x2000
	s_add_u32 s28, s34, 0xb0000
	v_lshl_add_u64 v[192:193], s[34:35], 0, v[136:137]
	s_addc_u32 s29, s35, 0
	s_add_i32 s78, s61, s43
	global_load_lds_dwordx4 v[192:193], off
	v_lshl_add_u64 v[224:225], s[28:29], 0, v[132:133]
	s_mov_b32 m0, s78
	v_lshl_add_u64 v[226:227], s[36:37], 0, v[134:135]
	global_load_lds_dwordx4 v[224:225], off
	v_lshl_add_u64 v[224:225], s[28:29], 0, v[136:137]
	s_add_i32 m0, s78, 0x2000
	s_nop 0
	global_load_lds_dwordx4 v[224:225], off
	v_lshl_add_u64 v[224:225], s[36:37], 0, v[130:131]
	s_waitcnt vmcnt(6)
	s_waitcnt lgkmcnt(0)
	s_barrier
	s_setprio 1
	s_waitcnt lgkmcnt(0)
	v_mfma_f32_16x16x32_bf16 v[60:63], v[146:149], v[188:191], v[60:63]
	v_mfma_f32_16x16x32_bf16 v[56:59], v[164:167], v[188:191], v[56:59]
	v_mfma_f32_16x16x32_bf16 v[44:47], v[146:149], v[200:203], v[44:47]
	v_mfma_f32_16x16x32_bf16 v[40:43], v[164:167], v[200:203], v[40:43]
	v_mfma_f32_16x16x32_bf16 v[28:31], v[146:149], v[208:211], v[28:31]
	v_mfma_f32_16x16x32_bf16 v[24:27], v[164:167], v[208:211], v[24:27]
	v_mfma_f32_16x16x32_bf16 v[12:15], v[146:149], v[216:219], v[12:15]
	v_mfma_f32_16x16x32_bf16 v[8:11], v[164:167], v[216:219], v[8:11]
	v_mfma_f32_16x16x32_bf16 v[60:63], v[160:163], v[196:199], v[60:63]
	v_mfma_f32_16x16x32_bf16 v[56:59], v[168:171], v[196:199], v[56:59]
	v_mfma_f32_16x16x32_bf16 v[44:47], v[160:163], v[204:207], v[44:47]
	v_mfma_f32_16x16x32_bf16 v[40:43], v[168:171], v[204:207], v[40:43]
	v_mfma_f32_16x16x32_bf16 v[28:31], v[160:163], v[212:215], v[28:31]
	v_mfma_f32_16x16x32_bf16 v[24:27], v[168:171], v[212:215], v[24:27]
	v_mfma_f32_16x16x32_bf16 v[12:15], v[160:163], v[220:223], v[12:15]
	v_mfma_f32_16x16x32_bf16 v[8:11], v[168:171], v[220:223], v[8:11]
	s_setprio 0
	s_setprio 1
	v_mfma_f32_16x16x32_bf16 v[52:55], v[172:175], v[188:191], v[52:55]
	v_mfma_f32_16x16x32_bf16 v[48:51], v[180:183], v[188:191], v[48:51]
	v_mfma_f32_16x16x32_bf16 v[36:39], v[172:175], v[200:203], v[36:39]
	v_mfma_f32_16x16x32_bf16 v[32:35], v[180:183], v[200:203], v[32:35]
	v_mfma_f32_16x16x32_bf16 v[20:23], v[172:175], v[208:211], v[20:23]
	v_mfma_f32_16x16x32_bf16 v[16:19], v[180:183], v[208:211], v[16:19]
	v_mfma_f32_16x16x32_bf16 v[4:7], v[172:175], v[216:219], v[4:7]
	v_mfma_f32_16x16x32_bf16 v[0:3], v[180:183], v[216:219], v[0:3]
	v_mfma_f32_16x16x32_bf16 v[52:55], v[176:179], v[196:199], v[52:55]
	v_mfma_f32_16x16x32_bf16 v[48:51], v[184:187], v[196:199], v[48:51]
	v_mfma_f32_16x16x32_bf16 v[36:39], v[176:179], v[204:207], v[36:39]
	v_mfma_f32_16x16x32_bf16 v[32:35], v[184:187], v[204:207], v[32:35]
	v_mfma_f32_16x16x32_bf16 v[20:23], v[176:179], v[212:215], v[20:23]
	v_mfma_f32_16x16x32_bf16 v[16:19], v[184:187], v[212:215], v[16:19]
	v_mfma_f32_16x16x32_bf16 v[4:7], v[176:179], v[220:223], v[4:7]
	v_mfma_f32_16x16x32_bf16 v[0:3], v[184:187], v[220:223], v[0:3]
	s_setprio 0
	s_barrier
	s_add_i32 s78, 0, 0x18000
	v_add_u32_e32 v159, s78, v153
	s_add_i32 s79, 0, 0x1c000
	ds_read_b128 v[146:149], v159
	ds_read_b128 v[160:163], v159 offset:1024
	ds_read_b128 v[164:167], v159 offset:2048
	ds_read_b128 v[168:171], v159 offset:3072
	v_add_u32_e32 v159, s79, v153
	ds_read_b128 v[172:175], v159
	ds_read_b128 v[176:179], v159 offset:1024
	ds_read_b128 v[180:183], v159 offset:2048
	ds_read_b128 v[184:187], v159 offset:3072
	s_add_u32 s28, s36, 0xb0000
	s_addc_u32 s29, s37, 0
	v_lshl_add_u64 v[228:229], s[28:29], 0, v[130:131]
	ds_read_b128 v[188:191], v157 offset:32768
	ds_read_b128 v[196:199], v157 offset:33792
	ds_read_b128 v[200:203], v157 offset:34816
	ds_read_b128 v[204:207], v157 offset:35840
	ds_read_b128 v[208:211], v157 offset:36864
	ds_read_b128 v[212:215], v157 offset:37888
	ds_read_b128 v[216:219], v157 offset:38912
	ds_read_b128 v[220:223], v157 offset:39936
	s_mov_b32 m0, s44
	s_nop 0
	global_load_lds_dwordx4 v[224:225], off
	s_mov_b32 m0, s45
	s_nop 0
	global_load_lds_dwordx4 v[226:227], off
	s_mov_b32 m0, s50
	s_nop 0
	global_load_lds_dwordx4 v[228:229], off
	v_lshl_add_u64 v[228:229], s[28:29], 0, v[134:135]
	s_mov_b32 m0, s51
	s_nop 0
	global_load_lds_dwordx4 v[228:229], off
	s_waitcnt vmcnt(8)
	s_waitcnt lgkmcnt(0)
	s_barrier
	s_setprio 1
	s_waitcnt lgkmcnt(0)
	v_mfma_f32_16x16x32_bf16 v[124:127], v[146:149], v[188:191], v[124:127]
	v_mfma_f32_16x16x32_bf16 v[120:123], v[164:167], v[188:191], v[120:123]
	v_mfma_f32_16x16x32_bf16 v[108:111], v[146:149], v[200:203], v[108:111]
	v_mfma_f32_16x16x32_bf16 v[104:107], v[164:167], v[200:203], v[104:107]
	v_mfma_f32_16x16x32_bf16 v[92:95], v[146:149], v[208:211], v[92:95]
	v_mfma_f32_16x16x32_bf16 v[88:91], v[164:167], v[208:211], v[88:91]
	v_mfma_f32_16x16x32_bf16 v[76:79], v[146:149], v[216:219], v[76:79]
	v_mfma_f32_16x16x32_bf16 v[72:75], v[164:167], v[216:219], v[72:75]
	v_mfma_f32_16x16x32_bf16 v[124:127], v[160:163], v[196:199], v[124:127]
	v_mfma_f32_16x16x32_bf16 v[120:123], v[168:171], v[196:199], v[120:123]
	v_mfma_f32_16x16x32_bf16 v[108:111], v[160:163], v[204:207], v[108:111]
	v_mfma_f32_16x16x32_bf16 v[104:107], v[168:171], v[204:207], v[104:107]
	v_mfma_f32_16x16x32_bf16 v[92:95], v[160:163], v[212:215], v[92:95]
	v_mfma_f32_16x16x32_bf16 v[88:91], v[168:171], v[212:215], v[88:91]
	v_mfma_f32_16x16x32_bf16 v[76:79], v[160:163], v[220:223], v[76:79]
	v_mfma_f32_16x16x32_bf16 v[72:75], v[168:171], v[220:223], v[72:75]
	s_setprio 0
	s_setprio 1
	v_mfma_f32_16x16x32_bf16 v[116:119], v[172:175], v[188:191], v[116:119]
	v_mfma_f32_16x16x32_bf16 v[112:115], v[180:183], v[188:191], v[112:115]
	v_mfma_f32_16x16x32_bf16 v[100:103], v[172:175], v[200:203], v[100:103]
	v_mfma_f32_16x16x32_bf16 v[96:99], v[180:183], v[200:203], v[96:99]
	v_mfma_f32_16x16x32_bf16 v[84:87], v[172:175], v[208:211], v[84:87]
	v_mfma_f32_16x16x32_bf16 v[80:83], v[180:183], v[208:211], v[80:83]
	v_mfma_f32_16x16x32_bf16 v[68:71], v[172:175], v[216:219], v[68:71]
	v_mfma_f32_16x16x32_bf16 v[64:67], v[180:183], v[216:219], v[64:67]
	v_mfma_f32_16x16x32_bf16 v[116:119], v[176:179], v[196:199], v[116:119]
	v_mfma_f32_16x16x32_bf16 v[112:115], v[184:187], v[196:199], v[112:115]
	v_mfma_f32_16x16x32_bf16 v[100:103], v[176:179], v[204:207], v[100:103]
	v_mfma_f32_16x16x32_bf16 v[96:99], v[184:187], v[204:207], v[96:99]
	v_mfma_f32_16x16x32_bf16 v[84:87], v[176:179], v[212:215], v[84:87]
	v_mfma_f32_16x16x32_bf16 v[80:83], v[184:187], v[212:215], v[80:83]
	v_mfma_f32_16x16x32_bf16 v[68:71], v[176:179], v[220:223], v[68:71]
	v_mfma_f32_16x16x32_bf16 v[64:67], v[184:187], v[220:223], v[64:67]
	s_setprio 0
	s_barrier
	s_add_i32 s28, s78, s43
	v_lshl_add_u64 v[150:151], v[150:151], 0, s[22:23]
	s_mov_b32 m0, s28
	ds_read_b128 v[188:191], v157 offset:49152
	ds_read_b128 v[196:199], v157 offset:50176
	ds_read_b128 v[200:203], v157 offset:51200
	ds_read_b128 v[204:207], v157 offset:52224
	ds_read_b128 v[208:211], v157 offset:53248
	ds_read_b128 v[212:215], v157 offset:54272
	ds_read_b128 v[216:219], v157 offset:55296
	ds_read_b128 v[220:223], v157 offset:56320
	global_load_lds_dwordx4 v[150:151], off
	s_add_i32 m0, s28, 0x2000
	s_add_u32 s28, s34, 0xb0080
	v_lshl_add_u64 v[150:151], v[192:193], 0, s[22:23]
	s_addc_u32 s29, s35, 0
	s_add_i32 s34, s79, s43
	global_load_lds_dwordx4 v[150:151], off
	v_lshl_add_u64 v[150:151], s[28:29], 0, v[132:133]
	s_mov_b32 m0, s34
	s_nop 0
	global_load_lds_dwordx4 v[150:151], off
	v_lshl_add_u64 v[150:151], s[28:29], 0, v[136:137]
	s_add_i32 m0, s34, 0x2000
	s_nop 0
	global_load_lds_dwordx4 v[150:151], off
	v_lshl_add_u64 v[150:151], v[224:225], 0, s[22:23]
	s_mov_b32 m0, s55
	s_nop 0
	global_load_lds_dwordx4 v[150:151], off
	v_lshl_add_u64 v[150:151], v[226:227], 0, s[22:23]
	s_mov_b32 m0, s58
	s_nop 0
	global_load_lds_dwordx4 v[150:151], off
	s_waitcnt vmcnt(8)
	s_waitcnt lgkmcnt(0)
	s_barrier
	s_setprio 1
	s_waitcnt lgkmcnt(0)
	v_mfma_f32_16x16x32_bf16 v[60:63], v[146:149], v[188:191], v[60:63]
	v_mfma_f32_16x16x32_bf16 v[56:59], v[164:167], v[188:191], v[56:59]
	v_mfma_f32_16x16x32_bf16 v[44:47], v[146:149], v[200:203], v[44:47]
	v_mfma_f32_16x16x32_bf16 v[40:43], v[164:167], v[200:203], v[40:43]
	v_mfma_f32_16x16x32_bf16 v[28:31], v[146:149], v[208:211], v[28:31]
	v_mfma_f32_16x16x32_bf16 v[24:27], v[164:167], v[208:211], v[24:27]
	v_mfma_f32_16x16x32_bf16 v[12:15], v[146:149], v[216:219], v[12:15]
	v_mfma_f32_16x16x32_bf16 v[8:11], v[164:167], v[216:219], v[8:11]
	v_mfma_f32_16x16x32_bf16 v[60:63], v[160:163], v[196:199], v[60:63]
	v_mfma_f32_16x16x32_bf16 v[56:59], v[168:171], v[196:199], v[56:59]
	v_mfma_f32_16x16x32_bf16 v[44:47], v[160:163], v[204:207], v[44:47]
	v_mfma_f32_16x16x32_bf16 v[40:43], v[168:171], v[204:207], v[40:43]
	v_mfma_f32_16x16x32_bf16 v[28:31], v[160:163], v[212:215], v[28:31]
	v_mfma_f32_16x16x32_bf16 v[24:27], v[168:171], v[212:215], v[24:27]
	v_mfma_f32_16x16x32_bf16 v[12:15], v[160:163], v[220:223], v[12:15]
	v_mfma_f32_16x16x32_bf16 v[8:11], v[168:171], v[220:223], v[8:11]
	s_setprio 0
	s_setprio 1
	v_mfma_f32_16x16x32_bf16 v[52:55], v[172:175], v[188:191], v[52:55]
	v_mfma_f32_16x16x32_bf16 v[48:51], v[180:183], v[188:191], v[48:51]
	v_mfma_f32_16x16x32_bf16 v[36:39], v[172:175], v[200:203], v[36:39]
	v_mfma_f32_16x16x32_bf16 v[32:35], v[180:183], v[200:203], v[32:35]
	v_mfma_f32_16x16x32_bf16 v[20:23], v[172:175], v[208:211], v[20:23]
	v_mfma_f32_16x16x32_bf16 v[16:19], v[180:183], v[208:211], v[16:19]
	v_mfma_f32_16x16x32_bf16 v[4:7], v[172:175], v[216:219], v[4:7]
	v_mfma_f32_16x16x32_bf16 v[0:3], v[180:183], v[216:219], v[0:3]
	v_mfma_f32_16x16x32_bf16 v[52:55], v[176:179], v[196:199], v[52:55]
	v_mfma_f32_16x16x32_bf16 v[48:51], v[184:187], v[196:199], v[48:51]
	v_mfma_f32_16x16x32_bf16 v[36:39], v[176:179], v[204:207], v[36:39]
	v_mfma_f32_16x16x32_bf16 v[32:35], v[184:187], v[204:207], v[32:35]
	v_mfma_f32_16x16x32_bf16 v[20:23], v[176:179], v[212:215], v[20:23]
	v_mfma_f32_16x16x32_bf16 v[16:19], v[184:187], v[212:215], v[16:19]
	v_mfma_f32_16x16x32_bf16 v[4:7], v[176:179], v[220:223], v[4:7]
	v_mfma_f32_16x16x32_bf16 v[0:3], v[184:187], v[220:223], v[0:3]
	s_setprio 0
	s_barrier
	s_add_i32 s77, s77, 2
	s_add_u32 s72, s72, 0x100
	s_addc_u32 s73, s73, 0
	s_cmp_gt_u32 s77, 41
	s_mov_b64 s[28:29], s[30:31]
	s_cbranch_scc0 .LBB0_532
	s_and_b64 vcc, exec, s[24:25]
	s_cbranch_vccz .LBB0_535
	s_barrier

.LBB0_626:
	ds_read_b128 v[152:155], v157
	ds_read_b128 v[162:165], v157 offset:1024
	ds_read_b128 v[166:169], v157 offset:2048
	ds_read_b128 v[170:173], v157 offset:3072
	ds_read_b128 v[174:177], v158
	ds_read_b128 v[178:181], v158 offset:1024
	ds_read_b128 v[182:185], v158 offset:2048
	ds_read_b128 v[186:189], v158 offset:3072
	s_add_u32 s40, s38, 0xfffc0080
	s_addc_u32 s41, s39, -1
	s_cmp_eq_u32 s86, 12
	s_cselect_b32 s43, s1, s41
	s_cselect_b32 s42, s11, s40
	s_cselect_b32 s41, s12, s85
	s_cselect_b32 s40, s29, s31
	v_lshl_add_u64 v[224:225], s[38:39], 0, v[144:145]
	s_add_i32 m0, s58, 0xc000
	ds_read_b128 v[190:193], v159
	ds_read_b128 v[196:199], v159 offset:1024
	ds_read_b128 v[200:203], v159 offset:2048
	ds_read_b128 v[204:207], v159 offset:3072
	ds_read_b128 v[208:211], v159 offset:4096
	ds_read_b128 v[212:215], v159 offset:5120
	ds_read_b128 v[216:219], v159 offset:6144
	ds_read_b128 v[220:223], v159 offset:7168
	global_load_lds_dwordx4 v[224:225], off
	v_lshl_add_u64 v[224:225], s[38:39], 0, v[146:147]
	s_add_i32 m0, s58, 0xe000
	s_nop 0
	global_load_lds_dwordx4 v[224:225], off
	s_waitcnt vmcnt(8)
	s_waitcnt lgkmcnt(0)
	s_barrier
	s_setprio 1
	s_waitcnt lgkmcnt(0)
	v_mfma_f32_16x16x32_bf16 v[124:127], v[152:155], v[190:193], v[124:127]
	v_mfma_f32_16x16x32_bf16 v[120:123], v[166:169], v[190:193], v[120:123]
	v_mfma_f32_16x16x32_bf16 v[108:111], v[152:155], v[200:203], v[108:111]
	v_mfma_f32_16x16x32_bf16 v[104:107], v[166:169], v[200:203], v[104:107]
	v_mfma_f32_16x16x32_bf16 v[92:95], v[152:155], v[208:211], v[92:95]
	v_mfma_f32_16x16x32_bf16 v[88:91], v[166:169], v[208:211], v[88:91]
	v_mfma_f32_16x16x32_bf16 v[76:79], v[152:155], v[216:219], v[76:79]
	v_mfma_f32_16x16x32_bf16 v[72:75], v[166:169], v[216:219], v[72:75]
	v_mfma_f32_16x16x32_bf16 v[124:127], v[162:165], v[196:199], v[124:127]
	v_mfma_f32_16x16x32_bf16 v[120:123], v[170:173], v[196:199], v[120:123]
	v_mfma_f32_16x16x32_bf16 v[108:111], v[162:165], v[204:207], v[108:111]
	v_mfma_f32_16x16x32_bf16 v[104:107], v[170:173], v[204:207], v[104:107]
	v_mfma_f32_16x16x32_bf16 v[92:95], v[162:165], v[212:215], v[92:95]
	v_mfma_f32_16x16x32_bf16 v[88:91], v[170:173], v[212:215], v[88:91]
	v_mfma_f32_16x16x32_bf16 v[76:79], v[162:165], v[220:223], v[76:79]
	v_mfma_f32_16x16x32_bf16 v[72:75], v[170:173], v[220:223], v[72:75]
	s_setprio 0
	s_setprio 1
	v_mfma_f32_16x16x32_bf16 v[116:119], v[174:177], v[190:193], v[116:119]
	v_mfma_f32_16x16x32_bf16 v[112:115], v[182:185], v[190:193], v[112:115]
	v_mfma_f32_16x16x32_bf16 v[100:103], v[174:177], v[200:203], v[100:103]
	v_mfma_f32_16x16x32_bf16 v[96:99], v[182:185], v[200:203], v[96:99]
	v_mfma_f32_16x16x32_bf16 v[84:87], v[174:177], v[208:211], v[84:87]
	v_mfma_f32_16x16x32_bf16 v[80:83], v[182:185], v[208:211], v[80:83]
	v_mfma_f32_16x16x32_bf16 v[68:71], v[174:177], v[216:219], v[68:71]
	v_mfma_f32_16x16x32_bf16 v[64:67], v[182:185], v[216:219], v[64:67]
	v_mfma_f32_16x16x32_bf16 v[116:119], v[178:181], v[196:199], v[116:119]
	v_mfma_f32_16x16x32_bf16 v[112:115], v[186:189], v[196:199], v[112:115]
	v_mfma_f32_16x16x32_bf16 v[100:103], v[178:181], v[204:207], v[100:103]
	v_mfma_f32_16x16x32_bf16 v[96:99], v[186:189], v[204:207], v[96:99]
	v_mfma_f32_16x16x32_bf16 v[84:87], v[178:181], v[212:215], v[84:87]
	v_mfma_f32_16x16x32_bf16 v[80:83], v[186:189], v[212:215], v[80:83]
	v_mfma_f32_16x16x32_bf16 v[68:71], v[178:181], v[220:223], v[68:71]
	v_mfma_f32_16x16x32_bf16 v[64:67], v[186:189], v[220:223], v[64:67]
	s_setprio 0
	s_barrier
	s_add_i32 s87, s73, s55
	v_lshl_add_u64 v[224:225], s[40:41], 0, v[130:131]
	s_mov_b32 m0, s87
	ds_read_b128 v[190:193], v159 offset:16384
	ds_read_b128 v[196:199], v159 offset:17408
	ds_read_b128 v[200:203], v159 offset:18432
	ds_read_b128 v[204:207], v159 offset:19456
	ds_read_b128 v[208:211], v159 offset:20480
	ds_read_b128 v[212:215], v159 offset:21504
	ds_read_b128 v[216:219], v159 offset:22528
	ds_read_b128 v[220:223], v159 offset:23552
	global_load_lds_dwordx4 v[224:225], off
	s_add_i32 m0, s87, 0x2000
	s_add_u32 s88, s40, 0x40000
	v_lshl_add_u64 v[226:227], s[40:41], 0, v[134:135]
	s_addc_u32 s89, s41, 0
	s_add_i32 s87, s77, s55
	global_load_lds_dwordx4 v[226:227], off
	v_lshl_add_u64 v[228:229], s[88:89], 0, v[130:131]
	s_mov_b32 m0, s87
	v_lshl_add_u64 v[230:231], s[42:43], 0, v[132:133]
	global_load_lds_dwordx4 v[228:229], off
	v_lshl_add_u64 v[228:229], s[88:89], 0, v[134:135]
	s_add_i32 m0, s87, 0x2000
	s_nop 0
	global_load_lds_dwordx4 v[228:229], off
	v_lshl_add_u64 v[228:229], s[42:43], 0, v[128:129]
	s_waitcnt vmcnt(6)
	s_waitcnt lgkmcnt(0)
	s_barrier
	s_setprio 1
	s_waitcnt lgkmcnt(0)
	v_mfma_f32_16x16x32_bf16 v[60:63], v[152:155], v[190:193], v[60:63]
	v_mfma_f32_16x16x32_bf16 v[56:59], v[166:169], v[190:193], v[56:59]
	v_mfma_f32_16x16x32_bf16 v[44:47], v[152:155], v[200:203], v[44:47]
	v_mfma_f32_16x16x32_bf16 v[40:43], v[166:169], v[200:203], v[40:43]
	v_mfma_f32_16x16x32_bf16 v[28:31], v[152:155], v[208:211], v[28:31]
	v_mfma_f32_16x16x32_bf16 v[24:27], v[166:169], v[208:211], v[24:27]
	v_mfma_f32_16x16x32_bf16 v[12:15], v[152:155], v[216:219], v[12:15]
	v_mfma_f32_16x16x32_bf16 v[8:11], v[166:169], v[216:219], v[8:11]
	v_mfma_f32_16x16x32_bf16 v[60:63], v[162:165], v[196:199], v[60:63]
	v_mfma_f32_16x16x32_bf16 v[56:59], v[170:173], v[196:199], v[56:59]
	v_mfma_f32_16x16x32_bf16 v[44:47], v[162:165], v[204:207], v[44:47]
	v_mfma_f32_16x16x32_bf16 v[40:43], v[170:173], v[204:207], v[40:43]
	v_mfma_f32_16x16x32_bf16 v[28:31], v[162:165], v[212:215], v[28:31]
	v_mfma_f32_16x16x32_bf16 v[24:27], v[170:173], v[212:215], v[24:27]
	v_mfma_f32_16x16x32_bf16 v[12:15], v[162:165], v[220:223], v[12:15]
	v_mfma_f32_16x16x32_bf16 v[8:11], v[170:173], v[220:223], v[8:11]
	s_setprio 0
	s_setprio 1
	v_mfma_f32_16x16x32_bf16 v[52:55], v[174:177], v[190:193], v[52:55]
	v_mfma_f32_16x16x32_bf16 v[48:51], v[182:185], v[190:193], v[48:51]
	v_mfma_f32_16x16x32_bf16 v[36:39], v[174:177], v[200:203], v[36:39]
	v_mfma_f32_16x16x32_bf16 v[32:35], v[182:185], v[200:203], v[32:35]
	v_mfma_f32_16x16x32_bf16 v[20:23], v[174:177], v[208:211], v[20:23]
	v_mfma_f32_16x16x32_bf16 v[16:19], v[182:185], v[208:211], v[16:19]
	v_mfma_f32_16x16x32_bf16 v[4:7], v[174:177], v[216:219], v[4:7]
	v_mfma_f32_16x16x32_bf16 v[0:3], v[182:185], v[216:219], v[0:3]
	v_mfma_f32_16x16x32_bf16 v[52:55], v[178:181], v[196:199], v[52:55]
	v_mfma_f32_16x16x32_bf16 v[48:51], v[186:189], v[196:199], v[48:51]
	v_mfma_f32_16x16x32_bf16 v[36:39], v[178:181], v[204:207], v[36:39]
	v_mfma_f32_16x16x32_bf16 v[32:35], v[186:189], v[204:207], v[32:35]
	v_mfma_f32_16x16x32_bf16 v[20:23], v[178:181], v[212:215], v[20:23]
	v_mfma_f32_16x16x32_bf16 v[16:19], v[186:189], v[212:215], v[16:19]
	v_mfma_f32_16x16x32_bf16 v[4:7], v[178:181], v[220:223], v[4:7]
	v_mfma_f32_16x16x32_bf16 v[0:3], v[186:189], v[220:223], v[0:3]
	s_setprio 0
	s_barrier
	s_add_i32 s87, 0, 0x18000
	v_add_u32_e32 v136, s87, v141
	s_add_i32 s88, 0, 0x1c000
	ds_read_b128 v[152:155], v136
	ds_read_b128 v[162:165], v136 offset:1024
	ds_read_b128 v[166:169], v136 offset:2048
	ds_read_b128 v[170:173], v136 offset:3072
	v_add_u32_e32 v136, s88, v141
	ds_read_b128 v[174:177], v136
	ds_read_b128 v[178:181], v136 offset:1024
	ds_read_b128 v[182:185], v136 offset:2048
	ds_read_b128 v[186:189], v136 offset:3072
	s_add_u32 s42, s42, 0x40000
	s_addc_u32 s43, s43, 0
	v_lshl_add_u64 v[232:233], s[42:43], 0, v[128:129]
	ds_read_b128 v[190:193], v159 offset:32768
	ds_read_b128 v[196:199], v159 offset:33792
	ds_read_b128 v[200:203], v159 offset:34816
	ds_read_b128 v[204:207], v159 offset:35840
	ds_read_b128 v[208:211], v159 offset:36864
	ds_read_b128 v[212:215], v159 offset:37888
	ds_read_b128 v[216:219], v159 offset:38912
	ds_read_b128 v[220:223], v159 offset:39936
	s_mov_b32 m0, s58
	s_nop 0
	global_load_lds_dwordx4 v[228:229], off
	s_mov_b32 m0, s59
	s_nop 0
	global_load_lds_dwordx4 v[230:231], off
	s_mov_b32 m0, s60
	s_nop 0
	global_load_lds_dwordx4 v[232:233], off
	v_lshl_add_u64 v[232:233], s[42:43], 0, v[132:133]
	s_mov_b32 m0, s61
	s_nop 0
	global_load_lds_dwordx4 v[232:233], off
	s_waitcnt vmcnt(8)
	s_waitcnt lgkmcnt(0)
	s_barrier
	s_setprio 1
	s_waitcnt lgkmcnt(0)
	v_mfma_f32_16x16x32_bf16 v[124:127], v[152:155], v[190:193], v[124:127]
	v_mfma_f32_16x16x32_bf16 v[120:123], v[166:169], v[190:193], v[120:123]
	v_mfma_f32_16x16x32_bf16 v[108:111], v[152:155], v[200:203], v[108:111]
	v_mfma_f32_16x16x32_bf16 v[104:107], v[166:169], v[200:203], v[104:107]
	v_mfma_f32_16x16x32_bf16 v[92:95], v[152:155], v[208:211], v[92:95]
	v_mfma_f32_16x16x32_bf16 v[88:91], v[166:169], v[208:211], v[88:91]
	v_mfma_f32_16x16x32_bf16 v[76:79], v[152:155], v[216:219], v[76:79]
	v_mfma_f32_16x16x32_bf16 v[72:75], v[166:169], v[216:219], v[72:75]
	v_mfma_f32_16x16x32_bf16 v[124:127], v[162:165], v[196:199], v[124:127]
	v_mfma_f32_16x16x32_bf16 v[120:123], v[170:173], v[196:199], v[120:123]
	v_mfma_f32_16x16x32_bf16 v[108:111], v[162:165], v[204:207], v[108:111]
	v_mfma_f32_16x16x32_bf16 v[104:107], v[170:173], v[204:207], v[104:107]
	v_mfma_f32_16x16x32_bf16 v[92:95], v[162:165], v[212:215], v[92:95]
	v_mfma_f32_16x16x32_bf16 v[88:91], v[170:173], v[212:215], v[88:91]
	v_mfma_f32_16x16x32_bf16 v[76:79], v[162:165], v[220:223], v[76:79]
	v_mfma_f32_16x16x32_bf16 v[72:75], v[170:173], v[220:223], v[72:75]
	s_setprio 0
	s_setprio 1
	v_mfma_f32_16x16x32_bf16 v[116:119], v[174:177], v[190:193], v[116:119]
	v_mfma_f32_16x16x32_bf16 v[112:115], v[182:185], v[190:193], v[112:115]
	v_mfma_f32_16x16x32_bf16 v[100:103], v[174:177], v[200:203], v[100:103]
	v_mfma_f32_16x16x32_bf16 v[96:99], v[182:185], v[200:203], v[96:99]
	v_mfma_f32_16x16x32_bf16 v[84:87], v[174:177], v[208:211], v[84:87]
	v_mfma_f32_16x16x32_bf16 v[80:83], v[182:185], v[208:211], v[80:83]
	v_mfma_f32_16x16x32_bf16 v[68:71], v[174:177], v[216:219], v[68:71]
	v_mfma_f32_16x16x32_bf16 v[64:67], v[182:185], v[216:219], v[64:67]
	v_mfma_f32_16x16x32_bf16 v[116:119], v[178:181], v[196:199], v[116:119]
	v_mfma_f32_16x16x32_bf16 v[112:115], v[186:189], v[196:199], v[112:115]
	v_mfma_f32_16x16x32_bf16 v[100:103], v[178:181], v[204:207], v[100:103]
	v_mfma_f32_16x16x32_bf16 v[96:99], v[186:189], v[204:207], v[96:99]
	v_mfma_f32_16x16x32_bf16 v[84:87], v[178:181], v[212:215], v[84:87]
	v_mfma_f32_16x16x32_bf16 v[80:83], v[186:189], v[212:215], v[80:83]
	v_mfma_f32_16x16x32_bf16 v[68:71], v[178:181], v[220:223], v[68:71]
	v_mfma_f32_16x16x32_bf16 v[64:67], v[186:189], v[220:223], v[64:67]
	s_setprio 0
	s_barrier
	s_add_i32 s42, s87, s55
	v_lshl_add_u64 v[224:225], v[224:225], 0, s[24:25]
	s_mov_b32 m0, s42
	ds_read_b128 v[190:193], v159 offset:49152
	ds_read_b128 v[196:199], v159 offset:50176
	ds_read_b128 v[200:203], v159 offset:51200
	ds_read_b128 v[204:207], v159 offset:52224
	ds_read_b128 v[208:211], v159 offset:53248
	ds_read_b128 v[212:215], v159 offset:54272
	ds_read_b128 v[216:219], v159 offset:55296
	ds_read_b128 v[220:223], v159 offset:56320
	global_load_lds_dwordx4 v[224:225], off
	s_add_i32 m0, s42, 0x2000
	s_add_u32 s40, s40, 0x40080
	v_lshl_add_u64 v[224:225], v[226:227], 0, s[24:25]
	s_addc_u32 s41, s41, 0
	s_add_i32 s42, s88, s55
	global_load_lds_dwordx4 v[224:225], off
	v_lshl_add_u64 v[224:225], s[40:41], 0, v[130:131]
	s_mov_b32 m0, s42
	s_nop 0
	global_load_lds_dwordx4 v[224:225], off
	v_lshl_add_u64 v[224:225], s[40:41], 0, v[134:135]
	s_add_i32 m0, s42, 0x2000
	s_nop 0
	global_load_lds_dwordx4 v[224:225], off
	v_lshl_add_u64 v[224:225], v[228:229], 0, s[24:25]
	s_mov_b32 m0, s70
	s_nop 0
	global_load_lds_dwordx4 v[224:225], off
	v_lshl_add_u64 v[224:225], v[230:231], 0, s[24:25]
	s_mov_b32 m0, s71
	s_nop 0
	global_load_lds_dwordx4 v[224:225], off
	s_waitcnt vmcnt(8)
	s_waitcnt lgkmcnt(0)
	s_barrier
	s_setprio 1
	s_waitcnt lgkmcnt(0)
	v_mfma_f32_16x16x32_bf16 v[60:63], v[152:155], v[190:193], v[60:63]
	v_mfma_f32_16x16x32_bf16 v[56:59], v[166:169], v[190:193], v[56:59]
	v_mfma_f32_16x16x32_bf16 v[44:47], v[152:155], v[200:203], v[44:47]
	v_mfma_f32_16x16x32_bf16 v[40:43], v[166:169], v[200:203], v[40:43]
	v_mfma_f32_16x16x32_bf16 v[28:31], v[152:155], v[208:211], v[28:31]
	v_mfma_f32_16x16x32_bf16 v[24:27], v[166:169], v[208:211], v[24:27]
	v_mfma_f32_16x16x32_bf16 v[12:15], v[152:155], v[216:219], v[12:15]
	v_mfma_f32_16x16x32_bf16 v[8:11], v[166:169], v[216:219], v[8:11]
	v_mfma_f32_16x16x32_bf16 v[60:63], v[162:165], v[196:199], v[60:63]
	v_mfma_f32_16x16x32_bf16 v[56:59], v[170:173], v[196:199], v[56:59]
	v_mfma_f32_16x16x32_bf16 v[44:47], v[162:165], v[204:207], v[44:47]
	v_mfma_f32_16x16x32_bf16 v[40:43], v[170:173], v[204:207], v[40:43]
	v_mfma_f32_16x16x32_bf16 v[28:31], v[162:165], v[212:215], v[28:31]
	v_mfma_f32_16x16x32_bf16 v[24:27], v[170:173], v[212:215], v[24:27]
	v_mfma_f32_16x16x32_bf16 v[12:15], v[162:165], v[220:223], v[12:15]
	v_mfma_f32_16x16x32_bf16 v[8:11], v[170:173], v[220:223], v[8:11]
	s_setprio 0
	s_setprio 1
	v_mfma_f32_16x16x32_bf16 v[52:55], v[174:177], v[190:193], v[52:55]
	v_mfma_f32_16x16x32_bf16 v[48:51], v[182:185], v[190:193], v[48:51]
	v_mfma_f32_16x16x32_bf16 v[36:39], v[174:177], v[200:203], v[36:39]
	v_mfma_f32_16x16x32_bf16 v[32:35], v[182:185], v[200:203], v[32:35]
	v_mfma_f32_16x16x32_bf16 v[20:23], v[174:177], v[208:211], v[20:23]
	v_mfma_f32_16x16x32_bf16 v[16:19], v[182:185], v[208:211], v[16:19]
	v_mfma_f32_16x16x32_bf16 v[4:7], v[174:177], v[216:219], v[4:7]
	v_mfma_f32_16x16x32_bf16 v[0:3], v[182:185], v[216:219], v[0:3]
	v_mfma_f32_16x16x32_bf16 v[52:55], v[178:181], v[196:199], v[52:55]
	v_mfma_f32_16x16x32_bf16 v[48:51], v[186:189], v[196:199], v[48:51]
	v_mfma_f32_16x16x32_bf16 v[36:39], v[178:181], v[204:207], v[36:39]
	v_mfma_f32_16x16x32_bf16 v[32:35], v[186:189], v[204:207], v[32:35]
	v_mfma_f32_16x16x32_bf16 v[20:23], v[178:181], v[212:215], v[20:23]
	v_mfma_f32_16x16x32_bf16 v[16:19], v[186:189], v[212:215], v[16:19]
	v_mfma_f32_16x16x32_bf16 v[4:7], v[178:181], v[220:223], v[4:7]
	v_mfma_f32_16x16x32_bf16 v[0:3], v[186:189], v[220:223], v[0:3]
	s_setprio 0
	s_barrier
	s_add_i32 s86, s86, 2
	s_add_u32 s38, s38, 0x100
	s_addc_u32 s39, s39, 0
	s_add_u32 s31, s31, 0x100
	s_addc_u32 s85, s85, 0
	s_cmp_gt_u32 s86, 13
	s_cbranch_scc0 .LBB0_626
	s_and_b64 vcc, exec, s[26:27]
	s_cbranch_vccz .LBB0_629
	s_barrier

.LBB0_760:
	ds_read_b128 v[148:151], v144
	ds_read_b128 v[152:155], v144 offset:1024
	ds_read_b128 v[156:159], v144 offset:2048
	ds_read_b128 v[160:163], v144 offset:3072
	ds_read_b128 v[164:167], v145
	ds_read_b128 v[168:171], v145 offset:1024
	ds_read_b128 v[172:175], v145 offset:2048
	ds_read_b128 v[176:179], v145 offset:3072
	s_add_u32 s36, s34, 0x100
	s_addc_u32 s37, s35, 0
	s_cmp_eq_u32 s83, 4
	s_cselect_b32 s41, s29, s37
	s_cselect_b32 s40, s28, s36
	s_cselect_b32 s39, s31, s25
	s_cselect_b32 s38, s30, s13
	v_lshl_add_u64 v[192:193], s[34:35], 0, v[138:139]
	s_add_i32 m0, s58, 0xc000
	ds_read_b128 v[180:183], v146
	ds_read_b128 v[184:187], v146 offset:1024
	ds_read_b128 v[188:191], v146 offset:2048
	ds_read_b128 v[196:199], v146 offset:3072
	ds_read_b128 v[200:203], v146 offset:4096
	ds_read_b128 v[204:207], v146 offset:5120
	ds_read_b128 v[208:211], v146 offset:6144
	ds_read_b128 v[212:215], v146 offset:7168
	global_load_lds_dwordx4 v[192:193], off
	v_lshl_add_u64 v[192:193], s[34:35], 0, v[140:141]
	s_add_i32 m0, s58, 0xe000
	s_nop 0
	global_load_lds_dwordx4 v[192:193], off
	s_waitcnt vmcnt(8)
	s_waitcnt lgkmcnt(0)
	s_barrier
	s_setprio 1
	s_waitcnt lgkmcnt(0)
	v_mfma_f32_16x16x32_bf16 v[124:127], v[148:151], v[180:183], v[124:127]
	v_mfma_f32_16x16x32_bf16 v[120:123], v[156:159], v[180:183], v[120:123]
	v_mfma_f32_16x16x32_bf16 v[116:119], v[148:151], v[188:191], v[116:119]
	v_mfma_f32_16x16x32_bf16 v[112:115], v[156:159], v[188:191], v[112:115]
	v_mfma_f32_16x16x32_bf16 v[104:107], v[148:151], v[200:203], v[104:107]
	v_mfma_f32_16x16x32_bf16 v[96:99], v[156:159], v[200:203], v[96:99]
	v_mfma_f32_16x16x32_bf16 v[88:91], v[148:151], v[208:211], v[88:91]
	v_mfma_f32_16x16x32_bf16 v[80:83], v[156:159], v[208:211], v[80:83]
	v_mfma_f32_16x16x32_bf16 v[124:127], v[152:155], v[184:187], v[124:127]
	v_mfma_f32_16x16x32_bf16 v[120:123], v[160:163], v[184:187], v[120:123]
	v_mfma_f32_16x16x32_bf16 v[116:119], v[152:155], v[196:199], v[116:119]
	v_mfma_f32_16x16x32_bf16 v[112:115], v[160:163], v[196:199], v[112:115]
	v_mfma_f32_16x16x32_bf16 v[104:107], v[152:155], v[204:207], v[104:107]
	v_mfma_f32_16x16x32_bf16 v[96:99], v[160:163], v[204:207], v[96:99]
	v_mfma_f32_16x16x32_bf16 v[88:91], v[152:155], v[212:215], v[88:91]
	v_mfma_f32_16x16x32_bf16 v[80:83], v[160:163], v[212:215], v[80:83]
	s_setprio 0
	s_setprio 1
	v_mfma_f32_16x16x32_bf16 v[108:111], v[164:167], v[180:183], v[108:111]
	v_mfma_f32_16x16x32_bf16 v[100:103], v[172:175], v[180:183], v[100:103]
	v_mfma_f32_16x16x32_bf16 v[92:95], v[164:167], v[188:191], v[92:95]
	v_mfma_f32_16x16x32_bf16 v[84:87], v[172:175], v[188:191], v[84:87]
	v_mfma_f32_16x16x32_bf16 v[76:79], v[164:167], v[200:203], v[76:79]
	v_mfma_f32_16x16x32_bf16 v[72:75], v[172:175], v[200:203], v[72:75]
	v_mfma_f32_16x16x32_bf16 v[68:71], v[164:167], v[208:211], v[68:71]
	v_mfma_f32_16x16x32_bf16 v[64:67], v[172:175], v[208:211], v[64:67]
	v_mfma_f32_16x16x32_bf16 v[108:111], v[168:171], v[184:187], v[108:111]
	v_mfma_f32_16x16x32_bf16 v[100:103], v[176:179], v[184:187], v[100:103]
	v_mfma_f32_16x16x32_bf16 v[92:95], v[168:171], v[196:199], v[92:95]
	v_mfma_f32_16x16x32_bf16 v[84:87], v[176:179], v[196:199], v[84:87]
	v_mfma_f32_16x16x32_bf16 v[76:79], v[168:171], v[204:207], v[76:79]
	v_mfma_f32_16x16x32_bf16 v[72:75], v[176:179], v[204:207], v[72:75]
	v_mfma_f32_16x16x32_bf16 v[68:71], v[168:171], v[212:215], v[68:71]
	v_mfma_f32_16x16x32_bf16 v[64:67], v[176:179], v[212:215], v[64:67]
	s_setprio 0
	s_barrier
	s_add_i32 s34, s77, s51
	v_lshl_add_u64 v[192:193], s[38:39], 0, v[132:133]
	s_mov_b32 m0, s34
	ds_read_b128 v[180:183], v146 offset:16384
	ds_read_b128 v[184:187], v146 offset:17408
	ds_read_b128 v[188:191], v146 offset:18432
	ds_read_b128 v[196:199], v146 offset:19456
	ds_read_b128 v[200:203], v146 offset:20480
	ds_read_b128 v[204:207], v146 offset:21504
	ds_read_b128 v[208:211], v146 offset:22528
	ds_read_b128 v[212:215], v146 offset:23552
	global_load_lds_dwordx4 v[192:193], off
	s_add_i32 m0, s34, 0x2000
	s_add_u32 s34, s38, 0x20000
	v_lshl_add_u64 v[216:217], s[38:39], 0, v[128:129]
	s_addc_u32 s35, s39, 0
	s_add_i32 s84, s78, s51
	global_load_lds_dwordx4 v[216:217], off
	v_lshl_add_u64 v[218:219], s[34:35], 0, v[132:133]
	s_mov_b32 m0, s84
	v_lshl_add_u64 v[220:221], s[40:41], 0, v[130:131]
	global_load_lds_dwordx4 v[218:219], off
	v_lshl_add_u64 v[218:219], s[34:35], 0, v[128:129]
	s_add_i32 m0, s84, 0x2000
	s_nop 0
	global_load_lds_dwordx4 v[218:219], off
	v_lshl_add_u64 v[218:219], s[40:41], 0, v[134:135]
	s_waitcnt vmcnt(6)
	s_waitcnt lgkmcnt(0)
	s_barrier
	s_setprio 1
	s_waitcnt lgkmcnt(0)
	v_mfma_f32_16x16x32_bf16 v[60:63], v[148:151], v[180:183], v[60:63]
	v_mfma_f32_16x16x32_bf16 v[56:59], v[156:159], v[180:183], v[56:59]
	v_mfma_f32_16x16x32_bf16 v[52:55], v[148:151], v[188:191], v[52:55]
	v_mfma_f32_16x16x32_bf16 v[48:51], v[156:159], v[188:191], v[48:51]
	v_mfma_f32_16x16x32_bf16 v[40:43], v[148:151], v[200:203], v[40:43]
	v_mfma_f32_16x16x32_bf16 v[32:35], v[156:159], v[200:203], v[32:35]
	v_mfma_f32_16x16x32_bf16 v[24:27], v[148:151], v[208:211], v[24:27]
	v_mfma_f32_16x16x32_bf16 v[16:19], v[156:159], v[208:211], v[16:19]
	v_mfma_f32_16x16x32_bf16 v[60:63], v[152:155], v[184:187], v[60:63]
	v_mfma_f32_16x16x32_bf16 v[56:59], v[160:163], v[184:187], v[56:59]
	v_mfma_f32_16x16x32_bf16 v[52:55], v[152:155], v[196:199], v[52:55]
	v_mfma_f32_16x16x32_bf16 v[48:51], v[160:163], v[196:199], v[48:51]
	v_mfma_f32_16x16x32_bf16 v[40:43], v[152:155], v[204:207], v[40:43]
	v_mfma_f32_16x16x32_bf16 v[32:35], v[160:163], v[204:207], v[32:35]
	v_mfma_f32_16x16x32_bf16 v[24:27], v[152:155], v[212:215], v[24:27]
	v_mfma_f32_16x16x32_bf16 v[16:19], v[160:163], v[212:215], v[16:19]
	s_setprio 0
	s_setprio 1
	v_mfma_f32_16x16x32_bf16 v[44:47], v[164:167], v[180:183], v[44:47]
	v_mfma_f32_16x16x32_bf16 v[36:39], v[172:175], v[180:183], v[36:39]
	v_mfma_f32_16x16x32_bf16 v[28:31], v[164:167], v[188:191], v[28:31]
	v_mfma_f32_16x16x32_bf16 v[20:23], v[172:175], v[188:191], v[20:23]
	v_mfma_f32_16x16x32_bf16 v[12:15], v[164:167], v[200:203], v[12:15]
	v_mfma_f32_16x16x32_bf16 v[8:11], v[172:175], v[200:203], v[8:11]
	v_mfma_f32_16x16x32_bf16 v[4:7], v[164:167], v[208:211], v[4:7]
	v_mfma_f32_16x16x32_bf16 v[0:3], v[172:175], v[208:211], v[0:3]
	v_mfma_f32_16x16x32_bf16 v[44:47], v[168:171], v[184:187], v[44:47]
	v_mfma_f32_16x16x32_bf16 v[36:39], v[176:179], v[184:187], v[36:39]
	v_mfma_f32_16x16x32_bf16 v[28:31], v[168:171], v[196:199], v[28:31]
	v_mfma_f32_16x16x32_bf16 v[20:23], v[176:179], v[196:199], v[20:23]
	v_mfma_f32_16x16x32_bf16 v[12:15], v[168:171], v[204:207], v[12:15]
	v_mfma_f32_16x16x32_bf16 v[8:11], v[176:179], v[204:207], v[8:11]
	v_mfma_f32_16x16x32_bf16 v[4:7], v[168:171], v[212:215], v[4:7]
	v_mfma_f32_16x16x32_bf16 v[0:3], v[176:179], v[212:215], v[0:3]
	s_setprio 0
	s_barrier
	s_add_i32 s84, 0, 0x18000
	v_add_u32_e32 v147, s84, v143
	s_add_i32 s85, 0, 0x1c000
	ds_read_b128 v[148:151], v147
	ds_read_b128 v[152:155], v147 offset:1024
	ds_read_b128 v[156:159], v147 offset:2048
	ds_read_b128 v[160:163], v147 offset:3072
	v_add_u32_e32 v147, s85, v143
	ds_read_b128 v[164:167], v147
	ds_read_b128 v[168:171], v147 offset:1024
	ds_read_b128 v[172:175], v147 offset:2048
	ds_read_b128 v[176:179], v147 offset:3072
	s_add_u32 s34, s40, 0x30000
	s_addc_u32 s35, s41, 0
	v_lshl_add_u64 v[222:223], s[34:35], 0, v[134:135]
	ds_read_b128 v[180:183], v146 offset:32768
	ds_read_b128 v[184:187], v146 offset:33792
	ds_read_b128 v[188:191], v146 offset:34816
	ds_read_b128 v[196:199], v146 offset:35840
	ds_read_b128 v[200:203], v146 offset:36864
	ds_read_b128 v[204:207], v146 offset:37888
	ds_read_b128 v[208:211], v146 offset:38912
	ds_read_b128 v[212:215], v146 offset:39936
	s_mov_b32 m0, s58
	s_nop 0
	global_load_lds_dwordx4 v[218:219], off
	s_mov_b32 m0, s59
	s_nop 0
	global_load_lds_dwordx4 v[220:221], off
	s_mov_b32 m0, s60
	s_nop 0
	global_load_lds_dwordx4 v[222:223], off
	v_lshl_add_u64 v[222:223], s[34:35], 0, v[130:131]
	s_mov_b32 m0, s61
	s_nop 0
	global_load_lds_dwordx4 v[222:223], off
	s_waitcnt vmcnt(8)
	s_waitcnt lgkmcnt(0)
	s_barrier
	s_setprio 1
	s_waitcnt lgkmcnt(0)
	v_mfma_f32_16x16x32_bf16 v[124:127], v[148:151], v[180:183], v[124:127]
	v_mfma_f32_16x16x32_bf16 v[120:123], v[156:159], v[180:183], v[120:123]
	v_mfma_f32_16x16x32_bf16 v[116:119], v[148:151], v[188:191], v[116:119]
	v_mfma_f32_16x16x32_bf16 v[112:115], v[156:159], v[188:191], v[112:115]
	v_mfma_f32_16x16x32_bf16 v[104:107], v[148:151], v[200:203], v[104:107]
	v_mfma_f32_16x16x32_bf16 v[96:99], v[156:159], v[200:203], v[96:99]
	v_mfma_f32_16x16x32_bf16 v[88:91], v[148:151], v[208:211], v[88:91]
	v_mfma_f32_16x16x32_bf16 v[80:83], v[156:159], v[208:211], v[80:83]
	v_mfma_f32_16x16x32_bf16 v[124:127], v[152:155], v[184:187], v[124:127]
	v_mfma_f32_16x16x32_bf16 v[120:123], v[160:163], v[184:187], v[120:123]
	v_mfma_f32_16x16x32_bf16 v[116:119], v[152:155], v[196:199], v[116:119]
	v_mfma_f32_16x16x32_bf16 v[112:115], v[160:163], v[196:199], v[112:115]
	v_mfma_f32_16x16x32_bf16 v[104:107], v[152:155], v[204:207], v[104:107]
	v_mfma_f32_16x16x32_bf16 v[96:99], v[160:163], v[204:207], v[96:99]
	v_mfma_f32_16x16x32_bf16 v[88:91], v[152:155], v[212:215], v[88:91]
	v_mfma_f32_16x16x32_bf16 v[80:83], v[160:163], v[212:215], v[80:83]
	s_setprio 0
	s_setprio 1
	v_mfma_f32_16x16x32_bf16 v[108:111], v[164:167], v[180:183], v[108:111]
	v_mfma_f32_16x16x32_bf16 v[100:103], v[172:175], v[180:183], v[100:103]
	v_mfma_f32_16x16x32_bf16 v[92:95], v[164:167], v[188:191], v[92:95]
	v_mfma_f32_16x16x32_bf16 v[84:87], v[172:175], v[188:191], v[84:87]
	v_mfma_f32_16x16x32_bf16 v[76:79], v[164:167], v[200:203], v[76:79]
	v_mfma_f32_16x16x32_bf16 v[72:75], v[172:175], v[200:203], v[72:75]
	v_mfma_f32_16x16x32_bf16 v[68:71], v[164:167], v[208:211], v[68:71]
	v_mfma_f32_16x16x32_bf16 v[64:67], v[172:175], v[208:211], v[64:67]
	v_mfma_f32_16x16x32_bf16 v[108:111], v[168:171], v[184:187], v[108:111]
	v_mfma_f32_16x16x32_bf16 v[100:103], v[176:179], v[184:187], v[100:103]
	v_mfma_f32_16x16x32_bf16 v[92:95], v[168:171], v[196:199], v[92:95]
	v_mfma_f32_16x16x32_bf16 v[84:87], v[176:179], v[196:199], v[84:87]
	v_mfma_f32_16x16x32_bf16 v[76:79], v[168:171], v[204:207], v[76:79]
	v_mfma_f32_16x16x32_bf16 v[72:75], v[176:179], v[204:207], v[72:75]
	v_mfma_f32_16x16x32_bf16 v[68:71], v[168:171], v[212:215], v[68:71]
	v_mfma_f32_16x16x32_bf16 v[64:67], v[176:179], v[212:215], v[64:67]
	s_setprio 0
	s_barrier
	s_add_i32 s34, s84, s51
	v_lshl_add_u64 v[192:193], v[192:193], 0, s[10:11]
	s_mov_b32 m0, s34
	ds_read_b128 v[180:183], v146 offset:49152
	ds_read_b128 v[184:187], v146 offset:50176
	ds_read_b128 v[188:191], v146 offset:51200
	ds_read_b128 v[196:199], v146 offset:52224
	ds_read_b128 v[200:203], v146 offset:53248
	ds_read_b128 v[204:207], v146 offset:54272
	ds_read_b128 v[208:211], v146 offset:55296
	ds_read_b128 v[212:215], v146 offset:56320
	global_load_lds_dwordx4 v[192:193], off
	s_add_i32 m0, s34, 0x2000
	s_add_u32 s34, s38, 0x20080
	v_lshl_add_u64 v[192:193], v[216:217], 0, s[10:11]
	s_addc_u32 s35, s39, 0
	s_add_i32 s38, s85, s51
	global_load_lds_dwordx4 v[192:193], off
	v_lshl_add_u64 v[192:193], s[34:35], 0, v[132:133]
	s_mov_b32 m0, s38
	s_nop 0
	global_load_lds_dwordx4 v[192:193], off
	v_lshl_add_u64 v[192:193], s[34:35], 0, v[128:129]
	s_add_i32 m0, s38, 0x2000
	s_nop 0
	global_load_lds_dwordx4 v[192:193], off
	v_lshl_add_u64 v[192:193], v[218:219], 0, s[10:11]
	s_mov_b32 m0, s71
	s_nop 0
	global_load_lds_dwordx4 v[192:193], off
	v_lshl_add_u64 v[192:193], v[220:221], 0, s[10:11]
	s_mov_b32 m0, s72
	s_nop 0
	global_load_lds_dwordx4 v[192:193], off
	s_waitcnt vmcnt(8)
	s_waitcnt lgkmcnt(0)
	s_barrier
	s_setprio 1
	s_waitcnt lgkmcnt(0)
	v_mfma_f32_16x16x32_bf16 v[60:63], v[148:151], v[180:183], v[60:63]
	v_mfma_f32_16x16x32_bf16 v[56:59], v[156:159], v[180:183], v[56:59]
	v_mfma_f32_16x16x32_bf16 v[52:55], v[148:151], v[188:191], v[52:55]
	v_mfma_f32_16x16x32_bf16 v[48:51], v[156:159], v[188:191], v[48:51]
	v_mfma_f32_16x16x32_bf16 v[40:43], v[148:151], v[200:203], v[40:43]
	v_mfma_f32_16x16x32_bf16 v[32:35], v[156:159], v[200:203], v[32:35]
	v_mfma_f32_16x16x32_bf16 v[24:27], v[148:151], v[208:211], v[24:27]
	v_mfma_f32_16x16x32_bf16 v[16:19], v[156:159], v[208:211], v[16:19]
	v_mfma_f32_16x16x32_bf16 v[60:63], v[152:155], v[184:187], v[60:63]
	v_mfma_f32_16x16x32_bf16 v[56:59], v[160:163], v[184:187], v[56:59]
	v_mfma_f32_16x16x32_bf16 v[52:55], v[152:155], v[196:199], v[52:55]
	v_mfma_f32_16x16x32_bf16 v[48:51], v[160:163], v[196:199], v[48:51]
	v_mfma_f32_16x16x32_bf16 v[40:43], v[152:155], v[204:207], v[40:43]
	v_mfma_f32_16x16x32_bf16 v[32:35], v[160:163], v[204:207], v[32:35]
	v_mfma_f32_16x16x32_bf16 v[24:27], v[152:155], v[212:215], v[24:27]
	v_mfma_f32_16x16x32_bf16 v[16:19], v[160:163], v[212:215], v[16:19]
	s_setprio 0
	s_setprio 1
	v_mfma_f32_16x16x32_bf16 v[44:47], v[164:167], v[180:183], v[44:47]
	v_mfma_f32_16x16x32_bf16 v[36:39], v[172:175], v[180:183], v[36:39]
	v_mfma_f32_16x16x32_bf16 v[28:31], v[164:167], v[188:191], v[28:31]
	v_mfma_f32_16x16x32_bf16 v[20:23], v[172:175], v[188:191], v[20:23]
	v_mfma_f32_16x16x32_bf16 v[12:15], v[164:167], v[200:203], v[12:15]
	v_mfma_f32_16x16x32_bf16 v[8:11], v[172:175], v[200:203], v[8:11]
	v_mfma_f32_16x16x32_bf16 v[4:7], v[164:167], v[208:211], v[4:7]
	v_mfma_f32_16x16x32_bf16 v[0:3], v[172:175], v[208:211], v[0:3]
	v_mfma_f32_16x16x32_bf16 v[44:47], v[168:171], v[184:187], v[44:47]
	v_mfma_f32_16x16x32_bf16 v[36:39], v[176:179], v[184:187], v[36:39]
	v_mfma_f32_16x16x32_bf16 v[28:31], v[168:171], v[196:199], v[28:31]
	v_mfma_f32_16x16x32_bf16 v[20:23], v[176:179], v[196:199], v[20:23]
	v_mfma_f32_16x16x32_bf16 v[12:15], v[168:171], v[204:207], v[12:15]
	v_mfma_f32_16x16x32_bf16 v[8:11], v[176:179], v[204:207], v[8:11]
	v_mfma_f32_16x16x32_bf16 v[4:7], v[168:171], v[212:215], v[4:7]
	v_mfma_f32_16x16x32_bf16 v[0:3], v[176:179], v[212:215], v[0:3]
	s_setprio 0
	s_barrier
	s_add_i32 s83, s83, 2
	s_add_u32 s13, s13, 0x100
	s_addc_u32 s25, s25, 0
	s_cmp_gt_u32 s83, 5
	s_mov_b64 s[34:35], s[36:37]
	s_cbranch_scc0 .LBB0_760
	s_and_b64 vcc, exec, s[16:17]
	s_cbranch_vccz .LBB0_763
	s_barrier

.LBB0_786:
	ds_read_b128 v[144:147], v153
	ds_read_b128 v[158:161], v153 offset:1024
	ds_read_b128 v[162:165], v153 offset:2048
	ds_read_b128 v[166:169], v153 offset:3072
	ds_read_b128 v[170:173], v154
	ds_read_b128 v[174:177], v154 offset:1024
	ds_read_b128 v[178:181], v154 offset:2048
	ds_read_b128 v[182:185], v154 offset:3072
	s_add_u32 s34, s30, 0xfffc0080
	s_addc_u32 s35, s31, -1
	s_cmp_eq_u32 s82, 12
	s_cselect_b32 s37, s25, s35
	s_cselect_b32 s36, s78, s34
	s_cselect_b32 s35, s23, s81
	s_cselect_b32 s34, s79, s80
	v_lshl_add_u64 v[148:149], s[30:31], 0, v[136:137]
	s_add_i32 m0, s50, 0xc000
	ds_read_b128 v[186:189], v155
	ds_read_b128 v[190:193], v155 offset:1024
	ds_read_b128 v[196:199], v155 offset:2048
	ds_read_b128 v[200:203], v155 offset:3072
	ds_read_b128 v[204:207], v155 offset:4096
	ds_read_b128 v[208:211], v155 offset:5120
	ds_read_b128 v[212:215], v155 offset:6144
	ds_read_b128 v[216:219], v155 offset:7168
	global_load_lds_dwordx4 v[148:149], off
	v_lshl_add_u64 v[148:149], s[30:31], 0, v[138:139]
	s_add_i32 m0, s50, 0xe000
	s_nop 0
	global_load_lds_dwordx4 v[148:149], off
	s_waitcnt vmcnt(8)
	s_waitcnt lgkmcnt(0)
	s_barrier
	s_setprio 1
	s_waitcnt lgkmcnt(0)
	v_mfma_f32_16x16x32_bf16 v[124:127], v[144:147], v[186:189], v[124:127]
	v_mfma_f32_16x16x32_bf16 v[120:123], v[162:165], v[186:189], v[120:123]
	v_mfma_f32_16x16x32_bf16 v[108:111], v[144:147], v[196:199], v[108:111]
	v_mfma_f32_16x16x32_bf16 v[104:107], v[162:165], v[196:199], v[104:107]
	v_mfma_f32_16x16x32_bf16 v[92:95], v[144:147], v[204:207], v[92:95]
	v_mfma_f32_16x16x32_bf16 v[88:91], v[162:165], v[204:207], v[88:91]
	v_mfma_f32_16x16x32_bf16 v[76:79], v[144:147], v[212:215], v[76:79]
	v_mfma_f32_16x16x32_bf16 v[72:75], v[162:165], v[212:215], v[72:75]
	v_mfma_f32_16x16x32_bf16 v[124:127], v[158:161], v[190:193], v[124:127]
	v_mfma_f32_16x16x32_bf16 v[120:123], v[166:169], v[190:193], v[120:123]
	v_mfma_f32_16x16x32_bf16 v[108:111], v[158:161], v[200:203], v[108:111]
	v_mfma_f32_16x16x32_bf16 v[104:107], v[166:169], v[200:203], v[104:107]
	v_mfma_f32_16x16x32_bf16 v[92:95], v[158:161], v[208:211], v[92:95]
	v_mfma_f32_16x16x32_bf16 v[88:91], v[166:169], v[208:211], v[88:91]
	v_mfma_f32_16x16x32_bf16 v[76:79], v[158:161], v[216:219], v[76:79]
	v_mfma_f32_16x16x32_bf16 v[72:75], v[166:169], v[216:219], v[72:75]
	s_setprio 0
	s_setprio 1
	v_mfma_f32_16x16x32_bf16 v[116:119], v[170:173], v[186:189], v[116:119]
	v_mfma_f32_16x16x32_bf16 v[112:115], v[178:181], v[186:189], v[112:115]
	v_mfma_f32_16x16x32_bf16 v[100:103], v[170:173], v[196:199], v[100:103]
	v_mfma_f32_16x16x32_bf16 v[96:99], v[178:181], v[196:199], v[96:99]
	v_mfma_f32_16x16x32_bf16 v[84:87], v[170:173], v[204:207], v[84:87]
	v_mfma_f32_16x16x32_bf16 v[80:83], v[178:181], v[204:207], v[80:83]
	v_mfma_f32_16x16x32_bf16 v[68:71], v[170:173], v[212:215], v[68:71]
	v_mfma_f32_16x16x32_bf16 v[64:67], v[178:181], v[212:215], v[64:67]
	v_mfma_f32_16x16x32_bf16 v[116:119], v[174:177], v[190:193], v[116:119]
	v_mfma_f32_16x16x32_bf16 v[112:115], v[182:185], v[190:193], v[112:115]
	v_mfma_f32_16x16x32_bf16 v[100:103], v[174:177], v[200:203], v[100:103]
	v_mfma_f32_16x16x32_bf16 v[96:99], v[182:185], v[200:203], v[96:99]
	v_mfma_f32_16x16x32_bf16 v[84:87], v[174:177], v[208:211], v[84:87]
	v_mfma_f32_16x16x32_bf16 v[80:83], v[182:185], v[208:211], v[80:83]
	v_mfma_f32_16x16x32_bf16 v[68:71], v[174:177], v[216:219], v[68:71]
	v_mfma_f32_16x16x32_bf16 v[64:67], v[182:185], v[216:219], v[64:67]
	s_setprio 0
	s_barrier
	s_add_i32 s83, s70, s45
	v_lshl_add_u64 v[148:149], s[34:35], 0, v[130:131]
	s_mov_b32 m0, s83
	ds_read_b128 v[186:189], v155 offset:16384
	ds_read_b128 v[190:193], v155 offset:17408
	ds_read_b128 v[196:199], v155 offset:18432
	ds_read_b128 v[200:203], v155 offset:19456
	ds_read_b128 v[204:207], v155 offset:20480
	ds_read_b128 v[208:211], v155 offset:21504
	ds_read_b128 v[212:215], v155 offset:22528
	ds_read_b128 v[216:219], v155 offset:23552
	global_load_lds_dwordx4 v[148:149], off
	s_add_i32 m0, s83, 0x2000
	s_add_u32 s84, s34, 0x40000
	v_lshl_add_u64 v[220:221], s[34:35], 0, v[134:135]
	s_addc_u32 s85, s35, 0
	s_add_i32 s83, s71, s45
	global_load_lds_dwordx4 v[220:221], off
	v_lshl_add_u64 v[222:223], s[84:85], 0, v[130:131]
	s_mov_b32 m0, s83
	v_lshl_add_u64 v[224:225], s[36:37], 0, v[132:133]
	global_load_lds_dwordx4 v[222:223], off
	v_lshl_add_u64 v[222:223], s[84:85], 0, v[134:135]
	s_add_i32 m0, s83, 0x2000
	s_nop 0
	global_load_lds_dwordx4 v[222:223], off
	v_lshl_add_u64 v[222:223], s[36:37], 0, v[128:129]
	s_waitcnt vmcnt(6)
	s_waitcnt lgkmcnt(0)
	s_barrier
	s_setprio 1
	s_waitcnt lgkmcnt(0)
	v_mfma_f32_16x16x32_bf16 v[60:63], v[144:147], v[186:189], v[60:63]
	v_mfma_f32_16x16x32_bf16 v[56:59], v[162:165], v[186:189], v[56:59]
	v_mfma_f32_16x16x32_bf16 v[44:47], v[144:147], v[196:199], v[44:47]
	v_mfma_f32_16x16x32_bf16 v[40:43], v[162:165], v[196:199], v[40:43]
	v_mfma_f32_16x16x32_bf16 v[28:31], v[144:147], v[204:207], v[28:31]
	v_mfma_f32_16x16x32_bf16 v[24:27], v[162:165], v[204:207], v[24:27]
	v_mfma_f32_16x16x32_bf16 v[12:15], v[144:147], v[212:215], v[12:15]
	v_mfma_f32_16x16x32_bf16 v[8:11], v[162:165], v[212:215], v[8:11]
	v_mfma_f32_16x16x32_bf16 v[60:63], v[158:161], v[190:193], v[60:63]
	v_mfma_f32_16x16x32_bf16 v[56:59], v[166:169], v[190:193], v[56:59]
	v_mfma_f32_16x16x32_bf16 v[44:47], v[158:161], v[200:203], v[44:47]
	v_mfma_f32_16x16x32_bf16 v[40:43], v[166:169], v[200:203], v[40:43]
	v_mfma_f32_16x16x32_bf16 v[28:31], v[158:161], v[208:211], v[28:31]
	v_mfma_f32_16x16x32_bf16 v[24:27], v[166:169], v[208:211], v[24:27]
	v_mfma_f32_16x16x32_bf16 v[12:15], v[158:161], v[216:219], v[12:15]
	v_mfma_f32_16x16x32_bf16 v[8:11], v[166:169], v[216:219], v[8:11]
	s_setprio 0
	s_setprio 1
	v_mfma_f32_16x16x32_bf16 v[52:55], v[170:173], v[186:189], v[52:55]
	v_mfma_f32_16x16x32_bf16 v[48:51], v[178:181], v[186:189], v[48:51]
	v_mfma_f32_16x16x32_bf16 v[36:39], v[170:173], v[196:199], v[36:39]
	v_mfma_f32_16x16x32_bf16 v[32:35], v[178:181], v[196:199], v[32:35]
	v_mfma_f32_16x16x32_bf16 v[20:23], v[170:173], v[204:207], v[20:23]
	v_mfma_f32_16x16x32_bf16 v[16:19], v[178:181], v[204:207], v[16:19]
	v_mfma_f32_16x16x32_bf16 v[4:7], v[170:173], v[212:215], v[4:7]
	v_mfma_f32_16x16x32_bf16 v[0:3], v[178:181], v[212:215], v[0:3]
	v_mfma_f32_16x16x32_bf16 v[52:55], v[174:177], v[190:193], v[52:55]
	v_mfma_f32_16x16x32_bf16 v[48:51], v[182:185], v[190:193], v[48:51]
	v_mfma_f32_16x16x32_bf16 v[36:39], v[174:177], v[200:203], v[36:39]
	v_mfma_f32_16x16x32_bf16 v[32:35], v[182:185], v[200:203], v[32:35]
	v_mfma_f32_16x16x32_bf16 v[20:23], v[174:177], v[208:211], v[20:23]
	v_mfma_f32_16x16x32_bf16 v[16:19], v[182:185], v[208:211], v[16:19]
	v_mfma_f32_16x16x32_bf16 v[4:7], v[174:177], v[216:219], v[4:7]
	v_mfma_f32_16x16x32_bf16 v[0:3], v[182:185], v[216:219], v[0:3]
	s_setprio 0
	s_barrier
	s_add_i32 s83, 0, 0x18000
	v_add_u32_e32 v157, s83, v151
	s_add_i32 s84, 0, 0x1c000
	ds_read_b128 v[144:147], v157
	ds_read_b128 v[158:161], v157 offset:1024
	ds_read_b128 v[162:165], v157 offset:2048
	ds_read_b128 v[166:169], v157 offset:3072
	v_add_u32_e32 v157, s84, v151
	ds_read_b128 v[170:173], v157
	ds_read_b128 v[174:177], v157 offset:1024
	ds_read_b128 v[178:181], v157 offset:2048
	ds_read_b128 v[182:185], v157 offset:3072
	s_add_u32 s36, s36, 0x40000
	s_addc_u32 s37, s37, 0
	v_lshl_add_u64 v[226:227], s[36:37], 0, v[128:129]
	ds_read_b128 v[186:189], v155 offset:32768
	ds_read_b128 v[190:193], v155 offset:33792
	ds_read_b128 v[196:199], v155 offset:34816
	ds_read_b128 v[200:203], v155 offset:35840
	ds_read_b128 v[204:207], v155 offset:36864
	ds_read_b128 v[208:211], v155 offset:37888
	ds_read_b128 v[212:215], v155 offset:38912
	ds_read_b128 v[216:219], v155 offset:39936
	s_mov_b32 m0, s50
	s_nop 0
	global_load_lds_dwordx4 v[222:223], off
	s_mov_b32 m0, s51
	s_nop 0
	global_load_lds_dwordx4 v[224:225], off
	s_mov_b32 m0, s58
	s_nop 0
	global_load_lds_dwordx4 v[226:227], off
	v_lshl_add_u64 v[226:227], s[36:37], 0, v[132:133]
	s_mov_b32 m0, s59
	s_nop 0
	global_load_lds_dwordx4 v[226:227], off
	s_waitcnt vmcnt(8)
	s_waitcnt lgkmcnt(0)
	s_barrier
	s_setprio 1
	s_waitcnt lgkmcnt(0)
	v_mfma_f32_16x16x32_bf16 v[124:127], v[144:147], v[186:189], v[124:127]
	v_mfma_f32_16x16x32_bf16 v[120:123], v[162:165], v[186:189], v[120:123]
	v_mfma_f32_16x16x32_bf16 v[108:111], v[144:147], v[196:199], v[108:111]
	v_mfma_f32_16x16x32_bf16 v[104:107], v[162:165], v[196:199], v[104:107]
	v_mfma_f32_16x16x32_bf16 v[92:95], v[144:147], v[204:207], v[92:95]
	v_mfma_f32_16x16x32_bf16 v[88:91], v[162:165], v[204:207], v[88:91]
	v_mfma_f32_16x16x32_bf16 v[76:79], v[144:147], v[212:215], v[76:79]
	v_mfma_f32_16x16x32_bf16 v[72:75], v[162:165], v[212:215], v[72:75]
	v_mfma_f32_16x16x32_bf16 v[124:127], v[158:161], v[190:193], v[124:127]
	v_mfma_f32_16x16x32_bf16 v[120:123], v[166:169], v[190:193], v[120:123]
	v_mfma_f32_16x16x32_bf16 v[108:111], v[158:161], v[200:203], v[108:111]
	v_mfma_f32_16x16x32_bf16 v[104:107], v[166:169], v[200:203], v[104:107]
	v_mfma_f32_16x16x32_bf16 v[92:95], v[158:161], v[208:211], v[92:95]
	v_mfma_f32_16x16x32_bf16 v[88:91], v[166:169], v[208:211], v[88:91]
	v_mfma_f32_16x16x32_bf16 v[76:79], v[158:161], v[216:219], v[76:79]
	v_mfma_f32_16x16x32_bf16 v[72:75], v[166:169], v[216:219], v[72:75]
	s_setprio 0
	s_setprio 1
	v_mfma_f32_16x16x32_bf16 v[116:119], v[170:173], v[186:189], v[116:119]
	v_mfma_f32_16x16x32_bf16 v[112:115], v[178:181], v[186:189], v[112:115]
	v_mfma_f32_16x16x32_bf16 v[100:103], v[170:173], v[196:199], v[100:103]
	v_mfma_f32_16x16x32_bf16 v[96:99], v[178:181], v[196:199], v[96:99]
	v_mfma_f32_16x16x32_bf16 v[84:87], v[170:173], v[204:207], v[84:87]
	v_mfma_f32_16x16x32_bf16 v[80:83], v[178:181], v[204:207], v[80:83]
	v_mfma_f32_16x16x32_bf16 v[68:71], v[170:173], v[212:215], v[68:71]
	v_mfma_f32_16x16x32_bf16 v[64:67], v[178:181], v[212:215], v[64:67]
	v_mfma_f32_16x16x32_bf16 v[116:119], v[174:177], v[190:193], v[116:119]
	v_mfma_f32_16x16x32_bf16 v[112:115], v[182:185], v[190:193], v[112:115]
	v_mfma_f32_16x16x32_bf16 v[100:103], v[174:177], v[200:203], v[100:103]
	v_mfma_f32_16x16x32_bf16 v[96:99], v[182:185], v[200:203], v[96:99]
	v_mfma_f32_16x16x32_bf16 v[84:87], v[174:177], v[208:211], v[84:87]
	v_mfma_f32_16x16x32_bf16 v[80:83], v[182:185], v[208:211], v[80:83]
	v_mfma_f32_16x16x32_bf16 v[68:71], v[174:177], v[216:219], v[68:71]
	v_mfma_f32_16x16x32_bf16 v[64:67], v[182:185], v[216:219], v[64:67]
	s_setprio 0
	s_barrier
	s_add_i32 s36, s83, s45
	v_lshl_add_u64 v[148:149], v[148:149], 0, s[18:19]
	s_mov_b32 m0, s36
	ds_read_b128 v[186:189], v155 offset:49152
	ds_read_b128 v[190:193], v155 offset:50176
	ds_read_b128 v[196:199], v155 offset:51200
	ds_read_b128 v[200:203], v155 offset:52224
	ds_read_b128 v[204:207], v155 offset:53248
	ds_read_b128 v[208:211], v155 offset:54272
	ds_read_b128 v[212:215], v155 offset:55296
	ds_read_b128 v[216:219], v155 offset:56320
	global_load_lds_dwordx4 v[148:149], off
	s_add_i32 m0, s36, 0x2000
	s_add_u32 s34, s34, 0x40080
	v_lshl_add_u64 v[148:149], v[220:221], 0, s[18:19]
	s_addc_u32 s35, s35, 0
	s_add_i32 s36, s84, s45
	global_load_lds_dwordx4 v[148:149], off
	v_lshl_add_u64 v[148:149], s[34:35], 0, v[130:131]
	s_mov_b32 m0, s36
	s_nop 0
	global_load_lds_dwordx4 v[148:149], off
	v_lshl_add_u64 v[148:149], s[34:35], 0, v[134:135]
	s_add_i32 m0, s36, 0x2000
	s_nop 0
	global_load_lds_dwordx4 v[148:149], off
	v_lshl_add_u64 v[148:149], v[222:223], 0, s[18:19]
	s_mov_b32 m0, s61
	s_nop 0
	global_load_lds_dwordx4 v[148:149], off
	v_lshl_add_u64 v[148:149], v[224:225], 0, s[18:19]
	s_mov_b32 m0, s62
	s_nop 0
	global_load_lds_dwordx4 v[148:149], off
	s_waitcnt vmcnt(8)
	s_waitcnt lgkmcnt(0)
	s_barrier
	s_setprio 1
	s_waitcnt lgkmcnt(0)
	v_mfma_f32_16x16x32_bf16 v[60:63], v[144:147], v[186:189], v[60:63]
	v_mfma_f32_16x16x32_bf16 v[56:59], v[162:165], v[186:189], v[56:59]
	v_mfma_f32_16x16x32_bf16 v[44:47], v[144:147], v[196:199], v[44:47]
	v_mfma_f32_16x16x32_bf16 v[40:43], v[162:165], v[196:199], v[40:43]
	v_mfma_f32_16x16x32_bf16 v[28:31], v[144:147], v[204:207], v[28:31]
	v_mfma_f32_16x16x32_bf16 v[24:27], v[162:165], v[204:207], v[24:27]
	v_mfma_f32_16x16x32_bf16 v[12:15], v[144:147], v[212:215], v[12:15]
	v_mfma_f32_16x16x32_bf16 v[8:11], v[162:165], v[212:215], v[8:11]
	v_mfma_f32_16x16x32_bf16 v[60:63], v[158:161], v[190:193], v[60:63]
	v_mfma_f32_16x16x32_bf16 v[56:59], v[166:169], v[190:193], v[56:59]
	v_mfma_f32_16x16x32_bf16 v[44:47], v[158:161], v[200:203], v[44:47]
	v_mfma_f32_16x16x32_bf16 v[40:43], v[166:169], v[200:203], v[40:43]
	v_mfma_f32_16x16x32_bf16 v[28:31], v[158:161], v[208:211], v[28:31]
	v_mfma_f32_16x16x32_bf16 v[24:27], v[166:169], v[208:211], v[24:27]
	v_mfma_f32_16x16x32_bf16 v[12:15], v[158:161], v[216:219], v[12:15]
	v_mfma_f32_16x16x32_bf16 v[8:11], v[166:169], v[216:219], v[8:11]
	s_setprio 0
	s_setprio 1
	v_mfma_f32_16x16x32_bf16 v[52:55], v[170:173], v[186:189], v[52:55]
	v_mfma_f32_16x16x32_bf16 v[48:51], v[178:181], v[186:189], v[48:51]
	v_mfma_f32_16x16x32_bf16 v[36:39], v[170:173], v[196:199], v[36:39]
	v_mfma_f32_16x16x32_bf16 v[32:35], v[178:181], v[196:199], v[32:35]
	v_mfma_f32_16x16x32_bf16 v[20:23], v[170:173], v[204:207], v[20:23]
	v_mfma_f32_16x16x32_bf16 v[16:19], v[178:181], v[204:207], v[16:19]
	v_mfma_f32_16x16x32_bf16 v[4:7], v[170:173], v[212:215], v[4:7]
	v_mfma_f32_16x16x32_bf16 v[0:3], v[178:181], v[212:215], v[0:3]
	v_mfma_f32_16x16x32_bf16 v[52:55], v[174:177], v[190:193], v[52:55]
	v_mfma_f32_16x16x32_bf16 v[48:51], v[182:185], v[190:193], v[48:51]
	v_mfma_f32_16x16x32_bf16 v[36:39], v[174:177], v[200:203], v[36:39]
	v_mfma_f32_16x16x32_bf16 v[32:35], v[182:185], v[200:203], v[32:35]
	v_mfma_f32_16x16x32_bf16 v[20:23], v[174:177], v[208:211], v[20:23]
	v_mfma_f32_16x16x32_bf16 v[16:19], v[182:185], v[208:211], v[16:19]
	v_mfma_f32_16x16x32_bf16 v[4:7], v[174:177], v[216:219], v[4:7]
	v_mfma_f32_16x16x32_bf16 v[0:3], v[182:185], v[216:219], v[0:3]
	s_setprio 0
	s_barrier
	s_add_i32 s82, s82, 2
	s_add_u32 s30, s30, 0x100
	s_addc_u32 s31, s31, 0
	s_add_u32 s80, s80, 0x100
	s_addc_u32 s81, s81, 0
	s_cmp_gt_u32 s82, 13
	s_cbranch_scc0 .LBB0_786
	s_and_b64 vcc, exec, s[20:21]
	s_cbranch_vccz .LBB0_789
	s_barrier

.LBB0_923:
	ds_read_b128 v[152:155], v148
	ds_read_b128 v[156:159], v148 offset:1024
	ds_read_b128 v[160:163], v148 offset:2048
	ds_read_b128 v[164:167], v148 offset:3072
	ds_read_b128 v[168:171], v149
	ds_read_b128 v[172:175], v149 offset:1024
	ds_read_b128 v[176:179], v149 offset:2048
	ds_read_b128 v[180:183], v149 offset:3072
	s_add_u32 s26, s24, 0x100
	s_addc_u32 s27, s25, 0
	s_cmp_eq_u32 s79, 8
	s_cselect_b32 s31, s21, s27
	s_cselect_b32 s30, s20, s26
	s_cselect_b32 s29, s23, s78
	s_cselect_b32 s28, s22, s73
	s_mov_b32 m0, s60
	v_lshl_add_u64 v[192:193], s[24:25], 0, v[138:139]
	ds_read_b128 v[184:187], v150
	ds_read_b128 v[188:191], v150 offset:1024
	ds_read_b128 v[196:199], v150 offset:2048
	ds_read_b128 v[200:203], v150 offset:3072
	ds_read_b128 v[204:207], v150 offset:4096
	ds_read_b128 v[208:211], v150 offset:5120
	ds_read_b128 v[212:215], v150 offset:6144
	ds_read_b128 v[216:219], v150 offset:7168
	global_load_lds_dwordx4 v[192:193], off
	v_lshl_add_u64 v[192:193], s[24:25], 0, v[140:141]
	s_add_i32 m0, s40, 0xe000
	s_nop 0
	global_load_lds_dwordx4 v[192:193], off
	s_waitcnt vmcnt(8)
	s_waitcnt lgkmcnt(0)
	s_barrier
	s_setprio 1
	s_waitcnt lgkmcnt(0)
	v_mfma_f32_16x16x32_bf16 v[124:127], v[152:155], v[184:187], v[124:127]
	v_mfma_f32_16x16x32_bf16 v[120:123], v[160:163], v[184:187], v[120:123]
	v_mfma_f32_16x16x32_bf16 v[108:111], v[152:155], v[196:199], v[108:111]
	v_mfma_f32_16x16x32_bf16 v[104:107], v[160:163], v[196:199], v[104:107]
	v_mfma_f32_16x16x32_bf16 v[92:95], v[152:155], v[204:207], v[92:95]
	v_mfma_f32_16x16x32_bf16 v[88:91], v[160:163], v[204:207], v[88:91]
	v_mfma_f32_16x16x32_bf16 v[76:79], v[152:155], v[212:215], v[76:79]
	v_mfma_f32_16x16x32_bf16 v[72:75], v[160:163], v[212:215], v[72:75]
	v_mfma_f32_16x16x32_bf16 v[124:127], v[156:159], v[188:191], v[124:127]
	v_mfma_f32_16x16x32_bf16 v[120:123], v[164:167], v[188:191], v[120:123]
	v_mfma_f32_16x16x32_bf16 v[108:111], v[156:159], v[200:203], v[108:111]
	v_mfma_f32_16x16x32_bf16 v[104:107], v[164:167], v[200:203], v[104:107]
	v_mfma_f32_16x16x32_bf16 v[92:95], v[156:159], v[208:211], v[92:95]
	v_mfma_f32_16x16x32_bf16 v[88:91], v[164:167], v[208:211], v[88:91]
	v_mfma_f32_16x16x32_bf16 v[76:79], v[156:159], v[216:219], v[76:79]
	v_mfma_f32_16x16x32_bf16 v[72:75], v[164:167], v[216:219], v[72:75]
	s_setprio 0
	s_setprio 1
	v_mfma_f32_16x16x32_bf16 v[116:119], v[168:171], v[184:187], v[116:119]
	v_mfma_f32_16x16x32_bf16 v[112:115], v[176:179], v[184:187], v[112:115]
	v_mfma_f32_16x16x32_bf16 v[100:103], v[168:171], v[196:199], v[100:103]
	v_mfma_f32_16x16x32_bf16 v[96:99], v[176:179], v[196:199], v[96:99]
	v_mfma_f32_16x16x32_bf16 v[84:87], v[168:171], v[204:207], v[84:87]
	v_mfma_f32_16x16x32_bf16 v[80:83], v[176:179], v[204:207], v[80:83]
	v_mfma_f32_16x16x32_bf16 v[68:71], v[168:171], v[212:215], v[68:71]
	v_mfma_f32_16x16x32_bf16 v[64:67], v[176:179], v[212:215], v[64:67]
	v_mfma_f32_16x16x32_bf16 v[116:119], v[172:175], v[188:191], v[116:119]
	v_mfma_f32_16x16x32_bf16 v[112:115], v[180:183], v[188:191], v[112:115]
	v_mfma_f32_16x16x32_bf16 v[100:103], v[172:175], v[200:203], v[100:103]
	v_mfma_f32_16x16x32_bf16 v[96:99], v[180:183], v[200:203], v[96:99]
	v_mfma_f32_16x16x32_bf16 v[84:87], v[172:175], v[208:211], v[84:87]
	v_mfma_f32_16x16x32_bf16 v[80:83], v[180:183], v[208:211], v[80:83]
	v_mfma_f32_16x16x32_bf16 v[68:71], v[172:175], v[216:219], v[68:71]
	v_mfma_f32_16x16x32_bf16 v[64:67], v[180:183], v[216:219], v[64:67]
	s_setprio 0
	s_barrier
	s_add_i32 s24, s58, s39
	v_lshl_add_u64 v[192:193], s[28:29], 0, v[132:133]
	s_mov_b32 m0, s24
	ds_read_b128 v[184:187], v150 offset:16384
	ds_read_b128 v[188:191], v150 offset:17408
	ds_read_b128 v[196:199], v150 offset:18432
	ds_read_b128 v[200:203], v150 offset:19456
	ds_read_b128 v[204:207], v150 offset:20480
	ds_read_b128 v[208:211], v150 offset:21504
	ds_read_b128 v[212:215], v150 offset:22528
	ds_read_b128 v[216:219], v150 offset:23552
	global_load_lds_dwordx4 v[192:193], off
	s_add_i32 m0, s24, 0x2000
	s_add_u32 s24, s28, 0x30000
	v_lshl_add_u64 v[220:221], s[28:29], 0, v[128:129]
	s_addc_u32 s25, s29, 0
	s_add_i32 s80, s59, s39
	global_load_lds_dwordx4 v[220:221], off
	v_lshl_add_u64 v[222:223], s[24:25], 0, v[132:133]
	s_mov_b32 m0, s80
	v_lshl_add_u64 v[224:225], s[30:31], 0, v[130:131]
	global_load_lds_dwordx4 v[222:223], off
	v_lshl_add_u64 v[222:223], s[24:25], 0, v[128:129]
	s_add_i32 m0, s80, 0x2000
	s_nop 0
	global_load_lds_dwordx4 v[222:223], off
	v_lshl_add_u64 v[222:223], s[30:31], 0, v[134:135]
	s_waitcnt vmcnt(6)
	s_waitcnt lgkmcnt(0)
	s_barrier
	s_setprio 1
	s_waitcnt lgkmcnt(0)
	v_mfma_f32_16x16x32_bf16 v[60:63], v[152:155], v[184:187], v[60:63]
	v_mfma_f32_16x16x32_bf16 v[56:59], v[160:163], v[184:187], v[56:59]
	v_mfma_f32_16x16x32_bf16 v[44:47], v[152:155], v[196:199], v[44:47]
	v_mfma_f32_16x16x32_bf16 v[40:43], v[160:163], v[196:199], v[40:43]
	v_mfma_f32_16x16x32_bf16 v[28:31], v[152:155], v[204:207], v[28:31]
	v_mfma_f32_16x16x32_bf16 v[24:27], v[160:163], v[204:207], v[24:27]
	v_mfma_f32_16x16x32_bf16 v[12:15], v[152:155], v[212:215], v[12:15]
	v_mfma_f32_16x16x32_bf16 v[8:11], v[160:163], v[212:215], v[8:11]
	v_mfma_f32_16x16x32_bf16 v[60:63], v[156:159], v[188:191], v[60:63]
	v_mfma_f32_16x16x32_bf16 v[56:59], v[164:167], v[188:191], v[56:59]
	v_mfma_f32_16x16x32_bf16 v[44:47], v[156:159], v[200:203], v[44:47]
	v_mfma_f32_16x16x32_bf16 v[40:43], v[164:167], v[200:203], v[40:43]
	v_mfma_f32_16x16x32_bf16 v[28:31], v[156:159], v[208:211], v[28:31]
	v_mfma_f32_16x16x32_bf16 v[24:27], v[164:167], v[208:211], v[24:27]
	v_mfma_f32_16x16x32_bf16 v[12:15], v[156:159], v[216:219], v[12:15]
	v_mfma_f32_16x16x32_bf16 v[8:11], v[164:167], v[216:219], v[8:11]
	s_setprio 0
	s_setprio 1
	v_mfma_f32_16x16x32_bf16 v[52:55], v[168:171], v[184:187], v[52:55]
	v_mfma_f32_16x16x32_bf16 v[48:51], v[176:179], v[184:187], v[48:51]
	v_mfma_f32_16x16x32_bf16 v[36:39], v[168:171], v[196:199], v[36:39]
	v_mfma_f32_16x16x32_bf16 v[32:35], v[176:179], v[196:199], v[32:35]
	v_mfma_f32_16x16x32_bf16 v[20:23], v[168:171], v[204:207], v[20:23]
	v_mfma_f32_16x16x32_bf16 v[16:19], v[176:179], v[204:207], v[16:19]
	v_mfma_f32_16x16x32_bf16 v[4:7], v[168:171], v[212:215], v[4:7]
	v_mfma_f32_16x16x32_bf16 v[0:3], v[176:179], v[212:215], v[0:3]
	v_mfma_f32_16x16x32_bf16 v[52:55], v[172:175], v[188:191], v[52:55]
	v_mfma_f32_16x16x32_bf16 v[48:51], v[180:183], v[188:191], v[48:51]
	v_mfma_f32_16x16x32_bf16 v[36:39], v[172:175], v[200:203], v[36:39]
	v_mfma_f32_16x16x32_bf16 v[32:35], v[180:183], v[200:203], v[32:35]
	v_mfma_f32_16x16x32_bf16 v[20:23], v[172:175], v[208:211], v[20:23]
	v_mfma_f32_16x16x32_bf16 v[16:19], v[180:183], v[208:211], v[16:19]
	v_mfma_f32_16x16x32_bf16 v[4:7], v[172:175], v[216:219], v[4:7]
	v_mfma_f32_16x16x32_bf16 v[0:3], v[180:183], v[216:219], v[0:3]
	s_setprio 0
	s_barrier
	s_add_i32 s80, 0, 0x18000
	v_add_u32_e32 v151, s80, v142
	s_add_i32 s81, 0, 0x1c000
	ds_read_b128 v[152:155], v151
	ds_read_b128 v[156:159], v151 offset:1024
	ds_read_b128 v[160:163], v151 offset:2048
	ds_read_b128 v[164:167], v151 offset:3072
	v_add_u32_e32 v151, s81, v142
	ds_read_b128 v[168:171], v151
	ds_read_b128 v[172:175], v151 offset:1024
	ds_read_b128 v[176:179], v151 offset:2048
	ds_read_b128 v[180:183], v151 offset:3072
	s_add_u32 s24, s30, 0x30000
	s_addc_u32 s25, s31, 0
	v_lshl_add_u64 v[226:227], s[24:25], 0, v[134:135]
	ds_read_b128 v[184:187], v150 offset:32768
	ds_read_b128 v[188:191], v150 offset:33792
	ds_read_b128 v[196:199], v150 offset:34816
	ds_read_b128 v[200:203], v150 offset:35840
	ds_read_b128 v[204:207], v150 offset:36864
	ds_read_b128 v[208:211], v150 offset:37888
	ds_read_b128 v[212:215], v150 offset:38912
	ds_read_b128 v[216:219], v150 offset:39936
	s_mov_b32 m0, s40
	s_nop 0
	global_load_lds_dwordx4 v[222:223], off
	s_mov_b32 m0, s41
	s_nop 0
	global_load_lds_dwordx4 v[224:225], off
	s_mov_b32 m0, s42
	s_nop 0
	global_load_lds_dwordx4 v[226:227], off
	v_lshl_add_u64 v[226:227], s[24:25], 0, v[130:131]
	s_mov_b32 m0, s43
	s_nop 0
	global_load_lds_dwordx4 v[226:227], off
	s_waitcnt vmcnt(8)
	s_waitcnt lgkmcnt(0)
	s_barrier
	s_setprio 1
	s_waitcnt lgkmcnt(0)
	v_mfma_f32_16x16x32_bf16 v[124:127], v[152:155], v[184:187], v[124:127]
	v_mfma_f32_16x16x32_bf16 v[120:123], v[160:163], v[184:187], v[120:123]
	v_mfma_f32_16x16x32_bf16 v[108:111], v[152:155], v[196:199], v[108:111]
	v_mfma_f32_16x16x32_bf16 v[104:107], v[160:163], v[196:199], v[104:107]
	v_mfma_f32_16x16x32_bf16 v[92:95], v[152:155], v[204:207], v[92:95]
	v_mfma_f32_16x16x32_bf16 v[88:91], v[160:163], v[204:207], v[88:91]
	v_mfma_f32_16x16x32_bf16 v[76:79], v[152:155], v[212:215], v[76:79]
	v_mfma_f32_16x16x32_bf16 v[72:75], v[160:163], v[212:215], v[72:75]
	v_mfma_f32_16x16x32_bf16 v[124:127], v[156:159], v[188:191], v[124:127]
	v_mfma_f32_16x16x32_bf16 v[120:123], v[164:167], v[188:191], v[120:123]
	v_mfma_f32_16x16x32_bf16 v[108:111], v[156:159], v[200:203], v[108:111]
	v_mfma_f32_16x16x32_bf16 v[104:107], v[164:167], v[200:203], v[104:107]
	v_mfma_f32_16x16x32_bf16 v[92:95], v[156:159], v[208:211], v[92:95]
	v_mfma_f32_16x16x32_bf16 v[88:91], v[164:167], v[208:211], v[88:91]
	v_mfma_f32_16x16x32_bf16 v[76:79], v[156:159], v[216:219], v[76:79]
	v_mfma_f32_16x16x32_bf16 v[72:75], v[164:167], v[216:219], v[72:75]
	s_setprio 0
	s_setprio 1
	v_mfma_f32_16x16x32_bf16 v[116:119], v[168:171], v[184:187], v[116:119]
	v_mfma_f32_16x16x32_bf16 v[112:115], v[176:179], v[184:187], v[112:115]
	v_mfma_f32_16x16x32_bf16 v[100:103], v[168:171], v[196:199], v[100:103]
	v_mfma_f32_16x16x32_bf16 v[96:99], v[176:179], v[196:199], v[96:99]
	v_mfma_f32_16x16x32_bf16 v[84:87], v[168:171], v[204:207], v[84:87]
	v_mfma_f32_16x16x32_bf16 v[80:83], v[176:179], v[204:207], v[80:83]
	v_mfma_f32_16x16x32_bf16 v[68:71], v[168:171], v[212:215], v[68:71]
	v_mfma_f32_16x16x32_bf16 v[64:67], v[176:179], v[212:215], v[64:67]
	v_mfma_f32_16x16x32_bf16 v[116:119], v[172:175], v[188:191], v[116:119]
	v_mfma_f32_16x16x32_bf16 v[112:115], v[180:183], v[188:191], v[112:115]
	v_mfma_f32_16x16x32_bf16 v[100:103], v[172:175], v[200:203], v[100:103]
	v_mfma_f32_16x16x32_bf16 v[96:99], v[180:183], v[200:203], v[96:99]
	v_mfma_f32_16x16x32_bf16 v[84:87], v[172:175], v[208:211], v[84:87]
	v_mfma_f32_16x16x32_bf16 v[80:83], v[180:183], v[208:211], v[80:83]
	v_mfma_f32_16x16x32_bf16 v[68:71], v[172:175], v[216:219], v[68:71]
	v_mfma_f32_16x16x32_bf16 v[64:67], v[180:183], v[216:219], v[64:67]
	s_setprio 0
	s_barrier
	s_add_i32 s24, s80, s39
	v_lshl_add_u64 v[192:193], v[192:193], 0, s[16:17]
	s_mov_b32 m0, s24
	ds_read_b128 v[184:187], v150 offset:49152
	ds_read_b128 v[188:191], v150 offset:50176
	ds_read_b128 v[196:199], v150 offset:51200
	ds_read_b128 v[200:203], v150 offset:52224
	ds_read_b128 v[204:207], v150 offset:53248
	ds_read_b128 v[208:211], v150 offset:54272
	ds_read_b128 v[212:215], v150 offset:55296
	ds_read_b128 v[216:219], v150 offset:56320
	global_load_lds_dwordx4 v[192:193], off
	s_add_i32 m0, s24, 0x2000
	s_add_u32 s24, s28, 0x30080
	v_lshl_add_u64 v[192:193], v[220:221], 0, s[16:17]
	s_addc_u32 s25, s29, 0
	s_add_i32 s28, s81, s39
	global_load_lds_dwordx4 v[192:193], off
	v_lshl_add_u64 v[192:193], s[24:25], 0, v[132:133]
	s_mov_b32 m0, s28
	s_nop 0
	global_load_lds_dwordx4 v[192:193], off
	v_lshl_add_u64 v[192:193], s[24:25], 0, v[128:129]
	s_add_i32 m0, s28, 0x2000
	s_nop 0
	global_load_lds_dwordx4 v[192:193], off
	v_lshl_add_u64 v[192:193], v[222:223], 0, s[16:17]
	s_mov_b32 m0, s45
	s_nop 0
	global_load_lds_dwordx4 v[192:193], off
	v_lshl_add_u64 v[192:193], v[224:225], 0, s[16:17]
	s_mov_b32 m0, s50
	s_nop 0
	global_load_lds_dwordx4 v[192:193], off
	s_waitcnt vmcnt(8)
	s_waitcnt lgkmcnt(0)
	s_barrier
	s_setprio 1
	s_waitcnt lgkmcnt(0)
	v_mfma_f32_16x16x32_bf16 v[60:63], v[152:155], v[184:187], v[60:63]
	v_mfma_f32_16x16x32_bf16 v[56:59], v[160:163], v[184:187], v[56:59]
	v_mfma_f32_16x16x32_bf16 v[44:47], v[152:155], v[196:199], v[44:47]
	v_mfma_f32_16x16x32_bf16 v[40:43], v[160:163], v[196:199], v[40:43]
	v_mfma_f32_16x16x32_bf16 v[28:31], v[152:155], v[204:207], v[28:31]
	v_mfma_f32_16x16x32_bf16 v[24:27], v[160:163], v[204:207], v[24:27]
	v_mfma_f32_16x16x32_bf16 v[12:15], v[152:155], v[212:215], v[12:15]
	v_mfma_f32_16x16x32_bf16 v[8:11], v[160:163], v[212:215], v[8:11]
	v_mfma_f32_16x16x32_bf16 v[60:63], v[156:159], v[188:191], v[60:63]
	v_mfma_f32_16x16x32_bf16 v[56:59], v[164:167], v[188:191], v[56:59]
	v_mfma_f32_16x16x32_bf16 v[44:47], v[156:159], v[200:203], v[44:47]
	v_mfma_f32_16x16x32_bf16 v[40:43], v[164:167], v[200:203], v[40:43]
	v_mfma_f32_16x16x32_bf16 v[28:31], v[156:159], v[208:211], v[28:31]
	v_mfma_f32_16x16x32_bf16 v[24:27], v[164:167], v[208:211], v[24:27]
	v_mfma_f32_16x16x32_bf16 v[12:15], v[156:159], v[216:219], v[12:15]
	v_mfma_f32_16x16x32_bf16 v[8:11], v[164:167], v[216:219], v[8:11]
	s_setprio 0
	s_setprio 1
	v_mfma_f32_16x16x32_bf16 v[52:55], v[168:171], v[184:187], v[52:55]
	v_mfma_f32_16x16x32_bf16 v[48:51], v[176:179], v[184:187], v[48:51]
	v_mfma_f32_16x16x32_bf16 v[36:39], v[168:171], v[196:199], v[36:39]
	v_mfma_f32_16x16x32_bf16 v[32:35], v[176:179], v[196:199], v[32:35]
	v_mfma_f32_16x16x32_bf16 v[20:23], v[168:171], v[204:207], v[20:23]
	v_mfma_f32_16x16x32_bf16 v[16:19], v[176:179], v[204:207], v[16:19]
	v_mfma_f32_16x16x32_bf16 v[4:7], v[168:171], v[212:215], v[4:7]
	v_mfma_f32_16x16x32_bf16 v[0:3], v[176:179], v[212:215], v[0:3]
	v_mfma_f32_16x16x32_bf16 v[52:55], v[172:175], v[188:191], v[52:55]
	v_mfma_f32_16x16x32_bf16 v[48:51], v[180:183], v[188:191], v[48:51]
	v_mfma_f32_16x16x32_bf16 v[36:39], v[172:175], v[200:203], v[36:39]
	v_mfma_f32_16x16x32_bf16 v[32:35], v[180:183], v[200:203], v[32:35]
	v_mfma_f32_16x16x32_bf16 v[20:23], v[172:175], v[208:211], v[20:23]
	v_mfma_f32_16x16x32_bf16 v[16:19], v[180:183], v[208:211], v[16:19]
	v_mfma_f32_16x16x32_bf16 v[4:7], v[172:175], v[216:219], v[4:7]
	v_mfma_f32_16x16x32_bf16 v[0:3], v[180:183], v[216:219], v[0:3]
	s_setprio 0
	s_barrier
	s_add_i32 s79, s79, 2
	s_add_u32 s73, s73, 0x100
	s_addc_u32 s78, s78, 0
	s_cmp_gt_u32 s79, 9
	s_mov_b64 s[24:25], s[26:27]
	s_cbranch_scc0 .LBB0_923
	s_and_b64 vcc, exec, s[18:19]
	s_cbranch_vccz .LBB0_926
	s_barrier

.LBB0_947:
	ds_read_b128 v[144:147], v153
	ds_read_b128 v[158:161], v153 offset:1024
	ds_read_b128 v[162:165], v153 offset:2048
	ds_read_b128 v[166:169], v153 offset:3072
	ds_read_b128 v[170:173], v154
	ds_read_b128 v[174:177], v154 offset:1024
	ds_read_b128 v[178:181], v154 offset:2048
	ds_read_b128 v[182:185], v154 offset:3072
	s_add_u32 s36, s34, 0xfffc0080
	s_addc_u32 s37, s35, -1
	s_cmp_eq_u32 s85, 12
	s_cselect_b32 s39, s27, s37
	s_cselect_b32 s38, s81, s36
	s_cselect_b32 s37, s25, s84
	s_cselect_b32 s36, s82, s83
	v_lshl_add_u64 v[148:149], s[34:35], 0, v[136:137]
	s_add_i32 m0, s59, 0xc000
	ds_read_b128 v[186:189], v155
	ds_read_b128 v[190:193], v155 offset:1024
	ds_read_b128 v[196:199], v155 offset:2048
	ds_read_b128 v[200:203], v155 offset:3072
	ds_read_b128 v[204:207], v155 offset:4096
	ds_read_b128 v[208:211], v155 offset:5120
	ds_read_b128 v[212:215], v155 offset:6144
	ds_read_b128 v[216:219], v155 offset:7168
	global_load_lds_dwordx4 v[148:149], off
	v_lshl_add_u64 v[148:149], s[34:35], 0, v[138:139]
	s_add_i32 m0, s59, 0xe000
	s_nop 0
	global_load_lds_dwordx4 v[148:149], off
	s_waitcnt vmcnt(8)
	s_waitcnt lgkmcnt(0)
	s_barrier
	s_setprio 1
	s_waitcnt lgkmcnt(0)
	v_mfma_f32_16x16x32_bf16 v[124:127], v[144:147], v[186:189], v[124:127]
	v_mfma_f32_16x16x32_bf16 v[120:123], v[162:165], v[186:189], v[120:123]
	v_mfma_f32_16x16x32_bf16 v[108:111], v[144:147], v[196:199], v[108:111]
	v_mfma_f32_16x16x32_bf16 v[104:107], v[162:165], v[196:199], v[104:107]
	v_mfma_f32_16x16x32_bf16 v[92:95], v[144:147], v[204:207], v[92:95]
	v_mfma_f32_16x16x32_bf16 v[88:91], v[162:165], v[204:207], v[88:91]
	v_mfma_f32_16x16x32_bf16 v[76:79], v[144:147], v[212:215], v[76:79]
	v_mfma_f32_16x16x32_bf16 v[72:75], v[162:165], v[212:215], v[72:75]
	v_mfma_f32_16x16x32_bf16 v[124:127], v[158:161], v[190:193], v[124:127]
	v_mfma_f32_16x16x32_bf16 v[120:123], v[166:169], v[190:193], v[120:123]
	v_mfma_f32_16x16x32_bf16 v[108:111], v[158:161], v[200:203], v[108:111]
	v_mfma_f32_16x16x32_bf16 v[104:107], v[166:169], v[200:203], v[104:107]
	v_mfma_f32_16x16x32_bf16 v[92:95], v[158:161], v[208:211], v[92:95]
	v_mfma_f32_16x16x32_bf16 v[88:91], v[166:169], v[208:211], v[88:91]
	v_mfma_f32_16x16x32_bf16 v[76:79], v[158:161], v[216:219], v[76:79]
	v_mfma_f32_16x16x32_bf16 v[72:75], v[166:169], v[216:219], v[72:75]
	s_setprio 0
	s_setprio 1
	v_mfma_f32_16x16x32_bf16 v[116:119], v[170:173], v[186:189], v[116:119]
	v_mfma_f32_16x16x32_bf16 v[112:115], v[178:181], v[186:189], v[112:115]
	v_mfma_f32_16x16x32_bf16 v[100:103], v[170:173], v[196:199], v[100:103]
	v_mfma_f32_16x16x32_bf16 v[96:99], v[178:181], v[196:199], v[96:99]
	v_mfma_f32_16x16x32_bf16 v[84:87], v[170:173], v[204:207], v[84:87]
	v_mfma_f32_16x16x32_bf16 v[80:83], v[178:181], v[204:207], v[80:83]
	v_mfma_f32_16x16x32_bf16 v[68:71], v[170:173], v[212:215], v[68:71]
	v_mfma_f32_16x16x32_bf16 v[64:67], v[178:181], v[212:215], v[64:67]
	v_mfma_f32_16x16x32_bf16 v[116:119], v[174:177], v[190:193], v[116:119]
	v_mfma_f32_16x16x32_bf16 v[112:115], v[182:185], v[190:193], v[112:115]
	v_mfma_f32_16x16x32_bf16 v[100:103], v[174:177], v[200:203], v[100:103]
	v_mfma_f32_16x16x32_bf16 v[96:99], v[182:185], v[200:203], v[96:99]
	v_mfma_f32_16x16x32_bf16 v[84:87], v[174:177], v[208:211], v[84:87]
	v_mfma_f32_16x16x32_bf16 v[80:83], v[182:185], v[208:211], v[80:83]
	v_mfma_f32_16x16x32_bf16 v[68:71], v[174:177], v[216:219], v[68:71]
	v_mfma_f32_16x16x32_bf16 v[64:67], v[182:185], v[216:219], v[64:67]
	s_setprio 0
	s_barrier
	s_add_i32 s86, s73, s58
	v_lshl_add_u64 v[148:149], s[36:37], 0, v[130:131]
	s_mov_b32 m0, s86
	ds_read_b128 v[186:189], v155 offset:16384
	ds_read_b128 v[190:193], v155 offset:17408
	ds_read_b128 v[196:199], v155 offset:18432
	ds_read_b128 v[200:203], v155 offset:19456
	ds_read_b128 v[204:207], v155 offset:20480
	ds_read_b128 v[208:211], v155 offset:21504
	ds_read_b128 v[212:215], v155 offset:22528
	ds_read_b128 v[216:219], v155 offset:23552
	global_load_lds_dwordx4 v[148:149], off
	s_add_i32 m0, s86, 0x2000
	s_add_u32 s86, s36, 0x40000
	v_lshl_add_u64 v[220:221], s[36:37], 0, v[134:135]
	s_addc_u32 s87, s37, 0
	s_add_i32 s88, s78, s58
	global_load_lds_dwordx4 v[220:221], off
	v_lshl_add_u64 v[222:223], s[86:87], 0, v[130:131]
	s_mov_b32 m0, s88
	v_lshl_add_u64 v[224:225], s[38:39], 0, v[132:133]
	global_load_lds_dwordx4 v[222:223], off
	v_lshl_add_u64 v[222:223], s[86:87], 0, v[134:135]
	s_add_i32 m0, s88, 0x2000
	s_nop 0
	global_load_lds_dwordx4 v[222:223], off
	v_lshl_add_u64 v[222:223], s[38:39], 0, v[128:129]
	s_waitcnt vmcnt(6)
	s_waitcnt lgkmcnt(0)
	s_barrier
	s_setprio 1
	s_waitcnt lgkmcnt(0)
	v_mfma_f32_16x16x32_bf16 v[60:63], v[144:147], v[186:189], v[60:63]
	v_mfma_f32_16x16x32_bf16 v[56:59], v[162:165], v[186:189], v[56:59]
	v_mfma_f32_16x16x32_bf16 v[44:47], v[144:147], v[196:199], v[44:47]
	v_mfma_f32_16x16x32_bf16 v[40:43], v[162:165], v[196:199], v[40:43]
	v_mfma_f32_16x16x32_bf16 v[28:31], v[144:147], v[204:207], v[28:31]
	v_mfma_f32_16x16x32_bf16 v[24:27], v[162:165], v[204:207], v[24:27]
	v_mfma_f32_16x16x32_bf16 v[12:15], v[144:147], v[212:215], v[12:15]
	v_mfma_f32_16x16x32_bf16 v[8:11], v[162:165], v[212:215], v[8:11]
	v_mfma_f32_16x16x32_bf16 v[60:63], v[158:161], v[190:193], v[60:63]
	v_mfma_f32_16x16x32_bf16 v[56:59], v[166:169], v[190:193], v[56:59]
	v_mfma_f32_16x16x32_bf16 v[44:47], v[158:161], v[200:203], v[44:47]
	v_mfma_f32_16x16x32_bf16 v[40:43], v[166:169], v[200:203], v[40:43]
	v_mfma_f32_16x16x32_bf16 v[28:31], v[158:161], v[208:211], v[28:31]
	v_mfma_f32_16x16x32_bf16 v[24:27], v[166:169], v[208:211], v[24:27]
	v_mfma_f32_16x16x32_bf16 v[12:15], v[158:161], v[216:219], v[12:15]
	v_mfma_f32_16x16x32_bf16 v[8:11], v[166:169], v[216:219], v[8:11]
	s_setprio 0
	s_setprio 1
	v_mfma_f32_16x16x32_bf16 v[52:55], v[170:173], v[186:189], v[52:55]
	v_mfma_f32_16x16x32_bf16 v[48:51], v[178:181], v[186:189], v[48:51]
	v_mfma_f32_16x16x32_bf16 v[36:39], v[170:173], v[196:199], v[36:39]
	v_mfma_f32_16x16x32_bf16 v[32:35], v[178:181], v[196:199], v[32:35]
	v_mfma_f32_16x16x32_bf16 v[20:23], v[170:173], v[204:207], v[20:23]
	v_mfma_f32_16x16x32_bf16 v[16:19], v[178:181], v[204:207], v[16:19]
	v_mfma_f32_16x16x32_bf16 v[4:7], v[170:173], v[212:215], v[4:7]
	v_mfma_f32_16x16x32_bf16 v[0:3], v[178:181], v[212:215], v[0:3]
	v_mfma_f32_16x16x32_bf16 v[52:55], v[174:177], v[190:193], v[52:55]
	v_mfma_f32_16x16x32_bf16 v[48:51], v[182:185], v[190:193], v[48:51]
	v_mfma_f32_16x16x32_bf16 v[36:39], v[174:177], v[200:203], v[36:39]
	v_mfma_f32_16x16x32_bf16 v[32:35], v[182:185], v[200:203], v[32:35]
	v_mfma_f32_16x16x32_bf16 v[20:23], v[174:177], v[208:211], v[20:23]
	v_mfma_f32_16x16x32_bf16 v[16:19], v[182:185], v[208:211], v[16:19]
	v_mfma_f32_16x16x32_bf16 v[4:7], v[174:177], v[216:219], v[4:7]
	v_mfma_f32_16x16x32_bf16 v[0:3], v[182:185], v[216:219], v[0:3]
	s_setprio 0
	s_barrier
	s_add_i32 s86, 0, 0x18000
	v_add_u32_e32 v157, s86, v151
	s_add_i32 s87, 0, 0x1c000
	ds_read_b128 v[144:147], v157
	ds_read_b128 v[158:161], v157 offset:1024
	ds_read_b128 v[162:165], v157 offset:2048
	ds_read_b128 v[166:169], v157 offset:3072
	v_add_u32_e32 v157, s87, v151
	ds_read_b128 v[170:173], v157
	ds_read_b128 v[174:177], v157 offset:1024
	ds_read_b128 v[178:181], v157 offset:2048
	ds_read_b128 v[182:185], v157 offset:3072
	s_add_u32 s38, s38, 0x40000
	s_addc_u32 s39, s39, 0
	v_lshl_add_u64 v[226:227], s[38:39], 0, v[128:129]
	ds_read_b128 v[186:189], v155 offset:32768
	ds_read_b128 v[190:193], v155 offset:33792
	ds_read_b128 v[196:199], v155 offset:34816
	ds_read_b128 v[200:203], v155 offset:35840
	ds_read_b128 v[204:207], v155 offset:36864
	ds_read_b128 v[208:211], v155 offset:37888
	ds_read_b128 v[212:215], v155 offset:38912
	ds_read_b128 v[216:219], v155 offset:39936
	s_mov_b32 m0, s59
	s_nop 0
	global_load_lds_dwordx4 v[222:223], off
	s_mov_b32 m0, s60
	s_nop 0
	global_load_lds_dwordx4 v[224:225], off
	s_mov_b32 m0, s61
	s_nop 0
	global_load_lds_dwordx4 v[226:227], off
	v_lshl_add_u64 v[226:227], s[38:39], 0, v[132:133]
	s_mov_b32 m0, s62
	s_nop 0
	global_load_lds_dwordx4 v[226:227], off
	s_waitcnt vmcnt(8)
	s_waitcnt lgkmcnt(0)
	s_barrier
	s_setprio 1
	s_waitcnt lgkmcnt(0)
	v_mfma_f32_16x16x32_bf16 v[124:127], v[144:147], v[186:189], v[124:127]
	v_mfma_f32_16x16x32_bf16 v[120:123], v[162:165], v[186:189], v[120:123]
	v_mfma_f32_16x16x32_bf16 v[108:111], v[144:147], v[196:199], v[108:111]
	v_mfma_f32_16x16x32_bf16 v[104:107], v[162:165], v[196:199], v[104:107]
	v_mfma_f32_16x16x32_bf16 v[92:95], v[144:147], v[204:207], v[92:95]
	v_mfma_f32_16x16x32_bf16 v[88:91], v[162:165], v[204:207], v[88:91]
	v_mfma_f32_16x16x32_bf16 v[76:79], v[144:147], v[212:215], v[76:79]
	v_mfma_f32_16x16x32_bf16 v[72:75], v[162:165], v[212:215], v[72:75]
	v_mfma_f32_16x16x32_bf16 v[124:127], v[158:161], v[190:193], v[124:127]
	v_mfma_f32_16x16x32_bf16 v[120:123], v[166:169], v[190:193], v[120:123]
	v_mfma_f32_16x16x32_bf16 v[108:111], v[158:161], v[200:203], v[108:111]
	v_mfma_f32_16x16x32_bf16 v[104:107], v[166:169], v[200:203], v[104:107]
	v_mfma_f32_16x16x32_bf16 v[92:95], v[158:161], v[208:211], v[92:95]
	v_mfma_f32_16x16x32_bf16 v[88:91], v[166:169], v[208:211], v[88:91]
	v_mfma_f32_16x16x32_bf16 v[76:79], v[158:161], v[216:219], v[76:79]
	v_mfma_f32_16x16x32_bf16 v[72:75], v[166:169], v[216:219], v[72:75]
	s_setprio 0
	s_setprio 1
	v_mfma_f32_16x16x32_bf16 v[116:119], v[170:173], v[186:189], v[116:119]
	v_mfma_f32_16x16x32_bf16 v[112:115], v[178:181], v[186:189], v[112:115]
	v_mfma_f32_16x16x32_bf16 v[100:103], v[170:173], v[196:199], v[100:103]
	v_mfma_f32_16x16x32_bf16 v[96:99], v[178:181], v[196:199], v[96:99]
	v_mfma_f32_16x16x32_bf16 v[84:87], v[170:173], v[204:207], v[84:87]
	v_mfma_f32_16x16x32_bf16 v[80:83], v[178:181], v[204:207], v[80:83]
	v_mfma_f32_16x16x32_bf16 v[68:71], v[170:173], v[212:215], v[68:71]
	v_mfma_f32_16x16x32_bf16 v[64:67], v[178:181], v[212:215], v[64:67]
	v_mfma_f32_16x16x32_bf16 v[116:119], v[174:177], v[190:193], v[116:119]
	v_mfma_f32_16x16x32_bf16 v[112:115], v[182:185], v[190:193], v[112:115]
	v_mfma_f32_16x16x32_bf16 v[100:103], v[174:177], v[200:203], v[100:103]
	v_mfma_f32_16x16x32_bf16 v[96:99], v[182:185], v[200:203], v[96:99]
	v_mfma_f32_16x16x32_bf16 v[84:87], v[174:177], v[208:211], v[84:87]
	v_mfma_f32_16x16x32_bf16 v[80:83], v[182:185], v[208:211], v[80:83]
	v_mfma_f32_16x16x32_bf16 v[68:71], v[174:177], v[216:219], v[68:71]
	v_mfma_f32_16x16x32_bf16 v[64:67], v[182:185], v[216:219], v[64:67]
	s_setprio 0
	s_barrier
	s_add_i32 s38, s86, s58
	v_lshl_add_u64 v[148:149], v[148:149], 0, s[20:21]
	s_mov_b32 m0, s38
	ds_read_b128 v[186:189], v155 offset:49152
	ds_read_b128 v[190:193], v155 offset:50176
	ds_read_b128 v[196:199], v155 offset:51200
	ds_read_b128 v[200:203], v155 offset:52224
	ds_read_b128 v[204:207], v155 offset:53248
	ds_read_b128 v[208:211], v155 offset:54272
	ds_read_b128 v[212:215], v155 offset:55296
	ds_read_b128 v[216:219], v155 offset:56320
	global_load_lds_dwordx4 v[148:149], off
	s_add_i32 m0, s38, 0x2000
	s_add_u32 s36, s36, 0x40080
	v_lshl_add_u64 v[148:149], v[220:221], 0, s[20:21]
	s_addc_u32 s37, s37, 0
	s_add_i32 s38, s87, s58
	global_load_lds_dwordx4 v[148:149], off
	v_lshl_add_u64 v[148:149], s[36:37], 0, v[130:131]
	s_mov_b32 m0, s38
	s_nop 0
	global_load_lds_dwordx4 v[148:149], off
	v_lshl_add_u64 v[148:149], s[36:37], 0, v[134:135]
	s_add_i32 m0, s38, 0x2000
	s_nop 0
	global_load_lds_dwordx4 v[148:149], off
	v_lshl_add_u64 v[148:149], v[222:223], 0, s[20:21]
	s_mov_b32 m0, s70
	s_nop 0
	global_load_lds_dwordx4 v[148:149], off
	v_lshl_add_u64 v[148:149], v[224:225], 0, s[20:21]
	s_mov_b32 m0, s71
	s_nop 0
	global_load_lds_dwordx4 v[148:149], off
	s_waitcnt vmcnt(8)
	s_waitcnt lgkmcnt(0)
	s_barrier
	s_setprio 1
	s_waitcnt lgkmcnt(0)
	v_mfma_f32_16x16x32_bf16 v[60:63], v[144:147], v[186:189], v[60:63]
	v_mfma_f32_16x16x32_bf16 v[56:59], v[162:165], v[186:189], v[56:59]
	v_mfma_f32_16x16x32_bf16 v[44:47], v[144:147], v[196:199], v[44:47]
	v_mfma_f32_16x16x32_bf16 v[40:43], v[162:165], v[196:199], v[40:43]
	v_mfma_f32_16x16x32_bf16 v[28:31], v[144:147], v[204:207], v[28:31]
	v_mfma_f32_16x16x32_bf16 v[24:27], v[162:165], v[204:207], v[24:27]
	v_mfma_f32_16x16x32_bf16 v[12:15], v[144:147], v[212:215], v[12:15]
	v_mfma_f32_16x16x32_bf16 v[8:11], v[162:165], v[212:215], v[8:11]
	v_mfma_f32_16x16x32_bf16 v[60:63], v[158:161], v[190:193], v[60:63]
	v_mfma_f32_16x16x32_bf16 v[56:59], v[166:169], v[190:193], v[56:59]
	v_mfma_f32_16x16x32_bf16 v[44:47], v[158:161], v[200:203], v[44:47]
	v_mfma_f32_16x16x32_bf16 v[40:43], v[166:169], v[200:203], v[40:43]
	v_mfma_f32_16x16x32_bf16 v[28:31], v[158:161], v[208:211], v[28:31]
	v_mfma_f32_16x16x32_bf16 v[24:27], v[166:169], v[208:211], v[24:27]
	v_mfma_f32_16x16x32_bf16 v[12:15], v[158:161], v[216:219], v[12:15]
	v_mfma_f32_16x16x32_bf16 v[8:11], v[166:169], v[216:219], v[8:11]
	s_setprio 0
	s_setprio 1
	v_mfma_f32_16x16x32_bf16 v[52:55], v[170:173], v[186:189], v[52:55]
	v_mfma_f32_16x16x32_bf16 v[48:51], v[178:181], v[186:189], v[48:51]
	v_mfma_f32_16x16x32_bf16 v[36:39], v[170:173], v[196:199], v[36:39]
	v_mfma_f32_16x16x32_bf16 v[32:35], v[178:181], v[196:199], v[32:35]
	v_mfma_f32_16x16x32_bf16 v[20:23], v[170:173], v[204:207], v[20:23]
	v_mfma_f32_16x16x32_bf16 v[16:19], v[178:181], v[204:207], v[16:19]
	v_mfma_f32_16x16x32_bf16 v[4:7], v[170:173], v[212:215], v[4:7]
	v_mfma_f32_16x16x32_bf16 v[0:3], v[178:181], v[212:215], v[0:3]
	v_mfma_f32_16x16x32_bf16 v[52:55], v[174:177], v[190:193], v[52:55]
	v_mfma_f32_16x16x32_bf16 v[48:51], v[182:185], v[190:193], v[48:51]
	v_mfma_f32_16x16x32_bf16 v[36:39], v[174:177], v[200:203], v[36:39]
	v_mfma_f32_16x16x32_bf16 v[32:35], v[182:185], v[200:203], v[32:35]
	v_mfma_f32_16x16x32_bf16 v[20:23], v[174:177], v[208:211], v[20:23]
	v_mfma_f32_16x16x32_bf16 v[16:19], v[182:185], v[208:211], v[16:19]
	v_mfma_f32_16x16x32_bf16 v[4:7], v[174:177], v[216:219], v[4:7]
	v_mfma_f32_16x16x32_bf16 v[0:3], v[182:185], v[216:219], v[0:3]
	s_setprio 0
	s_barrier
	s_add_i32 s85, s85, 2
	s_add_u32 s34, s34, 0x100
	s_addc_u32 s35, s35, 0
	s_add_u32 s83, s83, 0x100
	s_addc_u32 s84, s84, 0
	s_cmp_gt_u32 s85, 13
	s_cbranch_scc0 .LBB0_947
	s_and_b64 vcc, exec, s[22:23]
	s_cbranch_vccz .LBB0_950
	s_barrier

.LBB0_1023:
	ds_read_b128 v[144:147], v153
	ds_read_b128 v[156:159], v153 offset:1024
	ds_read_b128 v[160:163], v153 offset:2048
	ds_read_b128 v[164:167], v153 offset:3072
	ds_read_b128 v[168:171], v154
	ds_read_b128 v[172:175], v154 offset:1024
	ds_read_b128 v[176:179], v154 offset:2048
	ds_read_b128 v[180:183], v154 offset:3072
	s_add_u32 s44, s42, 0xfffe0080
	s_addc_u32 s45, s43, -1
	s_cmp_eq_u32 s87, 4
	s_cselect_b32 s59, s35, s45
	s_cselect_b32 s58, s83, s44
	s_cselect_b32 s45, s31, s86
	s_cselect_b32 s44, s84, s85
	v_lshl_add_u64 v[148:149], s[42:43], 0, v[136:137]
	s_add_i32 m0, s41, 0xc000
	ds_read_b128 v[184:187], v155
	ds_read_b128 v[188:191], v155 offset:1024
	ds_read_b128 v[196:199], v155 offset:2048
	ds_read_b128 v[200:203], v155 offset:3072
	ds_read_b128 v[204:207], v155 offset:4096
	ds_read_b128 v[208:211], v155 offset:5120
	ds_read_b128 v[212:215], v155 offset:6144
	ds_read_b128 v[216:219], v155 offset:7168
	global_load_lds_dwordx4 v[148:149], off
	v_lshl_add_u64 v[148:149], s[42:43], 0, v[138:139]
	s_add_i32 m0, s41, 0xe000
	s_nop 0
	global_load_lds_dwordx4 v[148:149], off
	s_waitcnt vmcnt(8)
	s_waitcnt lgkmcnt(0)
	s_barrier
	s_setprio 1
	s_waitcnt lgkmcnt(0)
	v_mfma_f32_16x16x32_bf16 v[124:127], v[144:147], v[184:187], v[124:127]
	v_mfma_f32_16x16x32_bf16 v[120:123], v[160:163], v[184:187], v[120:123]
	v_mfma_f32_16x16x32_bf16 v[108:111], v[144:147], v[196:199], v[108:111]
	v_mfma_f32_16x16x32_bf16 v[104:107], v[160:163], v[196:199], v[104:107]
	v_mfma_f32_16x16x32_bf16 v[92:95], v[144:147], v[204:207], v[92:95]
	v_mfma_f32_16x16x32_bf16 v[88:91], v[160:163], v[204:207], v[88:91]
	v_mfma_f32_16x16x32_bf16 v[76:79], v[144:147], v[212:215], v[76:79]
	v_mfma_f32_16x16x32_bf16 v[72:75], v[160:163], v[212:215], v[72:75]
	v_mfma_f32_16x16x32_bf16 v[124:127], v[156:159], v[188:191], v[124:127]
	v_mfma_f32_16x16x32_bf16 v[120:123], v[164:167], v[188:191], v[120:123]
	v_mfma_f32_16x16x32_bf16 v[108:111], v[156:159], v[200:203], v[108:111]
	v_mfma_f32_16x16x32_bf16 v[104:107], v[164:167], v[200:203], v[104:107]
	v_mfma_f32_16x16x32_bf16 v[92:95], v[156:159], v[208:211], v[92:95]
	v_mfma_f32_16x16x32_bf16 v[88:91], v[164:167], v[208:211], v[88:91]
	v_mfma_f32_16x16x32_bf16 v[76:79], v[156:159], v[216:219], v[76:79]
	v_mfma_f32_16x16x32_bf16 v[72:75], v[164:167], v[216:219], v[72:75]
	s_setprio 0
	s_setprio 1
	v_mfma_f32_16x16x32_bf16 v[116:119], v[168:171], v[184:187], v[116:119]
	v_mfma_f32_16x16x32_bf16 v[112:115], v[176:179], v[184:187], v[112:115]
	v_mfma_f32_16x16x32_bf16 v[100:103], v[168:171], v[196:199], v[100:103]
	v_mfma_f32_16x16x32_bf16 v[96:99], v[176:179], v[196:199], v[96:99]
	v_mfma_f32_16x16x32_bf16 v[84:87], v[168:171], v[204:207], v[84:87]
	v_mfma_f32_16x16x32_bf16 v[80:83], v[176:179], v[204:207], v[80:83]
	v_mfma_f32_16x16x32_bf16 v[68:71], v[168:171], v[212:215], v[68:71]
	v_mfma_f32_16x16x32_bf16 v[64:67], v[176:179], v[212:215], v[64:67]
	v_mfma_f32_16x16x32_bf16 v[116:119], v[172:175], v[188:191], v[116:119]
	v_mfma_f32_16x16x32_bf16 v[112:115], v[180:183], v[188:191], v[112:115]
	v_mfma_f32_16x16x32_bf16 v[100:103], v[172:175], v[200:203], v[100:103]
	v_mfma_f32_16x16x32_bf16 v[96:99], v[180:183], v[200:203], v[96:99]
	v_mfma_f32_16x16x32_bf16 v[84:87], v[172:175], v[208:211], v[84:87]
	v_mfma_f32_16x16x32_bf16 v[80:83], v[180:183], v[208:211], v[80:83]
	v_mfma_f32_16x16x32_bf16 v[68:71], v[172:175], v[216:219], v[68:71]
	v_mfma_f32_16x16x32_bf16 v[64:67], v[180:183], v[216:219], v[64:67]
	s_setprio 0
	s_barrier
	s_add_i32 s88, s80, s62
	v_lshl_add_u64 v[148:149], s[44:45], 0, v[130:131]
	s_mov_b32 m0, s88
	ds_read_b128 v[184:187], v155 offset:16384
	ds_read_b128 v[188:191], v155 offset:17408
	ds_read_b128 v[196:199], v155 offset:18432
	ds_read_b128 v[200:203], v155 offset:19456
	ds_read_b128 v[204:207], v155 offset:20480
	ds_read_b128 v[208:211], v155 offset:21504
	ds_read_b128 v[212:215], v155 offset:22528
	ds_read_b128 v[216:219], v155 offset:23552
	global_load_lds_dwordx4 v[148:149], off
	s_add_i32 m0, s88, 0x2000
	s_add_u32 s88, s44, 0x20000
	v_lshl_add_u64 v[192:193], s[44:45], 0, v[134:135]
	s_addc_u32 s89, s45, 0
	s_add_i32 s90, s81, s62
	global_load_lds_dwordx4 v[192:193], off
	v_lshl_add_u64 v[220:221], s[88:89], 0, v[130:131]
	s_mov_b32 m0, s90
	v_lshl_add_u64 v[222:223], s[58:59], 0, v[132:133]
	global_load_lds_dwordx4 v[220:221], off
	v_lshl_add_u64 v[220:221], s[88:89], 0, v[134:135]
	s_add_i32 m0, s90, 0x2000
	s_nop 0
	global_load_lds_dwordx4 v[220:221], off
	v_lshl_add_u64 v[220:221], s[58:59], 0, v[128:129]
	s_waitcnt vmcnt(6)
	s_waitcnt lgkmcnt(0)
	s_barrier
	s_setprio 1
	s_waitcnt lgkmcnt(0)
	v_mfma_f32_16x16x32_bf16 v[60:63], v[144:147], v[184:187], v[60:63]
	v_mfma_f32_16x16x32_bf16 v[56:59], v[160:163], v[184:187], v[56:59]
	v_mfma_f32_16x16x32_bf16 v[44:47], v[144:147], v[196:199], v[44:47]
	v_mfma_f32_16x16x32_bf16 v[40:43], v[160:163], v[196:199], v[40:43]
	v_mfma_f32_16x16x32_bf16 v[28:31], v[144:147], v[204:207], v[28:31]
	v_mfma_f32_16x16x32_bf16 v[24:27], v[160:163], v[204:207], v[24:27]
	v_mfma_f32_16x16x32_bf16 v[12:15], v[144:147], v[212:215], v[12:15]
	v_mfma_f32_16x16x32_bf16 v[8:11], v[160:163], v[212:215], v[8:11]
	v_mfma_f32_16x16x32_bf16 v[60:63], v[156:159], v[188:191], v[60:63]
	v_mfma_f32_16x16x32_bf16 v[56:59], v[164:167], v[188:191], v[56:59]
	v_mfma_f32_16x16x32_bf16 v[44:47], v[156:159], v[200:203], v[44:47]
	v_mfma_f32_16x16x32_bf16 v[40:43], v[164:167], v[200:203], v[40:43]
	v_mfma_f32_16x16x32_bf16 v[28:31], v[156:159], v[208:211], v[28:31]
	v_mfma_f32_16x16x32_bf16 v[24:27], v[164:167], v[208:211], v[24:27]
	v_mfma_f32_16x16x32_bf16 v[12:15], v[156:159], v[216:219], v[12:15]
	v_mfma_f32_16x16x32_bf16 v[8:11], v[164:167], v[216:219], v[8:11]
	s_setprio 0
	s_setprio 1
	v_mfma_f32_16x16x32_bf16 v[52:55], v[168:171], v[184:187], v[52:55]
	v_mfma_f32_16x16x32_bf16 v[48:51], v[176:179], v[184:187], v[48:51]
	v_mfma_f32_16x16x32_bf16 v[36:39], v[168:171], v[196:199], v[36:39]
	v_mfma_f32_16x16x32_bf16 v[32:35], v[176:179], v[196:199], v[32:35]
	v_mfma_f32_16x16x32_bf16 v[20:23], v[168:171], v[204:207], v[20:23]
	v_mfma_f32_16x16x32_bf16 v[16:19], v[176:179], v[204:207], v[16:19]
	v_mfma_f32_16x16x32_bf16 v[4:7], v[168:171], v[212:215], v[4:7]
	v_mfma_f32_16x16x32_bf16 v[0:3], v[176:179], v[212:215], v[0:3]
	v_mfma_f32_16x16x32_bf16 v[52:55], v[172:175], v[188:191], v[52:55]
	v_mfma_f32_16x16x32_bf16 v[48:51], v[180:183], v[188:191], v[48:51]
	v_mfma_f32_16x16x32_bf16 v[36:39], v[172:175], v[200:203], v[36:39]
	v_mfma_f32_16x16x32_bf16 v[32:35], v[180:183], v[200:203], v[32:35]
	v_mfma_f32_16x16x32_bf16 v[20:23], v[172:175], v[208:211], v[20:23]
	v_mfma_f32_16x16x32_bf16 v[16:19], v[180:183], v[208:211], v[16:19]
	v_mfma_f32_16x16x32_bf16 v[4:7], v[172:175], v[216:219], v[4:7]
	v_mfma_f32_16x16x32_bf16 v[0:3], v[180:183], v[216:219], v[0:3]
	s_setprio 0
	s_barrier
	s_add_i32 s88, 0, 0x18000
	s_add_i32 s89, 0, 0x1c000
	v_add_u32_e32 v164, s88, v151
	v_add_u32_e32 v180, s89, v151
	ds_read_b128 v[144:147], v164
	ds_read_b128 v[156:159], v164 offset:1024
	ds_read_b128 v[160:163], v164 offset:2048
	ds_read_b128 v[164:167], v164 offset:3072
	ds_read_b128 v[168:171], v180
	ds_read_b128 v[172:175], v180 offset:1024
	ds_read_b128 v[176:179], v180 offset:2048
	ds_read_b128 v[180:183], v180 offset:3072
	s_add_u32 s58, s58, 0x20000
	s_addc_u32 s59, s59, 0
	v_lshl_add_u64 v[224:225], s[58:59], 0, v[128:129]
	ds_read_b128 v[184:187], v155 offset:32768
	ds_read_b128 v[188:191], v155 offset:33792
	ds_read_b128 v[196:199], v155 offset:34816
	ds_read_b128 v[200:203], v155 offset:35840
	ds_read_b128 v[204:207], v155 offset:36864
	ds_read_b128 v[208:211], v155 offset:37888
	ds_read_b128 v[212:215], v155 offset:38912
	ds_read_b128 v[216:219], v155 offset:39936
	s_mov_b32 m0, s41
	s_nop 0
	global_load_lds_dwordx4 v[220:221], off
	s_mov_b32 m0, s63
	s_nop 0
	global_load_lds_dwordx4 v[222:223], off
	s_mov_b32 m0, s70
	s_nop 0
	global_load_lds_dwordx4 v[224:225], off
	v_lshl_add_u64 v[224:225], s[58:59], 0, v[132:133]
	s_mov_b32 m0, s71
	s_nop 0
	global_load_lds_dwordx4 v[224:225], off
	s_waitcnt vmcnt(8)
	s_waitcnt lgkmcnt(0)
	s_barrier
	s_setprio 1
	s_waitcnt lgkmcnt(0)
	v_mfma_f32_16x16x32_bf16 v[124:127], v[144:147], v[184:187], v[124:127]
	v_mfma_f32_16x16x32_bf16 v[120:123], v[160:163], v[184:187], v[120:123]
	v_mfma_f32_16x16x32_bf16 v[108:111], v[144:147], v[196:199], v[108:111]
	v_mfma_f32_16x16x32_bf16 v[104:107], v[160:163], v[196:199], v[104:107]
	v_mfma_f32_16x16x32_bf16 v[92:95], v[144:147], v[204:207], v[92:95]
	v_mfma_f32_16x16x32_bf16 v[88:91], v[160:163], v[204:207], v[88:91]
	v_mfma_f32_16x16x32_bf16 v[76:79], v[144:147], v[212:215], v[76:79]
	v_mfma_f32_16x16x32_bf16 v[72:75], v[160:163], v[212:215], v[72:75]
	v_mfma_f32_16x16x32_bf16 v[124:127], v[156:159], v[188:191], v[124:127]
	v_mfma_f32_16x16x32_bf16 v[120:123], v[164:167], v[188:191], v[120:123]
	v_mfma_f32_16x16x32_bf16 v[108:111], v[156:159], v[200:203], v[108:111]
	v_mfma_f32_16x16x32_bf16 v[104:107], v[164:167], v[200:203], v[104:107]
	v_mfma_f32_16x16x32_bf16 v[92:95], v[156:159], v[208:211], v[92:95]
	v_mfma_f32_16x16x32_bf16 v[88:91], v[164:167], v[208:211], v[88:91]
	v_mfma_f32_16x16x32_bf16 v[76:79], v[156:159], v[216:219], v[76:79]
	v_mfma_f32_16x16x32_bf16 v[72:75], v[164:167], v[216:219], v[72:75]
	s_setprio 0
	s_setprio 1
	v_mfma_f32_16x16x32_bf16 v[116:119], v[168:171], v[184:187], v[116:119]
	v_mfma_f32_16x16x32_bf16 v[112:115], v[176:179], v[184:187], v[112:115]
	v_mfma_f32_16x16x32_bf16 v[100:103], v[168:171], v[196:199], v[100:103]
	v_mfma_f32_16x16x32_bf16 v[96:99], v[176:179], v[196:199], v[96:99]
	v_mfma_f32_16x16x32_bf16 v[84:87], v[168:171], v[204:207], v[84:87]
	v_mfma_f32_16x16x32_bf16 v[80:83], v[176:179], v[204:207], v[80:83]
	v_mfma_f32_16x16x32_bf16 v[68:71], v[168:171], v[212:215], v[68:71]
	v_mfma_f32_16x16x32_bf16 v[64:67], v[176:179], v[212:215], v[64:67]
	v_mfma_f32_16x16x32_bf16 v[116:119], v[172:175], v[188:191], v[116:119]
	v_mfma_f32_16x16x32_bf16 v[112:115], v[180:183], v[188:191], v[112:115]
	v_mfma_f32_16x16x32_bf16 v[100:103], v[172:175], v[200:203], v[100:103]
	v_mfma_f32_16x16x32_bf16 v[96:99], v[180:183], v[200:203], v[96:99]
	v_mfma_f32_16x16x32_bf16 v[84:87], v[172:175], v[208:211], v[84:87]
	v_mfma_f32_16x16x32_bf16 v[80:83], v[180:183], v[208:211], v[80:83]
	v_mfma_f32_16x16x32_bf16 v[68:71], v[172:175], v[216:219], v[68:71]
	v_mfma_f32_16x16x32_bf16 v[64:67], v[180:183], v[216:219], v[64:67]
	s_setprio 0
	s_barrier
	s_add_i32 s58, s88, s62
	v_lshl_add_u64 v[148:149], v[148:149], 0, s[20:21]
	s_mov_b32 m0, s58
	ds_read_b128 v[184:187], v155 offset:49152
	ds_read_b128 v[188:191], v155 offset:50176
	ds_read_b128 v[196:199], v155 offset:51200
	ds_read_b128 v[200:203], v155 offset:52224
	ds_read_b128 v[204:207], v155 offset:53248
	ds_read_b128 v[208:211], v155 offset:54272
	ds_read_b128 v[212:215], v155 offset:55296
	ds_read_b128 v[216:219], v155 offset:56320
	global_load_lds_dwordx4 v[148:149], off
	s_add_i32 m0, s58, 0x2000
	s_add_u32 s44, s44, 0x20080
	v_lshl_add_u64 v[148:149], v[192:193], 0, s[20:21]
	s_addc_u32 s45, s45, 0
	s_add_i32 s58, s89, s62
	global_load_lds_dwordx4 v[148:149], off
	v_lshl_add_u64 v[148:149], s[44:45], 0, v[130:131]
	s_mov_b32 m0, s58
	s_nop 0
	global_load_lds_dwordx4 v[148:149], off
	v_lshl_add_u64 v[148:149], s[44:45], 0, v[134:135]
	s_add_i32 m0, s58, 0x2000
	s_nop 0
	global_load_lds_dwordx4 v[148:149], off
	v_lshl_add_u64 v[148:149], v[220:221], 0, s[20:21]
	s_mov_b32 m0, s73
	s_nop 0
	global_load_lds_dwordx4 v[148:149], off
	v_lshl_add_u64 v[148:149], v[222:223], 0, s[20:21]
	s_mov_b32 m0, s78
	s_nop 0
	global_load_lds_dwordx4 v[148:149], off
	s_waitcnt vmcnt(8)
	s_waitcnt lgkmcnt(0)
	s_barrier
	s_setprio 1
	s_waitcnt lgkmcnt(0)
	v_mfma_f32_16x16x32_bf16 v[60:63], v[144:147], v[184:187], v[60:63]
	v_mfma_f32_16x16x32_bf16 v[56:59], v[160:163], v[184:187], v[56:59]
	v_mfma_f32_16x16x32_bf16 v[44:47], v[144:147], v[196:199], v[44:47]
	v_mfma_f32_16x16x32_bf16 v[40:43], v[160:163], v[196:199], v[40:43]
	v_mfma_f32_16x16x32_bf16 v[28:31], v[144:147], v[204:207], v[28:31]
	v_mfma_f32_16x16x32_bf16 v[24:27], v[160:163], v[204:207], v[24:27]
	v_mfma_f32_16x16x32_bf16 v[12:15], v[144:147], v[212:215], v[12:15]
	v_mfma_f32_16x16x32_bf16 v[8:11], v[160:163], v[212:215], v[8:11]
	v_mfma_f32_16x16x32_bf16 v[60:63], v[156:159], v[188:191], v[60:63]
	v_mfma_f32_16x16x32_bf16 v[56:59], v[164:167], v[188:191], v[56:59]
	v_mfma_f32_16x16x32_bf16 v[44:47], v[156:159], v[200:203], v[44:47]
	v_mfma_f32_16x16x32_bf16 v[40:43], v[164:167], v[200:203], v[40:43]
	v_mfma_f32_16x16x32_bf16 v[28:31], v[156:159], v[208:211], v[28:31]
	v_mfma_f32_16x16x32_bf16 v[24:27], v[164:167], v[208:211], v[24:27]
	v_mfma_f32_16x16x32_bf16 v[12:15], v[156:159], v[216:219], v[12:15]
	v_mfma_f32_16x16x32_bf16 v[8:11], v[164:167], v[216:219], v[8:11]
	s_setprio 0
	s_setprio 1
	v_mfma_f32_16x16x32_bf16 v[52:55], v[168:171], v[184:187], v[52:55]
	v_mfma_f32_16x16x32_bf16 v[48:51], v[176:179], v[184:187], v[48:51]
	v_mfma_f32_16x16x32_bf16 v[36:39], v[168:171], v[196:199], v[36:39]
	v_mfma_f32_16x16x32_bf16 v[32:35], v[176:179], v[196:199], v[32:35]
	v_mfma_f32_16x16x32_bf16 v[20:23], v[168:171], v[204:207], v[20:23]
	v_mfma_f32_16x16x32_bf16 v[16:19], v[176:179], v[204:207], v[16:19]
	v_mfma_f32_16x16x32_bf16 v[4:7], v[168:171], v[212:215], v[4:7]
	v_mfma_f32_16x16x32_bf16 v[0:3], v[176:179], v[212:215], v[0:3]
	v_mfma_f32_16x16x32_bf16 v[52:55], v[172:175], v[188:191], v[52:55]
	v_mfma_f32_16x16x32_bf16 v[48:51], v[180:183], v[188:191], v[48:51]
	v_mfma_f32_16x16x32_bf16 v[36:39], v[172:175], v[200:203], v[36:39]
	v_mfma_f32_16x16x32_bf16 v[32:35], v[180:183], v[200:203], v[32:35]
	v_mfma_f32_16x16x32_bf16 v[20:23], v[172:175], v[208:211], v[20:23]
	v_mfma_f32_16x16x32_bf16 v[16:19], v[180:183], v[208:211], v[16:19]
	v_mfma_f32_16x16x32_bf16 v[4:7], v[172:175], v[216:219], v[4:7]
	v_mfma_f32_16x16x32_bf16 v[0:3], v[180:183], v[216:219], v[0:3]
	s_setprio 0
	s_barrier
	s_add_i32 s87, s87, 2
	s_add_u32 s42, s42, 0x100
	s_addc_u32 s43, s43, 0
	s_add_u32 s85, s85, 0x100
	s_addc_u32 s86, s86, 0
	s_cmp_gt_u32 s87, 5
	s_cbranch_scc0 .LBB0_1023
	s_and_b64 vcc, exec, s[22:23]
	s_cbranch_vccz .LBB0_1026
	s_barrier

.LBB0_1421:
	ds_read_b128 v[146:149], v155
	ds_read_b128 v[160:163], v155 offset:1024
	ds_read_b128 v[164:167], v155 offset:2048
	ds_read_b128 v[168:171], v155 offset:3072
	ds_read_b128 v[172:175], v156
	ds_read_b128 v[176:179], v156 offset:1024
	ds_read_b128 v[180:183], v156 offset:2048
	ds_read_b128 v[184:187], v156 offset:3072
	s_add_u32 s40, s0, 0xfffc0080
	s_addc_u32 s41, s1, -1
	s_cmp_eq_u32 s83, 12
	s_cselect_b32 s43, s25, s41
	s_cselect_b32 s42, s27, s40
	s_cselect_b32 s41, s31, s82
	s_cselect_b32 s40, s30, s29
	v_lshl_add_u64 v[150:151], s[0:1], 0, v[138:139]
	s_add_i32 m0, s39, 0xc000
	ds_read_b128 v[188:191], v157
	ds_read_b128 v[196:199], v157 offset:1024
	ds_read_b128 v[200:203], v157 offset:2048
	ds_read_b128 v[204:207], v157 offset:3072
	ds_read_b128 v[208:211], v157 offset:4096
	ds_read_b128 v[212:215], v157 offset:5120
	ds_read_b128 v[216:219], v157 offset:6144
	ds_read_b128 v[220:223], v157 offset:7168
	global_load_lds_dwordx4 v[150:151], off
	v_lshl_add_u64 v[150:151], s[0:1], 0, v[140:141]
	s_add_i32 m0, s39, 0xe000
	s_nop 0
	global_load_lds_dwordx4 v[150:151], off
	s_waitcnt vmcnt(8)
	s_waitcnt lgkmcnt(0)
	s_barrier
	s_setprio 1
	s_waitcnt lgkmcnt(0)
	v_mfma_f32_16x16x32_bf16 v[124:127], v[146:149], v[188:191], v[124:127]
	v_mfma_f32_16x16x32_bf16 v[120:123], v[164:167], v[188:191], v[120:123]
	v_mfma_f32_16x16x32_bf16 v[108:111], v[146:149], v[200:203], v[108:111]
	v_mfma_f32_16x16x32_bf16 v[104:107], v[164:167], v[200:203], v[104:107]
	v_mfma_f32_16x16x32_bf16 v[92:95], v[146:149], v[208:211], v[92:95]
	v_mfma_f32_16x16x32_bf16 v[88:91], v[164:167], v[208:211], v[88:91]
	v_mfma_f32_16x16x32_bf16 v[76:79], v[146:149], v[216:219], v[76:79]
	v_mfma_f32_16x16x32_bf16 v[72:75], v[164:167], v[216:219], v[72:75]
	v_mfma_f32_16x16x32_bf16 v[124:127], v[160:163], v[196:199], v[124:127]
	v_mfma_f32_16x16x32_bf16 v[120:123], v[168:171], v[196:199], v[120:123]
	v_mfma_f32_16x16x32_bf16 v[108:111], v[160:163], v[204:207], v[108:111]
	v_mfma_f32_16x16x32_bf16 v[104:107], v[168:171], v[204:207], v[104:107]
	v_mfma_f32_16x16x32_bf16 v[92:95], v[160:163], v[212:215], v[92:95]
	v_mfma_f32_16x16x32_bf16 v[88:91], v[168:171], v[212:215], v[88:91]
	v_mfma_f32_16x16x32_bf16 v[76:79], v[160:163], v[220:223], v[76:79]
	v_mfma_f32_16x16x32_bf16 v[72:75], v[168:171], v[220:223], v[72:75]
	s_setprio 0
	s_setprio 1
	v_mfma_f32_16x16x32_bf16 v[116:119], v[172:175], v[188:191], v[116:119]
	v_mfma_f32_16x16x32_bf16 v[112:115], v[180:183], v[188:191], v[112:115]
	v_mfma_f32_16x16x32_bf16 v[100:103], v[172:175], v[200:203], v[100:103]
	v_mfma_f32_16x16x32_bf16 v[96:99], v[180:183], v[200:203], v[96:99]
	v_mfma_f32_16x16x32_bf16 v[84:87], v[172:175], v[208:211], v[84:87]
	v_mfma_f32_16x16x32_bf16 v[80:83], v[180:183], v[208:211], v[80:83]
	v_mfma_f32_16x16x32_bf16 v[68:71], v[172:175], v[216:219], v[68:71]
	v_mfma_f32_16x16x32_bf16 v[64:67], v[180:183], v[216:219], v[64:67]
	v_mfma_f32_16x16x32_bf16 v[116:119], v[176:179], v[196:199], v[116:119]
	v_mfma_f32_16x16x32_bf16 v[112:115], v[184:187], v[196:199], v[112:115]
	v_mfma_f32_16x16x32_bf16 v[100:103], v[176:179], v[204:207], v[100:103]
	v_mfma_f32_16x16x32_bf16 v[96:99], v[184:187], v[204:207], v[96:99]
	v_mfma_f32_16x16x32_bf16 v[84:87], v[176:179], v[212:215], v[84:87]
	v_mfma_f32_16x16x32_bf16 v[80:83], v[184:187], v[212:215], v[80:83]
	v_mfma_f32_16x16x32_bf16 v[68:71], v[176:179], v[220:223], v[68:71]
	v_mfma_f32_16x16x32_bf16 v[64:67], v[184:187], v[220:223], v[64:67]
	s_setprio 0
	s_barrier
	s_add_i32 s84, s78, s60
	v_lshl_add_u64 v[150:151], s[40:41], 0, v[132:133]
	s_mov_b32 m0, s84
	ds_read_b128 v[188:191], v157 offset:16384
	ds_read_b128 v[196:199], v157 offset:17408
	ds_read_b128 v[200:203], v157 offset:18432
	ds_read_b128 v[204:207], v157 offset:19456
	ds_read_b128 v[208:211], v157 offset:20480
	ds_read_b128 v[212:215], v157 offset:21504
	ds_read_b128 v[216:219], v157 offset:22528
	ds_read_b128 v[220:223], v157 offset:23552
	global_load_lds_dwordx4 v[150:151], off
	s_add_i32 m0, s84, 0x2000
	s_add_u32 s84, s40, 0x40000
	v_lshl_add_u64 v[192:193], s[40:41], 0, v[136:137]
	s_addc_u32 s85, s41, 0
	s_add_i32 s86, s79, s60
	global_load_lds_dwordx4 v[192:193], off
	v_lshl_add_u64 v[224:225], s[84:85], 0, v[132:133]
	s_mov_b32 m0, s86
	v_lshl_add_u64 v[226:227], s[42:43], 0, v[134:135]
	global_load_lds_dwordx4 v[224:225], off
	v_lshl_add_u64 v[224:225], s[84:85], 0, v[136:137]
	s_add_i32 m0, s86, 0x2000
	s_nop 0
	global_load_lds_dwordx4 v[224:225], off
	v_lshl_add_u64 v[224:225], s[42:43], 0, v[130:131]
	s_waitcnt vmcnt(6)
	s_waitcnt lgkmcnt(0)
	s_barrier
	s_setprio 1
	s_waitcnt lgkmcnt(0)
	v_mfma_f32_16x16x32_bf16 v[60:63], v[146:149], v[188:191], v[60:63]
	v_mfma_f32_16x16x32_bf16 v[56:59], v[164:167], v[188:191], v[56:59]
	v_mfma_f32_16x16x32_bf16 v[44:47], v[146:149], v[200:203], v[44:47]
	v_mfma_f32_16x16x32_bf16 v[40:43], v[164:167], v[200:203], v[40:43]
	v_mfma_f32_16x16x32_bf16 v[28:31], v[146:149], v[208:211], v[28:31]
	v_mfma_f32_16x16x32_bf16 v[24:27], v[164:167], v[208:211], v[24:27]
	v_mfma_f32_16x16x32_bf16 v[12:15], v[146:149], v[216:219], v[12:15]
	v_mfma_f32_16x16x32_bf16 v[8:11], v[164:167], v[216:219], v[8:11]
	v_mfma_f32_16x16x32_bf16 v[60:63], v[160:163], v[196:199], v[60:63]
	v_mfma_f32_16x16x32_bf16 v[56:59], v[168:171], v[196:199], v[56:59]
	v_mfma_f32_16x16x32_bf16 v[44:47], v[160:163], v[204:207], v[44:47]
	v_mfma_f32_16x16x32_bf16 v[40:43], v[168:171], v[204:207], v[40:43]
	v_mfma_f32_16x16x32_bf16 v[28:31], v[160:163], v[212:215], v[28:31]
	v_mfma_f32_16x16x32_bf16 v[24:27], v[168:171], v[212:215], v[24:27]
	v_mfma_f32_16x16x32_bf16 v[12:15], v[160:163], v[220:223], v[12:15]
	v_mfma_f32_16x16x32_bf16 v[8:11], v[168:171], v[220:223], v[8:11]
	s_setprio 0
	s_setprio 1
	v_mfma_f32_16x16x32_bf16 v[52:55], v[172:175], v[188:191], v[52:55]
	v_mfma_f32_16x16x32_bf16 v[48:51], v[180:183], v[188:191], v[48:51]
	v_mfma_f32_16x16x32_bf16 v[36:39], v[172:175], v[200:203], v[36:39]
	v_mfma_f32_16x16x32_bf16 v[32:35], v[180:183], v[200:203], v[32:35]
	v_mfma_f32_16x16x32_bf16 v[20:23], v[172:175], v[208:211], v[20:23]
	v_mfma_f32_16x16x32_bf16 v[16:19], v[180:183], v[208:211], v[16:19]
	v_mfma_f32_16x16x32_bf16 v[4:7], v[172:175], v[216:219], v[4:7]
	v_mfma_f32_16x16x32_bf16 v[0:3], v[180:183], v[216:219], v[0:3]
	v_mfma_f32_16x16x32_bf16 v[52:55], v[176:179], v[196:199], v[52:55]
	v_mfma_f32_16x16x32_bf16 v[48:51], v[184:187], v[196:199], v[48:51]
	v_mfma_f32_16x16x32_bf16 v[36:39], v[176:179], v[204:207], v[36:39]
	v_mfma_f32_16x16x32_bf16 v[32:35], v[184:187], v[204:207], v[32:35]
	v_mfma_f32_16x16x32_bf16 v[20:23], v[176:179], v[212:215], v[20:23]
	v_mfma_f32_16x16x32_bf16 v[16:19], v[184:187], v[212:215], v[16:19]
	v_mfma_f32_16x16x32_bf16 v[4:7], v[176:179], v[220:223], v[4:7]
	v_mfma_f32_16x16x32_bf16 v[0:3], v[184:187], v[220:223], v[0:3]
	s_setprio 0
	s_barrier
	s_add_i32 s84, 0, 0x18000
	v_add_u32_e32 v159, s84, v153
	s_add_i32 s85, 0, 0x1c000
	ds_read_b128 v[146:149], v159
	ds_read_b128 v[160:163], v159 offset:1024
	ds_read_b128 v[164:167], v159 offset:2048
	ds_read_b128 v[168:171], v159 offset:3072
	v_add_u32_e32 v159, s85, v153
	ds_read_b128 v[172:175], v159
	ds_read_b128 v[176:179], v159 offset:1024
	ds_read_b128 v[180:183], v159 offset:2048
	ds_read_b128 v[184:187], v159 offset:3072
	s_add_u32 s42, s42, 0x40000
	s_addc_u32 s43, s43, 0
	v_lshl_add_u64 v[228:229], s[42:43], 0, v[130:131]
	ds_read_b128 v[188:191], v157 offset:32768
	ds_read_b128 v[196:199], v157 offset:33792
	ds_read_b128 v[200:203], v157 offset:34816
	ds_read_b128 v[204:207], v157 offset:35840
	ds_read_b128 v[208:211], v157 offset:36864
	ds_read_b128 v[212:215], v157 offset:37888
	ds_read_b128 v[216:219], v157 offset:38912
	ds_read_b128 v[220:223], v157 offset:39936
	s_mov_b32 m0, s39
	s_nop 0
	global_load_lds_dwordx4 v[224:225], off
	s_mov_b32 m0, s61
	s_nop 0
	global_load_lds_dwordx4 v[226:227], off
	s_mov_b32 m0, s62
	s_nop 0
	global_load_lds_dwordx4 v[228:229], off
	v_lshl_add_u64 v[228:229], s[42:43], 0, v[134:135]
	s_mov_b32 m0, s63
	s_nop 0
	global_load_lds_dwordx4 v[228:229], off
	s_waitcnt vmcnt(8)
	s_waitcnt lgkmcnt(0)
	s_barrier
	s_setprio 1
	s_waitcnt lgkmcnt(0)
	v_mfma_f32_16x16x32_bf16 v[124:127], v[146:149], v[188:191], v[124:127]
	v_mfma_f32_16x16x32_bf16 v[120:123], v[164:167], v[188:191], v[120:123]
	v_mfma_f32_16x16x32_bf16 v[108:111], v[146:149], v[200:203], v[108:111]
	v_mfma_f32_16x16x32_bf16 v[104:107], v[164:167], v[200:203], v[104:107]
	v_mfma_f32_16x16x32_bf16 v[92:95], v[146:149], v[208:211], v[92:95]
	v_mfma_f32_16x16x32_bf16 v[88:91], v[164:167], v[208:211], v[88:91]
	v_mfma_f32_16x16x32_bf16 v[76:79], v[146:149], v[216:219], v[76:79]
	v_mfma_f32_16x16x32_bf16 v[72:75], v[164:167], v[216:219], v[72:75]
	v_mfma_f32_16x16x32_bf16 v[124:127], v[160:163], v[196:199], v[124:127]
	v_mfma_f32_16x16x32_bf16 v[120:123], v[168:171], v[196:199], v[120:123]
	v_mfma_f32_16x16x32_bf16 v[108:111], v[160:163], v[204:207], v[108:111]
	v_mfma_f32_16x16x32_bf16 v[104:107], v[168:171], v[204:207], v[104:107]
	v_mfma_f32_16x16x32_bf16 v[92:95], v[160:163], v[212:215], v[92:95]
	v_mfma_f32_16x16x32_bf16 v[88:91], v[168:171], v[212:215], v[88:91]
	v_mfma_f32_16x16x32_bf16 v[76:79], v[160:163], v[220:223], v[76:79]
	v_mfma_f32_16x16x32_bf16 v[72:75], v[168:171], v[220:223], v[72:75]
	s_setprio 0
	s_setprio 1
	v_mfma_f32_16x16x32_bf16 v[116:119], v[172:175], v[188:191], v[116:119]
	v_mfma_f32_16x16x32_bf16 v[112:115], v[180:183], v[188:191], v[112:115]
	v_mfma_f32_16x16x32_bf16 v[100:103], v[172:175], v[200:203], v[100:103]
	v_mfma_f32_16x16x32_bf16 v[96:99], v[180:183], v[200:203], v[96:99]
	v_mfma_f32_16x16x32_bf16 v[84:87], v[172:175], v[208:211], v[84:87]
	v_mfma_f32_16x16x32_bf16 v[80:83], v[180:183], v[208:211], v[80:83]
	v_mfma_f32_16x16x32_bf16 v[68:71], v[172:175], v[216:219], v[68:71]
	v_mfma_f32_16x16x32_bf16 v[64:67], v[180:183], v[216:219], v[64:67]
	v_mfma_f32_16x16x32_bf16 v[116:119], v[176:179], v[196:199], v[116:119]
	v_mfma_f32_16x16x32_bf16 v[112:115], v[184:187], v[196:199], v[112:115]
	v_mfma_f32_16x16x32_bf16 v[100:103], v[176:179], v[204:207], v[100:103]
	v_mfma_f32_16x16x32_bf16 v[96:99], v[184:187], v[204:207], v[96:99]
	v_mfma_f32_16x16x32_bf16 v[84:87], v[176:179], v[212:215], v[84:87]
	v_mfma_f32_16x16x32_bf16 v[80:83], v[184:187], v[212:215], v[80:83]
	v_mfma_f32_16x16x32_bf16 v[68:71], v[176:179], v[220:223], v[68:71]
	v_mfma_f32_16x16x32_bf16 v[64:67], v[184:187], v[220:223], v[64:67]
	s_setprio 0
	s_barrier
	s_add_i32 s42, s84, s60
	v_lshl_add_u64 v[150:151], v[150:151], 0, s[20:21]
	s_mov_b32 m0, s42
	ds_read_b128 v[188:191], v157 offset:49152
	ds_read_b128 v[196:199], v157 offset:50176
	ds_read_b128 v[200:203], v157 offset:51200
	ds_read_b128 v[204:207], v157 offset:52224
	ds_read_b128 v[208:211], v157 offset:53248
	ds_read_b128 v[212:215], v157 offset:54272
	ds_read_b128 v[216:219], v157 offset:55296
	ds_read_b128 v[220:223], v157 offset:56320
	global_load_lds_dwordx4 v[150:151], off
	s_add_i32 m0, s42, 0x2000
	s_add_u32 s40, s40, 0x40080
	v_lshl_add_u64 v[150:151], v[192:193], 0, s[20:21]
	s_addc_u32 s41, s41, 0
	s_add_i32 s42, s85, s60
	global_load_lds_dwordx4 v[150:151], off
	v_lshl_add_u64 v[150:151], s[40:41], 0, v[132:133]
	s_mov_b32 m0, s42
	s_nop 0
	global_load_lds_dwordx4 v[150:151], off
	v_lshl_add_u64 v[150:151], s[40:41], 0, v[136:137]
	s_add_i32 m0, s42, 0x2000
	s_nop 0
	global_load_lds_dwordx4 v[150:151], off
	v_lshl_add_u64 v[150:151], v[224:225], 0, s[20:21]
	s_mov_b32 m0, s70
	s_nop 0
	global_load_lds_dwordx4 v[150:151], off
	v_lshl_add_u64 v[150:151], v[226:227], 0, s[20:21]
	s_mov_b32 m0, s71
	s_nop 0
	global_load_lds_dwordx4 v[150:151], off
	s_waitcnt vmcnt(8)
	s_waitcnt lgkmcnt(0)
	s_barrier
	s_setprio 1
	s_waitcnt lgkmcnt(0)
	v_mfma_f32_16x16x32_bf16 v[60:63], v[146:149], v[188:191], v[60:63]
	v_mfma_f32_16x16x32_bf16 v[56:59], v[164:167], v[188:191], v[56:59]
	v_mfma_f32_16x16x32_bf16 v[44:47], v[146:149], v[200:203], v[44:47]
	v_mfma_f32_16x16x32_bf16 v[40:43], v[164:167], v[200:203], v[40:43]
	v_mfma_f32_16x16x32_bf16 v[28:31], v[146:149], v[208:211], v[28:31]
	v_mfma_f32_16x16x32_bf16 v[24:27], v[164:167], v[208:211], v[24:27]
	v_mfma_f32_16x16x32_bf16 v[12:15], v[146:149], v[216:219], v[12:15]
	v_mfma_f32_16x16x32_bf16 v[8:11], v[164:167], v[216:219], v[8:11]
	v_mfma_f32_16x16x32_bf16 v[60:63], v[160:163], v[196:199], v[60:63]
	v_mfma_f32_16x16x32_bf16 v[56:59], v[168:171], v[196:199], v[56:59]
	v_mfma_f32_16x16x32_bf16 v[44:47], v[160:163], v[204:207], v[44:47]
	v_mfma_f32_16x16x32_bf16 v[40:43], v[168:171], v[204:207], v[40:43]
	v_mfma_f32_16x16x32_bf16 v[28:31], v[160:163], v[212:215], v[28:31]
	v_mfma_f32_16x16x32_bf16 v[24:27], v[168:171], v[212:215], v[24:27]
	v_mfma_f32_16x16x32_bf16 v[12:15], v[160:163], v[220:223], v[12:15]
	v_mfma_f32_16x16x32_bf16 v[8:11], v[168:171], v[220:223], v[8:11]
	s_setprio 0
	s_setprio 1
	v_mfma_f32_16x16x32_bf16 v[52:55], v[172:175], v[188:191], v[52:55]
	v_mfma_f32_16x16x32_bf16 v[48:51], v[180:183], v[188:191], v[48:51]
	v_mfma_f32_16x16x32_bf16 v[36:39], v[172:175], v[200:203], v[36:39]
	v_mfma_f32_16x16x32_bf16 v[32:35], v[180:183], v[200:203], v[32:35]
	v_mfma_f32_16x16x32_bf16 v[20:23], v[172:175], v[208:211], v[20:23]
	v_mfma_f32_16x16x32_bf16 v[16:19], v[180:183], v[208:211], v[16:19]
	v_mfma_f32_16x16x32_bf16 v[4:7], v[172:175], v[216:219], v[4:7]
	v_mfma_f32_16x16x32_bf16 v[0:3], v[180:183], v[216:219], v[0:3]
	v_mfma_f32_16x16x32_bf16 v[52:55], v[176:179], v[196:199], v[52:55]
	v_mfma_f32_16x16x32_bf16 v[48:51], v[184:187], v[196:199], v[48:51]
	v_mfma_f32_16x16x32_bf16 v[36:39], v[176:179], v[204:207], v[36:39]
	v_mfma_f32_16x16x32_bf16 v[32:35], v[184:187], v[204:207], v[32:35]
	v_mfma_f32_16x16x32_bf16 v[20:23], v[176:179], v[212:215], v[20:23]
	v_mfma_f32_16x16x32_bf16 v[16:19], v[184:187], v[212:215], v[16:19]
	v_mfma_f32_16x16x32_bf16 v[4:7], v[176:179], v[220:223], v[4:7]
	v_mfma_f32_16x16x32_bf16 v[0:3], v[184:187], v[220:223], v[0:3]
	s_setprio 0
	s_barrier
	s_add_i32 s83, s83, 2
	s_add_u32 s0, s0, 0x100
	s_addc_u32 s1, s1, 0
	s_add_u32 s29, s29, 0x100
	s_addc_u32 s82, s82, 0
	s_cmp_gt_u32 s83, 13
	s_cbranch_scc0 .LBB0_1421
	s_and_b64 vcc, exec, s[22:23]
	s_cbranch_vccz .LBB0_1424
	s_barrier

.LBB0_1451:
	ds_read_b128 v[144:147], v159
	ds_read_b128 v[148:151], v159 offset:1024
	ds_read_b128 v[152:155], v159 offset:2048
	ds_read_b128 v[162:165], v159 offset:3072
	ds_read_b128 v[166:169], v160
	ds_read_b128 v[170:173], v160 offset:1024
	ds_read_b128 v[174:177], v160 offset:2048
	ds_read_b128 v[178:181], v160 offset:3072
	s_add_u32 s41, s58, 0xfffe0080
	s_addc_u32 s43, s59, -1
	s_cmp_eq_u32 s39, 4
	s_cselect_b32 s71, s1, s43
	s_cselect_b32 s70, s0, s41
	s_cselect_b32 s63, s45, s17
	s_cselect_b32 s62, s44, s15
	v_lshl_add_u64 v[216:217], s[58:59], 0, v[136:137]
	s_add_i32 m0, s83, 0xc000
	ds_read_b128 v[182:185], v161
	ds_read_b128 v[186:189], v161 offset:1024
	ds_read_b128 v[190:193], v161 offset:2048
	ds_read_b128 v[196:199], v161 offset:3072
	ds_read_b128 v[200:203], v161 offset:4096
	ds_read_b128 v[204:207], v161 offset:5120
	ds_read_b128 v[208:211], v161 offset:6144
	ds_read_b128 v[212:215], v161 offset:7168
	global_load_lds_dwordx4 v[216:217], off
	v_lshl_add_u64 v[216:217], s[58:59], 0, v[138:139]
	s_add_i32 m0, s83, 0xe000
	s_nop 0
	global_load_lds_dwordx4 v[216:217], off
	s_waitcnt vmcnt(8)
	s_waitcnt lgkmcnt(0)
	s_barrier
	s_setprio 1
	s_waitcnt lgkmcnt(0)
	v_mfma_f32_16x16x32_bf16 v[124:127], v[144:147], v[182:185], v[124:127]
	v_mfma_f32_16x16x32_bf16 v[120:123], v[152:155], v[182:185], v[120:123]
	v_mfma_f32_16x16x32_bf16 v[108:111], v[144:147], v[190:193], v[108:111]
	v_mfma_f32_16x16x32_bf16 v[104:107], v[152:155], v[190:193], v[104:107]
	v_mfma_f32_16x16x32_bf16 v[92:95], v[144:147], v[200:203], v[92:95]
	v_mfma_f32_16x16x32_bf16 v[88:91], v[152:155], v[200:203], v[88:91]
	v_mfma_f32_16x16x32_bf16 v[76:79], v[144:147], v[208:211], v[76:79]
	v_mfma_f32_16x16x32_bf16 v[72:75], v[152:155], v[208:211], v[72:75]
	v_mfma_f32_16x16x32_bf16 v[124:127], v[148:151], v[186:189], v[124:127]
	v_mfma_f32_16x16x32_bf16 v[120:123], v[162:165], v[186:189], v[120:123]
	v_mfma_f32_16x16x32_bf16 v[108:111], v[148:151], v[196:199], v[108:111]
	v_mfma_f32_16x16x32_bf16 v[104:107], v[162:165], v[196:199], v[104:107]
	v_mfma_f32_16x16x32_bf16 v[92:95], v[148:151], v[204:207], v[92:95]
	v_mfma_f32_16x16x32_bf16 v[88:91], v[162:165], v[204:207], v[88:91]
	v_mfma_f32_16x16x32_bf16 v[76:79], v[148:151], v[212:215], v[76:79]
	v_mfma_f32_16x16x32_bf16 v[72:75], v[162:165], v[212:215], v[72:75]
	s_setprio 0
	s_setprio 1
	v_mfma_f32_16x16x32_bf16 v[116:119], v[166:169], v[182:185], v[116:119]
	v_mfma_f32_16x16x32_bf16 v[112:115], v[174:177], v[182:185], v[112:115]
	v_mfma_f32_16x16x32_bf16 v[100:103], v[166:169], v[190:193], v[100:103]
	v_mfma_f32_16x16x32_bf16 v[96:99], v[174:177], v[190:193], v[96:99]
	v_mfma_f32_16x16x32_bf16 v[84:87], v[166:169], v[200:203], v[84:87]
	v_mfma_f32_16x16x32_bf16 v[80:83], v[174:177], v[200:203], v[80:83]
	v_mfma_f32_16x16x32_bf16 v[68:71], v[166:169], v[208:211], v[68:71]
	v_mfma_f32_16x16x32_bf16 v[64:67], v[174:177], v[208:211], v[64:67]
	v_mfma_f32_16x16x32_bf16 v[116:119], v[170:173], v[186:189], v[116:119]
	v_mfma_f32_16x16x32_bf16 v[112:115], v[178:181], v[186:189], v[112:115]
	v_mfma_f32_16x16x32_bf16 v[100:103], v[170:173], v[196:199], v[100:103]
	v_mfma_f32_16x16x32_bf16 v[96:99], v[178:181], v[196:199], v[96:99]
	v_mfma_f32_16x16x32_bf16 v[84:87], v[170:173], v[204:207], v[84:87]
	v_mfma_f32_16x16x32_bf16 v[80:83], v[178:181], v[204:207], v[80:83]
	v_mfma_f32_16x16x32_bf16 v[68:71], v[170:173], v[212:215], v[68:71]
	v_mfma_f32_16x16x32_bf16 v[64:67], v[178:181], v[212:215], v[64:67]
	s_setprio 0
	s_barrier
	s_add_i32 s41, s90, s80
	v_lshl_add_u64 v[216:217], s[62:63], 0, v[130:131]
	s_mov_b32 m0, s41
	ds_read_b128 v[182:185], v161 offset:16384
	ds_read_b128 v[186:189], v161 offset:17408
	ds_read_b128 v[190:193], v161 offset:18432
	ds_read_b128 v[196:199], v161 offset:19456
	ds_read_b128 v[200:203], v161 offset:20480
	ds_read_b128 v[204:207], v161 offset:21504
	ds_read_b128 v[208:211], v161 offset:22528
	ds_read_b128 v[212:215], v161 offset:23552
	global_load_lds_dwordx4 v[216:217], off
	s_add_i32 m0, s41, 0x2000
	s_add_u32 s94, s62, 0x20000
	v_lshl_add_u64 v[218:219], s[62:63], 0, v[134:135]
	s_addc_u32 s95, s63, 0
	s_add_i32 s41, s91, s80
	global_load_lds_dwordx4 v[218:219], off
	v_lshl_add_u64 v[220:221], s[94:95], 0, v[130:131]
	s_mov_b32 m0, s41
	v_lshl_add_u64 v[222:223], s[70:71], 0, v[132:133]
	global_load_lds_dwordx4 v[220:221], off
	v_lshl_add_u64 v[220:221], s[94:95], 0, v[134:135]
	s_add_i32 m0, s41, 0x2000
	s_nop 0
	global_load_lds_dwordx4 v[220:221], off
	v_lshl_add_u64 v[220:221], s[70:71], 0, v[128:129]
	s_waitcnt vmcnt(6)
	s_waitcnt lgkmcnt(0)
	s_barrier
	s_setprio 1
	s_waitcnt lgkmcnt(0)
	v_mfma_f32_16x16x32_bf16 v[60:63], v[144:147], v[182:185], v[60:63]
	v_mfma_f32_16x16x32_bf16 v[56:59], v[152:155], v[182:185], v[56:59]
	v_mfma_f32_16x16x32_bf16 v[44:47], v[144:147], v[190:193], v[44:47]
	v_mfma_f32_16x16x32_bf16 v[40:43], v[152:155], v[190:193], v[40:43]
	v_mfma_f32_16x16x32_bf16 v[28:31], v[144:147], v[200:203], v[28:31]
	v_mfma_f32_16x16x32_bf16 v[24:27], v[152:155], v[200:203], v[24:27]
	v_mfma_f32_16x16x32_bf16 v[12:15], v[144:147], v[208:211], v[12:15]
	v_mfma_f32_16x16x32_bf16 v[8:11], v[152:155], v[208:211], v[8:11]
	v_mfma_f32_16x16x32_bf16 v[60:63], v[148:151], v[186:189], v[60:63]
	v_mfma_f32_16x16x32_bf16 v[56:59], v[162:165], v[186:189], v[56:59]
	v_mfma_f32_16x16x32_bf16 v[44:47], v[148:151], v[196:199], v[44:47]
	v_mfma_f32_16x16x32_bf16 v[40:43], v[162:165], v[196:199], v[40:43]
	v_mfma_f32_16x16x32_bf16 v[28:31], v[148:151], v[204:207], v[28:31]
	v_mfma_f32_16x16x32_bf16 v[24:27], v[162:165], v[204:207], v[24:27]
	v_mfma_f32_16x16x32_bf16 v[12:15], v[148:151], v[212:215], v[12:15]
	v_mfma_f32_16x16x32_bf16 v[8:11], v[162:165], v[212:215], v[8:11]
	s_setprio 0
	s_setprio 1
	v_mfma_f32_16x16x32_bf16 v[52:55], v[166:169], v[182:185], v[52:55]
	v_mfma_f32_16x16x32_bf16 v[48:51], v[174:177], v[182:185], v[48:51]
	v_mfma_f32_16x16x32_bf16 v[36:39], v[166:169], v[190:193], v[36:39]
	v_mfma_f32_16x16x32_bf16 v[32:35], v[174:177], v[190:193], v[32:35]
	v_mfma_f32_16x16x32_bf16 v[20:23], v[166:169], v[200:203], v[20:23]
	v_mfma_f32_16x16x32_bf16 v[16:19], v[174:177], v[200:203], v[16:19]
	v_mfma_f32_16x16x32_bf16 v[4:7], v[166:169], v[208:211], v[4:7]
	v_mfma_f32_16x16x32_bf16 v[0:3], v[174:177], v[208:211], v[0:3]
	v_mfma_f32_16x16x32_bf16 v[52:55], v[170:173], v[186:189], v[52:55]
	v_mfma_f32_16x16x32_bf16 v[48:51], v[178:181], v[186:189], v[48:51]
	v_mfma_f32_16x16x32_bf16 v[36:39], v[170:173], v[196:199], v[36:39]
	v_mfma_f32_16x16x32_bf16 v[32:35], v[178:181], v[196:199], v[32:35]
	v_mfma_f32_16x16x32_bf16 v[20:23], v[170:173], v[204:207], v[20:23]
	v_mfma_f32_16x16x32_bf16 v[16:19], v[178:181], v[204:207], v[16:19]
	v_mfma_f32_16x16x32_bf16 v[4:7], v[170:173], v[212:215], v[4:7]
	v_mfma_f32_16x16x32_bf16 v[0:3], v[178:181], v[212:215], v[0:3]
	s_setprio 0
	s_barrier
	s_add_i32 s41, 0, 0x18000
	s_add_i32 s43, 0, 0x1c000
	v_add_u32_e32 v162, s41, v157
	v_add_u32_e32 v178, s43, v157
	ds_read_b128 v[144:147], v162
	ds_read_b128 v[148:151], v162 offset:1024
	ds_read_b128 v[152:155], v162 offset:2048
	ds_read_b128 v[162:165], v162 offset:3072
	ds_read_b128 v[166:169], v178
	ds_read_b128 v[170:173], v178 offset:1024
	ds_read_b128 v[174:177], v178 offset:2048
	ds_read_b128 v[178:181], v178 offset:3072
	s_add_u32 s70, s70, 0x20000
	s_addc_u32 s71, s71, 0
	v_lshl_add_u64 v[224:225], s[70:71], 0, v[128:129]
	ds_read_b128 v[182:185], v161 offset:32768
	ds_read_b128 v[186:189], v161 offset:33792
	ds_read_b128 v[190:193], v161 offset:34816
	ds_read_b128 v[196:199], v161 offset:35840
	ds_read_b128 v[200:203], v161 offset:36864
	ds_read_b128 v[204:207], v161 offset:37888
	ds_read_b128 v[208:211], v161 offset:38912
	ds_read_b128 v[212:215], v161 offset:39936
	s_mov_b32 m0, s83
	s_nop 0
	global_load_lds_dwordx4 v[220:221], off
	s_mov_b32 m0, s84
	s_nop 0
	global_load_lds_dwordx4 v[222:223], off
	s_mov_b32 m0, s85
	s_nop 0
	global_load_lds_dwordx4 v[224:225], off
	v_lshl_add_u64 v[224:225], s[70:71], 0, v[132:133]
	s_mov_b32 m0, s86
	s_nop 0
	global_load_lds_dwordx4 v[224:225], off
	s_waitcnt vmcnt(8)
	s_waitcnt lgkmcnt(0)
	s_barrier
	s_setprio 1
	s_waitcnt lgkmcnt(0)
	v_mfma_f32_16x16x32_bf16 v[124:127], v[144:147], v[182:185], v[124:127]
	v_mfma_f32_16x16x32_bf16 v[120:123], v[152:155], v[182:185], v[120:123]
	v_mfma_f32_16x16x32_bf16 v[108:111], v[144:147], v[190:193], v[108:111]
	v_mfma_f32_16x16x32_bf16 v[104:107], v[152:155], v[190:193], v[104:107]
	v_mfma_f32_16x16x32_bf16 v[92:95], v[144:147], v[200:203], v[92:95]
	v_mfma_f32_16x16x32_bf16 v[88:91], v[152:155], v[200:203], v[88:91]
	v_mfma_f32_16x16x32_bf16 v[76:79], v[144:147], v[208:211], v[76:79]
	v_mfma_f32_16x16x32_bf16 v[72:75], v[152:155], v[208:211], v[72:75]
	v_mfma_f32_16x16x32_bf16 v[124:127], v[148:151], v[186:189], v[124:127]
	v_mfma_f32_16x16x32_bf16 v[120:123], v[162:165], v[186:189], v[120:123]
	v_mfma_f32_16x16x32_bf16 v[108:111], v[148:151], v[196:199], v[108:111]
	v_mfma_f32_16x16x32_bf16 v[104:107], v[162:165], v[196:199], v[104:107]
	v_mfma_f32_16x16x32_bf16 v[92:95], v[148:151], v[204:207], v[92:95]
	v_mfma_f32_16x16x32_bf16 v[88:91], v[162:165], v[204:207], v[88:91]
	v_mfma_f32_16x16x32_bf16 v[76:79], v[148:151], v[212:215], v[76:79]
	v_mfma_f32_16x16x32_bf16 v[72:75], v[162:165], v[212:215], v[72:75]
	s_setprio 0
	s_setprio 1
	v_mfma_f32_16x16x32_bf16 v[116:119], v[166:169], v[182:185], v[116:119]
	v_mfma_f32_16x16x32_bf16 v[112:115], v[174:177], v[182:185], v[112:115]
	v_mfma_f32_16x16x32_bf16 v[100:103], v[166:169], v[190:193], v[100:103]
	v_mfma_f32_16x16x32_bf16 v[96:99], v[174:177], v[190:193], v[96:99]
	v_mfma_f32_16x16x32_bf16 v[84:87], v[166:169], v[200:203], v[84:87]
	v_mfma_f32_16x16x32_bf16 v[80:83], v[174:177], v[200:203], v[80:83]
	v_mfma_f32_16x16x32_bf16 v[68:71], v[166:169], v[208:211], v[68:71]
	v_mfma_f32_16x16x32_bf16 v[64:67], v[174:177], v[208:211], v[64:67]
	v_mfma_f32_16x16x32_bf16 v[116:119], v[170:173], v[186:189], v[116:119]
	v_mfma_f32_16x16x32_bf16 v[112:115], v[178:181], v[186:189], v[112:115]
	v_mfma_f32_16x16x32_bf16 v[100:103], v[170:173], v[196:199], v[100:103]
	v_mfma_f32_16x16x32_bf16 v[96:99], v[178:181], v[196:199], v[96:99]
	v_mfma_f32_16x16x32_bf16 v[84:87], v[170:173], v[204:207], v[84:87]
	v_mfma_f32_16x16x32_bf16 v[80:83], v[178:181], v[204:207], v[80:83]
	v_mfma_f32_16x16x32_bf16 v[68:71], v[170:173], v[212:215], v[68:71]
	v_mfma_f32_16x16x32_bf16 v[64:67], v[178:181], v[212:215], v[64:67]
	s_setprio 0
	s_barrier
	s_add_i32 s41, s41, s80
	v_lshl_add_u64 v[216:217], v[216:217], 0, s[26:27]
	s_mov_b32 m0, s41
	ds_read_b128 v[182:185], v161 offset:49152
	ds_read_b128 v[186:189], v161 offset:50176
	ds_read_b128 v[190:193], v161 offset:51200
	ds_read_b128 v[196:199], v161 offset:52224
	ds_read_b128 v[200:203], v161 offset:53248
	ds_read_b128 v[204:207], v161 offset:54272
	ds_read_b128 v[208:211], v161 offset:55296
	ds_read_b128 v[212:215], v161 offset:56320
	global_load_lds_dwordx4 v[216:217], off
	s_add_i32 m0, s41, 0x2000
	s_add_u32 s62, s62, 0x20080
	v_lshl_add_u64 v[216:217], v[218:219], 0, s[26:27]
	s_addc_u32 s63, s63, 0
	s_add_i32 s41, s43, s80
	global_load_lds_dwordx4 v[216:217], off
	v_lshl_add_u64 v[216:217], s[62:63], 0, v[130:131]
	s_mov_b32 m0, s41
	s_nop 0
	global_load_lds_dwordx4 v[216:217], off
	v_lshl_add_u64 v[216:217], s[62:63], 0, v[134:135]
	s_add_i32 m0, s41, 0x2000
	s_nop 0
	global_load_lds_dwordx4 v[216:217], off
	v_lshl_add_u64 v[216:217], v[220:221], 0, s[26:27]
	s_mov_b32 m0, s87
	s_nop 0
	global_load_lds_dwordx4 v[216:217], off
	v_lshl_add_u64 v[216:217], v[222:223], 0, s[26:27]
	s_mov_b32 m0, s88
	s_nop 0
	global_load_lds_dwordx4 v[216:217], off
	s_waitcnt vmcnt(8)
	s_waitcnt lgkmcnt(0)
	s_barrier
	s_setprio 1
	s_waitcnt lgkmcnt(0)
	v_mfma_f32_16x16x32_bf16 v[60:63], v[144:147], v[182:185], v[60:63]
	v_mfma_f32_16x16x32_bf16 v[56:59], v[152:155], v[182:185], v[56:59]
	v_mfma_f32_16x16x32_bf16 v[44:47], v[144:147], v[190:193], v[44:47]
	v_mfma_f32_16x16x32_bf16 v[40:43], v[152:155], v[190:193], v[40:43]
	v_mfma_f32_16x16x32_bf16 v[28:31], v[144:147], v[200:203], v[28:31]
	v_mfma_f32_16x16x32_bf16 v[24:27], v[152:155], v[200:203], v[24:27]
	v_mfma_f32_16x16x32_bf16 v[12:15], v[144:147], v[208:211], v[12:15]
	v_mfma_f32_16x16x32_bf16 v[8:11], v[152:155], v[208:211], v[8:11]
	v_mfma_f32_16x16x32_bf16 v[60:63], v[148:151], v[186:189], v[60:63]
	v_mfma_f32_16x16x32_bf16 v[56:59], v[162:165], v[186:189], v[56:59]
	v_mfma_f32_16x16x32_bf16 v[44:47], v[148:151], v[196:199], v[44:47]
	v_mfma_f32_16x16x32_bf16 v[40:43], v[162:165], v[196:199], v[40:43]
	v_mfma_f32_16x16x32_bf16 v[28:31], v[148:151], v[204:207], v[28:31]
	v_mfma_f32_16x16x32_bf16 v[24:27], v[162:165], v[204:207], v[24:27]
	v_mfma_f32_16x16x32_bf16 v[12:15], v[148:151], v[212:215], v[12:15]
	v_mfma_f32_16x16x32_bf16 v[8:11], v[162:165], v[212:215], v[8:11]
	s_setprio 0
	s_setprio 1
	v_mfma_f32_16x16x32_bf16 v[52:55], v[166:169], v[182:185], v[52:55]
	v_mfma_f32_16x16x32_bf16 v[48:51], v[174:177], v[182:185], v[48:51]
	v_mfma_f32_16x16x32_bf16 v[36:39], v[166:169], v[190:193], v[36:39]
	v_mfma_f32_16x16x32_bf16 v[32:35], v[174:177], v[190:193], v[32:35]
	v_mfma_f32_16x16x32_bf16 v[20:23], v[166:169], v[200:203], v[20:23]
	v_mfma_f32_16x16x32_bf16 v[16:19], v[174:177], v[200:203], v[16:19]
	v_mfma_f32_16x16x32_bf16 v[4:7], v[166:169], v[208:211], v[4:7]
	v_mfma_f32_16x16x32_bf16 v[0:3], v[174:177], v[208:211], v[0:3]
	v_mfma_f32_16x16x32_bf16 v[52:55], v[170:173], v[186:189], v[52:55]
	v_mfma_f32_16x16x32_bf16 v[48:51], v[178:181], v[186:189], v[48:51]
	v_mfma_f32_16x16x32_bf16 v[36:39], v[170:173], v[196:199], v[36:39]
	v_mfma_f32_16x16x32_bf16 v[32:35], v[178:181], v[196:199], v[32:35]
	v_mfma_f32_16x16x32_bf16 v[20:23], v[170:173], v[204:207], v[20:23]
	v_mfma_f32_16x16x32_bf16 v[16:19], v[178:181], v[204:207], v[16:19]
	v_mfma_f32_16x16x32_bf16 v[4:7], v[170:173], v[212:215], v[4:7]
	v_mfma_f32_16x16x32_bf16 v[0:3], v[178:181], v[212:215], v[0:3]
	s_setprio 0
	s_barrier
	s_add_i32 s39, s39, 2
	s_add_u32 s58, s58, 0x100
	s_addc_u32 s59, s59, 0
	s_add_u32 s15, s15, 0x100
	s_addc_u32 s17, s17, 0
	s_cmp_gt_u32 s39, 5
	s_cbranch_scc0 .LBB0_1451
	s_and_b64 vcc, exec, s[28:29]
	s_cbranch_vccz .LBB0_1454
	s_barrier

.LBB0_1625:
	ds_read_b128 v[144:147], v151
	ds_read_b128 v[156:159], v151 offset:1024
	ds_read_b128 v[160:163], v151 offset:2048
	ds_read_b128 v[164:167], v151 offset:3072
	ds_read_b128 v[168:171], v152
	ds_read_b128 v[172:175], v152 offset:1024
	ds_read_b128 v[176:179], v152 offset:2048
	ds_read_b128 v[180:183], v152 offset:3072
	s_add_u32 s42, s40, 0xfffc0080
	s_addc_u32 s43, s41, -1
	s_cmp_eq_u32 s87, 12
	s_cselect_b32 s45, s31, s43
	s_cselect_b32 s44, s39, s42
	s_cselect_b32 s43, s29, s86
	s_cselect_b32 s42, s84, s85
	v_lshl_add_u64 v[192:193], s[40:41], 0, v[136:137]
	s_add_i32 m0, s63, 0xc000
	ds_read_b128 v[184:187], v153
	ds_read_b128 v[188:191], v153 offset:1024
	ds_read_b128 v[196:199], v153 offset:2048
	ds_read_b128 v[200:203], v153 offset:3072
	ds_read_b128 v[204:207], v153 offset:4096
	ds_read_b128 v[208:211], v153 offset:5120
	ds_read_b128 v[212:215], v153 offset:6144
	ds_read_b128 v[216:219], v153 offset:7168
	global_load_lds_dwordx4 v[192:193], off
	v_lshl_add_u64 v[192:193], s[40:41], 0, v[138:139]
	s_add_i32 m0, s63, 0xe000
	s_nop 0
	global_load_lds_dwordx4 v[192:193], off
	s_waitcnt vmcnt(8)
	s_waitcnt lgkmcnt(0)
	s_barrier
	s_setprio 1
	s_waitcnt lgkmcnt(0)
	v_mfma_f32_16x16x32_bf16 v[124:127], v[144:147], v[184:187], v[124:127]
	v_mfma_f32_16x16x32_bf16 v[120:123], v[160:163], v[184:187], v[120:123]
	v_mfma_f32_16x16x32_bf16 v[108:111], v[144:147], v[196:199], v[108:111]
	v_mfma_f32_16x16x32_bf16 v[104:107], v[160:163], v[196:199], v[104:107]
	v_mfma_f32_16x16x32_bf16 v[92:95], v[144:147], v[204:207], v[92:95]
	v_mfma_f32_16x16x32_bf16 v[88:91], v[160:163], v[204:207], v[88:91]
	v_mfma_f32_16x16x32_bf16 v[76:79], v[144:147], v[212:215], v[76:79]
	v_mfma_f32_16x16x32_bf16 v[72:75], v[160:163], v[212:215], v[72:75]
	v_mfma_f32_16x16x32_bf16 v[124:127], v[156:159], v[188:191], v[124:127]
	v_mfma_f32_16x16x32_bf16 v[120:123], v[164:167], v[188:191], v[120:123]
	v_mfma_f32_16x16x32_bf16 v[108:111], v[156:159], v[200:203], v[108:111]
	v_mfma_f32_16x16x32_bf16 v[104:107], v[164:167], v[200:203], v[104:107]
	v_mfma_f32_16x16x32_bf16 v[92:95], v[156:159], v[208:211], v[92:95]
	v_mfma_f32_16x16x32_bf16 v[88:91], v[164:167], v[208:211], v[88:91]
	v_mfma_f32_16x16x32_bf16 v[76:79], v[156:159], v[216:219], v[76:79]
	v_mfma_f32_16x16x32_bf16 v[72:75], v[164:167], v[216:219], v[72:75]
	s_setprio 0
	s_setprio 1
	v_mfma_f32_16x16x32_bf16 v[116:119], v[168:171], v[184:187], v[116:119]
	v_mfma_f32_16x16x32_bf16 v[112:115], v[176:179], v[184:187], v[112:115]
	v_mfma_f32_16x16x32_bf16 v[100:103], v[168:171], v[196:199], v[100:103]
	v_mfma_f32_16x16x32_bf16 v[96:99], v[176:179], v[196:199], v[96:99]
	v_mfma_f32_16x16x32_bf16 v[84:87], v[168:171], v[204:207], v[84:87]
	v_mfma_f32_16x16x32_bf16 v[80:83], v[176:179], v[204:207], v[80:83]
	v_mfma_f32_16x16x32_bf16 v[68:71], v[168:171], v[212:215], v[68:71]
	v_mfma_f32_16x16x32_bf16 v[64:67], v[176:179], v[212:215], v[64:67]
	v_mfma_f32_16x16x32_bf16 v[116:119], v[172:175], v[188:191], v[116:119]
	v_mfma_f32_16x16x32_bf16 v[112:115], v[180:183], v[188:191], v[112:115]
	v_mfma_f32_16x16x32_bf16 v[100:103], v[172:175], v[200:203], v[100:103]
	v_mfma_f32_16x16x32_bf16 v[96:99], v[180:183], v[200:203], v[96:99]
	v_mfma_f32_16x16x32_bf16 v[84:87], v[172:175], v[208:211], v[84:87]
	v_mfma_f32_16x16x32_bf16 v[80:83], v[180:183], v[208:211], v[80:83]
	v_mfma_f32_16x16x32_bf16 v[68:71], v[172:175], v[216:219], v[68:71]
	v_mfma_f32_16x16x32_bf16 v[64:67], v[180:183], v[216:219], v[64:67]
	s_setprio 0
	s_barrier
	s_add_i32 s88, s81, s62
	v_lshl_add_u64 v[192:193], s[42:43], 0, v[130:131]
	s_mov_b32 m0, s88
	ds_read_b128 v[184:187], v153 offset:16384
	ds_read_b128 v[188:191], v153 offset:17408
	ds_read_b128 v[196:199], v153 offset:18432
	ds_read_b128 v[200:203], v153 offset:19456
	ds_read_b128 v[204:207], v153 offset:20480
	ds_read_b128 v[208:211], v153 offset:21504
	ds_read_b128 v[212:215], v153 offset:22528
	ds_read_b128 v[216:219], v153 offset:23552
	global_load_lds_dwordx4 v[192:193], off
	s_add_i32 m0, s88, 0x2000
	s_add_u32 s88, s42, 0x40000
	v_lshl_add_u64 v[220:221], s[42:43], 0, v[134:135]
	s_addc_u32 s89, s43, 0
	s_add_i32 s90, s82, s62
	global_load_lds_dwordx4 v[220:221], off
	v_lshl_add_u64 v[222:223], s[88:89], 0, v[130:131]
	s_mov_b32 m0, s90
	v_lshl_add_u64 v[224:225], s[44:45], 0, v[132:133]
	global_load_lds_dwordx4 v[222:223], off
	v_lshl_add_u64 v[222:223], s[88:89], 0, v[134:135]
	s_add_i32 m0, s90, 0x2000
	s_nop 0
	global_load_lds_dwordx4 v[222:223], off
	v_lshl_add_u64 v[222:223], s[44:45], 0, v[128:129]
	s_waitcnt vmcnt(6)
	s_waitcnt lgkmcnt(0)
	s_barrier
	s_setprio 1
	s_waitcnt lgkmcnt(0)
	v_mfma_f32_16x16x32_bf16 v[60:63], v[144:147], v[184:187], v[60:63]
	v_mfma_f32_16x16x32_bf16 v[56:59], v[160:163], v[184:187], v[56:59]
	v_mfma_f32_16x16x32_bf16 v[44:47], v[144:147], v[196:199], v[44:47]
	v_mfma_f32_16x16x32_bf16 v[40:43], v[160:163], v[196:199], v[40:43]
	v_mfma_f32_16x16x32_bf16 v[28:31], v[144:147], v[204:207], v[28:31]
	v_mfma_f32_16x16x32_bf16 v[24:27], v[160:163], v[204:207], v[24:27]
	v_mfma_f32_16x16x32_bf16 v[12:15], v[144:147], v[212:215], v[12:15]
	v_mfma_f32_16x16x32_bf16 v[8:11], v[160:163], v[212:215], v[8:11]
	v_mfma_f32_16x16x32_bf16 v[60:63], v[156:159], v[188:191], v[60:63]
	v_mfma_f32_16x16x32_bf16 v[56:59], v[164:167], v[188:191], v[56:59]
	v_mfma_f32_16x16x32_bf16 v[44:47], v[156:159], v[200:203], v[44:47]
	v_mfma_f32_16x16x32_bf16 v[40:43], v[164:167], v[200:203], v[40:43]
	v_mfma_f32_16x16x32_bf16 v[28:31], v[156:159], v[208:211], v[28:31]
	v_mfma_f32_16x16x32_bf16 v[24:27], v[164:167], v[208:211], v[24:27]
	v_mfma_f32_16x16x32_bf16 v[12:15], v[156:159], v[216:219], v[12:15]
	v_mfma_f32_16x16x32_bf16 v[8:11], v[164:167], v[216:219], v[8:11]
	s_setprio 0
	s_setprio 1
	v_mfma_f32_16x16x32_bf16 v[52:55], v[168:171], v[184:187], v[52:55]
	v_mfma_f32_16x16x32_bf16 v[48:51], v[176:179], v[184:187], v[48:51]
	v_mfma_f32_16x16x32_bf16 v[36:39], v[168:171], v[196:199], v[36:39]
	v_mfma_f32_16x16x32_bf16 v[32:35], v[176:179], v[196:199], v[32:35]
	v_mfma_f32_16x16x32_bf16 v[20:23], v[168:171], v[204:207], v[20:23]
	v_mfma_f32_16x16x32_bf16 v[16:19], v[176:179], v[204:207], v[16:19]
	v_mfma_f32_16x16x32_bf16 v[4:7], v[168:171], v[212:215], v[4:7]
	v_mfma_f32_16x16x32_bf16 v[0:3], v[176:179], v[212:215], v[0:3]
	v_mfma_f32_16x16x32_bf16 v[52:55], v[172:175], v[188:191], v[52:55]
	v_mfma_f32_16x16x32_bf16 v[48:51], v[180:183], v[188:191], v[48:51]
	v_mfma_f32_16x16x32_bf16 v[36:39], v[172:175], v[200:203], v[36:39]
	v_mfma_f32_16x16x32_bf16 v[32:35], v[180:183], v[200:203], v[32:35]
	v_mfma_f32_16x16x32_bf16 v[20:23], v[172:175], v[208:211], v[20:23]
	v_mfma_f32_16x16x32_bf16 v[16:19], v[180:183], v[208:211], v[16:19]
	v_mfma_f32_16x16x32_bf16 v[4:7], v[172:175], v[216:219], v[4:7]
	v_mfma_f32_16x16x32_bf16 v[0:3], v[180:183], v[216:219], v[0:3]
	s_setprio 0
	s_barrier
	s_add_i32 s88, 0, 0x18000
	v_add_u32_e32 v155, s88, v149
	s_add_i32 s89, 0, 0x1c000
	ds_read_b128 v[144:147], v155
	ds_read_b128 v[156:159], v155 offset:1024
	ds_read_b128 v[160:163], v155 offset:2048
	ds_read_b128 v[164:167], v155 offset:3072
	v_add_u32_e32 v155, s89, v149
	ds_read_b128 v[168:171], v155
	ds_read_b128 v[172:175], v155 offset:1024
	ds_read_b128 v[176:179], v155 offset:2048
	ds_read_b128 v[180:183], v155 offset:3072
	s_add_u32 s44, s44, 0x40000
	s_addc_u32 s45, s45, 0
	v_lshl_add_u64 v[226:227], s[44:45], 0, v[128:129]
	ds_read_b128 v[184:187], v153 offset:32768
	ds_read_b128 v[188:191], v153 offset:33792
	ds_read_b128 v[196:199], v153 offset:34816
	ds_read_b128 v[200:203], v153 offset:35840
	ds_read_b128 v[204:207], v153 offset:36864
	ds_read_b128 v[208:211], v153 offset:37888
	ds_read_b128 v[212:215], v153 offset:38912
	ds_read_b128 v[216:219], v153 offset:39936
	s_mov_b32 m0, s63
	s_nop 0
	global_load_lds_dwordx4 v[222:223], off
	s_mov_b32 m0, s70
	s_nop 0
	global_load_lds_dwordx4 v[224:225], off
	s_mov_b32 m0, s71
	s_nop 0
	global_load_lds_dwordx4 v[226:227], off
	v_lshl_add_u64 v[226:227], s[44:45], 0, v[132:133]
	s_mov_b32 m0, s72
	s_nop 0
	global_load_lds_dwordx4 v[226:227], off
	s_waitcnt vmcnt(8)
	s_waitcnt lgkmcnt(0)
	s_barrier
	s_setprio 1
	s_waitcnt lgkmcnt(0)
	v_mfma_f32_16x16x32_bf16 v[124:127], v[144:147], v[184:187], v[124:127]
	v_mfma_f32_16x16x32_bf16 v[120:123], v[160:163], v[184:187], v[120:123]
	v_mfma_f32_16x16x32_bf16 v[108:111], v[144:147], v[196:199], v[108:111]
	v_mfma_f32_16x16x32_bf16 v[104:107], v[160:163], v[196:199], v[104:107]
	v_mfma_f32_16x16x32_bf16 v[92:95], v[144:147], v[204:207], v[92:95]
	v_mfma_f32_16x16x32_bf16 v[88:91], v[160:163], v[204:207], v[88:91]
	v_mfma_f32_16x16x32_bf16 v[76:79], v[144:147], v[212:215], v[76:79]
	v_mfma_f32_16x16x32_bf16 v[72:75], v[160:163], v[212:215], v[72:75]
	v_mfma_f32_16x16x32_bf16 v[124:127], v[156:159], v[188:191], v[124:127]
	v_mfma_f32_16x16x32_bf16 v[120:123], v[164:167], v[188:191], v[120:123]
	v_mfma_f32_16x16x32_bf16 v[108:111], v[156:159], v[200:203], v[108:111]
	v_mfma_f32_16x16x32_bf16 v[104:107], v[164:167], v[200:203], v[104:107]
	v_mfma_f32_16x16x32_bf16 v[92:95], v[156:159], v[208:211], v[92:95]
	v_mfma_f32_16x16x32_bf16 v[88:91], v[164:167], v[208:211], v[88:91]
	v_mfma_f32_16x16x32_bf16 v[76:79], v[156:159], v[216:219], v[76:79]
	v_mfma_f32_16x16x32_bf16 v[72:75], v[164:167], v[216:219], v[72:75]
	s_setprio 0
	s_setprio 1
	v_mfma_f32_16x16x32_bf16 v[116:119], v[168:171], v[184:187], v[116:119]
	v_mfma_f32_16x16x32_bf16 v[112:115], v[176:179], v[184:187], v[112:115]
	v_mfma_f32_16x16x32_bf16 v[100:103], v[168:171], v[196:199], v[100:103]
	v_mfma_f32_16x16x32_bf16 v[96:99], v[176:179], v[196:199], v[96:99]
	v_mfma_f32_16x16x32_bf16 v[84:87], v[168:171], v[204:207], v[84:87]
	v_mfma_f32_16x16x32_bf16 v[80:83], v[176:179], v[204:207], v[80:83]
	v_mfma_f32_16x16x32_bf16 v[68:71], v[168:171], v[212:215], v[68:71]
	v_mfma_f32_16x16x32_bf16 v[64:67], v[176:179], v[212:215], v[64:67]
	v_mfma_f32_16x16x32_bf16 v[116:119], v[172:175], v[188:191], v[116:119]
	v_mfma_f32_16x16x32_bf16 v[112:115], v[180:183], v[188:191], v[112:115]
	v_mfma_f32_16x16x32_bf16 v[100:103], v[172:175], v[200:203], v[100:103]
	v_mfma_f32_16x16x32_bf16 v[96:99], v[180:183], v[200:203], v[96:99]
	v_mfma_f32_16x16x32_bf16 v[84:87], v[172:175], v[208:211], v[84:87]
	v_mfma_f32_16x16x32_bf16 v[80:83], v[180:183], v[208:211], v[80:83]
	v_mfma_f32_16x16x32_bf16 v[68:71], v[172:175], v[216:219], v[68:71]
	v_mfma_f32_16x16x32_bf16 v[64:67], v[180:183], v[216:219], v[64:67]
	s_setprio 0
	s_barrier
	s_add_i32 s44, s88, s62
	v_lshl_add_u64 v[192:193], v[192:193], 0, s[24:25]
	s_mov_b32 m0, s44
	ds_read_b128 v[184:187], v153 offset:49152
	ds_read_b128 v[188:191], v153 offset:50176
	ds_read_b128 v[196:199], v153 offset:51200
	ds_read_b128 v[200:203], v153 offset:52224
	ds_read_b128 v[204:207], v153 offset:53248
	ds_read_b128 v[208:211], v153 offset:54272
	ds_read_b128 v[212:215], v153 offset:55296
	ds_read_b128 v[216:219], v153 offset:56320
	global_load_lds_dwordx4 v[192:193], off
	s_add_i32 m0, s44, 0x2000
	s_add_u32 s42, s42, 0x40080
	v_lshl_add_u64 v[192:193], v[220:221], 0, s[24:25]
	s_addc_u32 s43, s43, 0
	s_add_i32 s44, s89, s62
	global_load_lds_dwordx4 v[192:193], off
	v_lshl_add_u64 v[192:193], s[42:43], 0, v[130:131]
	s_mov_b32 m0, s44
	s_nop 0
	global_load_lds_dwordx4 v[192:193], off
	v_lshl_add_u64 v[192:193], s[42:43], 0, v[134:135]
	s_add_i32 m0, s44, 0x2000
	s_nop 0
	global_load_lds_dwordx4 v[192:193], off
	v_lshl_add_u64 v[192:193], v[222:223], 0, s[24:25]
	s_mov_b32 m0, s78
	s_nop 0
	global_load_lds_dwordx4 v[192:193], off
	v_lshl_add_u64 v[192:193], v[224:225], 0, s[24:25]
	s_mov_b32 m0, s79
	s_nop 0
	global_load_lds_dwordx4 v[192:193], off
	s_waitcnt vmcnt(8)
	s_waitcnt lgkmcnt(0)
	s_barrier
	s_setprio 1
	s_waitcnt lgkmcnt(0)
	v_mfma_f32_16x16x32_bf16 v[60:63], v[144:147], v[184:187], v[60:63]
	v_mfma_f32_16x16x32_bf16 v[56:59], v[160:163], v[184:187], v[56:59]
	v_mfma_f32_16x16x32_bf16 v[44:47], v[144:147], v[196:199], v[44:47]
	v_mfma_f32_16x16x32_bf16 v[40:43], v[160:163], v[196:199], v[40:43]
	v_mfma_f32_16x16x32_bf16 v[28:31], v[144:147], v[204:207], v[28:31]
	v_mfma_f32_16x16x32_bf16 v[24:27], v[160:163], v[204:207], v[24:27]
	v_mfma_f32_16x16x32_bf16 v[12:15], v[144:147], v[212:215], v[12:15]
	v_mfma_f32_16x16x32_bf16 v[8:11], v[160:163], v[212:215], v[8:11]
	v_mfma_f32_16x16x32_bf16 v[60:63], v[156:159], v[188:191], v[60:63]
	v_mfma_f32_16x16x32_bf16 v[56:59], v[164:167], v[188:191], v[56:59]
	v_mfma_f32_16x16x32_bf16 v[44:47], v[156:159], v[200:203], v[44:47]
	v_mfma_f32_16x16x32_bf16 v[40:43], v[164:167], v[200:203], v[40:43]
	v_mfma_f32_16x16x32_bf16 v[28:31], v[156:159], v[208:211], v[28:31]
	v_mfma_f32_16x16x32_bf16 v[24:27], v[164:167], v[208:211], v[24:27]
	v_mfma_f32_16x16x32_bf16 v[12:15], v[156:159], v[216:219], v[12:15]
	v_mfma_f32_16x16x32_bf16 v[8:11], v[164:167], v[216:219], v[8:11]
	s_setprio 0
	s_setprio 1
	v_mfma_f32_16x16x32_bf16 v[52:55], v[168:171], v[184:187], v[52:55]
	v_mfma_f32_16x16x32_bf16 v[48:51], v[176:179], v[184:187], v[48:51]
	v_mfma_f32_16x16x32_bf16 v[36:39], v[168:171], v[196:199], v[36:39]
	v_mfma_f32_16x16x32_bf16 v[32:35], v[176:179], v[196:199], v[32:35]
	v_mfma_f32_16x16x32_bf16 v[20:23], v[168:171], v[204:207], v[20:23]
	v_mfma_f32_16x16x32_bf16 v[16:19], v[176:179], v[204:207], v[16:19]
	v_mfma_f32_16x16x32_bf16 v[4:7], v[168:171], v[212:215], v[4:7]
	v_mfma_f32_16x16x32_bf16 v[0:3], v[176:179], v[212:215], v[0:3]
	v_mfma_f32_16x16x32_bf16 v[52:55], v[172:175], v[188:191], v[52:55]
	v_mfma_f32_16x16x32_bf16 v[48:51], v[180:183], v[188:191], v[48:51]
	v_mfma_f32_16x16x32_bf16 v[36:39], v[172:175], v[200:203], v[36:39]
	v_mfma_f32_16x16x32_bf16 v[32:35], v[180:183], v[200:203], v[32:35]
	v_mfma_f32_16x16x32_bf16 v[20:23], v[172:175], v[208:211], v[20:23]
	v_mfma_f32_16x16x32_bf16 v[16:19], v[180:183], v[208:211], v[16:19]
	v_mfma_f32_16x16x32_bf16 v[4:7], v[172:175], v[216:219], v[4:7]
	v_mfma_f32_16x16x32_bf16 v[0:3], v[180:183], v[216:219], v[0:3]
	s_setprio 0
	s_barrier
	s_add_i32 s87, s87, 2
	s_add_u32 s40, s40, 0x100
	s_addc_u32 s41, s41, 0
	s_add_u32 s85, s85, 0x100
	s_addc_u32 s86, s86, 0
	s_cmp_gt_u32 s87, 13
	s_cbranch_scc0 .LBB0_1625
	s_and_b64 vcc, exec, s[26:27]
	s_cbranch_vccz .LBB0_1628
	s_barrier

.LBB0_1709:
	ds_read_b128 v[154:157], v149
	ds_read_b128 v[158:161], v149 offset:1024
	ds_read_b128 v[162:165], v149 offset:2048
	ds_read_b128 v[166:169], v149 offset:3072
	ds_read_b128 v[170:173], v150
	ds_read_b128 v[174:177], v150 offset:1024
	ds_read_b128 v[178:181], v150 offset:2048
	ds_read_b128 v[182:185], v150 offset:3072
	s_add_u32 s38, s36, 0xfffc0080
	s_addc_u32 s39, s37, -1
	s_cmp_eq_u32 s84, 12
	s_cselect_b32 s41, s27, s39
	s_cselect_b32 s40, s80, s38
	s_cselect_b32 s39, s25, s83
	s_cselect_b32 s38, s81, s82
	v_lshl_add_u64 v[144:145], s[36:37], 0, v[136:137]
	s_add_i32 m0, s35, 0xc000
	ds_read_b128 v[186:189], v151
	ds_read_b128 v[190:193], v151 offset:1024
	ds_read_b128 v[196:199], v151 offset:2048
	ds_read_b128 v[200:203], v151 offset:3072
	ds_read_b128 v[204:207], v151 offset:4096
	ds_read_b128 v[208:211], v151 offset:5120
	ds_read_b128 v[212:215], v151 offset:6144
	ds_read_b128 v[216:219], v151 offset:7168
	global_load_lds_dwordx4 v[144:145], off
	v_lshl_add_u64 v[144:145], s[36:37], 0, v[138:139]
	s_add_i32 m0, s35, 0xe000
	s_nop 0
	global_load_lds_dwordx4 v[144:145], off
	s_waitcnt vmcnt(8)
	s_waitcnt lgkmcnt(0)
	s_barrier
	s_setprio 1
	s_waitcnt lgkmcnt(0)
	v_mfma_f32_16x16x32_bf16 v[116:119], v[154:157], v[186:189], v[116:119]
	v_mfma_f32_16x16x32_bf16 v[112:115], v[162:165], v[186:189], v[112:115]
	v_mfma_f32_16x16x32_bf16 v[100:103], v[154:157], v[196:199], v[100:103]
	v_mfma_f32_16x16x32_bf16 v[96:99], v[162:165], v[196:199], v[96:99]
	v_mfma_f32_16x16x32_bf16 v[84:87], v[154:157], v[204:207], v[84:87]
	v_mfma_f32_16x16x32_bf16 v[80:83], v[162:165], v[204:207], v[80:83]
	v_mfma_f32_16x16x32_bf16 v[68:71], v[154:157], v[212:215], v[68:71]
	v_mfma_f32_16x16x32_bf16 v[64:67], v[162:165], v[212:215], v[64:67]
	v_mfma_f32_16x16x32_bf16 v[116:119], v[158:161], v[190:193], v[116:119]
	v_mfma_f32_16x16x32_bf16 v[112:115], v[166:169], v[190:193], v[112:115]
	v_mfma_f32_16x16x32_bf16 v[100:103], v[158:161], v[200:203], v[100:103]
	v_mfma_f32_16x16x32_bf16 v[96:99], v[166:169], v[200:203], v[96:99]
	v_mfma_f32_16x16x32_bf16 v[84:87], v[158:161], v[208:211], v[84:87]
	v_mfma_f32_16x16x32_bf16 v[80:83], v[166:169], v[208:211], v[80:83]
	v_mfma_f32_16x16x32_bf16 v[68:71], v[158:161], v[216:219], v[68:71]
	v_mfma_f32_16x16x32_bf16 v[64:67], v[166:169], v[216:219], v[64:67]
	s_setprio 0
	s_setprio 1
	v_mfma_f32_16x16x32_bf16 v[124:127], v[170:173], v[186:189], v[124:127]
	v_mfma_f32_16x16x32_bf16 v[120:123], v[178:181], v[186:189], v[120:123]
	v_mfma_f32_16x16x32_bf16 v[108:111], v[170:173], v[196:199], v[108:111]
	v_mfma_f32_16x16x32_bf16 v[104:107], v[178:181], v[196:199], v[104:107]
	v_mfma_f32_16x16x32_bf16 v[92:95], v[170:173], v[204:207], v[92:95]
	v_mfma_f32_16x16x32_bf16 v[88:91], v[178:181], v[204:207], v[88:91]
	v_mfma_f32_16x16x32_bf16 v[76:79], v[170:173], v[212:215], v[76:79]
	v_mfma_f32_16x16x32_bf16 v[72:75], v[178:181], v[212:215], v[72:75]
	v_mfma_f32_16x16x32_bf16 v[124:127], v[174:177], v[190:193], v[124:127]
	v_mfma_f32_16x16x32_bf16 v[120:123], v[182:185], v[190:193], v[120:123]
	v_mfma_f32_16x16x32_bf16 v[108:111], v[174:177], v[200:203], v[108:111]
	v_mfma_f32_16x16x32_bf16 v[104:107], v[182:185], v[200:203], v[104:107]
	v_mfma_f32_16x16x32_bf16 v[92:95], v[174:177], v[208:211], v[92:95]
	v_mfma_f32_16x16x32_bf16 v[88:91], v[182:185], v[208:211], v[88:91]
	v_mfma_f32_16x16x32_bf16 v[76:79], v[174:177], v[216:219], v[76:79]
	v_mfma_f32_16x16x32_bf16 v[72:75], v[182:185], v[216:219], v[72:75]
	s_setprio 0
	s_barrier
	s_add_i32 s85, s71, s56
	v_lshl_add_u64 v[144:145], s[38:39], 0, v[132:133]
	s_mov_b32 m0, s85
	ds_read_b128 v[186:189], v151 offset:16384
	ds_read_b128 v[190:193], v151 offset:17408
	ds_read_b128 v[196:199], v151 offset:18432
	ds_read_b128 v[200:203], v151 offset:19456
	ds_read_b128 v[204:207], v151 offset:20480
	ds_read_b128 v[208:211], v151 offset:21504
	ds_read_b128 v[212:215], v151 offset:22528
	ds_read_b128 v[216:219], v151 offset:23552
	global_load_lds_dwordx4 v[144:145], off
	s_add_i32 m0, s85, 0x2000
	s_add_u32 s86, s38, 0x40000
	v_lshl_add_u64 v[220:221], s[38:39], 0, v[128:129]
	s_addc_u32 s87, s39, 0
	s_add_i32 s85, s72, s56
	global_load_lds_dwordx4 v[220:221], off
	v_lshl_add_u64 v[222:223], s[86:87], 0, v[132:133]
	s_mov_b32 m0, s85
	v_lshl_add_u64 v[224:225], s[40:41], 0, v[130:131]
	global_load_lds_dwordx4 v[222:223], off
	v_lshl_add_u64 v[222:223], s[86:87], 0, v[128:129]
	s_add_i32 m0, s85, 0x2000
	s_nop 0
	global_load_lds_dwordx4 v[222:223], off
	v_lshl_add_u64 v[222:223], s[40:41], 0, v[134:135]
	s_waitcnt vmcnt(6)
	s_waitcnt lgkmcnt(0)
	s_barrier
	s_setprio 1
	s_waitcnt lgkmcnt(0)
	v_mfma_f32_16x16x32_bf16 v[52:55], v[154:157], v[186:189], v[52:55]
	v_mfma_f32_16x16x32_bf16 v[48:51], v[162:165], v[186:189], v[48:51]
	v_mfma_f32_16x16x32_bf16 v[36:39], v[154:157], v[196:199], v[36:39]
	v_mfma_f32_16x16x32_bf16 v[32:35], v[162:165], v[196:199], v[32:35]
	v_mfma_f32_16x16x32_bf16 v[20:23], v[154:157], v[204:207], v[20:23]
	v_mfma_f32_16x16x32_bf16 v[16:19], v[162:165], v[204:207], v[16:19]
	v_mfma_f32_16x16x32_bf16 v[4:7], v[154:157], v[212:215], v[4:7]
	v_mfma_f32_16x16x32_bf16 v[0:3], v[162:165], v[212:215], v[0:3]
	v_mfma_f32_16x16x32_bf16 v[52:55], v[158:161], v[190:193], v[52:55]
	v_mfma_f32_16x16x32_bf16 v[48:51], v[166:169], v[190:193], v[48:51]
	v_mfma_f32_16x16x32_bf16 v[36:39], v[158:161], v[200:203], v[36:39]
	v_mfma_f32_16x16x32_bf16 v[32:35], v[166:169], v[200:203], v[32:35]
	v_mfma_f32_16x16x32_bf16 v[20:23], v[158:161], v[208:211], v[20:23]
	v_mfma_f32_16x16x32_bf16 v[16:19], v[166:169], v[208:211], v[16:19]
	v_mfma_f32_16x16x32_bf16 v[4:7], v[158:161], v[216:219], v[4:7]
	v_mfma_f32_16x16x32_bf16 v[0:3], v[166:169], v[216:219], v[0:3]
	s_setprio 0
	s_setprio 1
	v_mfma_f32_16x16x32_bf16 v[60:63], v[170:173], v[186:189], v[60:63]
	v_mfma_f32_16x16x32_bf16 v[56:59], v[178:181], v[186:189], v[56:59]
	v_mfma_f32_16x16x32_bf16 v[44:47], v[170:173], v[196:199], v[44:47]
	v_mfma_f32_16x16x32_bf16 v[40:43], v[178:181], v[196:199], v[40:43]
	v_mfma_f32_16x16x32_bf16 v[28:31], v[170:173], v[204:207], v[28:31]
	v_mfma_f32_16x16x32_bf16 v[24:27], v[178:181], v[204:207], v[24:27]
	v_mfma_f32_16x16x32_bf16 v[12:15], v[170:173], v[212:215], v[12:15]
	v_mfma_f32_16x16x32_bf16 v[8:11], v[178:181], v[212:215], v[8:11]
	v_mfma_f32_16x16x32_bf16 v[60:63], v[174:177], v[190:193], v[60:63]
	v_mfma_f32_16x16x32_bf16 v[56:59], v[182:185], v[190:193], v[56:59]
	v_mfma_f32_16x16x32_bf16 v[44:47], v[174:177], v[200:203], v[44:47]
	v_mfma_f32_16x16x32_bf16 v[40:43], v[182:185], v[200:203], v[40:43]
	v_mfma_f32_16x16x32_bf16 v[28:31], v[174:177], v[208:211], v[28:31]
	v_mfma_f32_16x16x32_bf16 v[24:27], v[182:185], v[208:211], v[24:27]
	v_mfma_f32_16x16x32_bf16 v[12:15], v[174:177], v[216:219], v[12:15]
	v_mfma_f32_16x16x32_bf16 v[8:11], v[182:185], v[216:219], v[8:11]
	s_setprio 0
	s_barrier
	s_add_i32 s85, 0, 0x18000
	v_add_u32_e32 v153, s85, v147
	s_add_i32 s86, 0, 0x1c000
	ds_read_b128 v[154:157], v153
	ds_read_b128 v[158:161], v153 offset:1024
	ds_read_b128 v[162:165], v153 offset:2048
	ds_read_b128 v[166:169], v153 offset:3072
	v_add_u32_e32 v153, s86, v147
	ds_read_b128 v[170:173], v153
	ds_read_b128 v[174:177], v153 offset:1024
	ds_read_b128 v[178:181], v153 offset:2048
	ds_read_b128 v[182:185], v153 offset:3072
	s_add_u32 s40, s40, 0x40000
	s_addc_u32 s41, s41, 0
	v_lshl_add_u64 v[226:227], s[40:41], 0, v[134:135]
	ds_read_b128 v[186:189], v151 offset:32768
	ds_read_b128 v[190:193], v151 offset:33792
	ds_read_b128 v[196:199], v151 offset:34816
	ds_read_b128 v[200:203], v151 offset:35840
	ds_read_b128 v[204:207], v151 offset:36864
	ds_read_b128 v[208:211], v151 offset:37888
	ds_read_b128 v[212:215], v151 offset:38912
	ds_read_b128 v[216:219], v151 offset:39936
	s_mov_b32 m0, s35
	s_nop 0
	global_load_lds_dwordx4 v[222:223], off
	s_mov_b32 m0, s58
	s_nop 0
	global_load_lds_dwordx4 v[224:225], off
	s_mov_b32 m0, s59
	s_nop 0
	global_load_lds_dwordx4 v[226:227], off
	v_lshl_add_u64 v[226:227], s[40:41], 0, v[130:131]
	s_mov_b32 m0, s60
	s_nop 0
	global_load_lds_dwordx4 v[226:227], off
	s_waitcnt vmcnt(8)
	s_waitcnt lgkmcnt(0)
	s_barrier
	s_setprio 1
	s_waitcnt lgkmcnt(0)
	v_mfma_f32_16x16x32_bf16 v[116:119], v[154:157], v[186:189], v[116:119]
	v_mfma_f32_16x16x32_bf16 v[112:115], v[162:165], v[186:189], v[112:115]
	v_mfma_f32_16x16x32_bf16 v[100:103], v[154:157], v[196:199], v[100:103]
	v_mfma_f32_16x16x32_bf16 v[96:99], v[162:165], v[196:199], v[96:99]
	v_mfma_f32_16x16x32_bf16 v[84:87], v[154:157], v[204:207], v[84:87]
	v_mfma_f32_16x16x32_bf16 v[80:83], v[162:165], v[204:207], v[80:83]
	v_mfma_f32_16x16x32_bf16 v[68:71], v[154:157], v[212:215], v[68:71]
	v_mfma_f32_16x16x32_bf16 v[64:67], v[162:165], v[212:215], v[64:67]
	v_mfma_f32_16x16x32_bf16 v[116:119], v[158:161], v[190:193], v[116:119]
	v_mfma_f32_16x16x32_bf16 v[112:115], v[166:169], v[190:193], v[112:115]
	v_mfma_f32_16x16x32_bf16 v[100:103], v[158:161], v[200:203], v[100:103]
	v_mfma_f32_16x16x32_bf16 v[96:99], v[166:169], v[200:203], v[96:99]
	v_mfma_f32_16x16x32_bf16 v[84:87], v[158:161], v[208:211], v[84:87]
	v_mfma_f32_16x16x32_bf16 v[80:83], v[166:169], v[208:211], v[80:83]
	v_mfma_f32_16x16x32_bf16 v[68:71], v[158:161], v[216:219], v[68:71]
	v_mfma_f32_16x16x32_bf16 v[64:67], v[166:169], v[216:219], v[64:67]
	s_setprio 0
	s_setprio 1
	v_mfma_f32_16x16x32_bf16 v[124:127], v[170:173], v[186:189], v[124:127]
	v_mfma_f32_16x16x32_bf16 v[120:123], v[178:181], v[186:189], v[120:123]
	v_mfma_f32_16x16x32_bf16 v[108:111], v[170:173], v[196:199], v[108:111]
	v_mfma_f32_16x16x32_bf16 v[104:107], v[178:181], v[196:199], v[104:107]
	v_mfma_f32_16x16x32_bf16 v[92:95], v[170:173], v[204:207], v[92:95]
	v_mfma_f32_16x16x32_bf16 v[88:91], v[178:181], v[204:207], v[88:91]
	v_mfma_f32_16x16x32_bf16 v[76:79], v[170:173], v[212:215], v[76:79]
	v_mfma_f32_16x16x32_bf16 v[72:75], v[178:181], v[212:215], v[72:75]
	v_mfma_f32_16x16x32_bf16 v[124:127], v[174:177], v[190:193], v[124:127]
	v_mfma_f32_16x16x32_bf16 v[120:123], v[182:185], v[190:193], v[120:123]
	v_mfma_f32_16x16x32_bf16 v[108:111], v[174:177], v[200:203], v[108:111]
	v_mfma_f32_16x16x32_bf16 v[104:107], v[182:185], v[200:203], v[104:107]
	v_mfma_f32_16x16x32_bf16 v[92:95], v[174:177], v[208:211], v[92:95]
	v_mfma_f32_16x16x32_bf16 v[88:91], v[182:185], v[208:211], v[88:91]
	v_mfma_f32_16x16x32_bf16 v[76:79], v[174:177], v[216:219], v[76:79]
	v_mfma_f32_16x16x32_bf16 v[72:75], v[182:185], v[216:219], v[72:75]
	s_setprio 0
	s_barrier
	s_add_i32 s40, s85, s56
	v_lshl_add_u64 v[144:145], v[144:145], 0, s[20:21]
	s_mov_b32 m0, s40
	ds_read_b128 v[186:189], v151 offset:49152
	ds_read_b128 v[190:193], v151 offset:50176
	ds_read_b128 v[196:199], v151 offset:51200
	ds_read_b128 v[200:203], v151 offset:52224
	ds_read_b128 v[204:207], v151 offset:53248
	ds_read_b128 v[208:211], v151 offset:54272
	ds_read_b128 v[212:215], v151 offset:55296
	ds_read_b128 v[216:219], v151 offset:56320
	global_load_lds_dwordx4 v[144:145], off
	s_add_i32 m0, s40, 0x2000
	s_add_u32 s38, s38, 0x40080
	v_lshl_add_u64 v[144:145], v[220:221], 0, s[20:21]
	s_addc_u32 s39, s39, 0
	s_add_i32 s40, s86, s56
	global_load_lds_dwordx4 v[144:145], off
	v_lshl_add_u64 v[144:145], s[38:39], 0, v[132:133]
	s_mov_b32 m0, s40
	s_nop 0
	global_load_lds_dwordx4 v[144:145], off
	v_lshl_add_u64 v[144:145], s[38:39], 0, v[128:129]
	s_add_i32 m0, s40, 0x2000
	s_nop 0
	global_load_lds_dwordx4 v[144:145], off
	v_lshl_add_u64 v[144:145], v[222:223], 0, s[20:21]
	s_mov_b32 m0, s62
	s_nop 0
	global_load_lds_dwordx4 v[144:145], off
	v_lshl_add_u64 v[144:145], v[224:225], 0, s[20:21]
	s_mov_b32 m0, s63
	s_nop 0
	global_load_lds_dwordx4 v[144:145], off
	s_waitcnt vmcnt(8)
	s_waitcnt lgkmcnt(0)
	s_barrier
	s_setprio 1
	s_waitcnt lgkmcnt(0)
	v_mfma_f32_16x16x32_bf16 v[52:55], v[154:157], v[186:189], v[52:55]
	v_mfma_f32_16x16x32_bf16 v[48:51], v[162:165], v[186:189], v[48:51]
	v_mfma_f32_16x16x32_bf16 v[36:39], v[154:157], v[196:199], v[36:39]
	v_mfma_f32_16x16x32_bf16 v[32:35], v[162:165], v[196:199], v[32:35]
	v_mfma_f32_16x16x32_bf16 v[20:23], v[154:157], v[204:207], v[20:23]
	v_mfma_f32_16x16x32_bf16 v[16:19], v[162:165], v[204:207], v[16:19]
	v_mfma_f32_16x16x32_bf16 v[4:7], v[154:157], v[212:215], v[4:7]
	v_mfma_f32_16x16x32_bf16 v[0:3], v[162:165], v[212:215], v[0:3]
	v_mfma_f32_16x16x32_bf16 v[52:55], v[158:161], v[190:193], v[52:55]
	v_mfma_f32_16x16x32_bf16 v[48:51], v[166:169], v[190:193], v[48:51]
	v_mfma_f32_16x16x32_bf16 v[36:39], v[158:161], v[200:203], v[36:39]
	v_mfma_f32_16x16x32_bf16 v[32:35], v[166:169], v[200:203], v[32:35]
	v_mfma_f32_16x16x32_bf16 v[20:23], v[158:161], v[208:211], v[20:23]
	v_mfma_f32_16x16x32_bf16 v[16:19], v[166:169], v[208:211], v[16:19]
	v_mfma_f32_16x16x32_bf16 v[4:7], v[158:161], v[216:219], v[4:7]
	v_mfma_f32_16x16x32_bf16 v[0:3], v[166:169], v[216:219], v[0:3]
	s_setprio 0
	s_setprio 1
	v_mfma_f32_16x16x32_bf16 v[60:63], v[170:173], v[186:189], v[60:63]
	v_mfma_f32_16x16x32_bf16 v[56:59], v[178:181], v[186:189], v[56:59]
	v_mfma_f32_16x16x32_bf16 v[44:47], v[170:173], v[196:199], v[44:47]
	v_mfma_f32_16x16x32_bf16 v[40:43], v[178:181], v[196:199], v[40:43]
	v_mfma_f32_16x16x32_bf16 v[28:31], v[170:173], v[204:207], v[28:31]
	v_mfma_f32_16x16x32_bf16 v[24:27], v[178:181], v[204:207], v[24:27]
	v_mfma_f32_16x16x32_bf16 v[12:15], v[170:173], v[212:215], v[12:15]
	v_mfma_f32_16x16x32_bf16 v[8:11], v[178:181], v[212:215], v[8:11]
	v_mfma_f32_16x16x32_bf16 v[60:63], v[174:177], v[190:193], v[60:63]
	v_mfma_f32_16x16x32_bf16 v[56:59], v[182:185], v[190:193], v[56:59]
	v_mfma_f32_16x16x32_bf16 v[44:47], v[174:177], v[200:203], v[44:47]
	v_mfma_f32_16x16x32_bf16 v[40:43], v[182:185], v[200:203], v[40:43]
	v_mfma_f32_16x16x32_bf16 v[28:31], v[174:177], v[208:211], v[28:31]
	v_mfma_f32_16x16x32_bf16 v[24:27], v[182:185], v[208:211], v[24:27]
	v_mfma_f32_16x16x32_bf16 v[12:15], v[174:177], v[216:219], v[12:15]
	v_mfma_f32_16x16x32_bf16 v[8:11], v[182:185], v[216:219], v[8:11]
	s_setprio 0
	s_barrier
	s_add_i32 s84, s84, 2
	s_add_u32 s36, s36, 0x100
	s_addc_u32 s37, s37, 0
	s_add_u32 s82, s82, 0x100
	s_addc_u32 s83, s83, 0
	s_cmp_gt_u32 s84, 13
	s_cbranch_scc0 .LBB0_1709
	s_and_b64 vcc, exec, s[22:23]
	s_cbranch_vccz .LBB0_1712
	s_barrier

.LBB0_1791:
	ds_read_b128 v[144:147], v151
	ds_read_b128 v[156:159], v151 offset:1024
	ds_read_b128 v[160:163], v151 offset:2048
	ds_read_b128 v[164:167], v151 offset:3072
	ds_read_b128 v[168:171], v152
	ds_read_b128 v[172:175], v152 offset:1024
	ds_read_b128 v[176:179], v152 offset:2048
	ds_read_b128 v[180:183], v152 offset:3072
	s_add_u32 s38, s36, 0x100
	s_addc_u32 s39, s37, 0
	s_cmp_eq_u32 s85, 40
	s_cselect_b32 s43, s1, s39
	s_cselect_b32 s42, s0, s38
	s_cselect_b32 s41, s35, s84
	s_cselect_b32 s40, s34, s83
	v_lshl_add_u64 v[192:193], s[36:37], 0, v[136:137]
	s_add_i32 m0, s59, 0xc000
	ds_read_b128 v[184:187], v153
	ds_read_b128 v[188:191], v153 offset:1024
	ds_read_b128 v[196:199], v153 offset:2048
	ds_read_b128 v[200:203], v153 offset:3072
	ds_read_b128 v[204:207], v153 offset:4096
	ds_read_b128 v[208:211], v153 offset:5120
	ds_read_b128 v[212:215], v153 offset:6144
	ds_read_b128 v[216:219], v153 offset:7168
	global_load_lds_dwordx4 v[192:193], off
	v_lshl_add_u64 v[192:193], s[36:37], 0, v[138:139]
	s_add_i32 m0, s59, 0xe000
	s_nop 0
	global_load_lds_dwordx4 v[192:193], off
	s_waitcnt vmcnt(8)
	s_waitcnt lgkmcnt(0)
	s_barrier
	s_setprio 1
	s_waitcnt lgkmcnt(0)
	v_mfma_f32_16x16x32_bf16 v[124:127], v[144:147], v[184:187], v[124:127]
	v_mfma_f32_16x16x32_bf16 v[120:123], v[160:163], v[184:187], v[120:123]
	v_mfma_f32_16x16x32_bf16 v[108:111], v[144:147], v[196:199], v[108:111]
	v_mfma_f32_16x16x32_bf16 v[104:107], v[160:163], v[196:199], v[104:107]
	v_mfma_f32_16x16x32_bf16 v[92:95], v[144:147], v[204:207], v[92:95]
	v_mfma_f32_16x16x32_bf16 v[88:91], v[160:163], v[204:207], v[88:91]
	v_mfma_f32_16x16x32_bf16 v[76:79], v[144:147], v[212:215], v[76:79]
	v_mfma_f32_16x16x32_bf16 v[72:75], v[160:163], v[212:215], v[72:75]
	v_mfma_f32_16x16x32_bf16 v[124:127], v[156:159], v[188:191], v[124:127]
	v_mfma_f32_16x16x32_bf16 v[120:123], v[164:167], v[188:191], v[120:123]
	v_mfma_f32_16x16x32_bf16 v[108:111], v[156:159], v[200:203], v[108:111]
	v_mfma_f32_16x16x32_bf16 v[104:107], v[164:167], v[200:203], v[104:107]
	v_mfma_f32_16x16x32_bf16 v[92:95], v[156:159], v[208:211], v[92:95]
	v_mfma_f32_16x16x32_bf16 v[88:91], v[164:167], v[208:211], v[88:91]
	v_mfma_f32_16x16x32_bf16 v[76:79], v[156:159], v[216:219], v[76:79]
	v_mfma_f32_16x16x32_bf16 v[72:75], v[164:167], v[216:219], v[72:75]
	s_setprio 0
	s_setprio 1
	v_mfma_f32_16x16x32_bf16 v[116:119], v[168:171], v[184:187], v[116:119]
	v_mfma_f32_16x16x32_bf16 v[112:115], v[176:179], v[184:187], v[112:115]
	v_mfma_f32_16x16x32_bf16 v[100:103], v[168:171], v[196:199], v[100:103]
	v_mfma_f32_16x16x32_bf16 v[96:99], v[176:179], v[196:199], v[96:99]
	v_mfma_f32_16x16x32_bf16 v[84:87], v[168:171], v[204:207], v[84:87]
	v_mfma_f32_16x16x32_bf16 v[80:83], v[176:179], v[204:207], v[80:83]
	v_mfma_f32_16x16x32_bf16 v[68:71], v[168:171], v[212:215], v[68:71]
	v_mfma_f32_16x16x32_bf16 v[64:67], v[176:179], v[212:215], v[64:67]
	v_mfma_f32_16x16x32_bf16 v[116:119], v[172:175], v[188:191], v[116:119]
	v_mfma_f32_16x16x32_bf16 v[112:115], v[180:183], v[188:191], v[112:115]
	v_mfma_f32_16x16x32_bf16 v[100:103], v[172:175], v[200:203], v[100:103]
	v_mfma_f32_16x16x32_bf16 v[96:99], v[180:183], v[200:203], v[96:99]
	v_mfma_f32_16x16x32_bf16 v[84:87], v[172:175], v[208:211], v[84:87]
	v_mfma_f32_16x16x32_bf16 v[80:83], v[180:183], v[208:211], v[80:83]
	v_mfma_f32_16x16x32_bf16 v[68:71], v[172:175], v[216:219], v[68:71]
	v_mfma_f32_16x16x32_bf16 v[64:67], v[180:183], v[216:219], v[64:67]
	s_setprio 0
	s_barrier
	s_add_i32 s36, s73, s58
	v_lshl_add_u64 v[192:193], s[40:41], 0, v[130:131]
	s_mov_b32 m0, s36
	ds_read_b128 v[184:187], v153 offset:16384
	ds_read_b128 v[188:191], v153 offset:17408
	ds_read_b128 v[196:199], v153 offset:18432
	ds_read_b128 v[200:203], v153 offset:19456
	ds_read_b128 v[204:207], v153 offset:20480
	ds_read_b128 v[208:211], v153 offset:21504
	ds_read_b128 v[212:215], v153 offset:22528
	ds_read_b128 v[216:219], v153 offset:23552
	global_load_lds_dwordx4 v[192:193], off
	s_add_i32 m0, s36, 0x2000
	s_add_u32 s36, s40, 0xb0000
	v_lshl_add_u64 v[220:221], s[40:41], 0, v[134:135]
	s_addc_u32 s37, s41, 0
	s_add_i32 s86, s78, s58
	global_load_lds_dwordx4 v[220:221], off
	v_lshl_add_u64 v[222:223], s[36:37], 0, v[130:131]
	s_mov_b32 m0, s86
	v_lshl_add_u64 v[224:225], s[42:43], 0, v[132:133]
	global_load_lds_dwordx4 v[222:223], off
	v_lshl_add_u64 v[222:223], s[36:37], 0, v[134:135]
	s_add_i32 m0, s86, 0x2000
	s_nop 0
	global_load_lds_dwordx4 v[222:223], off
	v_lshl_add_u64 v[222:223], s[42:43], 0, v[128:129]
	s_waitcnt vmcnt(6)
	s_waitcnt lgkmcnt(0)
	s_barrier
	s_setprio 1
	s_waitcnt lgkmcnt(0)
	v_mfma_f32_16x16x32_bf16 v[60:63], v[144:147], v[184:187], v[60:63]
	v_mfma_f32_16x16x32_bf16 v[56:59], v[160:163], v[184:187], v[56:59]
	v_mfma_f32_16x16x32_bf16 v[44:47], v[144:147], v[196:199], v[44:47]
	v_mfma_f32_16x16x32_bf16 v[40:43], v[160:163], v[196:199], v[40:43]
	v_mfma_f32_16x16x32_bf16 v[28:31], v[144:147], v[204:207], v[28:31]
	v_mfma_f32_16x16x32_bf16 v[24:27], v[160:163], v[204:207], v[24:27]
	v_mfma_f32_16x16x32_bf16 v[12:15], v[144:147], v[212:215], v[12:15]
	v_mfma_f32_16x16x32_bf16 v[8:11], v[160:163], v[212:215], v[8:11]
	v_mfma_f32_16x16x32_bf16 v[60:63], v[156:159], v[188:191], v[60:63]
	v_mfma_f32_16x16x32_bf16 v[56:59], v[164:167], v[188:191], v[56:59]
	v_mfma_f32_16x16x32_bf16 v[44:47], v[156:159], v[200:203], v[44:47]
	v_mfma_f32_16x16x32_bf16 v[40:43], v[164:167], v[200:203], v[40:43]
	v_mfma_f32_16x16x32_bf16 v[28:31], v[156:159], v[208:211], v[28:31]
	v_mfma_f32_16x16x32_bf16 v[24:27], v[164:167], v[208:211], v[24:27]
	v_mfma_f32_16x16x32_bf16 v[12:15], v[156:159], v[216:219], v[12:15]
	v_mfma_f32_16x16x32_bf16 v[8:11], v[164:167], v[216:219], v[8:11]
	s_setprio 0
	s_setprio 1
	v_mfma_f32_16x16x32_bf16 v[52:55], v[168:171], v[184:187], v[52:55]
	v_mfma_f32_16x16x32_bf16 v[48:51], v[176:179], v[184:187], v[48:51]
	v_mfma_f32_16x16x32_bf16 v[36:39], v[168:171], v[196:199], v[36:39]
	v_mfma_f32_16x16x32_bf16 v[32:35], v[176:179], v[196:199], v[32:35]
	v_mfma_f32_16x16x32_bf16 v[20:23], v[168:171], v[204:207], v[20:23]
	v_mfma_f32_16x16x32_bf16 v[16:19], v[176:179], v[204:207], v[16:19]
	v_mfma_f32_16x16x32_bf16 v[4:7], v[168:171], v[212:215], v[4:7]
	v_mfma_f32_16x16x32_bf16 v[0:3], v[176:179], v[212:215], v[0:3]
	v_mfma_f32_16x16x32_bf16 v[52:55], v[172:175], v[188:191], v[52:55]
	v_mfma_f32_16x16x32_bf16 v[48:51], v[180:183], v[188:191], v[48:51]
	v_mfma_f32_16x16x32_bf16 v[36:39], v[172:175], v[200:203], v[36:39]
	v_mfma_f32_16x16x32_bf16 v[32:35], v[180:183], v[200:203], v[32:35]
	v_mfma_f32_16x16x32_bf16 v[20:23], v[172:175], v[208:211], v[20:23]
	v_mfma_f32_16x16x32_bf16 v[16:19], v[180:183], v[208:211], v[16:19]
	v_mfma_f32_16x16x32_bf16 v[4:7], v[172:175], v[216:219], v[4:7]
	v_mfma_f32_16x16x32_bf16 v[0:3], v[180:183], v[216:219], v[0:3]
	s_setprio 0
	s_barrier
	s_add_i32 s86, 0, 0x18000
	v_add_u32_e32 v155, s86, v149
	s_add_i32 s87, 0, 0x1c000
	ds_read_b128 v[144:147], v155
	ds_read_b128 v[156:159], v155 offset:1024
	ds_read_b128 v[160:163], v155 offset:2048
	ds_read_b128 v[164:167], v155 offset:3072
	v_add_u32_e32 v155, s87, v149
	ds_read_b128 v[168:171], v155
	ds_read_b128 v[172:175], v155 offset:1024
	ds_read_b128 v[176:179], v155 offset:2048
	ds_read_b128 v[180:183], v155 offset:3072
	s_add_u32 s36, s42, 0xb0000
	s_addc_u32 s37, s43, 0
	v_lshl_add_u64 v[226:227], s[36:37], 0, v[128:129]
	ds_read_b128 v[184:187], v153 offset:32768
	ds_read_b128 v[188:191], v153 offset:33792
	ds_read_b128 v[196:199], v153 offset:34816
	ds_read_b128 v[200:203], v153 offset:35840
	ds_read_b128 v[204:207], v153 offset:36864
	ds_read_b128 v[208:211], v153 offset:37888
	ds_read_b128 v[212:215], v153 offset:38912
	ds_read_b128 v[216:219], v153 offset:39936
	s_mov_b32 m0, s59
	s_nop 0
	global_load_lds_dwordx4 v[222:223], off
	s_mov_b32 m0, s60
	s_nop 0
	global_load_lds_dwordx4 v[224:225], off
	s_mov_b32 m0, s61
	s_nop 0
	global_load_lds_dwordx4 v[226:227], off
	v_lshl_add_u64 v[226:227], s[36:37], 0, v[132:133]
	s_mov_b32 m0, s62
	s_nop 0
	global_load_lds_dwordx4 v[226:227], off
	s_waitcnt vmcnt(8)
	s_waitcnt lgkmcnt(0)
	s_barrier
	s_setprio 1
	s_waitcnt lgkmcnt(0)
	v_mfma_f32_16x16x32_bf16 v[124:127], v[144:147], v[184:187], v[124:127]
	v_mfma_f32_16x16x32_bf16 v[120:123], v[160:163], v[184:187], v[120:123]
	v_mfma_f32_16x16x32_bf16 v[108:111], v[144:147], v[196:199], v[108:111]
	v_mfma_f32_16x16x32_bf16 v[104:107], v[160:163], v[196:199], v[104:107]
	v_mfma_f32_16x16x32_bf16 v[92:95], v[144:147], v[204:207], v[92:95]
	v_mfma_f32_16x16x32_bf16 v[88:91], v[160:163], v[204:207], v[88:91]
	v_mfma_f32_16x16x32_bf16 v[76:79], v[144:147], v[212:215], v[76:79]
	v_mfma_f32_16x16x32_bf16 v[72:75], v[160:163], v[212:215], v[72:75]
	v_mfma_f32_16x16x32_bf16 v[124:127], v[156:159], v[188:191], v[124:127]
	v_mfma_f32_16x16x32_bf16 v[120:123], v[164:167], v[188:191], v[120:123]
	v_mfma_f32_16x16x32_bf16 v[108:111], v[156:159], v[200:203], v[108:111]
	v_mfma_f32_16x16x32_bf16 v[104:107], v[164:167], v[200:203], v[104:107]
	v_mfma_f32_16x16x32_bf16 v[92:95], v[156:159], v[208:211], v[92:95]
	v_mfma_f32_16x16x32_bf16 v[88:91], v[164:167], v[208:211], v[88:91]
	v_mfma_f32_16x16x32_bf16 v[76:79], v[156:159], v[216:219], v[76:79]
	v_mfma_f32_16x16x32_bf16 v[72:75], v[164:167], v[216:219], v[72:75]
	s_setprio 0
	s_setprio 1
	v_mfma_f32_16x16x32_bf16 v[116:119], v[168:171], v[184:187], v[116:119]
	v_mfma_f32_16x16x32_bf16 v[112:115], v[176:179], v[184:187], v[112:115]
	v_mfma_f32_16x16x32_bf16 v[100:103], v[168:171], v[196:199], v[100:103]
	v_mfma_f32_16x16x32_bf16 v[96:99], v[176:179], v[196:199], v[96:99]
	v_mfma_f32_16x16x32_bf16 v[84:87], v[168:171], v[204:207], v[84:87]
	v_mfma_f32_16x16x32_bf16 v[80:83], v[176:179], v[204:207], v[80:83]
	v_mfma_f32_16x16x32_bf16 v[68:71], v[168:171], v[212:215], v[68:71]
	v_mfma_f32_16x16x32_bf16 v[64:67], v[176:179], v[212:215], v[64:67]
	v_mfma_f32_16x16x32_bf16 v[116:119], v[172:175], v[188:191], v[116:119]
	v_mfma_f32_16x16x32_bf16 v[112:115], v[180:183], v[188:191], v[112:115]
	v_mfma_f32_16x16x32_bf16 v[100:103], v[172:175], v[200:203], v[100:103]
	v_mfma_f32_16x16x32_bf16 v[96:99], v[180:183], v[200:203], v[96:99]
	v_mfma_f32_16x16x32_bf16 v[84:87], v[172:175], v[208:211], v[84:87]
	v_mfma_f32_16x16x32_bf16 v[80:83], v[180:183], v[208:211], v[80:83]
	v_mfma_f32_16x16x32_bf16 v[68:71], v[172:175], v[216:219], v[68:71]
	v_mfma_f32_16x16x32_bf16 v[64:67], v[180:183], v[216:219], v[64:67]
	s_setprio 0
	s_barrier
	s_add_i32 s36, s86, s58
	v_lshl_add_u64 v[192:193], v[192:193], 0, s[28:29]
	s_mov_b32 m0, s36
	ds_read_b128 v[184:187], v153 offset:49152
	ds_read_b128 v[188:191], v153 offset:50176
	ds_read_b128 v[196:199], v153 offset:51200
	ds_read_b128 v[200:203], v153 offset:52224
	ds_read_b128 v[204:207], v153 offset:53248
	ds_read_b128 v[208:211], v153 offset:54272
	ds_read_b128 v[212:215], v153 offset:55296
	ds_read_b128 v[216:219], v153 offset:56320
	global_load_lds_dwordx4 v[192:193], off
	s_add_i32 m0, s36, 0x2000
	s_add_u32 s36, s40, 0xb0080
	v_lshl_add_u64 v[192:193], v[220:221], 0, s[28:29]
	s_addc_u32 s37, s41, 0
	s_add_i32 s40, s87, s58
	global_load_lds_dwordx4 v[192:193], off
	v_lshl_add_u64 v[192:193], s[36:37], 0, v[130:131]
	s_mov_b32 m0, s40
	s_nop 0
	global_load_lds_dwordx4 v[192:193], off
	v_lshl_add_u64 v[192:193], s[36:37], 0, v[134:135]
	s_add_i32 m0, s40, 0x2000
	s_nop 0
	global_load_lds_dwordx4 v[192:193], off
	v_lshl_add_u64 v[192:193], v[222:223], 0, s[28:29]
	s_mov_b32 m0, s70
	s_nop 0
	global_load_lds_dwordx4 v[192:193], off
	v_lshl_add_u64 v[192:193], v[224:225], 0, s[28:29]
	s_mov_b32 m0, s71
	s_nop 0
	global_load_lds_dwordx4 v[192:193], off
	s_waitcnt vmcnt(8)
	s_waitcnt lgkmcnt(0)
	s_barrier
	s_setprio 1
	s_waitcnt lgkmcnt(0)
	v_mfma_f32_16x16x32_bf16 v[60:63], v[144:147], v[184:187], v[60:63]
	v_mfma_f32_16x16x32_bf16 v[56:59], v[160:163], v[184:187], v[56:59]
	v_mfma_f32_16x16x32_bf16 v[44:47], v[144:147], v[196:199], v[44:47]
	v_mfma_f32_16x16x32_bf16 v[40:43], v[160:163], v[196:199], v[40:43]
	v_mfma_f32_16x16x32_bf16 v[28:31], v[144:147], v[204:207], v[28:31]
	v_mfma_f32_16x16x32_bf16 v[24:27], v[160:163], v[204:207], v[24:27]
	v_mfma_f32_16x16x32_bf16 v[12:15], v[144:147], v[212:215], v[12:15]
	v_mfma_f32_16x16x32_bf16 v[8:11], v[160:163], v[212:215], v[8:11]
	v_mfma_f32_16x16x32_bf16 v[60:63], v[156:159], v[188:191], v[60:63]
	v_mfma_f32_16x16x32_bf16 v[56:59], v[164:167], v[188:191], v[56:59]
	v_mfma_f32_16x16x32_bf16 v[44:47], v[156:159], v[200:203], v[44:47]
	v_mfma_f32_16x16x32_bf16 v[40:43], v[164:167], v[200:203], v[40:43]
	v_mfma_f32_16x16x32_bf16 v[28:31], v[156:159], v[208:211], v[28:31]
	v_mfma_f32_16x16x32_bf16 v[24:27], v[164:167], v[208:211], v[24:27]
	v_mfma_f32_16x16x32_bf16 v[12:15], v[156:159], v[216:219], v[12:15]
	v_mfma_f32_16x16x32_bf16 v[8:11], v[164:167], v[216:219], v[8:11]
	s_setprio 0
	s_setprio 1
	v_mfma_f32_16x16x32_bf16 v[52:55], v[168:171], v[184:187], v[52:55]
	v_mfma_f32_16x16x32_bf16 v[48:51], v[176:179], v[184:187], v[48:51]
	v_mfma_f32_16x16x32_bf16 v[36:39], v[168:171], v[196:199], v[36:39]
	v_mfma_f32_16x16x32_bf16 v[32:35], v[176:179], v[196:199], v[32:35]
	v_mfma_f32_16x16x32_bf16 v[20:23], v[168:171], v[204:207], v[20:23]
	v_mfma_f32_16x16x32_bf16 v[16:19], v[176:179], v[204:207], v[16:19]
	v_mfma_f32_16x16x32_bf16 v[4:7], v[168:171], v[212:215], v[4:7]
	v_mfma_f32_16x16x32_bf16 v[0:3], v[176:179], v[212:215], v[0:3]
	v_mfma_f32_16x16x32_bf16 v[52:55], v[172:175], v[188:191], v[52:55]
	v_mfma_f32_16x16x32_bf16 v[48:51], v[180:183], v[188:191], v[48:51]
	v_mfma_f32_16x16x32_bf16 v[36:39], v[172:175], v[200:203], v[36:39]
	v_mfma_f32_16x16x32_bf16 v[32:35], v[180:183], v[200:203], v[32:35]
	v_mfma_f32_16x16x32_bf16 v[20:23], v[172:175], v[208:211], v[20:23]
	v_mfma_f32_16x16x32_bf16 v[16:19], v[180:183], v[208:211], v[16:19]
	v_mfma_f32_16x16x32_bf16 v[4:7], v[172:175], v[216:219], v[4:7]
	v_mfma_f32_16x16x32_bf16 v[0:3], v[180:183], v[216:219], v[0:3]
	s_setprio 0
	s_barrier
	s_add_i32 s85, s85, 2
	s_add_u32 s83, s83, 0x100
	s_addc_u32 s84, s84, 0
	s_cmp_gt_u32 s85, 41
	s_mov_b64 s[36:37], s[38:39]
	s_cbranch_scc0 .LBB0_1791
	s_and_b64 vcc, exec, s[30:31]
	s_cbranch_vccz .LBB0_1794
	s_barrier

.LBB0_2142:
	ds_read_b128 v[144:147], v151
	ds_read_b128 v[156:159], v151 offset:1024
	ds_read_b128 v[160:163], v151 offset:2048
	ds_read_b128 v[164:167], v151 offset:3072
	ds_read_b128 v[168:171], v152
	ds_read_b128 v[172:175], v152 offset:1024
	ds_read_b128 v[176:179], v152 offset:2048
	ds_read_b128 v[180:183], v152 offset:3072
	s_add_u32 s38, s36, 0x100
	s_addc_u32 s39, s37, 0
	s_cmp_eq_u32 s83, 40
	s_cselect_b32 s43, s1, s39
	s_cselect_b32 s42, s0, s38
	s_cselect_b32 s41, s35, s82
	s_cselect_b32 s40, s34, s81
	v_lshl_add_u64 v[192:193], s[36:37], 0, v[136:137]
	s_add_i32 m0, s57, 0xc000
	ds_read_b128 v[184:187], v153
	ds_read_b128 v[188:191], v153 offset:1024
	ds_read_b128 v[196:199], v153 offset:2048
	ds_read_b128 v[200:203], v153 offset:3072
	ds_read_b128 v[204:207], v153 offset:4096
	ds_read_b128 v[208:211], v153 offset:5120
	ds_read_b128 v[212:215], v153 offset:6144
	ds_read_b128 v[216:219], v153 offset:7168
	global_load_lds_dwordx4 v[192:193], off
	v_lshl_add_u64 v[192:193], s[36:37], 0, v[138:139]
	s_add_i32 m0, s57, 0xe000
	s_nop 0
	global_load_lds_dwordx4 v[192:193], off
	s_waitcnt vmcnt(8)
	s_waitcnt lgkmcnt(0)
	s_barrier
	s_setprio 1
	s_waitcnt lgkmcnt(0)
	v_mfma_f32_16x16x32_bf16 v[124:127], v[144:147], v[184:187], v[124:127]
	v_mfma_f32_16x16x32_bf16 v[120:123], v[160:163], v[184:187], v[120:123]
	v_mfma_f32_16x16x32_bf16 v[108:111], v[144:147], v[196:199], v[108:111]
	v_mfma_f32_16x16x32_bf16 v[104:107], v[160:163], v[196:199], v[104:107]
	v_mfma_f32_16x16x32_bf16 v[92:95], v[144:147], v[204:207], v[92:95]
	v_mfma_f32_16x16x32_bf16 v[88:91], v[160:163], v[204:207], v[88:91]
	v_mfma_f32_16x16x32_bf16 v[76:79], v[144:147], v[212:215], v[76:79]
	v_mfma_f32_16x16x32_bf16 v[72:75], v[160:163], v[212:215], v[72:75]
	v_mfma_f32_16x16x32_bf16 v[124:127], v[156:159], v[188:191], v[124:127]
	v_mfma_f32_16x16x32_bf16 v[120:123], v[164:167], v[188:191], v[120:123]
	v_mfma_f32_16x16x32_bf16 v[108:111], v[156:159], v[200:203], v[108:111]
	v_mfma_f32_16x16x32_bf16 v[104:107], v[164:167], v[200:203], v[104:107]
	v_mfma_f32_16x16x32_bf16 v[92:95], v[156:159], v[208:211], v[92:95]
	v_mfma_f32_16x16x32_bf16 v[88:91], v[164:167], v[208:211], v[88:91]
	v_mfma_f32_16x16x32_bf16 v[76:79], v[156:159], v[216:219], v[76:79]
	v_mfma_f32_16x16x32_bf16 v[72:75], v[164:167], v[216:219], v[72:75]
	s_setprio 0
	s_setprio 1
	v_mfma_f32_16x16x32_bf16 v[116:119], v[168:171], v[184:187], v[116:119]
	v_mfma_f32_16x16x32_bf16 v[112:115], v[176:179], v[184:187], v[112:115]
	v_mfma_f32_16x16x32_bf16 v[100:103], v[168:171], v[196:199], v[100:103]
	v_mfma_f32_16x16x32_bf16 v[96:99], v[176:179], v[196:199], v[96:99]
	v_mfma_f32_16x16x32_bf16 v[84:87], v[168:171], v[204:207], v[84:87]
	v_mfma_f32_16x16x32_bf16 v[80:83], v[176:179], v[204:207], v[80:83]
	v_mfma_f32_16x16x32_bf16 v[68:71], v[168:171], v[212:215], v[68:71]
	v_mfma_f32_16x16x32_bf16 v[64:67], v[176:179], v[212:215], v[64:67]
	v_mfma_f32_16x16x32_bf16 v[116:119], v[172:175], v[188:191], v[116:119]
	v_mfma_f32_16x16x32_bf16 v[112:115], v[180:183], v[188:191], v[112:115]
	v_mfma_f32_16x16x32_bf16 v[100:103], v[172:175], v[200:203], v[100:103]
	v_mfma_f32_16x16x32_bf16 v[96:99], v[180:183], v[200:203], v[96:99]
	v_mfma_f32_16x16x32_bf16 v[84:87], v[172:175], v[208:211], v[84:87]
	v_mfma_f32_16x16x32_bf16 v[80:83], v[180:183], v[208:211], v[80:83]
	v_mfma_f32_16x16x32_bf16 v[68:71], v[172:175], v[216:219], v[68:71]
	v_mfma_f32_16x16x32_bf16 v[64:67], v[180:183], v[216:219], v[64:67]
	s_setprio 0
	s_barrier
	s_add_i32 s36, s71, s56
	v_lshl_add_u64 v[192:193], s[40:41], 0, v[130:131]
	s_mov_b32 m0, s36
	ds_read_b128 v[184:187], v153 offset:16384
	ds_read_b128 v[188:191], v153 offset:17408
	ds_read_b128 v[196:199], v153 offset:18432
	ds_read_b128 v[200:203], v153 offset:19456
	ds_read_b128 v[204:207], v153 offset:20480
	ds_read_b128 v[208:211], v153 offset:21504
	ds_read_b128 v[212:215], v153 offset:22528
	ds_read_b128 v[216:219], v153 offset:23552
	global_load_lds_dwordx4 v[192:193], off
	s_add_i32 m0, s36, 0x2000
	s_add_u32 s36, s40, 0xb0000
	v_lshl_add_u64 v[220:221], s[40:41], 0, v[134:135]
	s_addc_u32 s37, s41, 0
	s_add_i32 s84, s72, s56
	global_load_lds_dwordx4 v[220:221], off
	v_lshl_add_u64 v[222:223], s[36:37], 0, v[130:131]
	s_mov_b32 m0, s84
	v_lshl_add_u64 v[224:225], s[42:43], 0, v[132:133]
	global_load_lds_dwordx4 v[222:223], off
	v_lshl_add_u64 v[222:223], s[36:37], 0, v[134:135]
	s_add_i32 m0, s84, 0x2000
	s_nop 0
	global_load_lds_dwordx4 v[222:223], off
	v_lshl_add_u64 v[222:223], s[42:43], 0, v[128:129]
	s_waitcnt vmcnt(6)
	s_waitcnt lgkmcnt(0)
	s_barrier
	s_setprio 1
	s_waitcnt lgkmcnt(0)
	v_mfma_f32_16x16x32_bf16 v[60:63], v[144:147], v[184:187], v[60:63]
	v_mfma_f32_16x16x32_bf16 v[56:59], v[160:163], v[184:187], v[56:59]
	v_mfma_f32_16x16x32_bf16 v[44:47], v[144:147], v[196:199], v[44:47]
	v_mfma_f32_16x16x32_bf16 v[40:43], v[160:163], v[196:199], v[40:43]
	v_mfma_f32_16x16x32_bf16 v[28:31], v[144:147], v[204:207], v[28:31]
	v_mfma_f32_16x16x32_bf16 v[24:27], v[160:163], v[204:207], v[24:27]
	v_mfma_f32_16x16x32_bf16 v[12:15], v[144:147], v[212:215], v[12:15]
	v_mfma_f32_16x16x32_bf16 v[8:11], v[160:163], v[212:215], v[8:11]
	v_mfma_f32_16x16x32_bf16 v[60:63], v[156:159], v[188:191], v[60:63]
	v_mfma_f32_16x16x32_bf16 v[56:59], v[164:167], v[188:191], v[56:59]
	v_mfma_f32_16x16x32_bf16 v[44:47], v[156:159], v[200:203], v[44:47]
	v_mfma_f32_16x16x32_bf16 v[40:43], v[164:167], v[200:203], v[40:43]
	v_mfma_f32_16x16x32_bf16 v[28:31], v[156:159], v[208:211], v[28:31]
	v_mfma_f32_16x16x32_bf16 v[24:27], v[164:167], v[208:211], v[24:27]
	v_mfma_f32_16x16x32_bf16 v[12:15], v[156:159], v[216:219], v[12:15]
	v_mfma_f32_16x16x32_bf16 v[8:11], v[164:167], v[216:219], v[8:11]
	s_setprio 0
	s_setprio 1
	v_mfma_f32_16x16x32_bf16 v[52:55], v[168:171], v[184:187], v[52:55]
	v_mfma_f32_16x16x32_bf16 v[48:51], v[176:179], v[184:187], v[48:51]
	v_mfma_f32_16x16x32_bf16 v[36:39], v[168:171], v[196:199], v[36:39]
	v_mfma_f32_16x16x32_bf16 v[32:35], v[176:179], v[196:199], v[32:35]
	v_mfma_f32_16x16x32_bf16 v[20:23], v[168:171], v[204:207], v[20:23]
	v_mfma_f32_16x16x32_bf16 v[16:19], v[176:179], v[204:207], v[16:19]
	v_mfma_f32_16x16x32_bf16 v[4:7], v[168:171], v[212:215], v[4:7]
	v_mfma_f32_16x16x32_bf16 v[0:3], v[176:179], v[212:215], v[0:3]
	v_mfma_f32_16x16x32_bf16 v[52:55], v[172:175], v[188:191], v[52:55]
	v_mfma_f32_16x16x32_bf16 v[48:51], v[180:183], v[188:191], v[48:51]
	v_mfma_f32_16x16x32_bf16 v[36:39], v[172:175], v[200:203], v[36:39]
	v_mfma_f32_16x16x32_bf16 v[32:35], v[180:183], v[200:203], v[32:35]
	v_mfma_f32_16x16x32_bf16 v[20:23], v[172:175], v[208:211], v[20:23]
	v_mfma_f32_16x16x32_bf16 v[16:19], v[180:183], v[208:211], v[16:19]
	v_mfma_f32_16x16x32_bf16 v[4:7], v[172:175], v[216:219], v[4:7]
	v_mfma_f32_16x16x32_bf16 v[0:3], v[180:183], v[216:219], v[0:3]
	s_setprio 0
	s_barrier
	s_add_i32 s84, 0, 0x18000
	v_add_u32_e32 v155, s84, v149
	s_add_i32 s85, 0, 0x1c000
	ds_read_b128 v[144:147], v155
	ds_read_b128 v[156:159], v155 offset:1024
	ds_read_b128 v[160:163], v155 offset:2048
	ds_read_b128 v[164:167], v155 offset:3072
	v_add_u32_e32 v155, s85, v149
	ds_read_b128 v[168:171], v155
	ds_read_b128 v[172:175], v155 offset:1024
	ds_read_b128 v[176:179], v155 offset:2048
	ds_read_b128 v[180:183], v155 offset:3072
	s_add_u32 s36, s42, 0xb0000
	s_addc_u32 s37, s43, 0
	v_lshl_add_u64 v[226:227], s[36:37], 0, v[128:129]
	ds_read_b128 v[184:187], v153 offset:32768
	ds_read_b128 v[188:191], v153 offset:33792
	ds_read_b128 v[196:199], v153 offset:34816
	ds_read_b128 v[200:203], v153 offset:35840
	ds_read_b128 v[204:207], v153 offset:36864
	ds_read_b128 v[208:211], v153 offset:37888
	ds_read_b128 v[212:215], v153 offset:38912
	ds_read_b128 v[216:219], v153 offset:39936
	s_mov_b32 m0, s57
	s_nop 0
	global_load_lds_dwordx4 v[222:223], off
	s_mov_b32 m0, s58
	s_nop 0
	global_load_lds_dwordx4 v[224:225], off
	s_mov_b32 m0, s59
	s_nop 0
	global_load_lds_dwordx4 v[226:227], off
	v_lshl_add_u64 v[226:227], s[36:37], 0, v[132:133]
	s_mov_b32 m0, s60
	s_nop 0
	global_load_lds_dwordx4 v[226:227], off
	s_waitcnt vmcnt(8)
	s_waitcnt lgkmcnt(0)
	s_barrier
	s_setprio 1
	s_waitcnt lgkmcnt(0)
	v_mfma_f32_16x16x32_bf16 v[124:127], v[144:147], v[184:187], v[124:127]
	v_mfma_f32_16x16x32_bf16 v[120:123], v[160:163], v[184:187], v[120:123]
	v_mfma_f32_16x16x32_bf16 v[108:111], v[144:147], v[196:199], v[108:111]
	v_mfma_f32_16x16x32_bf16 v[104:107], v[160:163], v[196:199], v[104:107]
	v_mfma_f32_16x16x32_bf16 v[92:95], v[144:147], v[204:207], v[92:95]
	v_mfma_f32_16x16x32_bf16 v[88:91], v[160:163], v[204:207], v[88:91]
	v_mfma_f32_16x16x32_bf16 v[76:79], v[144:147], v[212:215], v[76:79]
	v_mfma_f32_16x16x32_bf16 v[72:75], v[160:163], v[212:215], v[72:75]
	v_mfma_f32_16x16x32_bf16 v[124:127], v[156:159], v[188:191], v[124:127]
	v_mfma_f32_16x16x32_bf16 v[120:123], v[164:167], v[188:191], v[120:123]
	v_mfma_f32_16x16x32_bf16 v[108:111], v[156:159], v[200:203], v[108:111]
	v_mfma_f32_16x16x32_bf16 v[104:107], v[164:167], v[200:203], v[104:107]
	v_mfma_f32_16x16x32_bf16 v[92:95], v[156:159], v[208:211], v[92:95]
	v_mfma_f32_16x16x32_bf16 v[88:91], v[164:167], v[208:211], v[88:91]
	v_mfma_f32_16x16x32_bf16 v[76:79], v[156:159], v[216:219], v[76:79]
	v_mfma_f32_16x16x32_bf16 v[72:75], v[164:167], v[216:219], v[72:75]
	s_setprio 0
	s_setprio 1
	v_mfma_f32_16x16x32_bf16 v[116:119], v[168:171], v[184:187], v[116:119]
	v_mfma_f32_16x16x32_bf16 v[112:115], v[176:179], v[184:187], v[112:115]
	v_mfma_f32_16x16x32_bf16 v[100:103], v[168:171], v[196:199], v[100:103]
	v_mfma_f32_16x16x32_bf16 v[96:99], v[176:179], v[196:199], v[96:99]
	v_mfma_f32_16x16x32_bf16 v[84:87], v[168:171], v[204:207], v[84:87]
	v_mfma_f32_16x16x32_bf16 v[80:83], v[176:179], v[204:207], v[80:83]
	v_mfma_f32_16x16x32_bf16 v[68:71], v[168:171], v[212:215], v[68:71]
	v_mfma_f32_16x16x32_bf16 v[64:67], v[176:179], v[212:215], v[64:67]
	v_mfma_f32_16x16x32_bf16 v[116:119], v[172:175], v[188:191], v[116:119]
	v_mfma_f32_16x16x32_bf16 v[112:115], v[180:183], v[188:191], v[112:115]
	v_mfma_f32_16x16x32_bf16 v[100:103], v[172:175], v[200:203], v[100:103]
	v_mfma_f32_16x16x32_bf16 v[96:99], v[180:183], v[200:203], v[96:99]
	v_mfma_f32_16x16x32_bf16 v[84:87], v[172:175], v[208:211], v[84:87]
	v_mfma_f32_16x16x32_bf16 v[80:83], v[180:183], v[208:211], v[80:83]
	v_mfma_f32_16x16x32_bf16 v[68:71], v[172:175], v[216:219], v[68:71]
	v_mfma_f32_16x16x32_bf16 v[64:67], v[180:183], v[216:219], v[64:67]
	s_setprio 0
	s_barrier
	s_add_i32 s36, s84, s56
	v_lshl_add_u64 v[192:193], v[192:193], 0, s[28:29]
	s_mov_b32 m0, s36
	ds_read_b128 v[184:187], v153 offset:49152
	ds_read_b128 v[188:191], v153 offset:50176
	ds_read_b128 v[196:199], v153 offset:51200
	ds_read_b128 v[200:203], v153 offset:52224
	ds_read_b128 v[204:207], v153 offset:53248
	ds_read_b128 v[208:211], v153 offset:54272
	ds_read_b128 v[212:215], v153 offset:55296
	ds_read_b128 v[216:219], v153 offset:56320
	global_load_lds_dwordx4 v[192:193], off
	s_add_i32 m0, s36, 0x2000
	s_add_u32 s36, s40, 0xb0080
	v_lshl_add_u64 v[192:193], v[220:221], 0, s[28:29]
	s_addc_u32 s37, s41, 0
	s_add_i32 s40, s85, s56
	global_load_lds_dwordx4 v[192:193], off
	v_lshl_add_u64 v[192:193], s[36:37], 0, v[130:131]
	s_mov_b32 m0, s40
	s_nop 0
	global_load_lds_dwordx4 v[192:193], off
	v_lshl_add_u64 v[192:193], s[36:37], 0, v[134:135]
	s_add_i32 m0, s40, 0x2000
	s_nop 0
	global_load_lds_dwordx4 v[192:193], off
	v_lshl_add_u64 v[192:193], v[222:223], 0, s[28:29]
	s_mov_b32 m0, s62
	s_nop 0
	global_load_lds_dwordx4 v[192:193], off
	v_lshl_add_u64 v[192:193], v[224:225], 0, s[28:29]
	s_mov_b32 m0, s63
	s_nop 0
	global_load_lds_dwordx4 v[192:193], off
	s_waitcnt vmcnt(8)
	s_waitcnt lgkmcnt(0)
	s_barrier
	s_setprio 1
	s_waitcnt lgkmcnt(0)
	v_mfma_f32_16x16x32_bf16 v[60:63], v[144:147], v[184:187], v[60:63]
	v_mfma_f32_16x16x32_bf16 v[56:59], v[160:163], v[184:187], v[56:59]
	v_mfma_f32_16x16x32_bf16 v[44:47], v[144:147], v[196:199], v[44:47]
	v_mfma_f32_16x16x32_bf16 v[40:43], v[160:163], v[196:199], v[40:43]
	v_mfma_f32_16x16x32_bf16 v[28:31], v[144:147], v[204:207], v[28:31]
	v_mfma_f32_16x16x32_bf16 v[24:27], v[160:163], v[204:207], v[24:27]
	v_mfma_f32_16x16x32_bf16 v[12:15], v[144:147], v[212:215], v[12:15]
	v_mfma_f32_16x16x32_bf16 v[8:11], v[160:163], v[212:215], v[8:11]
	v_mfma_f32_16x16x32_bf16 v[60:63], v[156:159], v[188:191], v[60:63]
	v_mfma_f32_16x16x32_bf16 v[56:59], v[164:167], v[188:191], v[56:59]
	v_mfma_f32_16x16x32_bf16 v[44:47], v[156:159], v[200:203], v[44:47]
	v_mfma_f32_16x16x32_bf16 v[40:43], v[164:167], v[200:203], v[40:43]
	v_mfma_f32_16x16x32_bf16 v[28:31], v[156:159], v[208:211], v[28:31]
	v_mfma_f32_16x16x32_bf16 v[24:27], v[164:167], v[208:211], v[24:27]
	v_mfma_f32_16x16x32_bf16 v[12:15], v[156:159], v[216:219], v[12:15]
	v_mfma_f32_16x16x32_bf16 v[8:11], v[164:167], v[216:219], v[8:11]
	s_setprio 0
	s_setprio 1
	v_mfma_f32_16x16x32_bf16 v[52:55], v[168:171], v[184:187], v[52:55]
	v_mfma_f32_16x16x32_bf16 v[48:51], v[176:179], v[184:187], v[48:51]
	v_mfma_f32_16x16x32_bf16 v[36:39], v[168:171], v[196:199], v[36:39]
	v_mfma_f32_16x16x32_bf16 v[32:35], v[176:179], v[196:199], v[32:35]
	v_mfma_f32_16x16x32_bf16 v[20:23], v[168:171], v[204:207], v[20:23]
	v_mfma_f32_16x16x32_bf16 v[16:19], v[176:179], v[204:207], v[16:19]
	v_mfma_f32_16x16x32_bf16 v[4:7], v[168:171], v[212:215], v[4:7]
	v_mfma_f32_16x16x32_bf16 v[0:3], v[176:179], v[212:215], v[0:3]
	v_mfma_f32_16x16x32_bf16 v[52:55], v[172:175], v[188:191], v[52:55]
	v_mfma_f32_16x16x32_bf16 v[48:51], v[180:183], v[188:191], v[48:51]
	v_mfma_f32_16x16x32_bf16 v[36:39], v[172:175], v[200:203], v[36:39]
	v_mfma_f32_16x16x32_bf16 v[32:35], v[180:183], v[200:203], v[32:35]
	v_mfma_f32_16x16x32_bf16 v[20:23], v[172:175], v[208:211], v[20:23]
	v_mfma_f32_16x16x32_bf16 v[16:19], v[180:183], v[208:211], v[16:19]
	v_mfma_f32_16x16x32_bf16 v[4:7], v[172:175], v[216:219], v[4:7]
	v_mfma_f32_16x16x32_bf16 v[0:3], v[180:183], v[216:219], v[0:3]
	s_setprio 0
	s_barrier
	s_add_i32 s83, s83, 2
	s_add_u32 s81, s81, 0x100
	s_addc_u32 s82, s82, 0
	s_cmp_gt_u32 s83, 41
	s_mov_b64 s[36:37], s[38:39]
	s_cbranch_scc0 .LBB0_2142
	s_and_b64 vcc, exec, s[30:31]
	s_cbranch_vccz .LBB0_2145
	s_barrier

.LBB0_2236:
	ds_read_b128 v[152:155], v157
	ds_read_b128 v[162:165], v157 offset:1024
	ds_read_b128 v[166:169], v157 offset:2048
	ds_read_b128 v[170:173], v157 offset:3072
	ds_read_b128 v[174:177], v158
	ds_read_b128 v[178:181], v158 offset:1024
	ds_read_b128 v[182:185], v158 offset:2048
	ds_read_b128 v[186:189], v158 offset:3072
	s_add_u32 s42, s40, 0xfffc0080
	s_addc_u32 s43, s41, -1
	s_cmp_eq_u32 s88, 12
	s_cselect_b32 s45, s1, s43
	s_cselect_b32 s44, s15, s42
	s_cselect_b32 s43, s16, s87
	s_cselect_b32 s42, s31, s35
	v_lshl_add_u64 v[224:225], s[40:41], 0, v[144:145]
	s_add_i32 m0, s59, 0xc000
	ds_read_b128 v[190:193], v159
	ds_read_b128 v[196:199], v159 offset:1024
	ds_read_b128 v[200:203], v159 offset:2048
	ds_read_b128 v[204:207], v159 offset:3072
	ds_read_b128 v[208:211], v159 offset:4096
	ds_read_b128 v[212:215], v159 offset:5120
	ds_read_b128 v[216:219], v159 offset:6144
	ds_read_b128 v[220:223], v159 offset:7168
	global_load_lds_dwordx4 v[224:225], off
	v_lshl_add_u64 v[224:225], s[40:41], 0, v[146:147]
	s_add_i32 m0, s59, 0xe000
	s_nop 0
	global_load_lds_dwordx4 v[224:225], off
	s_waitcnt vmcnt(8)
	s_waitcnt lgkmcnt(0)
	s_barrier
	s_setprio 1
	s_waitcnt lgkmcnt(0)
	v_mfma_f32_16x16x32_bf16 v[124:127], v[152:155], v[190:193], v[124:127]
	v_mfma_f32_16x16x32_bf16 v[120:123], v[166:169], v[190:193], v[120:123]
	v_mfma_f32_16x16x32_bf16 v[108:111], v[152:155], v[200:203], v[108:111]
	v_mfma_f32_16x16x32_bf16 v[104:107], v[166:169], v[200:203], v[104:107]
	v_mfma_f32_16x16x32_bf16 v[92:95], v[152:155], v[208:211], v[92:95]
	v_mfma_f32_16x16x32_bf16 v[88:91], v[166:169], v[208:211], v[88:91]
	v_mfma_f32_16x16x32_bf16 v[76:79], v[152:155], v[216:219], v[76:79]
	v_mfma_f32_16x16x32_bf16 v[72:75], v[166:169], v[216:219], v[72:75]
	v_mfma_f32_16x16x32_bf16 v[124:127], v[162:165], v[196:199], v[124:127]
	v_mfma_f32_16x16x32_bf16 v[120:123], v[170:173], v[196:199], v[120:123]
	v_mfma_f32_16x16x32_bf16 v[108:111], v[162:165], v[204:207], v[108:111]
	v_mfma_f32_16x16x32_bf16 v[104:107], v[170:173], v[204:207], v[104:107]
	v_mfma_f32_16x16x32_bf16 v[92:95], v[162:165], v[212:215], v[92:95]
	v_mfma_f32_16x16x32_bf16 v[88:91], v[170:173], v[212:215], v[88:91]
	v_mfma_f32_16x16x32_bf16 v[76:79], v[162:165], v[220:223], v[76:79]
	v_mfma_f32_16x16x32_bf16 v[72:75], v[170:173], v[220:223], v[72:75]
	s_setprio 0
	s_setprio 1
	v_mfma_f32_16x16x32_bf16 v[116:119], v[174:177], v[190:193], v[116:119]
	v_mfma_f32_16x16x32_bf16 v[112:115], v[182:185], v[190:193], v[112:115]
	v_mfma_f32_16x16x32_bf16 v[100:103], v[174:177], v[200:203], v[100:103]
	v_mfma_f32_16x16x32_bf16 v[96:99], v[182:185], v[200:203], v[96:99]
	v_mfma_f32_16x16x32_bf16 v[84:87], v[174:177], v[208:211], v[84:87]
	v_mfma_f32_16x16x32_bf16 v[80:83], v[182:185], v[208:211], v[80:83]
	v_mfma_f32_16x16x32_bf16 v[68:71], v[174:177], v[216:219], v[68:71]
	v_mfma_f32_16x16x32_bf16 v[64:67], v[182:185], v[216:219], v[64:67]
	v_mfma_f32_16x16x32_bf16 v[116:119], v[178:181], v[196:199], v[116:119]
	v_mfma_f32_16x16x32_bf16 v[112:115], v[186:189], v[196:199], v[112:115]
	v_mfma_f32_16x16x32_bf16 v[100:103], v[178:181], v[204:207], v[100:103]
	v_mfma_f32_16x16x32_bf16 v[96:99], v[186:189], v[204:207], v[96:99]
	v_mfma_f32_16x16x32_bf16 v[84:87], v[178:181], v[212:215], v[84:87]
	v_mfma_f32_16x16x32_bf16 v[80:83], v[186:189], v[212:215], v[80:83]
	v_mfma_f32_16x16x32_bf16 v[68:71], v[178:181], v[220:223], v[68:71]
	v_mfma_f32_16x16x32_bf16 v[64:67], v[186:189], v[220:223], v[64:67]
	s_setprio 0
	s_barrier
	s_add_i32 s89, s78, s58
	v_lshl_add_u64 v[224:225], s[42:43], 0, v[130:131]
	s_mov_b32 m0, s89
	ds_read_b128 v[190:193], v159 offset:16384
	ds_read_b128 v[196:199], v159 offset:17408
	ds_read_b128 v[200:203], v159 offset:18432
	ds_read_b128 v[204:207], v159 offset:19456
	ds_read_b128 v[208:211], v159 offset:20480
	ds_read_b128 v[212:215], v159 offset:21504
	ds_read_b128 v[216:219], v159 offset:22528
	ds_read_b128 v[220:223], v159 offset:23552
	global_load_lds_dwordx4 v[224:225], off
	s_add_i32 m0, s89, 0x2000
	s_add_u32 s90, s42, 0x40000
	v_lshl_add_u64 v[226:227], s[42:43], 0, v[134:135]
	s_addc_u32 s91, s43, 0
	s_add_i32 s89, s79, s58
	global_load_lds_dwordx4 v[226:227], off
	v_lshl_add_u64 v[228:229], s[90:91], 0, v[130:131]
	s_mov_b32 m0, s89
	v_lshl_add_u64 v[230:231], s[44:45], 0, v[132:133]
	global_load_lds_dwordx4 v[228:229], off
	v_lshl_add_u64 v[228:229], s[90:91], 0, v[134:135]
	s_add_i32 m0, s89, 0x2000
	s_nop 0
	global_load_lds_dwordx4 v[228:229], off
	v_lshl_add_u64 v[228:229], s[44:45], 0, v[128:129]
	s_waitcnt vmcnt(6)
	s_waitcnt lgkmcnt(0)
	s_barrier
	s_setprio 1
	s_waitcnt lgkmcnt(0)
	v_mfma_f32_16x16x32_bf16 v[60:63], v[152:155], v[190:193], v[60:63]
	v_mfma_f32_16x16x32_bf16 v[56:59], v[166:169], v[190:193], v[56:59]
	v_mfma_f32_16x16x32_bf16 v[44:47], v[152:155], v[200:203], v[44:47]
	v_mfma_f32_16x16x32_bf16 v[40:43], v[166:169], v[200:203], v[40:43]
	v_mfma_f32_16x16x32_bf16 v[28:31], v[152:155], v[208:211], v[28:31]
	v_mfma_f32_16x16x32_bf16 v[24:27], v[166:169], v[208:211], v[24:27]
	v_mfma_f32_16x16x32_bf16 v[12:15], v[152:155], v[216:219], v[12:15]
	v_mfma_f32_16x16x32_bf16 v[8:11], v[166:169], v[216:219], v[8:11]
	v_mfma_f32_16x16x32_bf16 v[60:63], v[162:165], v[196:199], v[60:63]
	v_mfma_f32_16x16x32_bf16 v[56:59], v[170:173], v[196:199], v[56:59]
	v_mfma_f32_16x16x32_bf16 v[44:47], v[162:165], v[204:207], v[44:47]
	v_mfma_f32_16x16x32_bf16 v[40:43], v[170:173], v[204:207], v[40:43]
	v_mfma_f32_16x16x32_bf16 v[28:31], v[162:165], v[212:215], v[28:31]
	v_mfma_f32_16x16x32_bf16 v[24:27], v[170:173], v[212:215], v[24:27]
	v_mfma_f32_16x16x32_bf16 v[12:15], v[162:165], v[220:223], v[12:15]
	v_mfma_f32_16x16x32_bf16 v[8:11], v[170:173], v[220:223], v[8:11]
	s_setprio 0
	s_setprio 1
	v_mfma_f32_16x16x32_bf16 v[52:55], v[174:177], v[190:193], v[52:55]
	v_mfma_f32_16x16x32_bf16 v[48:51], v[182:185], v[190:193], v[48:51]
	v_mfma_f32_16x16x32_bf16 v[36:39], v[174:177], v[200:203], v[36:39]
	v_mfma_f32_16x16x32_bf16 v[32:35], v[182:185], v[200:203], v[32:35]
	v_mfma_f32_16x16x32_bf16 v[20:23], v[174:177], v[208:211], v[20:23]
	v_mfma_f32_16x16x32_bf16 v[16:19], v[182:185], v[208:211], v[16:19]
	v_mfma_f32_16x16x32_bf16 v[4:7], v[174:177], v[216:219], v[4:7]
	v_mfma_f32_16x16x32_bf16 v[0:3], v[182:185], v[216:219], v[0:3]
	v_mfma_f32_16x16x32_bf16 v[52:55], v[178:181], v[196:199], v[52:55]
	v_mfma_f32_16x16x32_bf16 v[48:51], v[186:189], v[196:199], v[48:51]
	v_mfma_f32_16x16x32_bf16 v[36:39], v[178:181], v[204:207], v[36:39]
	v_mfma_f32_16x16x32_bf16 v[32:35], v[186:189], v[204:207], v[32:35]
	v_mfma_f32_16x16x32_bf16 v[20:23], v[178:181], v[212:215], v[20:23]
	v_mfma_f32_16x16x32_bf16 v[16:19], v[186:189], v[212:215], v[16:19]
	v_mfma_f32_16x16x32_bf16 v[4:7], v[178:181], v[220:223], v[4:7]
	v_mfma_f32_16x16x32_bf16 v[0:3], v[186:189], v[220:223], v[0:3]
	s_setprio 0
	s_barrier
	s_add_i32 s89, 0, 0x18000
	v_add_u32_e32 v136, s89, v141
	s_add_i32 s90, 0, 0x1c000
	ds_read_b128 v[152:155], v136
	ds_read_b128 v[162:165], v136 offset:1024
	ds_read_b128 v[166:169], v136 offset:2048
	ds_read_b128 v[170:173], v136 offset:3072
	v_add_u32_e32 v136, s90, v141
	ds_read_b128 v[174:177], v136
	ds_read_b128 v[178:181], v136 offset:1024
	ds_read_b128 v[182:185], v136 offset:2048
	ds_read_b128 v[186:189], v136 offset:3072
	s_add_u32 s44, s44, 0x40000
	s_addc_u32 s45, s45, 0
	v_lshl_add_u64 v[232:233], s[44:45], 0, v[128:129]
	ds_read_b128 v[190:193], v159 offset:32768
	ds_read_b128 v[196:199], v159 offset:33792
	ds_read_b128 v[200:203], v159 offset:34816
	ds_read_b128 v[204:207], v159 offset:35840
	ds_read_b128 v[208:211], v159 offset:36864
	ds_read_b128 v[212:215], v159 offset:37888
	ds_read_b128 v[216:219], v159 offset:38912
	ds_read_b128 v[220:223], v159 offset:39936
	s_mov_b32 m0, s59
	s_nop 0
	global_load_lds_dwordx4 v[228:229], off
	s_mov_b32 m0, s60
	s_nop 0
	global_load_lds_dwordx4 v[230:231], off
	s_mov_b32 m0, s61
	s_nop 0
	global_load_lds_dwordx4 v[232:233], off
	v_lshl_add_u64 v[232:233], s[44:45], 0, v[132:133]
	s_mov_b32 m0, s62
	s_nop 0
	global_load_lds_dwordx4 v[232:233], off
	s_waitcnt vmcnt(8)
	s_waitcnt lgkmcnt(0)
	s_barrier
	s_setprio 1
	s_waitcnt lgkmcnt(0)
	v_mfma_f32_16x16x32_bf16 v[124:127], v[152:155], v[190:193], v[124:127]
	v_mfma_f32_16x16x32_bf16 v[120:123], v[166:169], v[190:193], v[120:123]
	v_mfma_f32_16x16x32_bf16 v[108:111], v[152:155], v[200:203], v[108:111]
	v_mfma_f32_16x16x32_bf16 v[104:107], v[166:169], v[200:203], v[104:107]
	v_mfma_f32_16x16x32_bf16 v[92:95], v[152:155], v[208:211], v[92:95]
	v_mfma_f32_16x16x32_bf16 v[88:91], v[166:169], v[208:211], v[88:91]
	v_mfma_f32_16x16x32_bf16 v[76:79], v[152:155], v[216:219], v[76:79]
	v_mfma_f32_16x16x32_bf16 v[72:75], v[166:169], v[216:219], v[72:75]
	v_mfma_f32_16x16x32_bf16 v[124:127], v[162:165], v[196:199], v[124:127]
	v_mfma_f32_16x16x32_bf16 v[120:123], v[170:173], v[196:199], v[120:123]
	v_mfma_f32_16x16x32_bf16 v[108:111], v[162:165], v[204:207], v[108:111]
	v_mfma_f32_16x16x32_bf16 v[104:107], v[170:173], v[204:207], v[104:107]
	v_mfma_f32_16x16x32_bf16 v[92:95], v[162:165], v[212:215], v[92:95]
	v_mfma_f32_16x16x32_bf16 v[88:91], v[170:173], v[212:215], v[88:91]
	v_mfma_f32_16x16x32_bf16 v[76:79], v[162:165], v[220:223], v[76:79]
	v_mfma_f32_16x16x32_bf16 v[72:75], v[170:173], v[220:223], v[72:75]
	s_setprio 0
	s_setprio 1
	v_mfma_f32_16x16x32_bf16 v[116:119], v[174:177], v[190:193], v[116:119]
	v_mfma_f32_16x16x32_bf16 v[112:115], v[182:185], v[190:193], v[112:115]
	v_mfma_f32_16x16x32_bf16 v[100:103], v[174:177], v[200:203], v[100:103]
	v_mfma_f32_16x16x32_bf16 v[96:99], v[182:185], v[200:203], v[96:99]
	v_mfma_f32_16x16x32_bf16 v[84:87], v[174:177], v[208:211], v[84:87]
	v_mfma_f32_16x16x32_bf16 v[80:83], v[182:185], v[208:211], v[80:83]
	v_mfma_f32_16x16x32_bf16 v[68:71], v[174:177], v[216:219], v[68:71]
	v_mfma_f32_16x16x32_bf16 v[64:67], v[182:185], v[216:219], v[64:67]
	v_mfma_f32_16x16x32_bf16 v[116:119], v[178:181], v[196:199], v[116:119]
	v_mfma_f32_16x16x32_bf16 v[112:115], v[186:189], v[196:199], v[112:115]
	v_mfma_f32_16x16x32_bf16 v[100:103], v[178:181], v[204:207], v[100:103]
	v_mfma_f32_16x16x32_bf16 v[96:99], v[186:189], v[204:207], v[96:99]
	v_mfma_f32_16x16x32_bf16 v[84:87], v[178:181], v[212:215], v[84:87]
	v_mfma_f32_16x16x32_bf16 v[80:83], v[186:189], v[212:215], v[80:83]
	v_mfma_f32_16x16x32_bf16 v[68:71], v[178:181], v[220:223], v[68:71]
	v_mfma_f32_16x16x32_bf16 v[64:67], v[186:189], v[220:223], v[64:67]
	s_setprio 0
	s_barrier
	s_add_i32 s44, s89, s58
	v_lshl_add_u64 v[224:225], v[224:225], 0, s[26:27]
	s_mov_b32 m0, s44
	ds_read_b128 v[190:193], v159 offset:49152
	ds_read_b128 v[196:199], v159 offset:50176
	ds_read_b128 v[200:203], v159 offset:51200
	ds_read_b128 v[204:207], v159 offset:52224
	ds_read_b128 v[208:211], v159 offset:53248
	ds_read_b128 v[212:215], v159 offset:54272
	ds_read_b128 v[216:219], v159 offset:55296
	ds_read_b128 v[220:223], v159 offset:56320
	global_load_lds_dwordx4 v[224:225], off
	s_add_i32 m0, s44, 0x2000
	s_add_u32 s42, s42, 0x40080
	v_lshl_add_u64 v[224:225], v[226:227], 0, s[26:27]
	s_addc_u32 s43, s43, 0
	s_add_i32 s44, s90, s58
	global_load_lds_dwordx4 v[224:225], off
	v_lshl_add_u64 v[224:225], s[42:43], 0, v[130:131]
	s_mov_b32 m0, s44
	s_nop 0
	global_load_lds_dwordx4 v[224:225], off
	v_lshl_add_u64 v[224:225], s[42:43], 0, v[134:135]
	s_add_i32 m0, s44, 0x2000
	s_nop 0
	global_load_lds_dwordx4 v[224:225], off
	v_lshl_add_u64 v[224:225], v[228:229], 0, s[26:27]
	s_mov_b32 m0, s71
	s_nop 0
	global_load_lds_dwordx4 v[224:225], off
	v_lshl_add_u64 v[224:225], v[230:231], 0, s[26:27]
	s_mov_b32 m0, s72
	s_nop 0
	global_load_lds_dwordx4 v[224:225], off
	s_waitcnt vmcnt(8)
	s_waitcnt lgkmcnt(0)
	s_barrier
	s_setprio 1
	s_waitcnt lgkmcnt(0)
	v_mfma_f32_16x16x32_bf16 v[60:63], v[152:155], v[190:193], v[60:63]
	v_mfma_f32_16x16x32_bf16 v[56:59], v[166:169], v[190:193], v[56:59]
	v_mfma_f32_16x16x32_bf16 v[44:47], v[152:155], v[200:203], v[44:47]
	v_mfma_f32_16x16x32_bf16 v[40:43], v[166:169], v[200:203], v[40:43]
	v_mfma_f32_16x16x32_bf16 v[28:31], v[152:155], v[208:211], v[28:31]
	v_mfma_f32_16x16x32_bf16 v[24:27], v[166:169], v[208:211], v[24:27]
	v_mfma_f32_16x16x32_bf16 v[12:15], v[152:155], v[216:219], v[12:15]
	v_mfma_f32_16x16x32_bf16 v[8:11], v[166:169], v[216:219], v[8:11]
	v_mfma_f32_16x16x32_bf16 v[60:63], v[162:165], v[196:199], v[60:63]
	v_mfma_f32_16x16x32_bf16 v[56:59], v[170:173], v[196:199], v[56:59]
	v_mfma_f32_16x16x32_bf16 v[44:47], v[162:165], v[204:207], v[44:47]
	v_mfma_f32_16x16x32_bf16 v[40:43], v[170:173], v[204:207], v[40:43]
	v_mfma_f32_16x16x32_bf16 v[28:31], v[162:165], v[212:215], v[28:31]
	v_mfma_f32_16x16x32_bf16 v[24:27], v[170:173], v[212:215], v[24:27]
	v_mfma_f32_16x16x32_bf16 v[12:15], v[162:165], v[220:223], v[12:15]
	v_mfma_f32_16x16x32_bf16 v[8:11], v[170:173], v[220:223], v[8:11]
	s_setprio 0
	s_setprio 1
	v_mfma_f32_16x16x32_bf16 v[52:55], v[174:177], v[190:193], v[52:55]
	v_mfma_f32_16x16x32_bf16 v[48:51], v[182:185], v[190:193], v[48:51]
	v_mfma_f32_16x16x32_bf16 v[36:39], v[174:177], v[200:203], v[36:39]
	v_mfma_f32_16x16x32_bf16 v[32:35], v[182:185], v[200:203], v[32:35]
	v_mfma_f32_16x16x32_bf16 v[20:23], v[174:177], v[208:211], v[20:23]
	v_mfma_f32_16x16x32_bf16 v[16:19], v[182:185], v[208:211], v[16:19]
	v_mfma_f32_16x16x32_bf16 v[4:7], v[174:177], v[216:219], v[4:7]
	v_mfma_f32_16x16x32_bf16 v[0:3], v[182:185], v[216:219], v[0:3]
	v_mfma_f32_16x16x32_bf16 v[52:55], v[178:181], v[196:199], v[52:55]
	v_mfma_f32_16x16x32_bf16 v[48:51], v[186:189], v[196:199], v[48:51]
	v_mfma_f32_16x16x32_bf16 v[36:39], v[178:181], v[204:207], v[36:39]
	v_mfma_f32_16x16x32_bf16 v[32:35], v[186:189], v[204:207], v[32:35]
	v_mfma_f32_16x16x32_bf16 v[20:23], v[178:181], v[212:215], v[20:23]
	v_mfma_f32_16x16x32_bf16 v[16:19], v[186:189], v[212:215], v[16:19]
	v_mfma_f32_16x16x32_bf16 v[4:7], v[178:181], v[220:223], v[4:7]
	v_mfma_f32_16x16x32_bf16 v[0:3], v[186:189], v[220:223], v[0:3]
	s_setprio 0
	s_barrier
	s_add_i32 s88, s88, 2
	s_add_u32 s40, s40, 0x100
	s_addc_u32 s41, s41, 0
	s_add_u32 s35, s35, 0x100
	s_addc_u32 s87, s87, 0
	s_cmp_gt_u32 s88, 13
	s_cbranch_scc0 .LBB0_2236
	s_and_b64 vcc, exec, s[28:29]
	s_cbranch_vccz .LBB0_2239
	s_barrier

.LBB0_2370:
	ds_read_b128 v[148:151], v144
	ds_read_b128 v[152:155], v144 offset:1024
	ds_read_b128 v[156:159], v144 offset:2048
	ds_read_b128 v[160:163], v144 offset:3072
	ds_read_b128 v[164:167], v145
	ds_read_b128 v[168:171], v145 offset:1024
	ds_read_b128 v[172:175], v145 offset:2048
	ds_read_b128 v[176:179], v145 offset:3072
	s_add_u32 s38, s36, 0x100
	s_addc_u32 s39, s37, 0
	s_cmp_eq_u32 s81, 4
	s_cselect_b32 s43, s31, s39
	s_cselect_b32 s42, s30, s38
	s_cselect_b32 s41, s35, s27
	s_cselect_b32 s40, s34, s17
	v_lshl_add_u64 v[192:193], s[36:37], 0, v[138:139]
	s_add_i32 m0, s55, 0xc000
	ds_read_b128 v[180:183], v146
	ds_read_b128 v[184:187], v146 offset:1024
	ds_read_b128 v[188:191], v146 offset:2048
	ds_read_b128 v[196:199], v146 offset:3072
	ds_read_b128 v[200:203], v146 offset:4096
	ds_read_b128 v[204:207], v146 offset:5120
	ds_read_b128 v[208:211], v146 offset:6144
	ds_read_b128 v[212:215], v146 offset:7168
	global_load_lds_dwordx4 v[192:193], off
	v_lshl_add_u64 v[192:193], s[36:37], 0, v[140:141]
	s_add_i32 m0, s55, 0xe000
	s_nop 0
	global_load_lds_dwordx4 v[192:193], off
	s_waitcnt vmcnt(8)
	s_waitcnt lgkmcnt(0)
	s_barrier
	s_setprio 1
	s_waitcnt lgkmcnt(0)
	v_mfma_f32_16x16x32_bf16 v[124:127], v[148:151], v[180:183], v[124:127]
	v_mfma_f32_16x16x32_bf16 v[120:123], v[156:159], v[180:183], v[120:123]
	v_mfma_f32_16x16x32_bf16 v[116:119], v[148:151], v[188:191], v[116:119]
	v_mfma_f32_16x16x32_bf16 v[112:115], v[156:159], v[188:191], v[112:115]
	v_mfma_f32_16x16x32_bf16 v[104:107], v[148:151], v[200:203], v[104:107]
	v_mfma_f32_16x16x32_bf16 v[96:99], v[156:159], v[200:203], v[96:99]
	v_mfma_f32_16x16x32_bf16 v[88:91], v[148:151], v[208:211], v[88:91]
	v_mfma_f32_16x16x32_bf16 v[80:83], v[156:159], v[208:211], v[80:83]
	v_mfma_f32_16x16x32_bf16 v[124:127], v[152:155], v[184:187], v[124:127]
	v_mfma_f32_16x16x32_bf16 v[120:123], v[160:163], v[184:187], v[120:123]
	v_mfma_f32_16x16x32_bf16 v[116:119], v[152:155], v[196:199], v[116:119]
	v_mfma_f32_16x16x32_bf16 v[112:115], v[160:163], v[196:199], v[112:115]
	v_mfma_f32_16x16x32_bf16 v[104:107], v[152:155], v[204:207], v[104:107]
	v_mfma_f32_16x16x32_bf16 v[96:99], v[160:163], v[204:207], v[96:99]
	v_mfma_f32_16x16x32_bf16 v[88:91], v[152:155], v[212:215], v[88:91]
	v_mfma_f32_16x16x32_bf16 v[80:83], v[160:163], v[212:215], v[80:83]
	s_setprio 0
	s_setprio 1
	v_mfma_f32_16x16x32_bf16 v[108:111], v[164:167], v[180:183], v[108:111]
	v_mfma_f32_16x16x32_bf16 v[100:103], v[172:175], v[180:183], v[100:103]
	v_mfma_f32_16x16x32_bf16 v[92:95], v[164:167], v[188:191], v[92:95]
	v_mfma_f32_16x16x32_bf16 v[84:87], v[172:175], v[188:191], v[84:87]
	v_mfma_f32_16x16x32_bf16 v[76:79], v[164:167], v[200:203], v[76:79]
	v_mfma_f32_16x16x32_bf16 v[72:75], v[172:175], v[200:203], v[72:75]
	v_mfma_f32_16x16x32_bf16 v[68:71], v[164:167], v[208:211], v[68:71]
	v_mfma_f32_16x16x32_bf16 v[64:67], v[172:175], v[208:211], v[64:67]
	v_mfma_f32_16x16x32_bf16 v[108:111], v[168:171], v[184:187], v[108:111]
	v_mfma_f32_16x16x32_bf16 v[100:103], v[176:179], v[184:187], v[100:103]
	v_mfma_f32_16x16x32_bf16 v[92:95], v[168:171], v[196:199], v[92:95]
	v_mfma_f32_16x16x32_bf16 v[84:87], v[176:179], v[196:199], v[84:87]
	v_mfma_f32_16x16x32_bf16 v[76:79], v[168:171], v[204:207], v[76:79]
	v_mfma_f32_16x16x32_bf16 v[72:75], v[176:179], v[204:207], v[72:75]
	v_mfma_f32_16x16x32_bf16 v[68:71], v[168:171], v[212:215], v[68:71]
	v_mfma_f32_16x16x32_bf16 v[64:67], v[176:179], v[212:215], v[64:67]
	s_setprio 0
	s_barrier
	s_add_i32 s36, s71, s54
	v_lshl_add_u64 v[192:193], s[40:41], 0, v[132:133]
	s_mov_b32 m0, s36
	ds_read_b128 v[180:183], v146 offset:16384
	ds_read_b128 v[184:187], v146 offset:17408
	ds_read_b128 v[188:191], v146 offset:18432
	ds_read_b128 v[196:199], v146 offset:19456
	ds_read_b128 v[200:203], v146 offset:20480
	ds_read_b128 v[204:207], v146 offset:21504
	ds_read_b128 v[208:211], v146 offset:22528
	ds_read_b128 v[212:215], v146 offset:23552
	global_load_lds_dwordx4 v[192:193], off
	s_add_i32 m0, s36, 0x2000
	s_add_u32 s36, s40, 0x20000
	v_lshl_add_u64 v[216:217], s[40:41], 0, v[128:129]
	s_addc_u32 s37, s41, 0
	s_add_i32 s82, s72, s54
	global_load_lds_dwordx4 v[216:217], off
	v_lshl_add_u64 v[218:219], s[36:37], 0, v[132:133]
	s_mov_b32 m0, s82
	v_lshl_add_u64 v[220:221], s[42:43], 0, v[130:131]
	global_load_lds_dwordx4 v[218:219], off
	v_lshl_add_u64 v[218:219], s[36:37], 0, v[128:129]
	s_add_i32 m0, s82, 0x2000
	s_nop 0
	global_load_lds_dwordx4 v[218:219], off
	v_lshl_add_u64 v[218:219], s[42:43], 0, v[134:135]
	s_waitcnt vmcnt(6)
	s_waitcnt lgkmcnt(0)
	s_barrier
	s_setprio 1
	s_waitcnt lgkmcnt(0)
	v_mfma_f32_16x16x32_bf16 v[60:63], v[148:151], v[180:183], v[60:63]
	v_mfma_f32_16x16x32_bf16 v[56:59], v[156:159], v[180:183], v[56:59]
	v_mfma_f32_16x16x32_bf16 v[52:55], v[148:151], v[188:191], v[52:55]
	v_mfma_f32_16x16x32_bf16 v[48:51], v[156:159], v[188:191], v[48:51]
	v_mfma_f32_16x16x32_bf16 v[40:43], v[148:151], v[200:203], v[40:43]
	v_mfma_f32_16x16x32_bf16 v[32:35], v[156:159], v[200:203], v[32:35]
	v_mfma_f32_16x16x32_bf16 v[24:27], v[148:151], v[208:211], v[24:27]
	v_mfma_f32_16x16x32_bf16 v[16:19], v[156:159], v[208:211], v[16:19]
	v_mfma_f32_16x16x32_bf16 v[60:63], v[152:155], v[184:187], v[60:63]
	v_mfma_f32_16x16x32_bf16 v[56:59], v[160:163], v[184:187], v[56:59]
	v_mfma_f32_16x16x32_bf16 v[52:55], v[152:155], v[196:199], v[52:55]
	v_mfma_f32_16x16x32_bf16 v[48:51], v[160:163], v[196:199], v[48:51]
	v_mfma_f32_16x16x32_bf16 v[40:43], v[152:155], v[204:207], v[40:43]
	v_mfma_f32_16x16x32_bf16 v[32:35], v[160:163], v[204:207], v[32:35]
	v_mfma_f32_16x16x32_bf16 v[24:27], v[152:155], v[212:215], v[24:27]
	v_mfma_f32_16x16x32_bf16 v[16:19], v[160:163], v[212:215], v[16:19]
	s_setprio 0
	s_setprio 1
	v_mfma_f32_16x16x32_bf16 v[44:47], v[164:167], v[180:183], v[44:47]
	v_mfma_f32_16x16x32_bf16 v[36:39], v[172:175], v[180:183], v[36:39]
	v_mfma_f32_16x16x32_bf16 v[28:31], v[164:167], v[188:191], v[28:31]
	v_mfma_f32_16x16x32_bf16 v[20:23], v[172:175], v[188:191], v[20:23]
	v_mfma_f32_16x16x32_bf16 v[12:15], v[164:167], v[200:203], v[12:15]
	v_mfma_f32_16x16x32_bf16 v[8:11], v[172:175], v[200:203], v[8:11]
	v_mfma_f32_16x16x32_bf16 v[4:7], v[164:167], v[208:211], v[4:7]
	v_mfma_f32_16x16x32_bf16 v[0:3], v[172:175], v[208:211], v[0:3]
	v_mfma_f32_16x16x32_bf16 v[44:47], v[168:171], v[184:187], v[44:47]
	v_mfma_f32_16x16x32_bf16 v[36:39], v[176:179], v[184:187], v[36:39]
	v_mfma_f32_16x16x32_bf16 v[28:31], v[168:171], v[196:199], v[28:31]
	v_mfma_f32_16x16x32_bf16 v[20:23], v[176:179], v[196:199], v[20:23]
	v_mfma_f32_16x16x32_bf16 v[12:15], v[168:171], v[204:207], v[12:15]
	v_mfma_f32_16x16x32_bf16 v[8:11], v[176:179], v[204:207], v[8:11]
	v_mfma_f32_16x16x32_bf16 v[4:7], v[168:171], v[212:215], v[4:7]
	v_mfma_f32_16x16x32_bf16 v[0:3], v[176:179], v[212:215], v[0:3]
	s_setprio 0
	s_barrier
	s_add_i32 s82, 0, 0x18000
	v_add_u32_e32 v147, s82, v143
	s_add_i32 s83, 0, 0x1c000
	ds_read_b128 v[148:151], v147
	ds_read_b128 v[152:155], v147 offset:1024
	ds_read_b128 v[156:159], v147 offset:2048
	ds_read_b128 v[160:163], v147 offset:3072
	v_add_u32_e32 v147, s83, v143
	ds_read_b128 v[164:167], v147
	ds_read_b128 v[168:171], v147 offset:1024
	ds_read_b128 v[172:175], v147 offset:2048
	ds_read_b128 v[176:179], v147 offset:3072
	s_add_u32 s36, s42, 0x30000
	s_addc_u32 s37, s43, 0
	v_lshl_add_u64 v[222:223], s[36:37], 0, v[134:135]
	ds_read_b128 v[180:183], v146 offset:32768
	ds_read_b128 v[184:187], v146 offset:33792
	ds_read_b128 v[188:191], v146 offset:34816
	ds_read_b128 v[196:199], v146 offset:35840
	ds_read_b128 v[200:203], v146 offset:36864
	ds_read_b128 v[204:207], v146 offset:37888
	ds_read_b128 v[208:211], v146 offset:38912
	ds_read_b128 v[212:215], v146 offset:39936
	s_mov_b32 m0, s55
	s_nop 0
	global_load_lds_dwordx4 v[218:219], off
	s_mov_b32 m0, s56
	s_nop 0
	global_load_lds_dwordx4 v[220:221], off
	s_mov_b32 m0, s57
	s_nop 0
	global_load_lds_dwordx4 v[222:223], off
	v_lshl_add_u64 v[222:223], s[36:37], 0, v[130:131]
	s_mov_b32 m0, s58
	s_nop 0
	global_load_lds_dwordx4 v[222:223], off
	s_waitcnt vmcnt(8)
	s_waitcnt lgkmcnt(0)
	s_barrier
	s_setprio 1
	s_waitcnt lgkmcnt(0)
	v_mfma_f32_16x16x32_bf16 v[124:127], v[148:151], v[180:183], v[124:127]
	v_mfma_f32_16x16x32_bf16 v[120:123], v[156:159], v[180:183], v[120:123]
	v_mfma_f32_16x16x32_bf16 v[116:119], v[148:151], v[188:191], v[116:119]
	v_mfma_f32_16x16x32_bf16 v[112:115], v[156:159], v[188:191], v[112:115]
	v_mfma_f32_16x16x32_bf16 v[104:107], v[148:151], v[200:203], v[104:107]
	v_mfma_f32_16x16x32_bf16 v[96:99], v[156:159], v[200:203], v[96:99]
	v_mfma_f32_16x16x32_bf16 v[88:91], v[148:151], v[208:211], v[88:91]
	v_mfma_f32_16x16x32_bf16 v[80:83], v[156:159], v[208:211], v[80:83]
	v_mfma_f32_16x16x32_bf16 v[124:127], v[152:155], v[184:187], v[124:127]
	v_mfma_f32_16x16x32_bf16 v[120:123], v[160:163], v[184:187], v[120:123]
	v_mfma_f32_16x16x32_bf16 v[116:119], v[152:155], v[196:199], v[116:119]
	v_mfma_f32_16x16x32_bf16 v[112:115], v[160:163], v[196:199], v[112:115]
	v_mfma_f32_16x16x32_bf16 v[104:107], v[152:155], v[204:207], v[104:107]
	v_mfma_f32_16x16x32_bf16 v[96:99], v[160:163], v[204:207], v[96:99]
	v_mfma_f32_16x16x32_bf16 v[88:91], v[152:155], v[212:215], v[88:91]
	v_mfma_f32_16x16x32_bf16 v[80:83], v[160:163], v[212:215], v[80:83]
	s_setprio 0
	s_setprio 1
	v_mfma_f32_16x16x32_bf16 v[108:111], v[164:167], v[180:183], v[108:111]
	v_mfma_f32_16x16x32_bf16 v[100:103], v[172:175], v[180:183], v[100:103]
	v_mfma_f32_16x16x32_bf16 v[92:95], v[164:167], v[188:191], v[92:95]
	v_mfma_f32_16x16x32_bf16 v[84:87], v[172:175], v[188:191], v[84:87]
	v_mfma_f32_16x16x32_bf16 v[76:79], v[164:167], v[200:203], v[76:79]
	v_mfma_f32_16x16x32_bf16 v[72:75], v[172:175], v[200:203], v[72:75]
	v_mfma_f32_16x16x32_bf16 v[68:71], v[164:167], v[208:211], v[68:71]
	v_mfma_f32_16x16x32_bf16 v[64:67], v[172:175], v[208:211], v[64:67]
	v_mfma_f32_16x16x32_bf16 v[108:111], v[168:171], v[184:187], v[108:111]
	v_mfma_f32_16x16x32_bf16 v[100:103], v[176:179], v[184:187], v[100:103]
	v_mfma_f32_16x16x32_bf16 v[92:95], v[168:171], v[196:199], v[92:95]
	v_mfma_f32_16x16x32_bf16 v[84:87], v[176:179], v[196:199], v[84:87]
	v_mfma_f32_16x16x32_bf16 v[76:79], v[168:171], v[204:207], v[76:79]
	v_mfma_f32_16x16x32_bf16 v[72:75], v[176:179], v[204:207], v[72:75]
	v_mfma_f32_16x16x32_bf16 v[68:71], v[168:171], v[212:215], v[68:71]
	v_mfma_f32_16x16x32_bf16 v[64:67], v[176:179], v[212:215], v[64:67]
	s_setprio 0
	s_barrier
	s_add_i32 s36, s82, s54
	v_lshl_add_u64 v[192:193], v[192:193], 0, s[14:15]
	s_mov_b32 m0, s36
	ds_read_b128 v[180:183], v146 offset:49152
	ds_read_b128 v[184:187], v146 offset:50176
	ds_read_b128 v[188:191], v146 offset:51200
	ds_read_b128 v[196:199], v146 offset:52224
	ds_read_b128 v[200:203], v146 offset:53248
	ds_read_b128 v[204:207], v146 offset:54272
	ds_read_b128 v[208:211], v146 offset:55296
	ds_read_b128 v[212:215], v146 offset:56320
	global_load_lds_dwordx4 v[192:193], off
	s_add_i32 m0, s36, 0x2000
	s_add_u32 s36, s40, 0x20080
	v_lshl_add_u64 v[192:193], v[216:217], 0, s[14:15]
	s_addc_u32 s37, s41, 0
	s_add_i32 s40, s83, s54
	global_load_lds_dwordx4 v[192:193], off
	v_lshl_add_u64 v[192:193], s[36:37], 0, v[132:133]
	s_mov_b32 m0, s40
	s_nop 0
	global_load_lds_dwordx4 v[192:193], off
	v_lshl_add_u64 v[192:193], s[36:37], 0, v[128:129]
	s_add_i32 m0, s40, 0x2000
	s_nop 0
	global_load_lds_dwordx4 v[192:193], off
	v_lshl_add_u64 v[192:193], v[218:219], 0, s[14:15]
	s_mov_b32 m0, s62
	s_nop 0
	global_load_lds_dwordx4 v[192:193], off
	v_lshl_add_u64 v[192:193], v[220:221], 0, s[14:15]
	s_mov_b32 m0, s63
	s_nop 0
	global_load_lds_dwordx4 v[192:193], off
	s_waitcnt vmcnt(8)
	s_waitcnt lgkmcnt(0)
	s_barrier
	s_setprio 1
	s_waitcnt lgkmcnt(0)
	v_mfma_f32_16x16x32_bf16 v[60:63], v[148:151], v[180:183], v[60:63]
	v_mfma_f32_16x16x32_bf16 v[56:59], v[156:159], v[180:183], v[56:59]
	v_mfma_f32_16x16x32_bf16 v[52:55], v[148:151], v[188:191], v[52:55]
	v_mfma_f32_16x16x32_bf16 v[48:51], v[156:159], v[188:191], v[48:51]
	v_mfma_f32_16x16x32_bf16 v[40:43], v[148:151], v[200:203], v[40:43]
	v_mfma_f32_16x16x32_bf16 v[32:35], v[156:159], v[200:203], v[32:35]
	v_mfma_f32_16x16x32_bf16 v[24:27], v[148:151], v[208:211], v[24:27]
	v_mfma_f32_16x16x32_bf16 v[16:19], v[156:159], v[208:211], v[16:19]
	v_mfma_f32_16x16x32_bf16 v[60:63], v[152:155], v[184:187], v[60:63]
	v_mfma_f32_16x16x32_bf16 v[56:59], v[160:163], v[184:187], v[56:59]
	v_mfma_f32_16x16x32_bf16 v[52:55], v[152:155], v[196:199], v[52:55]
	v_mfma_f32_16x16x32_bf16 v[48:51], v[160:163], v[196:199], v[48:51]
	v_mfma_f32_16x16x32_bf16 v[40:43], v[152:155], v[204:207], v[40:43]
	v_mfma_f32_16x16x32_bf16 v[32:35], v[160:163], v[204:207], v[32:35]
	v_mfma_f32_16x16x32_bf16 v[24:27], v[152:155], v[212:215], v[24:27]
	v_mfma_f32_16x16x32_bf16 v[16:19], v[160:163], v[212:215], v[16:19]
	s_setprio 0
	s_setprio 1
	v_mfma_f32_16x16x32_bf16 v[44:47], v[164:167], v[180:183], v[44:47]
	v_mfma_f32_16x16x32_bf16 v[36:39], v[172:175], v[180:183], v[36:39]
	v_mfma_f32_16x16x32_bf16 v[28:31], v[164:167], v[188:191], v[28:31]
	v_mfma_f32_16x16x32_bf16 v[20:23], v[172:175], v[188:191], v[20:23]
	v_mfma_f32_16x16x32_bf16 v[12:15], v[164:167], v[200:203], v[12:15]
	v_mfma_f32_16x16x32_bf16 v[8:11], v[172:175], v[200:203], v[8:11]
	v_mfma_f32_16x16x32_bf16 v[4:7], v[164:167], v[208:211], v[4:7]
	v_mfma_f32_16x16x32_bf16 v[0:3], v[172:175], v[208:211], v[0:3]
	v_mfma_f32_16x16x32_bf16 v[44:47], v[168:171], v[184:187], v[44:47]
	v_mfma_f32_16x16x32_bf16 v[36:39], v[176:179], v[184:187], v[36:39]
	v_mfma_f32_16x16x32_bf16 v[28:31], v[168:171], v[196:199], v[28:31]
	v_mfma_f32_16x16x32_bf16 v[20:23], v[176:179], v[196:199], v[20:23]
	v_mfma_f32_16x16x32_bf16 v[12:15], v[168:171], v[204:207], v[12:15]
	v_mfma_f32_16x16x32_bf16 v[8:11], v[176:179], v[204:207], v[8:11]
	v_mfma_f32_16x16x32_bf16 v[4:7], v[168:171], v[212:215], v[4:7]
	v_mfma_f32_16x16x32_bf16 v[0:3], v[176:179], v[212:215], v[0:3]
	s_setprio 0
	s_barrier
	s_add_i32 s81, s81, 2
	s_add_u32 s17, s17, 0x100
	s_addc_u32 s27, s27, 0
	s_cmp_gt_u32 s81, 5
	s_mov_b64 s[36:37], s[38:39]
	s_cbranch_scc0 .LBB0_2370
	s_and_b64 vcc, exec, s[18:19]
	s_cbranch_vccz .LBB0_2373
	s_barrier

.LBB0_2396:
	ds_read_b128 v[144:147], v153
	ds_read_b128 v[158:161], v153 offset:1024
	ds_read_b128 v[162:165], v153 offset:2048
	ds_read_b128 v[166:169], v153 offset:3072
	ds_read_b128 v[170:173], v154
	ds_read_b128 v[174:177], v154 offset:1024
	ds_read_b128 v[178:181], v154 offset:2048
	ds_read_b128 v[182:185], v154 offset:3072
	s_add_u32 s36, s34, 0xfffc0080
	s_addc_u32 s37, s35, -1
	s_cmp_eq_u32 s78, 12
	s_cselect_b32 s39, s27, s37
	s_cselect_b32 s38, s71, s36
	s_cselect_b32 s37, s25, s77
	s_cselect_b32 s36, s72, s73
	v_lshl_add_u64 v[148:149], s[34:35], 0, v[136:137]
	s_add_i32 m0, s53, 0xc000
	ds_read_b128 v[186:189], v155
	ds_read_b128 v[190:193], v155 offset:1024
	ds_read_b128 v[196:199], v155 offset:2048
	ds_read_b128 v[200:203], v155 offset:3072
	ds_read_b128 v[204:207], v155 offset:4096
	ds_read_b128 v[208:211], v155 offset:5120
	ds_read_b128 v[212:215], v155 offset:6144
	ds_read_b128 v[216:219], v155 offset:7168
	global_load_lds_dwordx4 v[148:149], off
	v_lshl_add_u64 v[148:149], s[34:35], 0, v[138:139]
	s_add_i32 m0, s53, 0xe000
	s_nop 0
	global_load_lds_dwordx4 v[148:149], off
	s_waitcnt vmcnt(8)
	s_waitcnt lgkmcnt(0)
	s_barrier
	s_setprio 1
	s_waitcnt lgkmcnt(0)
	v_mfma_f32_16x16x32_bf16 v[124:127], v[144:147], v[186:189], v[124:127]
	v_mfma_f32_16x16x32_bf16 v[120:123], v[162:165], v[186:189], v[120:123]
	v_mfma_f32_16x16x32_bf16 v[108:111], v[144:147], v[196:199], v[108:111]
	v_mfma_f32_16x16x32_bf16 v[104:107], v[162:165], v[196:199], v[104:107]
	v_mfma_f32_16x16x32_bf16 v[92:95], v[144:147], v[204:207], v[92:95]
	v_mfma_f32_16x16x32_bf16 v[88:91], v[162:165], v[204:207], v[88:91]
	v_mfma_f32_16x16x32_bf16 v[76:79], v[144:147], v[212:215], v[76:79]
	v_mfma_f32_16x16x32_bf16 v[72:75], v[162:165], v[212:215], v[72:75]
	v_mfma_f32_16x16x32_bf16 v[124:127], v[158:161], v[190:193], v[124:127]
	v_mfma_f32_16x16x32_bf16 v[120:123], v[166:169], v[190:193], v[120:123]
	v_mfma_f32_16x16x32_bf16 v[108:111], v[158:161], v[200:203], v[108:111]
	v_mfma_f32_16x16x32_bf16 v[104:107], v[166:169], v[200:203], v[104:107]
	v_mfma_f32_16x16x32_bf16 v[92:95], v[158:161], v[208:211], v[92:95]
	v_mfma_f32_16x16x32_bf16 v[88:91], v[166:169], v[208:211], v[88:91]
	v_mfma_f32_16x16x32_bf16 v[76:79], v[158:161], v[216:219], v[76:79]
	v_mfma_f32_16x16x32_bf16 v[72:75], v[166:169], v[216:219], v[72:75]
	s_setprio 0
	s_setprio 1
	v_mfma_f32_16x16x32_bf16 v[116:119], v[170:173], v[186:189], v[116:119]
	v_mfma_f32_16x16x32_bf16 v[112:115], v[178:181], v[186:189], v[112:115]
	v_mfma_f32_16x16x32_bf16 v[100:103], v[170:173], v[196:199], v[100:103]
	v_mfma_f32_16x16x32_bf16 v[96:99], v[178:181], v[196:199], v[96:99]
	v_mfma_f32_16x16x32_bf16 v[84:87], v[170:173], v[204:207], v[84:87]
	v_mfma_f32_16x16x32_bf16 v[80:83], v[178:181], v[204:207], v[80:83]
	v_mfma_f32_16x16x32_bf16 v[68:71], v[170:173], v[212:215], v[68:71]
	v_mfma_f32_16x16x32_bf16 v[64:67], v[178:181], v[212:215], v[64:67]
	v_mfma_f32_16x16x32_bf16 v[116:119], v[174:177], v[190:193], v[116:119]
	v_mfma_f32_16x16x32_bf16 v[112:115], v[182:185], v[190:193], v[112:115]
	v_mfma_f32_16x16x32_bf16 v[100:103], v[174:177], v[200:203], v[100:103]
	v_mfma_f32_16x16x32_bf16 v[96:99], v[182:185], v[200:203], v[96:99]
	v_mfma_f32_16x16x32_bf16 v[84:87], v[174:177], v[208:211], v[84:87]
	v_mfma_f32_16x16x32_bf16 v[80:83], v[182:185], v[208:211], v[80:83]
	v_mfma_f32_16x16x32_bf16 v[68:71], v[174:177], v[216:219], v[68:71]
	v_mfma_f32_16x16x32_bf16 v[64:67], v[182:185], v[216:219], v[64:67]
	s_setprio 0
	s_barrier
	s_add_i32 s79, s61, s52
	v_lshl_add_u64 v[148:149], s[36:37], 0, v[130:131]
	s_mov_b32 m0, s79
	ds_read_b128 v[186:189], v155 offset:16384
	ds_read_b128 v[190:193], v155 offset:17408
	ds_read_b128 v[196:199], v155 offset:18432
	ds_read_b128 v[200:203], v155 offset:19456
	ds_read_b128 v[204:207], v155 offset:20480
	ds_read_b128 v[208:211], v155 offset:21504
	ds_read_b128 v[212:215], v155 offset:22528
	ds_read_b128 v[216:219], v155 offset:23552
	global_load_lds_dwordx4 v[148:149], off
	s_add_i32 m0, s79, 0x2000
	s_add_u32 s80, s36, 0x40000
	v_lshl_add_u64 v[220:221], s[36:37], 0, v[134:135]
	s_addc_u32 s81, s37, 0
	s_add_i32 s79, s62, s52
	global_load_lds_dwordx4 v[220:221], off
	v_lshl_add_u64 v[222:223], s[80:81], 0, v[130:131]
	s_mov_b32 m0, s79
	v_lshl_add_u64 v[224:225], s[38:39], 0, v[132:133]
	global_load_lds_dwordx4 v[222:223], off
	v_lshl_add_u64 v[222:223], s[80:81], 0, v[134:135]
	s_add_i32 m0, s79, 0x2000
	s_nop 0
	global_load_lds_dwordx4 v[222:223], off
	v_lshl_add_u64 v[222:223], s[38:39], 0, v[128:129]
	s_waitcnt vmcnt(6)
	s_waitcnt lgkmcnt(0)
	s_barrier
	s_setprio 1
	s_waitcnt lgkmcnt(0)
	v_mfma_f32_16x16x32_bf16 v[60:63], v[144:147], v[186:189], v[60:63]
	v_mfma_f32_16x16x32_bf16 v[56:59], v[162:165], v[186:189], v[56:59]
	v_mfma_f32_16x16x32_bf16 v[44:47], v[144:147], v[196:199], v[44:47]
	v_mfma_f32_16x16x32_bf16 v[40:43], v[162:165], v[196:199], v[40:43]
	v_mfma_f32_16x16x32_bf16 v[28:31], v[144:147], v[204:207], v[28:31]
	v_mfma_f32_16x16x32_bf16 v[24:27], v[162:165], v[204:207], v[24:27]
	v_mfma_f32_16x16x32_bf16 v[12:15], v[144:147], v[212:215], v[12:15]
	v_mfma_f32_16x16x32_bf16 v[8:11], v[162:165], v[212:215], v[8:11]
	v_mfma_f32_16x16x32_bf16 v[60:63], v[158:161], v[190:193], v[60:63]
	v_mfma_f32_16x16x32_bf16 v[56:59], v[166:169], v[190:193], v[56:59]
	v_mfma_f32_16x16x32_bf16 v[44:47], v[158:161], v[200:203], v[44:47]
	v_mfma_f32_16x16x32_bf16 v[40:43], v[166:169], v[200:203], v[40:43]
	v_mfma_f32_16x16x32_bf16 v[28:31], v[158:161], v[208:211], v[28:31]
	v_mfma_f32_16x16x32_bf16 v[24:27], v[166:169], v[208:211], v[24:27]
	v_mfma_f32_16x16x32_bf16 v[12:15], v[158:161], v[216:219], v[12:15]
	v_mfma_f32_16x16x32_bf16 v[8:11], v[166:169], v[216:219], v[8:11]
	s_setprio 0
	s_setprio 1
	v_mfma_f32_16x16x32_bf16 v[52:55], v[170:173], v[186:189], v[52:55]
	v_mfma_f32_16x16x32_bf16 v[48:51], v[178:181], v[186:189], v[48:51]
	v_mfma_f32_16x16x32_bf16 v[36:39], v[170:173], v[196:199], v[36:39]
	v_mfma_f32_16x16x32_bf16 v[32:35], v[178:181], v[196:199], v[32:35]
	v_mfma_f32_16x16x32_bf16 v[20:23], v[170:173], v[204:207], v[20:23]
	v_mfma_f32_16x16x32_bf16 v[16:19], v[178:181], v[204:207], v[16:19]
	v_mfma_f32_16x16x32_bf16 v[4:7], v[170:173], v[212:215], v[4:7]
	v_mfma_f32_16x16x32_bf16 v[0:3], v[178:181], v[212:215], v[0:3]
	v_mfma_f32_16x16x32_bf16 v[52:55], v[174:177], v[190:193], v[52:55]
	v_mfma_f32_16x16x32_bf16 v[48:51], v[182:185], v[190:193], v[48:51]
	v_mfma_f32_16x16x32_bf16 v[36:39], v[174:177], v[200:203], v[36:39]
	v_mfma_f32_16x16x32_bf16 v[32:35], v[182:185], v[200:203], v[32:35]
	v_mfma_f32_16x16x32_bf16 v[20:23], v[174:177], v[208:211], v[20:23]
	v_mfma_f32_16x16x32_bf16 v[16:19], v[182:185], v[208:211], v[16:19]
	v_mfma_f32_16x16x32_bf16 v[4:7], v[174:177], v[216:219], v[4:7]
	v_mfma_f32_16x16x32_bf16 v[0:3], v[182:185], v[216:219], v[0:3]
	s_setprio 0
	s_barrier
	s_add_i32 s79, 0, 0x18000
	v_add_u32_e32 v157, s79, v151
	s_add_i32 s80, 0, 0x1c000
	ds_read_b128 v[144:147], v157
	ds_read_b128 v[158:161], v157 offset:1024
	ds_read_b128 v[162:165], v157 offset:2048
	ds_read_b128 v[166:169], v157 offset:3072
	v_add_u32_e32 v157, s80, v151
	ds_read_b128 v[170:173], v157
	ds_read_b128 v[174:177], v157 offset:1024
	ds_read_b128 v[178:181], v157 offset:2048
	ds_read_b128 v[182:185], v157 offset:3072
	s_add_u32 s38, s38, 0x40000
	s_addc_u32 s39, s39, 0
	v_lshl_add_u64 v[226:227], s[38:39], 0, v[128:129]
	ds_read_b128 v[186:189], v155 offset:32768
	ds_read_b128 v[190:193], v155 offset:33792
	ds_read_b128 v[196:199], v155 offset:34816
	ds_read_b128 v[200:203], v155 offset:35840
	ds_read_b128 v[204:207], v155 offset:36864
	ds_read_b128 v[208:211], v155 offset:37888
	ds_read_b128 v[212:215], v155 offset:38912
	ds_read_b128 v[216:219], v155 offset:39936
	s_mov_b32 m0, s53
	s_nop 0
	global_load_lds_dwordx4 v[222:223], off
	s_mov_b32 m0, s54
	s_nop 0
	global_load_lds_dwordx4 v[224:225], off
	s_mov_b32 m0, s55
	s_nop 0
	global_load_lds_dwordx4 v[226:227], off
	v_lshl_add_u64 v[226:227], s[38:39], 0, v[132:133]
	s_mov_b32 m0, s56
	s_nop 0
	global_load_lds_dwordx4 v[226:227], off
	s_waitcnt vmcnt(8)
	s_waitcnt lgkmcnt(0)
	s_barrier
	s_setprio 1
	s_waitcnt lgkmcnt(0)
	v_mfma_f32_16x16x32_bf16 v[124:127], v[144:147], v[186:189], v[124:127]
	v_mfma_f32_16x16x32_bf16 v[120:123], v[162:165], v[186:189], v[120:123]
	v_mfma_f32_16x16x32_bf16 v[108:111], v[144:147], v[196:199], v[108:111]
	v_mfma_f32_16x16x32_bf16 v[104:107], v[162:165], v[196:199], v[104:107]
	v_mfma_f32_16x16x32_bf16 v[92:95], v[144:147], v[204:207], v[92:95]
	v_mfma_f32_16x16x32_bf16 v[88:91], v[162:165], v[204:207], v[88:91]
	v_mfma_f32_16x16x32_bf16 v[76:79], v[144:147], v[212:215], v[76:79]
	v_mfma_f32_16x16x32_bf16 v[72:75], v[162:165], v[212:215], v[72:75]
	v_mfma_f32_16x16x32_bf16 v[124:127], v[158:161], v[190:193], v[124:127]
	v_mfma_f32_16x16x32_bf16 v[120:123], v[166:169], v[190:193], v[120:123]
	v_mfma_f32_16x16x32_bf16 v[108:111], v[158:161], v[200:203], v[108:111]
	v_mfma_f32_16x16x32_bf16 v[104:107], v[166:169], v[200:203], v[104:107]
	v_mfma_f32_16x16x32_bf16 v[92:95], v[158:161], v[208:211], v[92:95]
	v_mfma_f32_16x16x32_bf16 v[88:91], v[166:169], v[208:211], v[88:91]
	v_mfma_f32_16x16x32_bf16 v[76:79], v[158:161], v[216:219], v[76:79]
	v_mfma_f32_16x16x32_bf16 v[72:75], v[166:169], v[216:219], v[72:75]
	s_setprio 0
	s_setprio 1
	v_mfma_f32_16x16x32_bf16 v[116:119], v[170:173], v[186:189], v[116:119]
	v_mfma_f32_16x16x32_bf16 v[112:115], v[178:181], v[186:189], v[112:115]
	v_mfma_f32_16x16x32_bf16 v[100:103], v[170:173], v[196:199], v[100:103]
	v_mfma_f32_16x16x32_bf16 v[96:99], v[178:181], v[196:199], v[96:99]
	v_mfma_f32_16x16x32_bf16 v[84:87], v[170:173], v[204:207], v[84:87]
	v_mfma_f32_16x16x32_bf16 v[80:83], v[178:181], v[204:207], v[80:83]
	v_mfma_f32_16x16x32_bf16 v[68:71], v[170:173], v[212:215], v[68:71]
	v_mfma_f32_16x16x32_bf16 v[64:67], v[178:181], v[212:215], v[64:67]
	v_mfma_f32_16x16x32_bf16 v[116:119], v[174:177], v[190:193], v[116:119]
	v_mfma_f32_16x16x32_bf16 v[112:115], v[182:185], v[190:193], v[112:115]
	v_mfma_f32_16x16x32_bf16 v[100:103], v[174:177], v[200:203], v[100:103]
	v_mfma_f32_16x16x32_bf16 v[96:99], v[182:185], v[200:203], v[96:99]
	v_mfma_f32_16x16x32_bf16 v[84:87], v[174:177], v[208:211], v[84:87]
	v_mfma_f32_16x16x32_bf16 v[80:83], v[182:185], v[208:211], v[80:83]
	v_mfma_f32_16x16x32_bf16 v[68:71], v[174:177], v[216:219], v[68:71]
	v_mfma_f32_16x16x32_bf16 v[64:67], v[182:185], v[216:219], v[64:67]
	s_setprio 0
	s_barrier
	s_add_i32 s38, s79, s52
	v_lshl_add_u64 v[148:149], v[148:149], 0, s[20:21]
	s_mov_b32 m0, s38
	ds_read_b128 v[186:189], v155 offset:49152
	ds_read_b128 v[190:193], v155 offset:50176
	ds_read_b128 v[196:199], v155 offset:51200
	ds_read_b128 v[200:203], v155 offset:52224
	ds_read_b128 v[204:207], v155 offset:53248
	ds_read_b128 v[208:211], v155 offset:54272
	ds_read_b128 v[212:215], v155 offset:55296
	ds_read_b128 v[216:219], v155 offset:56320
	global_load_lds_dwordx4 v[148:149], off
	s_add_i32 m0, s38, 0x2000
	s_add_u32 s36, s36, 0x40080
	v_lshl_add_u64 v[148:149], v[220:221], 0, s[20:21]
	s_addc_u32 s37, s37, 0
	s_add_i32 s38, s80, s52
	global_load_lds_dwordx4 v[148:149], off
	v_lshl_add_u64 v[148:149], s[36:37], 0, v[130:131]
	s_mov_b32 m0, s38
	s_nop 0
	global_load_lds_dwordx4 v[148:149], off
	v_lshl_add_u64 v[148:149], s[36:37], 0, v[134:135]
	s_add_i32 m0, s38, 0x2000
	s_nop 0
	global_load_lds_dwordx4 v[148:149], off
	v_lshl_add_u64 v[148:149], v[222:223], 0, s[20:21]
	s_mov_b32 m0, s58
	s_nop 0
	global_load_lds_dwordx4 v[148:149], off
	v_lshl_add_u64 v[148:149], v[224:225], 0, s[20:21]
	s_mov_b32 m0, s59
	s_nop 0
	global_load_lds_dwordx4 v[148:149], off
	s_waitcnt vmcnt(8)
	s_waitcnt lgkmcnt(0)
	s_barrier
	s_setprio 1
	s_waitcnt lgkmcnt(0)
	v_mfma_f32_16x16x32_bf16 v[60:63], v[144:147], v[186:189], v[60:63]
	v_mfma_f32_16x16x32_bf16 v[56:59], v[162:165], v[186:189], v[56:59]
	v_mfma_f32_16x16x32_bf16 v[44:47], v[144:147], v[196:199], v[44:47]
	v_mfma_f32_16x16x32_bf16 v[40:43], v[162:165], v[196:199], v[40:43]
	v_mfma_f32_16x16x32_bf16 v[28:31], v[144:147], v[204:207], v[28:31]
	v_mfma_f32_16x16x32_bf16 v[24:27], v[162:165], v[204:207], v[24:27]
	v_mfma_f32_16x16x32_bf16 v[12:15], v[144:147], v[212:215], v[12:15]
	v_mfma_f32_16x16x32_bf16 v[8:11], v[162:165], v[212:215], v[8:11]
	v_mfma_f32_16x16x32_bf16 v[60:63], v[158:161], v[190:193], v[60:63]
	v_mfma_f32_16x16x32_bf16 v[56:59], v[166:169], v[190:193], v[56:59]
	v_mfma_f32_16x16x32_bf16 v[44:47], v[158:161], v[200:203], v[44:47]
	v_mfma_f32_16x16x32_bf16 v[40:43], v[166:169], v[200:203], v[40:43]
	v_mfma_f32_16x16x32_bf16 v[28:31], v[158:161], v[208:211], v[28:31]
	v_mfma_f32_16x16x32_bf16 v[24:27], v[166:169], v[208:211], v[24:27]
	v_mfma_f32_16x16x32_bf16 v[12:15], v[158:161], v[216:219], v[12:15]
	v_mfma_f32_16x16x32_bf16 v[8:11], v[166:169], v[216:219], v[8:11]
	s_setprio 0
	s_setprio 1
	v_mfma_f32_16x16x32_bf16 v[52:55], v[170:173], v[186:189], v[52:55]
	v_mfma_f32_16x16x32_bf16 v[48:51], v[178:181], v[186:189], v[48:51]
	v_mfma_f32_16x16x32_bf16 v[36:39], v[170:173], v[196:199], v[36:39]
	v_mfma_f32_16x16x32_bf16 v[32:35], v[178:181], v[196:199], v[32:35]
	v_mfma_f32_16x16x32_bf16 v[20:23], v[170:173], v[204:207], v[20:23]
	v_mfma_f32_16x16x32_bf16 v[16:19], v[178:181], v[204:207], v[16:19]
	v_mfma_f32_16x16x32_bf16 v[4:7], v[170:173], v[212:215], v[4:7]
	v_mfma_f32_16x16x32_bf16 v[0:3], v[178:181], v[212:215], v[0:3]
	v_mfma_f32_16x16x32_bf16 v[52:55], v[174:177], v[190:193], v[52:55]
	v_mfma_f32_16x16x32_bf16 v[48:51], v[182:185], v[190:193], v[48:51]
	v_mfma_f32_16x16x32_bf16 v[36:39], v[174:177], v[200:203], v[36:39]
	v_mfma_f32_16x16x32_bf16 v[32:35], v[182:185], v[200:203], v[32:35]
	v_mfma_f32_16x16x32_bf16 v[20:23], v[174:177], v[208:211], v[20:23]
	v_mfma_f32_16x16x32_bf16 v[16:19], v[182:185], v[208:211], v[16:19]
	v_mfma_f32_16x16x32_bf16 v[4:7], v[174:177], v[216:219], v[4:7]
	v_mfma_f32_16x16x32_bf16 v[0:3], v[182:185], v[216:219], v[0:3]
	s_setprio 0
	s_barrier
	s_add_i32 s78, s78, 2
	s_add_u32 s34, s34, 0x100
	s_addc_u32 s35, s35, 0
	s_add_u32 s73, s73, 0x100
	s_addc_u32 s77, s77, 0
	s_cmp_gt_u32 s78, 13
	s_cbranch_scc0 .LBB0_2396
	s_and_b64 vcc, exec, s[22:23]
	s_cbranch_vccz .LBB0_2399
	s_barrier

.LBB0_2533:
	ds_read_b128 v[152:155], v148
	ds_read_b128 v[156:159], v148 offset:1024
	ds_read_b128 v[160:163], v148 offset:2048
	ds_read_b128 v[164:167], v148 offset:3072
	ds_read_b128 v[168:171], v149
	ds_read_b128 v[172:175], v149 offset:1024
	ds_read_b128 v[176:179], v149 offset:2048
	ds_read_b128 v[180:183], v149 offset:3072
	s_add_u32 s26, s24, 0x100
	s_addc_u32 s27, s25, 0
	s_cmp_eq_u32 s62, 8
	s_cselect_b32 s31, s21, s27
	s_cselect_b32 s30, s20, s26
	s_cselect_b32 s29, s23, s61
	s_cselect_b32 s28, s22, s60
	s_mov_b32 m0, s53
	v_lshl_add_u64 v[192:193], s[24:25], 0, v[138:139]
	ds_read_b128 v[184:187], v150
	ds_read_b128 v[188:191], v150 offset:1024
	ds_read_b128 v[196:199], v150 offset:2048
	ds_read_b128 v[200:203], v150 offset:3072
	ds_read_b128 v[204:207], v150 offset:4096
	ds_read_b128 v[208:211], v150 offset:5120
	ds_read_b128 v[212:215], v150 offset:6144
	ds_read_b128 v[216:219], v150 offset:7168
	global_load_lds_dwordx4 v[192:193], off
	v_lshl_add_u64 v[192:193], s[24:25], 0, v[140:141]
	s_add_i32 m0, s40, 0xe000
	s_nop 0
	global_load_lds_dwordx4 v[192:193], off
	s_waitcnt vmcnt(8)
	s_waitcnt lgkmcnt(0)
	s_barrier
	s_setprio 1
	s_waitcnt lgkmcnt(0)
	v_mfma_f32_16x16x32_bf16 v[124:127], v[152:155], v[184:187], v[124:127]
	v_mfma_f32_16x16x32_bf16 v[120:123], v[160:163], v[184:187], v[120:123]
	v_mfma_f32_16x16x32_bf16 v[108:111], v[152:155], v[196:199], v[108:111]
	v_mfma_f32_16x16x32_bf16 v[104:107], v[160:163], v[196:199], v[104:107]
	v_mfma_f32_16x16x32_bf16 v[92:95], v[152:155], v[204:207], v[92:95]
	v_mfma_f32_16x16x32_bf16 v[88:91], v[160:163], v[204:207], v[88:91]
	v_mfma_f32_16x16x32_bf16 v[76:79], v[152:155], v[212:215], v[76:79]
	v_mfma_f32_16x16x32_bf16 v[72:75], v[160:163], v[212:215], v[72:75]
	v_mfma_f32_16x16x32_bf16 v[124:127], v[156:159], v[188:191], v[124:127]
	v_mfma_f32_16x16x32_bf16 v[120:123], v[164:167], v[188:191], v[120:123]
	v_mfma_f32_16x16x32_bf16 v[108:111], v[156:159], v[200:203], v[108:111]
	v_mfma_f32_16x16x32_bf16 v[104:107], v[164:167], v[200:203], v[104:107]
	v_mfma_f32_16x16x32_bf16 v[92:95], v[156:159], v[208:211], v[92:95]
	v_mfma_f32_16x16x32_bf16 v[88:91], v[164:167], v[208:211], v[88:91]
	v_mfma_f32_16x16x32_bf16 v[76:79], v[156:159], v[216:219], v[76:79]
	v_mfma_f32_16x16x32_bf16 v[72:75], v[164:167], v[216:219], v[72:75]
	s_setprio 0
	s_setprio 1
	v_mfma_f32_16x16x32_bf16 v[116:119], v[168:171], v[184:187], v[116:119]
	v_mfma_f32_16x16x32_bf16 v[112:115], v[176:179], v[184:187], v[112:115]
	v_mfma_f32_16x16x32_bf16 v[100:103], v[168:171], v[196:199], v[100:103]
	v_mfma_f32_16x16x32_bf16 v[96:99], v[176:179], v[196:199], v[96:99]
	v_mfma_f32_16x16x32_bf16 v[84:87], v[168:171], v[204:207], v[84:87]
	v_mfma_f32_16x16x32_bf16 v[80:83], v[176:179], v[204:207], v[80:83]
	v_mfma_f32_16x16x32_bf16 v[68:71], v[168:171], v[212:215], v[68:71]
	v_mfma_f32_16x16x32_bf16 v[64:67], v[176:179], v[212:215], v[64:67]
	v_mfma_f32_16x16x32_bf16 v[116:119], v[172:175], v[188:191], v[116:119]
	v_mfma_f32_16x16x32_bf16 v[112:115], v[180:183], v[188:191], v[112:115]
	v_mfma_f32_16x16x32_bf16 v[100:103], v[172:175], v[200:203], v[100:103]
	v_mfma_f32_16x16x32_bf16 v[96:99], v[180:183], v[200:203], v[96:99]
	v_mfma_f32_16x16x32_bf16 v[84:87], v[172:175], v[208:211], v[84:87]
	v_mfma_f32_16x16x32_bf16 v[80:83], v[180:183], v[208:211], v[80:83]
	v_mfma_f32_16x16x32_bf16 v[68:71], v[172:175], v[216:219], v[68:71]
	v_mfma_f32_16x16x32_bf16 v[64:67], v[180:183], v[216:219], v[64:67]
	s_setprio 0
	s_barrier
	s_add_i32 s24, s51, s39
	v_lshl_add_u64 v[192:193], s[28:29], 0, v[132:133]
	s_mov_b32 m0, s24
	ds_read_b128 v[184:187], v150 offset:16384
	ds_read_b128 v[188:191], v150 offset:17408
	ds_read_b128 v[196:199], v150 offset:18432
	ds_read_b128 v[200:203], v150 offset:19456
	ds_read_b128 v[204:207], v150 offset:20480
	ds_read_b128 v[208:211], v150 offset:21504
	ds_read_b128 v[212:215], v150 offset:22528
	ds_read_b128 v[216:219], v150 offset:23552
	global_load_lds_dwordx4 v[192:193], off
	s_add_i32 m0, s24, 0x2000
	s_add_u32 s24, s28, 0x30000
	v_lshl_add_u64 v[220:221], s[28:29], 0, v[128:129]
	s_addc_u32 s25, s29, 0
	s_add_i32 s63, s52, s39
	global_load_lds_dwordx4 v[220:221], off
	v_lshl_add_u64 v[222:223], s[24:25], 0, v[132:133]
	s_mov_b32 m0, s63
	v_lshl_add_u64 v[224:225], s[30:31], 0, v[130:131]
	global_load_lds_dwordx4 v[222:223], off
	v_lshl_add_u64 v[222:223], s[24:25], 0, v[128:129]
	s_add_i32 m0, s63, 0x2000
	s_nop 0
	global_load_lds_dwordx4 v[222:223], off
	v_lshl_add_u64 v[222:223], s[30:31], 0, v[134:135]
	s_waitcnt vmcnt(6)
	s_waitcnt lgkmcnt(0)
	s_barrier
	s_setprio 1
	s_waitcnt lgkmcnt(0)
	v_mfma_f32_16x16x32_bf16 v[60:63], v[152:155], v[184:187], v[60:63]
	v_mfma_f32_16x16x32_bf16 v[56:59], v[160:163], v[184:187], v[56:59]
	v_mfma_f32_16x16x32_bf16 v[44:47], v[152:155], v[196:199], v[44:47]
	v_mfma_f32_16x16x32_bf16 v[40:43], v[160:163], v[196:199], v[40:43]
	v_mfma_f32_16x16x32_bf16 v[28:31], v[152:155], v[204:207], v[28:31]
	v_mfma_f32_16x16x32_bf16 v[24:27], v[160:163], v[204:207], v[24:27]
	v_mfma_f32_16x16x32_bf16 v[12:15], v[152:155], v[212:215], v[12:15]
	v_mfma_f32_16x16x32_bf16 v[8:11], v[160:163], v[212:215], v[8:11]
	v_mfma_f32_16x16x32_bf16 v[60:63], v[156:159], v[188:191], v[60:63]
	v_mfma_f32_16x16x32_bf16 v[56:59], v[164:167], v[188:191], v[56:59]
	v_mfma_f32_16x16x32_bf16 v[44:47], v[156:159], v[200:203], v[44:47]
	v_mfma_f32_16x16x32_bf16 v[40:43], v[164:167], v[200:203], v[40:43]
	v_mfma_f32_16x16x32_bf16 v[28:31], v[156:159], v[208:211], v[28:31]
	v_mfma_f32_16x16x32_bf16 v[24:27], v[164:167], v[208:211], v[24:27]
	v_mfma_f32_16x16x32_bf16 v[12:15], v[156:159], v[216:219], v[12:15]
	v_mfma_f32_16x16x32_bf16 v[8:11], v[164:167], v[216:219], v[8:11]
	s_setprio 0
	s_setprio 1
	v_mfma_f32_16x16x32_bf16 v[52:55], v[168:171], v[184:187], v[52:55]
	v_mfma_f32_16x16x32_bf16 v[48:51], v[176:179], v[184:187], v[48:51]
	v_mfma_f32_16x16x32_bf16 v[36:39], v[168:171], v[196:199], v[36:39]
	v_mfma_f32_16x16x32_bf16 v[32:35], v[176:179], v[196:199], v[32:35]
	v_mfma_f32_16x16x32_bf16 v[20:23], v[168:171], v[204:207], v[20:23]
	v_mfma_f32_16x16x32_bf16 v[16:19], v[176:179], v[204:207], v[16:19]
	v_mfma_f32_16x16x32_bf16 v[4:7], v[168:171], v[212:215], v[4:7]
	v_mfma_f32_16x16x32_bf16 v[0:3], v[176:179], v[212:215], v[0:3]
	v_mfma_f32_16x16x32_bf16 v[52:55], v[172:175], v[188:191], v[52:55]
	v_mfma_f32_16x16x32_bf16 v[48:51], v[180:183], v[188:191], v[48:51]
	v_mfma_f32_16x16x32_bf16 v[36:39], v[172:175], v[200:203], v[36:39]
	v_mfma_f32_16x16x32_bf16 v[32:35], v[180:183], v[200:203], v[32:35]
	v_mfma_f32_16x16x32_bf16 v[20:23], v[172:175], v[208:211], v[20:23]
	v_mfma_f32_16x16x32_bf16 v[16:19], v[180:183], v[208:211], v[16:19]
	v_mfma_f32_16x16x32_bf16 v[4:7], v[172:175], v[216:219], v[4:7]
	v_mfma_f32_16x16x32_bf16 v[0:3], v[180:183], v[216:219], v[0:3]
	s_setprio 0
	s_barrier
	s_add_i32 s63, 0, 0x18000
	v_add_u32_e32 v151, s63, v142
	s_add_i32 s70, 0, 0x1c000
	ds_read_b128 v[152:155], v151
	ds_read_b128 v[156:159], v151 offset:1024
	ds_read_b128 v[160:163], v151 offset:2048
	ds_read_b128 v[164:167], v151 offset:3072
	v_add_u32_e32 v151, s70, v142
	ds_read_b128 v[168:171], v151
	ds_read_b128 v[172:175], v151 offset:1024
	ds_read_b128 v[176:179], v151 offset:2048
	ds_read_b128 v[180:183], v151 offset:3072
	s_add_u32 s24, s30, 0x30000
	s_addc_u32 s25, s31, 0
	v_lshl_add_u64 v[226:227], s[24:25], 0, v[134:135]
	ds_read_b128 v[184:187], v150 offset:32768
	ds_read_b128 v[188:191], v150 offset:33792
	ds_read_b128 v[196:199], v150 offset:34816
	ds_read_b128 v[200:203], v150 offset:35840
	ds_read_b128 v[204:207], v150 offset:36864
	ds_read_b128 v[208:211], v150 offset:37888
	ds_read_b128 v[212:215], v150 offset:38912
	ds_read_b128 v[216:219], v150 offset:39936
	s_mov_b32 m0, s40
	s_nop 0
	global_load_lds_dwordx4 v[222:223], off
	s_mov_b32 m0, s41
	s_nop 0
	global_load_lds_dwordx4 v[224:225], off
	s_mov_b32 m0, s42
	s_nop 0
	global_load_lds_dwordx4 v[226:227], off
	v_lshl_add_u64 v[226:227], s[24:25], 0, v[130:131]
	s_mov_b32 m0, s43
	s_nop 0
	global_load_lds_dwordx4 v[226:227], off
	s_waitcnt vmcnt(8)
	s_waitcnt lgkmcnt(0)
	s_barrier
	s_setprio 1
	s_waitcnt lgkmcnt(0)
	v_mfma_f32_16x16x32_bf16 v[124:127], v[152:155], v[184:187], v[124:127]
	v_mfma_f32_16x16x32_bf16 v[120:123], v[160:163], v[184:187], v[120:123]
	v_mfma_f32_16x16x32_bf16 v[108:111], v[152:155], v[196:199], v[108:111]
	v_mfma_f32_16x16x32_bf16 v[104:107], v[160:163], v[196:199], v[104:107]
	v_mfma_f32_16x16x32_bf16 v[92:95], v[152:155], v[204:207], v[92:95]
	v_mfma_f32_16x16x32_bf16 v[88:91], v[160:163], v[204:207], v[88:91]
	v_mfma_f32_16x16x32_bf16 v[76:79], v[152:155], v[212:215], v[76:79]
	v_mfma_f32_16x16x32_bf16 v[72:75], v[160:163], v[212:215], v[72:75]
	v_mfma_f32_16x16x32_bf16 v[124:127], v[156:159], v[188:191], v[124:127]
	v_mfma_f32_16x16x32_bf16 v[120:123], v[164:167], v[188:191], v[120:123]
	v_mfma_f32_16x16x32_bf16 v[108:111], v[156:159], v[200:203], v[108:111]
	v_mfma_f32_16x16x32_bf16 v[104:107], v[164:167], v[200:203], v[104:107]
	v_mfma_f32_16x16x32_bf16 v[92:95], v[156:159], v[208:211], v[92:95]
	v_mfma_f32_16x16x32_bf16 v[88:91], v[164:167], v[208:211], v[88:91]
	v_mfma_f32_16x16x32_bf16 v[76:79], v[156:159], v[216:219], v[76:79]
	v_mfma_f32_16x16x32_bf16 v[72:75], v[164:167], v[216:219], v[72:75]
	s_setprio 0
	s_setprio 1
	v_mfma_f32_16x16x32_bf16 v[116:119], v[168:171], v[184:187], v[116:119]
	v_mfma_f32_16x16x32_bf16 v[112:115], v[176:179], v[184:187], v[112:115]
	v_mfma_f32_16x16x32_bf16 v[100:103], v[168:171], v[196:199], v[100:103]
	v_mfma_f32_16x16x32_bf16 v[96:99], v[176:179], v[196:199], v[96:99]
	v_mfma_f32_16x16x32_bf16 v[84:87], v[168:171], v[204:207], v[84:87]
	v_mfma_f32_16x16x32_bf16 v[80:83], v[176:179], v[204:207], v[80:83]
	v_mfma_f32_16x16x32_bf16 v[68:71], v[168:171], v[212:215], v[68:71]
	v_mfma_f32_16x16x32_bf16 v[64:67], v[176:179], v[212:215], v[64:67]
	v_mfma_f32_16x16x32_bf16 v[116:119], v[172:175], v[188:191], v[116:119]
	v_mfma_f32_16x16x32_bf16 v[112:115], v[180:183], v[188:191], v[112:115]
	v_mfma_f32_16x16x32_bf16 v[100:103], v[172:175], v[200:203], v[100:103]
	v_mfma_f32_16x16x32_bf16 v[96:99], v[180:183], v[200:203], v[96:99]
	v_mfma_f32_16x16x32_bf16 v[84:87], v[172:175], v[208:211], v[84:87]
	v_mfma_f32_16x16x32_bf16 v[80:83], v[180:183], v[208:211], v[80:83]
	v_mfma_f32_16x16x32_bf16 v[68:71], v[172:175], v[216:219], v[68:71]
	v_mfma_f32_16x16x32_bf16 v[64:67], v[180:183], v[216:219], v[64:67]
	s_setprio 0
	s_barrier
	s_add_i32 s24, s63, s39
	v_lshl_add_u64 v[192:193], v[192:193], 0, s[16:17]
	s_mov_b32 m0, s24
	ds_read_b128 v[184:187], v150 offset:49152
	ds_read_b128 v[188:191], v150 offset:50176
	ds_read_b128 v[196:199], v150 offset:51200
	ds_read_b128 v[200:203], v150 offset:52224
	ds_read_b128 v[204:207], v150 offset:53248
	ds_read_b128 v[208:211], v150 offset:54272
	ds_read_b128 v[212:215], v150 offset:55296
	ds_read_b128 v[216:219], v150 offset:56320
	global_load_lds_dwordx4 v[192:193], off
	s_add_i32 m0, s24, 0x2000
	s_add_u32 s24, s28, 0x30080
	v_lshl_add_u64 v[192:193], v[220:221], 0, s[16:17]
	s_addc_u32 s25, s29, 0
	s_add_i32 s28, s70, s39
	global_load_lds_dwordx4 v[192:193], off
	v_lshl_add_u64 v[192:193], s[24:25], 0, v[132:133]
	s_mov_b32 m0, s28
	s_nop 0
	global_load_lds_dwordx4 v[192:193], off
	v_lshl_add_u64 v[192:193], s[24:25], 0, v[128:129]
	s_add_i32 m0, s28, 0x2000
	s_nop 0
	global_load_lds_dwordx4 v[192:193], off
	v_lshl_add_u64 v[192:193], v[222:223], 0, s[16:17]
	s_mov_b32 m0, s45
	s_nop 0
	global_load_lds_dwordx4 v[192:193], off
	v_lshl_add_u64 v[192:193], v[224:225], 0, s[16:17]
	s_mov_b32 m0, s48
	s_nop 0
	global_load_lds_dwordx4 v[192:193], off
	s_waitcnt vmcnt(8)
	s_waitcnt lgkmcnt(0)
	s_barrier
	s_setprio 1
	s_waitcnt lgkmcnt(0)
	v_mfma_f32_16x16x32_bf16 v[60:63], v[152:155], v[184:187], v[60:63]
	v_mfma_f32_16x16x32_bf16 v[56:59], v[160:163], v[184:187], v[56:59]
	v_mfma_f32_16x16x32_bf16 v[44:47], v[152:155], v[196:199], v[44:47]
	v_mfma_f32_16x16x32_bf16 v[40:43], v[160:163], v[196:199], v[40:43]
	v_mfma_f32_16x16x32_bf16 v[28:31], v[152:155], v[204:207], v[28:31]
	v_mfma_f32_16x16x32_bf16 v[24:27], v[160:163], v[204:207], v[24:27]
	v_mfma_f32_16x16x32_bf16 v[12:15], v[152:155], v[212:215], v[12:15]
	v_mfma_f32_16x16x32_bf16 v[8:11], v[160:163], v[212:215], v[8:11]
	v_mfma_f32_16x16x32_bf16 v[60:63], v[156:159], v[188:191], v[60:63]
	v_mfma_f32_16x16x32_bf16 v[56:59], v[164:167], v[188:191], v[56:59]
	v_mfma_f32_16x16x32_bf16 v[44:47], v[156:159], v[200:203], v[44:47]
	v_mfma_f32_16x16x32_bf16 v[40:43], v[164:167], v[200:203], v[40:43]
	v_mfma_f32_16x16x32_bf16 v[28:31], v[156:159], v[208:211], v[28:31]
	v_mfma_f32_16x16x32_bf16 v[24:27], v[164:167], v[208:211], v[24:27]
	v_mfma_f32_16x16x32_bf16 v[12:15], v[156:159], v[216:219], v[12:15]
	v_mfma_f32_16x16x32_bf16 v[8:11], v[164:167], v[216:219], v[8:11]
	s_setprio 0
	s_setprio 1
	v_mfma_f32_16x16x32_bf16 v[52:55], v[168:171], v[184:187], v[52:55]
	v_mfma_f32_16x16x32_bf16 v[48:51], v[176:179], v[184:187], v[48:51]
	v_mfma_f32_16x16x32_bf16 v[36:39], v[168:171], v[196:199], v[36:39]
	v_mfma_f32_16x16x32_bf16 v[32:35], v[176:179], v[196:199], v[32:35]
	v_mfma_f32_16x16x32_bf16 v[20:23], v[168:171], v[204:207], v[20:23]
	v_mfma_f32_16x16x32_bf16 v[16:19], v[176:179], v[204:207], v[16:19]
	v_mfma_f32_16x16x32_bf16 v[4:7], v[168:171], v[212:215], v[4:7]
	v_mfma_f32_16x16x32_bf16 v[0:3], v[176:179], v[212:215], v[0:3]
	v_mfma_f32_16x16x32_bf16 v[52:55], v[172:175], v[188:191], v[52:55]
	v_mfma_f32_16x16x32_bf16 v[48:51], v[180:183], v[188:191], v[48:51]
	v_mfma_f32_16x16x32_bf16 v[36:39], v[172:175], v[200:203], v[36:39]
	v_mfma_f32_16x16x32_bf16 v[32:35], v[180:183], v[200:203], v[32:35]
	v_mfma_f32_16x16x32_bf16 v[20:23], v[172:175], v[208:211], v[20:23]
	v_mfma_f32_16x16x32_bf16 v[16:19], v[180:183], v[208:211], v[16:19]
	v_mfma_f32_16x16x32_bf16 v[4:7], v[172:175], v[216:219], v[4:7]
	v_mfma_f32_16x16x32_bf16 v[0:3], v[180:183], v[216:219], v[0:3]
	s_setprio 0
	s_barrier
	s_add_i32 s62, s62, 2
	s_add_u32 s60, s60, 0x100
	s_addc_u32 s61, s61, 0
	s_cmp_gt_u32 s62, 9
	s_mov_b64 s[24:25], s[26:27]
	s_cbranch_scc0 .LBB0_2533
	s_and_b64 vcc, exec, s[18:19]
	s_cbranch_vccz .LBB0_2536
	s_barrier

.LBB0_2557:
	ds_read_b128 v[144:147], v153
	ds_read_b128 v[158:161], v153 offset:1024
	ds_read_b128 v[162:165], v153 offset:2048
	ds_read_b128 v[166:169], v153 offset:3072
	ds_read_b128 v[170:173], v154
	ds_read_b128 v[174:177], v154 offset:1024
	ds_read_b128 v[178:181], v154 offset:2048
	ds_read_b128 v[182:185], v154 offset:3072
	s_add_u32 s36, s34, 0xfffc0080
	s_addc_u32 s37, s35, -1
	s_cmp_eq_u32 s73, 12
	s_cselect_b32 s39, s27, s37
	s_cselect_b32 s38, s63, s36
	s_cselect_b32 s37, s25, s72
	s_cselect_b32 s36, s70, s71
	v_lshl_add_u64 v[148:149], s[34:35], 0, v[136:137]
	s_add_i32 m0, s51, 0xc000
	ds_read_b128 v[186:189], v155
	ds_read_b128 v[190:193], v155 offset:1024
	ds_read_b128 v[196:199], v155 offset:2048
	ds_read_b128 v[200:203], v155 offset:3072
	ds_read_b128 v[204:207], v155 offset:4096
	ds_read_b128 v[208:211], v155 offset:5120
	ds_read_b128 v[212:215], v155 offset:6144
	ds_read_b128 v[216:219], v155 offset:7168
	global_load_lds_dwordx4 v[148:149], off
	v_lshl_add_u64 v[148:149], s[34:35], 0, v[138:139]
	s_add_i32 m0, s51, 0xe000
	s_nop 0
	global_load_lds_dwordx4 v[148:149], off
	s_waitcnt vmcnt(8)
	s_waitcnt lgkmcnt(0)
	s_barrier
	s_setprio 1
	s_waitcnt lgkmcnt(0)
	v_mfma_f32_16x16x32_bf16 v[124:127], v[144:147], v[186:189], v[124:127]
	v_mfma_f32_16x16x32_bf16 v[120:123], v[162:165], v[186:189], v[120:123]
	v_mfma_f32_16x16x32_bf16 v[108:111], v[144:147], v[196:199], v[108:111]
	v_mfma_f32_16x16x32_bf16 v[104:107], v[162:165], v[196:199], v[104:107]
	v_mfma_f32_16x16x32_bf16 v[92:95], v[144:147], v[204:207], v[92:95]
	v_mfma_f32_16x16x32_bf16 v[88:91], v[162:165], v[204:207], v[88:91]
	v_mfma_f32_16x16x32_bf16 v[76:79], v[144:147], v[212:215], v[76:79]
	v_mfma_f32_16x16x32_bf16 v[72:75], v[162:165], v[212:215], v[72:75]
	v_mfma_f32_16x16x32_bf16 v[124:127], v[158:161], v[190:193], v[124:127]
	v_mfma_f32_16x16x32_bf16 v[120:123], v[166:169], v[190:193], v[120:123]
	v_mfma_f32_16x16x32_bf16 v[108:111], v[158:161], v[200:203], v[108:111]
	v_mfma_f32_16x16x32_bf16 v[104:107], v[166:169], v[200:203], v[104:107]
	v_mfma_f32_16x16x32_bf16 v[92:95], v[158:161], v[208:211], v[92:95]
	v_mfma_f32_16x16x32_bf16 v[88:91], v[166:169], v[208:211], v[88:91]
	v_mfma_f32_16x16x32_bf16 v[76:79], v[158:161], v[216:219], v[76:79]
	v_mfma_f32_16x16x32_bf16 v[72:75], v[166:169], v[216:219], v[72:75]
	s_setprio 0
	s_setprio 1
	v_mfma_f32_16x16x32_bf16 v[116:119], v[170:173], v[186:189], v[116:119]
	v_mfma_f32_16x16x32_bf16 v[112:115], v[178:181], v[186:189], v[112:115]
	v_mfma_f32_16x16x32_bf16 v[100:103], v[170:173], v[196:199], v[100:103]
	v_mfma_f32_16x16x32_bf16 v[96:99], v[178:181], v[196:199], v[96:99]
	v_mfma_f32_16x16x32_bf16 v[84:87], v[170:173], v[204:207], v[84:87]
	v_mfma_f32_16x16x32_bf16 v[80:83], v[178:181], v[204:207], v[80:83]
	v_mfma_f32_16x16x32_bf16 v[68:71], v[170:173], v[212:215], v[68:71]
	v_mfma_f32_16x16x32_bf16 v[64:67], v[178:181], v[212:215], v[64:67]
	v_mfma_f32_16x16x32_bf16 v[116:119], v[174:177], v[190:193], v[116:119]
	v_mfma_f32_16x16x32_bf16 v[112:115], v[182:185], v[190:193], v[112:115]
	v_mfma_f32_16x16x32_bf16 v[100:103], v[174:177], v[200:203], v[100:103]
	v_mfma_f32_16x16x32_bf16 v[96:99], v[182:185], v[200:203], v[96:99]
	v_mfma_f32_16x16x32_bf16 v[84:87], v[174:177], v[208:211], v[84:87]
	v_mfma_f32_16x16x32_bf16 v[80:83], v[182:185], v[208:211], v[80:83]
	v_mfma_f32_16x16x32_bf16 v[68:71], v[174:177], v[216:219], v[68:71]
	v_mfma_f32_16x16x32_bf16 v[64:67], v[182:185], v[216:219], v[64:67]
	s_setprio 0
	s_barrier
	s_add_i32 s77, s59, s49
	v_lshl_add_u64 v[148:149], s[36:37], 0, v[130:131]
	s_mov_b32 m0, s77
	ds_read_b128 v[186:189], v155 offset:16384
	ds_read_b128 v[190:193], v155 offset:17408
	ds_read_b128 v[196:199], v155 offset:18432
	ds_read_b128 v[200:203], v155 offset:19456
	ds_read_b128 v[204:207], v155 offset:20480
	ds_read_b128 v[208:211], v155 offset:21504
	ds_read_b128 v[212:215], v155 offset:22528
	ds_read_b128 v[216:219], v155 offset:23552
	global_load_lds_dwordx4 v[148:149], off
	s_add_i32 m0, s77, 0x2000
	s_add_u32 s78, s36, 0x40000
	v_lshl_add_u64 v[220:221], s[36:37], 0, v[134:135]
	s_addc_u32 s79, s37, 0
	s_add_i32 s77, s60, s49
	global_load_lds_dwordx4 v[220:221], off
	v_lshl_add_u64 v[222:223], s[78:79], 0, v[130:131]
	s_mov_b32 m0, s77
	v_lshl_add_u64 v[224:225], s[38:39], 0, v[132:133]
	global_load_lds_dwordx4 v[222:223], off
	v_lshl_add_u64 v[222:223], s[78:79], 0, v[134:135]
	s_add_i32 m0, s77, 0x2000
	s_nop 0
	global_load_lds_dwordx4 v[222:223], off
	v_lshl_add_u64 v[222:223], s[38:39], 0, v[128:129]
	s_waitcnt vmcnt(6)
	s_waitcnt lgkmcnt(0)
	s_barrier
	s_setprio 1
	s_waitcnt lgkmcnt(0)
	v_mfma_f32_16x16x32_bf16 v[60:63], v[144:147], v[186:189], v[60:63]
	v_mfma_f32_16x16x32_bf16 v[56:59], v[162:165], v[186:189], v[56:59]
	v_mfma_f32_16x16x32_bf16 v[44:47], v[144:147], v[196:199], v[44:47]
	v_mfma_f32_16x16x32_bf16 v[40:43], v[162:165], v[196:199], v[40:43]
	v_mfma_f32_16x16x32_bf16 v[28:31], v[144:147], v[204:207], v[28:31]
	v_mfma_f32_16x16x32_bf16 v[24:27], v[162:165], v[204:207], v[24:27]
	v_mfma_f32_16x16x32_bf16 v[12:15], v[144:147], v[212:215], v[12:15]
	v_mfma_f32_16x16x32_bf16 v[8:11], v[162:165], v[212:215], v[8:11]
	v_mfma_f32_16x16x32_bf16 v[60:63], v[158:161], v[190:193], v[60:63]
	v_mfma_f32_16x16x32_bf16 v[56:59], v[166:169], v[190:193], v[56:59]
	v_mfma_f32_16x16x32_bf16 v[44:47], v[158:161], v[200:203], v[44:47]
	v_mfma_f32_16x16x32_bf16 v[40:43], v[166:169], v[200:203], v[40:43]
	v_mfma_f32_16x16x32_bf16 v[28:31], v[158:161], v[208:211], v[28:31]
	v_mfma_f32_16x16x32_bf16 v[24:27], v[166:169], v[208:211], v[24:27]
	v_mfma_f32_16x16x32_bf16 v[12:15], v[158:161], v[216:219], v[12:15]
	v_mfma_f32_16x16x32_bf16 v[8:11], v[166:169], v[216:219], v[8:11]
	s_setprio 0
	s_setprio 1
	v_mfma_f32_16x16x32_bf16 v[52:55], v[170:173], v[186:189], v[52:55]
	v_mfma_f32_16x16x32_bf16 v[48:51], v[178:181], v[186:189], v[48:51]
	v_mfma_f32_16x16x32_bf16 v[36:39], v[170:173], v[196:199], v[36:39]
	v_mfma_f32_16x16x32_bf16 v[32:35], v[178:181], v[196:199], v[32:35]
	v_mfma_f32_16x16x32_bf16 v[20:23], v[170:173], v[204:207], v[20:23]
	v_mfma_f32_16x16x32_bf16 v[16:19], v[178:181], v[204:207], v[16:19]
	v_mfma_f32_16x16x32_bf16 v[4:7], v[170:173], v[212:215], v[4:7]
	v_mfma_f32_16x16x32_bf16 v[0:3], v[178:181], v[212:215], v[0:3]
	v_mfma_f32_16x16x32_bf16 v[52:55], v[174:177], v[190:193], v[52:55]
	v_mfma_f32_16x16x32_bf16 v[48:51], v[182:185], v[190:193], v[48:51]
	v_mfma_f32_16x16x32_bf16 v[36:39], v[174:177], v[200:203], v[36:39]
	v_mfma_f32_16x16x32_bf16 v[32:35], v[182:185], v[200:203], v[32:35]
	v_mfma_f32_16x16x32_bf16 v[20:23], v[174:177], v[208:211], v[20:23]
	v_mfma_f32_16x16x32_bf16 v[16:19], v[182:185], v[208:211], v[16:19]
	v_mfma_f32_16x16x32_bf16 v[4:7], v[174:177], v[216:219], v[4:7]
	v_mfma_f32_16x16x32_bf16 v[0:3], v[182:185], v[216:219], v[0:3]
	s_setprio 0
	s_barrier
	s_add_i32 s77, 0, 0x18000
	v_add_u32_e32 v157, s77, v151
	s_add_i32 s78, 0, 0x1c000
	ds_read_b128 v[144:147], v157
	ds_read_b128 v[158:161], v157 offset:1024
	ds_read_b128 v[162:165], v157 offset:2048
	ds_read_b128 v[166:169], v157 offset:3072
	v_add_u32_e32 v157, s78, v151
	ds_read_b128 v[170:173], v157
	ds_read_b128 v[174:177], v157 offset:1024
	ds_read_b128 v[178:181], v157 offset:2048
	ds_read_b128 v[182:185], v157 offset:3072
	s_add_u32 s38, s38, 0x40000
	s_addc_u32 s39, s39, 0
	v_lshl_add_u64 v[226:227], s[38:39], 0, v[128:129]
	ds_read_b128 v[186:189], v155 offset:32768
	ds_read_b128 v[190:193], v155 offset:33792
	ds_read_b128 v[196:199], v155 offset:34816
	ds_read_b128 v[200:203], v155 offset:35840
	ds_read_b128 v[204:207], v155 offset:36864
	ds_read_b128 v[208:211], v155 offset:37888
	ds_read_b128 v[212:215], v155 offset:38912
	ds_read_b128 v[216:219], v155 offset:39936
	s_mov_b32 m0, s51
	s_nop 0
	global_load_lds_dwordx4 v[222:223], off
	s_mov_b32 m0, s52
	s_nop 0
	global_load_lds_dwordx4 v[224:225], off
	s_mov_b32 m0, s53
	s_nop 0
	global_load_lds_dwordx4 v[226:227], off
	v_lshl_add_u64 v[226:227], s[38:39], 0, v[132:133]
	s_mov_b32 m0, s54
	s_nop 0
	global_load_lds_dwordx4 v[226:227], off
	s_waitcnt vmcnt(8)
	s_waitcnt lgkmcnt(0)
	s_barrier
	s_setprio 1
	s_waitcnt lgkmcnt(0)
	v_mfma_f32_16x16x32_bf16 v[124:127], v[144:147], v[186:189], v[124:127]
	v_mfma_f32_16x16x32_bf16 v[120:123], v[162:165], v[186:189], v[120:123]
	v_mfma_f32_16x16x32_bf16 v[108:111], v[144:147], v[196:199], v[108:111]
	v_mfma_f32_16x16x32_bf16 v[104:107], v[162:165], v[196:199], v[104:107]
	v_mfma_f32_16x16x32_bf16 v[92:95], v[144:147], v[204:207], v[92:95]
	v_mfma_f32_16x16x32_bf16 v[88:91], v[162:165], v[204:207], v[88:91]
	v_mfma_f32_16x16x32_bf16 v[76:79], v[144:147], v[212:215], v[76:79]
	v_mfma_f32_16x16x32_bf16 v[72:75], v[162:165], v[212:215], v[72:75]
	v_mfma_f32_16x16x32_bf16 v[124:127], v[158:161], v[190:193], v[124:127]
	v_mfma_f32_16x16x32_bf16 v[120:123], v[166:169], v[190:193], v[120:123]
	v_mfma_f32_16x16x32_bf16 v[108:111], v[158:161], v[200:203], v[108:111]
	v_mfma_f32_16x16x32_bf16 v[104:107], v[166:169], v[200:203], v[104:107]
	v_mfma_f32_16x16x32_bf16 v[92:95], v[158:161], v[208:211], v[92:95]
	v_mfma_f32_16x16x32_bf16 v[88:91], v[166:169], v[208:211], v[88:91]
	v_mfma_f32_16x16x32_bf16 v[76:79], v[158:161], v[216:219], v[76:79]
	v_mfma_f32_16x16x32_bf16 v[72:75], v[166:169], v[216:219], v[72:75]
	s_setprio 0
	s_setprio 1
	v_mfma_f32_16x16x32_bf16 v[116:119], v[170:173], v[186:189], v[116:119]
	v_mfma_f32_16x16x32_bf16 v[112:115], v[178:181], v[186:189], v[112:115]
	v_mfma_f32_16x16x32_bf16 v[100:103], v[170:173], v[196:199], v[100:103]
	v_mfma_f32_16x16x32_bf16 v[96:99], v[178:181], v[196:199], v[96:99]
	v_mfma_f32_16x16x32_bf16 v[84:87], v[170:173], v[204:207], v[84:87]
	v_mfma_f32_16x16x32_bf16 v[80:83], v[178:181], v[204:207], v[80:83]
	v_mfma_f32_16x16x32_bf16 v[68:71], v[170:173], v[212:215], v[68:71]
	v_mfma_f32_16x16x32_bf16 v[64:67], v[178:181], v[212:215], v[64:67]
	v_mfma_f32_16x16x32_bf16 v[116:119], v[174:177], v[190:193], v[116:119]
	v_mfma_f32_16x16x32_bf16 v[112:115], v[182:185], v[190:193], v[112:115]
	v_mfma_f32_16x16x32_bf16 v[100:103], v[174:177], v[200:203], v[100:103]
	v_mfma_f32_16x16x32_bf16 v[96:99], v[182:185], v[200:203], v[96:99]
	v_mfma_f32_16x16x32_bf16 v[84:87], v[174:177], v[208:211], v[84:87]
	v_mfma_f32_16x16x32_bf16 v[80:83], v[182:185], v[208:211], v[80:83]
	v_mfma_f32_16x16x32_bf16 v[68:71], v[174:177], v[216:219], v[68:71]
	v_mfma_f32_16x16x32_bf16 v[64:67], v[182:185], v[216:219], v[64:67]
	s_setprio 0
	s_barrier
	s_add_i32 s38, s77, s49
	v_lshl_add_u64 v[148:149], v[148:149], 0, s[20:21]
	s_mov_b32 m0, s38
	ds_read_b128 v[186:189], v155 offset:49152
	ds_read_b128 v[190:193], v155 offset:50176
	ds_read_b128 v[196:199], v155 offset:51200
	ds_read_b128 v[200:203], v155 offset:52224
	ds_read_b128 v[204:207], v155 offset:53248
	ds_read_b128 v[208:211], v155 offset:54272
	ds_read_b128 v[212:215], v155 offset:55296
	ds_read_b128 v[216:219], v155 offset:56320
	global_load_lds_dwordx4 v[148:149], off
	s_add_i32 m0, s38, 0x2000
	s_add_u32 s36, s36, 0x40080
	v_lshl_add_u64 v[148:149], v[220:221], 0, s[20:21]
	s_addc_u32 s37, s37, 0
	s_add_i32 s38, s78, s49
	global_load_lds_dwordx4 v[148:149], off
	v_lshl_add_u64 v[148:149], s[36:37], 0, v[130:131]
	s_mov_b32 m0, s38
	s_nop 0
	global_load_lds_dwordx4 v[148:149], off
	v_lshl_add_u64 v[148:149], s[36:37], 0, v[134:135]
	s_add_i32 m0, s38, 0x2000
	s_nop 0
	global_load_lds_dwordx4 v[148:149], off
	v_lshl_add_u64 v[148:149], v[222:223], 0, s[20:21]
	s_mov_b32 m0, s56
	s_nop 0
	global_load_lds_dwordx4 v[148:149], off
	v_lshl_add_u64 v[148:149], v[224:225], 0, s[20:21]
	s_mov_b32 m0, s57
	s_nop 0
	global_load_lds_dwordx4 v[148:149], off
	s_waitcnt vmcnt(8)
	s_waitcnt lgkmcnt(0)
	s_barrier
	s_setprio 1
	s_waitcnt lgkmcnt(0)
	v_mfma_f32_16x16x32_bf16 v[60:63], v[144:147], v[186:189], v[60:63]
	v_mfma_f32_16x16x32_bf16 v[56:59], v[162:165], v[186:189], v[56:59]
	v_mfma_f32_16x16x32_bf16 v[44:47], v[144:147], v[196:199], v[44:47]
	v_mfma_f32_16x16x32_bf16 v[40:43], v[162:165], v[196:199], v[40:43]
	v_mfma_f32_16x16x32_bf16 v[28:31], v[144:147], v[204:207], v[28:31]
	v_mfma_f32_16x16x32_bf16 v[24:27], v[162:165], v[204:207], v[24:27]
	v_mfma_f32_16x16x32_bf16 v[12:15], v[144:147], v[212:215], v[12:15]
	v_mfma_f32_16x16x32_bf16 v[8:11], v[162:165], v[212:215], v[8:11]
	v_mfma_f32_16x16x32_bf16 v[60:63], v[158:161], v[190:193], v[60:63]
	v_mfma_f32_16x16x32_bf16 v[56:59], v[166:169], v[190:193], v[56:59]
	v_mfma_f32_16x16x32_bf16 v[44:47], v[158:161], v[200:203], v[44:47]
	v_mfma_f32_16x16x32_bf16 v[40:43], v[166:169], v[200:203], v[40:43]
	v_mfma_f32_16x16x32_bf16 v[28:31], v[158:161], v[208:211], v[28:31]
	v_mfma_f32_16x16x32_bf16 v[24:27], v[166:169], v[208:211], v[24:27]
	v_mfma_f32_16x16x32_bf16 v[12:15], v[158:161], v[216:219], v[12:15]
	v_mfma_f32_16x16x32_bf16 v[8:11], v[166:169], v[216:219], v[8:11]
	s_setprio 0
	s_setprio 1
	v_mfma_f32_16x16x32_bf16 v[52:55], v[170:173], v[186:189], v[52:55]
	v_mfma_f32_16x16x32_bf16 v[48:51], v[178:181], v[186:189], v[48:51]
	v_mfma_f32_16x16x32_bf16 v[36:39], v[170:173], v[196:199], v[36:39]
	v_mfma_f32_16x16x32_bf16 v[32:35], v[178:181], v[196:199], v[32:35]
	v_mfma_f32_16x16x32_bf16 v[20:23], v[170:173], v[204:207], v[20:23]
	v_mfma_f32_16x16x32_bf16 v[16:19], v[178:181], v[204:207], v[16:19]
	v_mfma_f32_16x16x32_bf16 v[4:7], v[170:173], v[212:215], v[4:7]
	v_mfma_f32_16x16x32_bf16 v[0:3], v[178:181], v[212:215], v[0:3]
	v_mfma_f32_16x16x32_bf16 v[52:55], v[174:177], v[190:193], v[52:55]
	v_mfma_f32_16x16x32_bf16 v[48:51], v[182:185], v[190:193], v[48:51]
	v_mfma_f32_16x16x32_bf16 v[36:39], v[174:177], v[200:203], v[36:39]
	v_mfma_f32_16x16x32_bf16 v[32:35], v[182:185], v[200:203], v[32:35]
	v_mfma_f32_16x16x32_bf16 v[20:23], v[174:177], v[208:211], v[20:23]
	v_mfma_f32_16x16x32_bf16 v[16:19], v[182:185], v[208:211], v[16:19]
	v_mfma_f32_16x16x32_bf16 v[4:7], v[174:177], v[216:219], v[4:7]
	v_mfma_f32_16x16x32_bf16 v[0:3], v[182:185], v[216:219], v[0:3]
	s_setprio 0
	s_barrier
	s_add_i32 s73, s73, 2
	s_add_u32 s34, s34, 0x100
	s_addc_u32 s35, s35, 0
	s_add_u32 s71, s71, 0x100
	s_addc_u32 s72, s72, 0
	s_cmp_gt_u32 s73, 13
	s_cbranch_scc0 .LBB0_2557
	s_and_b64 vcc, exec, s[22:23]
	s_cbranch_vccz .LBB0_2560
	s_barrier

.LBB0_2633:
	ds_read_b128 v[144:147], v153
	ds_read_b128 v[156:159], v153 offset:1024
	ds_read_b128 v[160:163], v153 offset:2048
	ds_read_b128 v[164:167], v153 offset:3072
	ds_read_b128 v[168:171], v154
	ds_read_b128 v[172:175], v154 offset:1024
	ds_read_b128 v[176:179], v154 offset:2048
	ds_read_b128 v[180:183], v154 offset:3072
	s_add_u32 s42, s40, 0xfffe0080
	s_addc_u32 s43, s41, -1
	s_cmp_eq_u32 s73, 4
	s_cselect_b32 s45, s31, s43
	s_cselect_b32 s44, s63, s42
	s_cselect_b32 s43, s29, s72
	s_cselect_b32 s42, s70, s71
	v_lshl_add_u64 v[148:149], s[40:41], 0, v[136:137]
	s_add_i32 m0, s39, 0xc000
	ds_read_b128 v[184:187], v155
	ds_read_b128 v[188:191], v155 offset:1024
	ds_read_b128 v[196:199], v155 offset:2048
	ds_read_b128 v[200:203], v155 offset:3072
	ds_read_b128 v[204:207], v155 offset:4096
	ds_read_b128 v[208:211], v155 offset:5120
	ds_read_b128 v[212:215], v155 offset:6144
	ds_read_b128 v[216:219], v155 offset:7168
	global_load_lds_dwordx4 v[148:149], off
	v_lshl_add_u64 v[148:149], s[40:41], 0, v[138:139]
	s_add_i32 m0, s39, 0xe000
	s_nop 0
	global_load_lds_dwordx4 v[148:149], off
	s_waitcnt vmcnt(8)
	s_waitcnt lgkmcnt(0)
	s_barrier
	s_setprio 1
	s_waitcnt lgkmcnt(0)
	v_mfma_f32_16x16x32_bf16 v[124:127], v[144:147], v[184:187], v[124:127]
	v_mfma_f32_16x16x32_bf16 v[120:123], v[160:163], v[184:187], v[120:123]
	v_mfma_f32_16x16x32_bf16 v[108:111], v[144:147], v[196:199], v[108:111]
	v_mfma_f32_16x16x32_bf16 v[104:107], v[160:163], v[196:199], v[104:107]
	v_mfma_f32_16x16x32_bf16 v[92:95], v[144:147], v[204:207], v[92:95]
	v_mfma_f32_16x16x32_bf16 v[88:91], v[160:163], v[204:207], v[88:91]
	v_mfma_f32_16x16x32_bf16 v[76:79], v[144:147], v[212:215], v[76:79]
	v_mfma_f32_16x16x32_bf16 v[72:75], v[160:163], v[212:215], v[72:75]
	v_mfma_f32_16x16x32_bf16 v[124:127], v[156:159], v[188:191], v[124:127]
	v_mfma_f32_16x16x32_bf16 v[120:123], v[164:167], v[188:191], v[120:123]
	v_mfma_f32_16x16x32_bf16 v[108:111], v[156:159], v[200:203], v[108:111]
	v_mfma_f32_16x16x32_bf16 v[104:107], v[164:167], v[200:203], v[104:107]
	v_mfma_f32_16x16x32_bf16 v[92:95], v[156:159], v[208:211], v[92:95]
	v_mfma_f32_16x16x32_bf16 v[88:91], v[164:167], v[208:211], v[88:91]
	v_mfma_f32_16x16x32_bf16 v[76:79], v[156:159], v[216:219], v[76:79]
	v_mfma_f32_16x16x32_bf16 v[72:75], v[164:167], v[216:219], v[72:75]
	s_setprio 0
	s_setprio 1
	v_mfma_f32_16x16x32_bf16 v[116:119], v[168:171], v[184:187], v[116:119]
	v_mfma_f32_16x16x32_bf16 v[112:115], v[176:179], v[184:187], v[112:115]
	v_mfma_f32_16x16x32_bf16 v[100:103], v[168:171], v[196:199], v[100:103]
	v_mfma_f32_16x16x32_bf16 v[96:99], v[176:179], v[196:199], v[96:99]
	v_mfma_f32_16x16x32_bf16 v[84:87], v[168:171], v[204:207], v[84:87]
	v_mfma_f32_16x16x32_bf16 v[80:83], v[176:179], v[204:207], v[80:83]
	v_mfma_f32_16x16x32_bf16 v[68:71], v[168:171], v[212:215], v[68:71]
	v_mfma_f32_16x16x32_bf16 v[64:67], v[176:179], v[212:215], v[64:67]
	v_mfma_f32_16x16x32_bf16 v[116:119], v[172:175], v[188:191], v[116:119]
	v_mfma_f32_16x16x32_bf16 v[112:115], v[180:183], v[188:191], v[112:115]
	v_mfma_f32_16x16x32_bf16 v[100:103], v[172:175], v[200:203], v[100:103]
	v_mfma_f32_16x16x32_bf16 v[96:99], v[180:183], v[200:203], v[96:99]
	v_mfma_f32_16x16x32_bf16 v[84:87], v[172:175], v[208:211], v[84:87]
	v_mfma_f32_16x16x32_bf16 v[80:83], v[180:183], v[208:211], v[80:83]
	v_mfma_f32_16x16x32_bf16 v[68:71], v[172:175], v[216:219], v[68:71]
	v_mfma_f32_16x16x32_bf16 v[64:67], v[180:183], v[216:219], v[64:67]
	s_setprio 0
	s_barrier
	s_add_i32 s77, s60, s52
	v_lshl_add_u64 v[148:149], s[42:43], 0, v[130:131]
	s_mov_b32 m0, s77
	ds_read_b128 v[184:187], v155 offset:16384
	ds_read_b128 v[188:191], v155 offset:17408
	ds_read_b128 v[196:199], v155 offset:18432
	ds_read_b128 v[200:203], v155 offset:19456
	ds_read_b128 v[204:207], v155 offset:20480
	ds_read_b128 v[208:211], v155 offset:21504
	ds_read_b128 v[212:215], v155 offset:22528
	ds_read_b128 v[216:219], v155 offset:23552
	global_load_lds_dwordx4 v[148:149], off
	s_add_i32 m0, s77, 0x2000
	s_add_u32 s78, s42, 0x20000
	v_lshl_add_u64 v[192:193], s[42:43], 0, v[134:135]
	s_addc_u32 s79, s43, 0
	s_add_i32 s77, s61, s52
	global_load_lds_dwordx4 v[192:193], off
	v_lshl_add_u64 v[220:221], s[78:79], 0, v[130:131]
	s_mov_b32 m0, s77
	v_lshl_add_u64 v[222:223], s[44:45], 0, v[132:133]
	global_load_lds_dwordx4 v[220:221], off
	v_lshl_add_u64 v[220:221], s[78:79], 0, v[134:135]
	s_add_i32 m0, s77, 0x2000
	s_nop 0
	global_load_lds_dwordx4 v[220:221], off
	v_lshl_add_u64 v[220:221], s[44:45], 0, v[128:129]
	s_waitcnt vmcnt(6)
	s_waitcnt lgkmcnt(0)
	s_barrier
	s_setprio 1
	s_waitcnt lgkmcnt(0)
	v_mfma_f32_16x16x32_bf16 v[60:63], v[144:147], v[184:187], v[60:63]
	v_mfma_f32_16x16x32_bf16 v[56:59], v[160:163], v[184:187], v[56:59]
	v_mfma_f32_16x16x32_bf16 v[44:47], v[144:147], v[196:199], v[44:47]
	v_mfma_f32_16x16x32_bf16 v[40:43], v[160:163], v[196:199], v[40:43]
	v_mfma_f32_16x16x32_bf16 v[28:31], v[144:147], v[204:207], v[28:31]
	v_mfma_f32_16x16x32_bf16 v[24:27], v[160:163], v[204:207], v[24:27]
	v_mfma_f32_16x16x32_bf16 v[12:15], v[144:147], v[212:215], v[12:15]
	v_mfma_f32_16x16x32_bf16 v[8:11], v[160:163], v[212:215], v[8:11]
	v_mfma_f32_16x16x32_bf16 v[60:63], v[156:159], v[188:191], v[60:63]
	v_mfma_f32_16x16x32_bf16 v[56:59], v[164:167], v[188:191], v[56:59]
	v_mfma_f32_16x16x32_bf16 v[44:47], v[156:159], v[200:203], v[44:47]
	v_mfma_f32_16x16x32_bf16 v[40:43], v[164:167], v[200:203], v[40:43]
	v_mfma_f32_16x16x32_bf16 v[28:31], v[156:159], v[208:211], v[28:31]
	v_mfma_f32_16x16x32_bf16 v[24:27], v[164:167], v[208:211], v[24:27]
	v_mfma_f32_16x16x32_bf16 v[12:15], v[156:159], v[216:219], v[12:15]
	v_mfma_f32_16x16x32_bf16 v[8:11], v[164:167], v[216:219], v[8:11]
	s_setprio 0
	s_setprio 1
	v_mfma_f32_16x16x32_bf16 v[52:55], v[168:171], v[184:187], v[52:55]
	v_mfma_f32_16x16x32_bf16 v[48:51], v[176:179], v[184:187], v[48:51]
	v_mfma_f32_16x16x32_bf16 v[36:39], v[168:171], v[196:199], v[36:39]
	v_mfma_f32_16x16x32_bf16 v[32:35], v[176:179], v[196:199], v[32:35]
	v_mfma_f32_16x16x32_bf16 v[20:23], v[168:171], v[204:207], v[20:23]
	v_mfma_f32_16x16x32_bf16 v[16:19], v[176:179], v[204:207], v[16:19]
	v_mfma_f32_16x16x32_bf16 v[4:7], v[168:171], v[212:215], v[4:7]
	v_mfma_f32_16x16x32_bf16 v[0:3], v[176:179], v[212:215], v[0:3]
	v_mfma_f32_16x16x32_bf16 v[52:55], v[172:175], v[188:191], v[52:55]
	v_mfma_f32_16x16x32_bf16 v[48:51], v[180:183], v[188:191], v[48:51]
	v_mfma_f32_16x16x32_bf16 v[36:39], v[172:175], v[200:203], v[36:39]
	v_mfma_f32_16x16x32_bf16 v[32:35], v[180:183], v[200:203], v[32:35]
	v_mfma_f32_16x16x32_bf16 v[20:23], v[172:175], v[208:211], v[20:23]
	v_mfma_f32_16x16x32_bf16 v[16:19], v[180:183], v[208:211], v[16:19]
	v_mfma_f32_16x16x32_bf16 v[4:7], v[172:175], v[216:219], v[4:7]
	v_mfma_f32_16x16x32_bf16 v[0:3], v[180:183], v[216:219], v[0:3]
	s_setprio 0
	s_barrier
	s_add_i32 s77, 0, 0x18000
	s_add_i32 s78, 0, 0x1c000
	v_add_u32_e32 v164, s77, v151
	v_add_u32_e32 v180, s78, v151
	ds_read_b128 v[144:147], v164
	ds_read_b128 v[156:159], v164 offset:1024
	ds_read_b128 v[160:163], v164 offset:2048
	ds_read_b128 v[164:167], v164 offset:3072
	ds_read_b128 v[168:171], v180
	ds_read_b128 v[172:175], v180 offset:1024
	ds_read_b128 v[176:179], v180 offset:2048
	ds_read_b128 v[180:183], v180 offset:3072
	s_add_u32 s44, s44, 0x20000
	s_addc_u32 s45, s45, 0
	v_lshl_add_u64 v[224:225], s[44:45], 0, v[128:129]
	ds_read_b128 v[184:187], v155 offset:32768
	ds_read_b128 v[188:191], v155 offset:33792
	ds_read_b128 v[196:199], v155 offset:34816
	ds_read_b128 v[200:203], v155 offset:35840
	ds_read_b128 v[204:207], v155 offset:36864
	ds_read_b128 v[208:211], v155 offset:37888
	ds_read_b128 v[212:215], v155 offset:38912
	ds_read_b128 v[216:219], v155 offset:39936
	s_mov_b32 m0, s39
	s_nop 0
	global_load_lds_dwordx4 v[220:221], off
	s_mov_b32 m0, s53
	s_nop 0
	global_load_lds_dwordx4 v[222:223], off
	s_mov_b32 m0, s54
	s_nop 0
	global_load_lds_dwordx4 v[224:225], off
	v_lshl_add_u64 v[224:225], s[44:45], 0, v[132:133]
	s_mov_b32 m0, s55
	s_nop 0
	global_load_lds_dwordx4 v[224:225], off
	s_waitcnt vmcnt(8)
	s_waitcnt lgkmcnt(0)
	s_barrier
	s_setprio 1
	s_waitcnt lgkmcnt(0)
	v_mfma_f32_16x16x32_bf16 v[124:127], v[144:147], v[184:187], v[124:127]
	v_mfma_f32_16x16x32_bf16 v[120:123], v[160:163], v[184:187], v[120:123]
	v_mfma_f32_16x16x32_bf16 v[108:111], v[144:147], v[196:199], v[108:111]
	v_mfma_f32_16x16x32_bf16 v[104:107], v[160:163], v[196:199], v[104:107]
	v_mfma_f32_16x16x32_bf16 v[92:95], v[144:147], v[204:207], v[92:95]
	v_mfma_f32_16x16x32_bf16 v[88:91], v[160:163], v[204:207], v[88:91]
	v_mfma_f32_16x16x32_bf16 v[76:79], v[144:147], v[212:215], v[76:79]
	v_mfma_f32_16x16x32_bf16 v[72:75], v[160:163], v[212:215], v[72:75]
	v_mfma_f32_16x16x32_bf16 v[124:127], v[156:159], v[188:191], v[124:127]
	v_mfma_f32_16x16x32_bf16 v[120:123], v[164:167], v[188:191], v[120:123]
	v_mfma_f32_16x16x32_bf16 v[108:111], v[156:159], v[200:203], v[108:111]
	v_mfma_f32_16x16x32_bf16 v[104:107], v[164:167], v[200:203], v[104:107]
	v_mfma_f32_16x16x32_bf16 v[92:95], v[156:159], v[208:211], v[92:95]
	v_mfma_f32_16x16x32_bf16 v[88:91], v[164:167], v[208:211], v[88:91]
	v_mfma_f32_16x16x32_bf16 v[76:79], v[156:159], v[216:219], v[76:79]
	v_mfma_f32_16x16x32_bf16 v[72:75], v[164:167], v[216:219], v[72:75]
	s_setprio 0
	s_setprio 1
	v_mfma_f32_16x16x32_bf16 v[116:119], v[168:171], v[184:187], v[116:119]
	v_mfma_f32_16x16x32_bf16 v[112:115], v[176:179], v[184:187], v[112:115]
	v_mfma_f32_16x16x32_bf16 v[100:103], v[168:171], v[196:199], v[100:103]
	v_mfma_f32_16x16x32_bf16 v[96:99], v[176:179], v[196:199], v[96:99]
	v_mfma_f32_16x16x32_bf16 v[84:87], v[168:171], v[204:207], v[84:87]
	v_mfma_f32_16x16x32_bf16 v[80:83], v[176:179], v[204:207], v[80:83]
	v_mfma_f32_16x16x32_bf16 v[68:71], v[168:171], v[212:215], v[68:71]
	v_mfma_f32_16x16x32_bf16 v[64:67], v[176:179], v[212:215], v[64:67]
	v_mfma_f32_16x16x32_bf16 v[116:119], v[172:175], v[188:191], v[116:119]
	v_mfma_f32_16x16x32_bf16 v[112:115], v[180:183], v[188:191], v[112:115]
	v_mfma_f32_16x16x32_bf16 v[100:103], v[172:175], v[200:203], v[100:103]
	v_mfma_f32_16x16x32_bf16 v[96:99], v[180:183], v[200:203], v[96:99]
	v_mfma_f32_16x16x32_bf16 v[84:87], v[172:175], v[208:211], v[84:87]
	v_mfma_f32_16x16x32_bf16 v[80:83], v[180:183], v[208:211], v[80:83]
	v_mfma_f32_16x16x32_bf16 v[68:71], v[172:175], v[216:219], v[68:71]
	v_mfma_f32_16x16x32_bf16 v[64:67], v[180:183], v[216:219], v[64:67]
	s_setprio 0
	s_barrier
	s_add_i32 s44, s77, s52
	v_lshl_add_u64 v[148:149], v[148:149], 0, s[18:19]
	s_mov_b32 m0, s44
	ds_read_b128 v[184:187], v155 offset:49152
	ds_read_b128 v[188:191], v155 offset:50176
	ds_read_b128 v[196:199], v155 offset:51200
	ds_read_b128 v[200:203], v155 offset:52224
	ds_read_b128 v[204:207], v155 offset:53248
	ds_read_b128 v[208:211], v155 offset:54272
	ds_read_b128 v[212:215], v155 offset:55296
	ds_read_b128 v[216:219], v155 offset:56320
	global_load_lds_dwordx4 v[148:149], off
	s_add_i32 m0, s44, 0x2000
	s_add_u32 s42, s42, 0x20080
	v_lshl_add_u64 v[148:149], v[192:193], 0, s[18:19]
	s_addc_u32 s43, s43, 0
	s_add_i32 s44, s78, s52
	global_load_lds_dwordx4 v[148:149], off
	v_lshl_add_u64 v[148:149], s[42:43], 0, v[130:131]
	s_mov_b32 m0, s44
	s_nop 0
	global_load_lds_dwordx4 v[148:149], off
	v_lshl_add_u64 v[148:149], s[42:43], 0, v[134:135]
	s_add_i32 m0, s44, 0x2000
	s_nop 0
	global_load_lds_dwordx4 v[148:149], off
	v_lshl_add_u64 v[148:149], v[220:221], 0, s[18:19]
	s_mov_b32 m0, s57
	s_nop 0
	global_load_lds_dwordx4 v[148:149], off
	v_lshl_add_u64 v[148:149], v[222:223], 0, s[18:19]
	s_mov_b32 m0, s58
	s_nop 0
	global_load_lds_dwordx4 v[148:149], off
	s_waitcnt vmcnt(8)
	s_waitcnt lgkmcnt(0)
	s_barrier
	s_setprio 1
	s_waitcnt lgkmcnt(0)
	v_mfma_f32_16x16x32_bf16 v[60:63], v[144:147], v[184:187], v[60:63]
	v_mfma_f32_16x16x32_bf16 v[56:59], v[160:163], v[184:187], v[56:59]
	v_mfma_f32_16x16x32_bf16 v[44:47], v[144:147], v[196:199], v[44:47]
	v_mfma_f32_16x16x32_bf16 v[40:43], v[160:163], v[196:199], v[40:43]
	v_mfma_f32_16x16x32_bf16 v[28:31], v[144:147], v[204:207], v[28:31]
	v_mfma_f32_16x16x32_bf16 v[24:27], v[160:163], v[204:207], v[24:27]
	v_mfma_f32_16x16x32_bf16 v[12:15], v[144:147], v[212:215], v[12:15]
	v_mfma_f32_16x16x32_bf16 v[8:11], v[160:163], v[212:215], v[8:11]
	v_mfma_f32_16x16x32_bf16 v[60:63], v[156:159], v[188:191], v[60:63]
	v_mfma_f32_16x16x32_bf16 v[56:59], v[164:167], v[188:191], v[56:59]
	v_mfma_f32_16x16x32_bf16 v[44:47], v[156:159], v[200:203], v[44:47]
	v_mfma_f32_16x16x32_bf16 v[40:43], v[164:167], v[200:203], v[40:43]
	v_mfma_f32_16x16x32_bf16 v[28:31], v[156:159], v[208:211], v[28:31]
	v_mfma_f32_16x16x32_bf16 v[24:27], v[164:167], v[208:211], v[24:27]
	v_mfma_f32_16x16x32_bf16 v[12:15], v[156:159], v[216:219], v[12:15]
	v_mfma_f32_16x16x32_bf16 v[8:11], v[164:167], v[216:219], v[8:11]
	s_setprio 0
	s_setprio 1
	v_mfma_f32_16x16x32_bf16 v[52:55], v[168:171], v[184:187], v[52:55]
	v_mfma_f32_16x16x32_bf16 v[48:51], v[176:179], v[184:187], v[48:51]
	v_mfma_f32_16x16x32_bf16 v[36:39], v[168:171], v[196:199], v[36:39]
	v_mfma_f32_16x16x32_bf16 v[32:35], v[176:179], v[196:199], v[32:35]
	v_mfma_f32_16x16x32_bf16 v[20:23], v[168:171], v[204:207], v[20:23]
	v_mfma_f32_16x16x32_bf16 v[16:19], v[176:179], v[204:207], v[16:19]
	v_mfma_f32_16x16x32_bf16 v[4:7], v[168:171], v[212:215], v[4:7]
	v_mfma_f32_16x16x32_bf16 v[0:3], v[176:179], v[212:215], v[0:3]
	v_mfma_f32_16x16x32_bf16 v[52:55], v[172:175], v[188:191], v[52:55]
	v_mfma_f32_16x16x32_bf16 v[48:51], v[180:183], v[188:191], v[48:51]
	v_mfma_f32_16x16x32_bf16 v[36:39], v[172:175], v[200:203], v[36:39]
	v_mfma_f32_16x16x32_bf16 v[32:35], v[180:183], v[200:203], v[32:35]
	v_mfma_f32_16x16x32_bf16 v[20:23], v[172:175], v[208:211], v[20:23]
	v_mfma_f32_16x16x32_bf16 v[16:19], v[180:183], v[208:211], v[16:19]
	v_mfma_f32_16x16x32_bf16 v[4:7], v[172:175], v[216:219], v[4:7]
	v_mfma_f32_16x16x32_bf16 v[0:3], v[180:183], v[216:219], v[0:3]
	s_setprio 0
	s_barrier
	s_add_i32 s73, s73, 2
	s_add_u32 s40, s40, 0x100
	s_addc_u32 s41, s41, 0
	s_add_u32 s71, s71, 0x100
	s_addc_u32 s72, s72, 0
	s_cmp_gt_u32 s73, 5
	s_cbranch_scc0 .LBB0_2633
	s_and_b64 vcc, exec, s[20:21]
	s_cbranch_vccz .LBB0_2636
	s_barrier

.LBB0_2657:
	ds_read_b128 v[144:147], v153
	ds_read_b128 v[158:161], v153 offset:1024
	ds_read_b128 v[162:165], v153 offset:2048
	ds_read_b128 v[166:169], v153 offset:3072
	ds_read_b128 v[170:173], v154
	ds_read_b128 v[174:177], v154 offset:1024
	ds_read_b128 v[178:181], v154 offset:2048
	ds_read_b128 v[182:185], v154 offset:3072
	s_add_u32 s34, s30, 0xfffc0080
	s_addc_u32 s35, s31, -1
	s_cmp_eq_u32 s70, 12
	s_cselect_b32 s37, s25, s35
	s_cselect_b32 s36, s60, s34
	s_cselect_b32 s35, s23, s63
	s_cselect_b32 s34, s61, s62
	v_lshl_add_u64 v[148:149], s[30:31], 0, v[136:137]
	s_add_i32 m0, s48, 0xc000
	ds_read_b128 v[186:189], v155
	ds_read_b128 v[190:193], v155 offset:1024
	ds_read_b128 v[196:199], v155 offset:2048
	ds_read_b128 v[200:203], v155 offset:3072
	ds_read_b128 v[204:207], v155 offset:4096
	ds_read_b128 v[208:211], v155 offset:5120
	ds_read_b128 v[212:215], v155 offset:6144
	ds_read_b128 v[216:219], v155 offset:7168
	global_load_lds_dwordx4 v[148:149], off
	v_lshl_add_u64 v[148:149], s[30:31], 0, v[138:139]
	s_add_i32 m0, s48, 0xe000
	s_nop 0
	global_load_lds_dwordx4 v[148:149], off
	s_waitcnt vmcnt(8)
	s_waitcnt lgkmcnt(0)
	s_barrier
	s_setprio 1
	s_waitcnt lgkmcnt(0)
	v_mfma_f32_16x16x32_bf16 v[124:127], v[144:147], v[186:189], v[124:127]
	v_mfma_f32_16x16x32_bf16 v[120:123], v[162:165], v[186:189], v[120:123]
	v_mfma_f32_16x16x32_bf16 v[108:111], v[144:147], v[196:199], v[108:111]
	v_mfma_f32_16x16x32_bf16 v[104:107], v[162:165], v[196:199], v[104:107]
	v_mfma_f32_16x16x32_bf16 v[92:95], v[144:147], v[204:207], v[92:95]
	v_mfma_f32_16x16x32_bf16 v[88:91], v[162:165], v[204:207], v[88:91]
	v_mfma_f32_16x16x32_bf16 v[76:79], v[144:147], v[212:215], v[76:79]
	v_mfma_f32_16x16x32_bf16 v[72:75], v[162:165], v[212:215], v[72:75]
	v_mfma_f32_16x16x32_bf16 v[124:127], v[158:161], v[190:193], v[124:127]
	v_mfma_f32_16x16x32_bf16 v[120:123], v[166:169], v[190:193], v[120:123]
	v_mfma_f32_16x16x32_bf16 v[108:111], v[158:161], v[200:203], v[108:111]
	v_mfma_f32_16x16x32_bf16 v[104:107], v[166:169], v[200:203], v[104:107]
	v_mfma_f32_16x16x32_bf16 v[92:95], v[158:161], v[208:211], v[92:95]
	v_mfma_f32_16x16x32_bf16 v[88:91], v[166:169], v[208:211], v[88:91]
	v_mfma_f32_16x16x32_bf16 v[76:79], v[158:161], v[216:219], v[76:79]
	v_mfma_f32_16x16x32_bf16 v[72:75], v[166:169], v[216:219], v[72:75]
	s_setprio 0
	s_setprio 1
	v_mfma_f32_16x16x32_bf16 v[116:119], v[170:173], v[186:189], v[116:119]
	v_mfma_f32_16x16x32_bf16 v[112:115], v[178:181], v[186:189], v[112:115]
	v_mfma_f32_16x16x32_bf16 v[100:103], v[170:173], v[196:199], v[100:103]
	v_mfma_f32_16x16x32_bf16 v[96:99], v[178:181], v[196:199], v[96:99]
	v_mfma_f32_16x16x32_bf16 v[84:87], v[170:173], v[204:207], v[84:87]
	v_mfma_f32_16x16x32_bf16 v[80:83], v[178:181], v[204:207], v[80:83]
	v_mfma_f32_16x16x32_bf16 v[68:71], v[170:173], v[212:215], v[68:71]
	v_mfma_f32_16x16x32_bf16 v[64:67], v[178:181], v[212:215], v[64:67]
	v_mfma_f32_16x16x32_bf16 v[116:119], v[174:177], v[190:193], v[116:119]
	v_mfma_f32_16x16x32_bf16 v[112:115], v[182:185], v[190:193], v[112:115]
	v_mfma_f32_16x16x32_bf16 v[100:103], v[174:177], v[200:203], v[100:103]
	v_mfma_f32_16x16x32_bf16 v[96:99], v[182:185], v[200:203], v[96:99]
	v_mfma_f32_16x16x32_bf16 v[84:87], v[174:177], v[208:211], v[84:87]
	v_mfma_f32_16x16x32_bf16 v[80:83], v[182:185], v[208:211], v[80:83]
	v_mfma_f32_16x16x32_bf16 v[68:71], v[174:177], v[216:219], v[68:71]
	v_mfma_f32_16x16x32_bf16 v[64:67], v[182:185], v[216:219], v[64:67]
	s_setprio 0
	s_barrier
	s_add_i32 s71, s56, s45
	v_lshl_add_u64 v[148:149], s[34:35], 0, v[130:131]
	s_mov_b32 m0, s71
	ds_read_b128 v[186:189], v155 offset:16384
	ds_read_b128 v[190:193], v155 offset:17408
	ds_read_b128 v[196:199], v155 offset:18432
	ds_read_b128 v[200:203], v155 offset:19456
	ds_read_b128 v[204:207], v155 offset:20480
	ds_read_b128 v[208:211], v155 offset:21504
	ds_read_b128 v[212:215], v155 offset:22528
	ds_read_b128 v[216:219], v155 offset:23552
	global_load_lds_dwordx4 v[148:149], off
	s_add_i32 m0, s71, 0x2000
	s_add_u32 s72, s34, 0x40000
	v_lshl_add_u64 v[220:221], s[34:35], 0, v[134:135]
	s_addc_u32 s73, s35, 0
	s_add_i32 s71, s57, s45
	global_load_lds_dwordx4 v[220:221], off
	v_lshl_add_u64 v[222:223], s[72:73], 0, v[130:131]
	s_mov_b32 m0, s71
	v_lshl_add_u64 v[224:225], s[36:37], 0, v[132:133]
	global_load_lds_dwordx4 v[222:223], off
	v_lshl_add_u64 v[222:223], s[72:73], 0, v[134:135]
	s_add_i32 m0, s71, 0x2000
	s_nop 0
	global_load_lds_dwordx4 v[222:223], off
	v_lshl_add_u64 v[222:223], s[36:37], 0, v[128:129]
	s_waitcnt vmcnt(6)
	s_waitcnt lgkmcnt(0)
	s_barrier
	s_setprio 1
	s_waitcnt lgkmcnt(0)
	v_mfma_f32_16x16x32_bf16 v[60:63], v[144:147], v[186:189], v[60:63]
	v_mfma_f32_16x16x32_bf16 v[56:59], v[162:165], v[186:189], v[56:59]
	v_mfma_f32_16x16x32_bf16 v[44:47], v[144:147], v[196:199], v[44:47]
	v_mfma_f32_16x16x32_bf16 v[40:43], v[162:165], v[196:199], v[40:43]
	v_mfma_f32_16x16x32_bf16 v[28:31], v[144:147], v[204:207], v[28:31]
	v_mfma_f32_16x16x32_bf16 v[24:27], v[162:165], v[204:207], v[24:27]
	v_mfma_f32_16x16x32_bf16 v[12:15], v[144:147], v[212:215], v[12:15]
	v_mfma_f32_16x16x32_bf16 v[8:11], v[162:165], v[212:215], v[8:11]
	v_mfma_f32_16x16x32_bf16 v[60:63], v[158:161], v[190:193], v[60:63]
	v_mfma_f32_16x16x32_bf16 v[56:59], v[166:169], v[190:193], v[56:59]
	v_mfma_f32_16x16x32_bf16 v[44:47], v[158:161], v[200:203], v[44:47]
	v_mfma_f32_16x16x32_bf16 v[40:43], v[166:169], v[200:203], v[40:43]
	v_mfma_f32_16x16x32_bf16 v[28:31], v[158:161], v[208:211], v[28:31]
	v_mfma_f32_16x16x32_bf16 v[24:27], v[166:169], v[208:211], v[24:27]
	v_mfma_f32_16x16x32_bf16 v[12:15], v[158:161], v[216:219], v[12:15]
	v_mfma_f32_16x16x32_bf16 v[8:11], v[166:169], v[216:219], v[8:11]
	s_setprio 0
	s_setprio 1
	v_mfma_f32_16x16x32_bf16 v[52:55], v[170:173], v[186:189], v[52:55]
	v_mfma_f32_16x16x32_bf16 v[48:51], v[178:181], v[186:189], v[48:51]
	v_mfma_f32_16x16x32_bf16 v[36:39], v[170:173], v[196:199], v[36:39]
	v_mfma_f32_16x16x32_bf16 v[32:35], v[178:181], v[196:199], v[32:35]
	v_mfma_f32_16x16x32_bf16 v[20:23], v[170:173], v[204:207], v[20:23]
	v_mfma_f32_16x16x32_bf16 v[16:19], v[178:181], v[204:207], v[16:19]
	v_mfma_f32_16x16x32_bf16 v[4:7], v[170:173], v[212:215], v[4:7]
	v_mfma_f32_16x16x32_bf16 v[0:3], v[178:181], v[212:215], v[0:3]
	v_mfma_f32_16x16x32_bf16 v[52:55], v[174:177], v[190:193], v[52:55]
	v_mfma_f32_16x16x32_bf16 v[48:51], v[182:185], v[190:193], v[48:51]
	v_mfma_f32_16x16x32_bf16 v[36:39], v[174:177], v[200:203], v[36:39]
	v_mfma_f32_16x16x32_bf16 v[32:35], v[182:185], v[200:203], v[32:35]
	v_mfma_f32_16x16x32_bf16 v[20:23], v[174:177], v[208:211], v[20:23]
	v_mfma_f32_16x16x32_bf16 v[16:19], v[182:185], v[208:211], v[16:19]
	v_mfma_f32_16x16x32_bf16 v[4:7], v[174:177], v[216:219], v[4:7]
	v_mfma_f32_16x16x32_bf16 v[0:3], v[182:185], v[216:219], v[0:3]
	s_setprio 0
	s_barrier
	s_add_i32 s71, 0, 0x18000
	v_add_u32_e32 v157, s71, v151
	s_add_i32 s72, 0, 0x1c000
	ds_read_b128 v[144:147], v157
	ds_read_b128 v[158:161], v157 offset:1024
	ds_read_b128 v[162:165], v157 offset:2048
	ds_read_b128 v[166:169], v157 offset:3072
	v_add_u32_e32 v157, s72, v151
	ds_read_b128 v[170:173], v157
	ds_read_b128 v[174:177], v157 offset:1024
	ds_read_b128 v[178:181], v157 offset:2048
	ds_read_b128 v[182:185], v157 offset:3072
	s_add_u32 s36, s36, 0x40000
	s_addc_u32 s37, s37, 0
	v_lshl_add_u64 v[226:227], s[36:37], 0, v[128:129]
	ds_read_b128 v[186:189], v155 offset:32768
	ds_read_b128 v[190:193], v155 offset:33792
	ds_read_b128 v[196:199], v155 offset:34816
	ds_read_b128 v[200:203], v155 offset:35840
	ds_read_b128 v[204:207], v155 offset:36864
	ds_read_b128 v[208:211], v155 offset:37888
	ds_read_b128 v[212:215], v155 offset:38912
	ds_read_b128 v[216:219], v155 offset:39936
	s_mov_b32 m0, s48
	s_nop 0
	global_load_lds_dwordx4 v[222:223], off
	s_mov_b32 m0, s49
	s_nop 0
	global_load_lds_dwordx4 v[224:225], off
	s_mov_b32 m0, s50
	s_nop 0
	global_load_lds_dwordx4 v[226:227], off
	v_lshl_add_u64 v[226:227], s[36:37], 0, v[132:133]
	s_mov_b32 m0, s51
	s_nop 0
	global_load_lds_dwordx4 v[226:227], off
	s_waitcnt vmcnt(8)
	s_waitcnt lgkmcnt(0)
	s_barrier
	s_setprio 1
	s_waitcnt lgkmcnt(0)
	v_mfma_f32_16x16x32_bf16 v[124:127], v[144:147], v[186:189], v[124:127]
	v_mfma_f32_16x16x32_bf16 v[120:123], v[162:165], v[186:189], v[120:123]
	v_mfma_f32_16x16x32_bf16 v[108:111], v[144:147], v[196:199], v[108:111]
	v_mfma_f32_16x16x32_bf16 v[104:107], v[162:165], v[196:199], v[104:107]
	v_mfma_f32_16x16x32_bf16 v[92:95], v[144:147], v[204:207], v[92:95]
	v_mfma_f32_16x16x32_bf16 v[88:91], v[162:165], v[204:207], v[88:91]
	v_mfma_f32_16x16x32_bf16 v[76:79], v[144:147], v[212:215], v[76:79]
	v_mfma_f32_16x16x32_bf16 v[72:75], v[162:165], v[212:215], v[72:75]
	v_mfma_f32_16x16x32_bf16 v[124:127], v[158:161], v[190:193], v[124:127]
	v_mfma_f32_16x16x32_bf16 v[120:123], v[166:169], v[190:193], v[120:123]
	v_mfma_f32_16x16x32_bf16 v[108:111], v[158:161], v[200:203], v[108:111]
	v_mfma_f32_16x16x32_bf16 v[104:107], v[166:169], v[200:203], v[104:107]
	v_mfma_f32_16x16x32_bf16 v[92:95], v[158:161], v[208:211], v[92:95]
	v_mfma_f32_16x16x32_bf16 v[88:91], v[166:169], v[208:211], v[88:91]
	v_mfma_f32_16x16x32_bf16 v[76:79], v[158:161], v[216:219], v[76:79]
	v_mfma_f32_16x16x32_bf16 v[72:75], v[166:169], v[216:219], v[72:75]
	s_setprio 0
	s_setprio 1
	v_mfma_f32_16x16x32_bf16 v[116:119], v[170:173], v[186:189], v[116:119]
	v_mfma_f32_16x16x32_bf16 v[112:115], v[178:181], v[186:189], v[112:115]
	v_mfma_f32_16x16x32_bf16 v[100:103], v[170:173], v[196:199], v[100:103]
	v_mfma_f32_16x16x32_bf16 v[96:99], v[178:181], v[196:199], v[96:99]
	v_mfma_f32_16x16x32_bf16 v[84:87], v[170:173], v[204:207], v[84:87]
	v_mfma_f32_16x16x32_bf16 v[80:83], v[178:181], v[204:207], v[80:83]
	v_mfma_f32_16x16x32_bf16 v[68:71], v[170:173], v[212:215], v[68:71]
	v_mfma_f32_16x16x32_bf16 v[64:67], v[178:181], v[212:215], v[64:67]
	v_mfma_f32_16x16x32_bf16 v[116:119], v[174:177], v[190:193], v[116:119]
	v_mfma_f32_16x16x32_bf16 v[112:115], v[182:185], v[190:193], v[112:115]
	v_mfma_f32_16x16x32_bf16 v[100:103], v[174:177], v[200:203], v[100:103]
	v_mfma_f32_16x16x32_bf16 v[96:99], v[182:185], v[200:203], v[96:99]
	v_mfma_f32_16x16x32_bf16 v[84:87], v[174:177], v[208:211], v[84:87]
	v_mfma_f32_16x16x32_bf16 v[80:83], v[182:185], v[208:211], v[80:83]
	v_mfma_f32_16x16x32_bf16 v[68:71], v[174:177], v[216:219], v[68:71]
	v_mfma_f32_16x16x32_bf16 v[64:67], v[182:185], v[216:219], v[64:67]
	s_setprio 0
	s_barrier
	s_add_i32 s36, s71, s45
	v_lshl_add_u64 v[148:149], v[148:149], 0, s[18:19]
	s_mov_b32 m0, s36
	ds_read_b128 v[186:189], v155 offset:49152
	ds_read_b128 v[190:193], v155 offset:50176
	ds_read_b128 v[196:199], v155 offset:51200
	ds_read_b128 v[200:203], v155 offset:52224
	ds_read_b128 v[204:207], v155 offset:53248
	ds_read_b128 v[208:211], v155 offset:54272
	ds_read_b128 v[212:215], v155 offset:55296
	ds_read_b128 v[216:219], v155 offset:56320
	global_load_lds_dwordx4 v[148:149], off
	s_add_i32 m0, s36, 0x2000
	s_add_u32 s34, s34, 0x40080
	v_lshl_add_u64 v[148:149], v[220:221], 0, s[18:19]
	s_addc_u32 s35, s35, 0
	s_add_i32 s36, s72, s45
	global_load_lds_dwordx4 v[148:149], off
	v_lshl_add_u64 v[148:149], s[34:35], 0, v[130:131]
	s_mov_b32 m0, s36
	s_nop 0
	global_load_lds_dwordx4 v[148:149], off
	v_lshl_add_u64 v[148:149], s[34:35], 0, v[134:135]
	s_add_i32 m0, s36, 0x2000
	s_nop 0
	global_load_lds_dwordx4 v[148:149], off
	v_lshl_add_u64 v[148:149], v[222:223], 0, s[18:19]
	s_mov_b32 m0, s53
	s_nop 0
	global_load_lds_dwordx4 v[148:149], off
	v_lshl_add_u64 v[148:149], v[224:225], 0, s[18:19]
	s_mov_b32 m0, s54
	s_nop 0
	global_load_lds_dwordx4 v[148:149], off
	s_waitcnt vmcnt(8)
	s_waitcnt lgkmcnt(0)
	s_barrier
	s_setprio 1
	s_waitcnt lgkmcnt(0)
	v_mfma_f32_16x16x32_bf16 v[60:63], v[144:147], v[186:189], v[60:63]
	v_mfma_f32_16x16x32_bf16 v[56:59], v[162:165], v[186:189], v[56:59]
	v_mfma_f32_16x16x32_bf16 v[44:47], v[144:147], v[196:199], v[44:47]
	v_mfma_f32_16x16x32_bf16 v[40:43], v[162:165], v[196:199], v[40:43]
	v_mfma_f32_16x16x32_bf16 v[28:31], v[144:147], v[204:207], v[28:31]
	v_mfma_f32_16x16x32_bf16 v[24:27], v[162:165], v[204:207], v[24:27]
	v_mfma_f32_16x16x32_bf16 v[12:15], v[144:147], v[212:215], v[12:15]
	v_mfma_f32_16x16x32_bf16 v[8:11], v[162:165], v[212:215], v[8:11]
	v_mfma_f32_16x16x32_bf16 v[60:63], v[158:161], v[190:193], v[60:63]
	v_mfma_f32_16x16x32_bf16 v[56:59], v[166:169], v[190:193], v[56:59]
	v_mfma_f32_16x16x32_bf16 v[44:47], v[158:161], v[200:203], v[44:47]
	v_mfma_f32_16x16x32_bf16 v[40:43], v[166:169], v[200:203], v[40:43]
	v_mfma_f32_16x16x32_bf16 v[28:31], v[158:161], v[208:211], v[28:31]
	v_mfma_f32_16x16x32_bf16 v[24:27], v[166:169], v[208:211], v[24:27]
	v_mfma_f32_16x16x32_bf16 v[12:15], v[158:161], v[216:219], v[12:15]
	v_mfma_f32_16x16x32_bf16 v[8:11], v[166:169], v[216:219], v[8:11]
	s_setprio 0
	s_setprio 1
	v_mfma_f32_16x16x32_bf16 v[52:55], v[170:173], v[186:189], v[52:55]
	v_mfma_f32_16x16x32_bf16 v[48:51], v[178:181], v[186:189], v[48:51]
	v_mfma_f32_16x16x32_bf16 v[36:39], v[170:173], v[196:199], v[36:39]
	v_mfma_f32_16x16x32_bf16 v[32:35], v[178:181], v[196:199], v[32:35]
	v_mfma_f32_16x16x32_bf16 v[20:23], v[170:173], v[204:207], v[20:23]
	v_mfma_f32_16x16x32_bf16 v[16:19], v[178:181], v[204:207], v[16:19]
	v_mfma_f32_16x16x32_bf16 v[4:7], v[170:173], v[212:215], v[4:7]
	v_mfma_f32_16x16x32_bf16 v[0:3], v[178:181], v[212:215], v[0:3]
	v_mfma_f32_16x16x32_bf16 v[52:55], v[174:177], v[190:193], v[52:55]
	v_mfma_f32_16x16x32_bf16 v[48:51], v[182:185], v[190:193], v[48:51]
	v_mfma_f32_16x16x32_bf16 v[36:39], v[174:177], v[200:203], v[36:39]
	v_mfma_f32_16x16x32_bf16 v[32:35], v[182:185], v[200:203], v[32:35]
	v_mfma_f32_16x16x32_bf16 v[20:23], v[174:177], v[208:211], v[20:23]
	v_mfma_f32_16x16x32_bf16 v[16:19], v[182:185], v[208:211], v[16:19]
	v_mfma_f32_16x16x32_bf16 v[4:7], v[174:177], v[216:219], v[4:7]
	v_mfma_f32_16x16x32_bf16 v[0:3], v[182:185], v[216:219], v[0:3]
	s_setprio 0
	s_barrier
	s_add_i32 s70, s70, 2
	s_add_u32 s30, s30, 0x100
	s_addc_u32 s31, s31, 0
	s_add_u32 s62, s62, 0x100
	s_addc_u32 s63, s63, 0
	s_cmp_gt_u32 s70, 13
	s_cbranch_scc0 .LBB0_2657
	s_and_b64 vcc, exec, s[20:21]
	s_cbranch_vccz .LBB0_2660
	s_barrier

.LBB0_3031:
	ds_read_b128 v[146:149], v155
	ds_read_b128 v[160:163], v155 offset:1024
	ds_read_b128 v[164:167], v155 offset:2048
	ds_read_b128 v[168:171], v155 offset:3072
	ds_read_b128 v[172:175], v156
	ds_read_b128 v[176:179], v156 offset:1024
	ds_read_b128 v[180:183], v156 offset:2048
	ds_read_b128 v[184:187], v156 offset:3072
	s_add_u32 s36, s0, 0xfffc0080
	s_addc_u32 s37, s1, -1
	s_cmp_eq_u32 s60, 12
	s_cselect_b32 s39, s21, s37
	s_cselect_b32 s38, s23, s36
	s_cselect_b32 s37, s27, s59
	s_cselect_b32 s36, s26, s25
	v_lshl_add_u64 v[150:151], s[0:1], 0, v[138:139]
	s_add_i32 m0, s35, 0xc000
	ds_read_b128 v[188:191], v157
	ds_read_b128 v[196:199], v157 offset:1024
	ds_read_b128 v[200:203], v157 offset:2048
	ds_read_b128 v[204:207], v157 offset:3072
	ds_read_b128 v[208:211], v157 offset:4096
	ds_read_b128 v[212:215], v157 offset:5120
	ds_read_b128 v[216:219], v157 offset:6144
	ds_read_b128 v[220:223], v157 offset:7168
	global_load_lds_dwordx4 v[150:151], off
	v_lshl_add_u64 v[150:151], s[0:1], 0, v[140:141]
	s_add_i32 m0, s35, 0xe000
	s_nop 0
	global_load_lds_dwordx4 v[150:151], off
	s_waitcnt vmcnt(8)
	s_waitcnt lgkmcnt(0)
	s_barrier
	s_setprio 1
	s_waitcnt lgkmcnt(0)
	v_mfma_f32_16x16x32_bf16 v[124:127], v[146:149], v[188:191], v[124:127]
	v_mfma_f32_16x16x32_bf16 v[120:123], v[164:167], v[188:191], v[120:123]
	v_mfma_f32_16x16x32_bf16 v[108:111], v[146:149], v[200:203], v[108:111]
	v_mfma_f32_16x16x32_bf16 v[104:107], v[164:167], v[200:203], v[104:107]
	v_mfma_f32_16x16x32_bf16 v[92:95], v[146:149], v[208:211], v[92:95]
	v_mfma_f32_16x16x32_bf16 v[88:91], v[164:167], v[208:211], v[88:91]
	v_mfma_f32_16x16x32_bf16 v[76:79], v[146:149], v[216:219], v[76:79]
	v_mfma_f32_16x16x32_bf16 v[72:75], v[164:167], v[216:219], v[72:75]
	v_mfma_f32_16x16x32_bf16 v[124:127], v[160:163], v[196:199], v[124:127]
	v_mfma_f32_16x16x32_bf16 v[120:123], v[168:171], v[196:199], v[120:123]
	v_mfma_f32_16x16x32_bf16 v[108:111], v[160:163], v[204:207], v[108:111]
	v_mfma_f32_16x16x32_bf16 v[104:107], v[168:171], v[204:207], v[104:107]
	v_mfma_f32_16x16x32_bf16 v[92:95], v[160:163], v[212:215], v[92:95]
	v_mfma_f32_16x16x32_bf16 v[88:91], v[168:171], v[212:215], v[88:91]
	v_mfma_f32_16x16x32_bf16 v[76:79], v[160:163], v[220:223], v[76:79]
	v_mfma_f32_16x16x32_bf16 v[72:75], v[168:171], v[220:223], v[72:75]
	s_setprio 0
	s_setprio 1
	v_mfma_f32_16x16x32_bf16 v[116:119], v[172:175], v[188:191], v[116:119]
	v_mfma_f32_16x16x32_bf16 v[112:115], v[180:183], v[188:191], v[112:115]
	v_mfma_f32_16x16x32_bf16 v[100:103], v[172:175], v[200:203], v[100:103]
	v_mfma_f32_16x16x32_bf16 v[96:99], v[180:183], v[200:203], v[96:99]
	v_mfma_f32_16x16x32_bf16 v[84:87], v[172:175], v[208:211], v[84:87]
	v_mfma_f32_16x16x32_bf16 v[80:83], v[180:183], v[208:211], v[80:83]
	v_mfma_f32_16x16x32_bf16 v[68:71], v[172:175], v[216:219], v[68:71]
	v_mfma_f32_16x16x32_bf16 v[64:67], v[180:183], v[216:219], v[64:67]
	v_mfma_f32_16x16x32_bf16 v[116:119], v[176:179], v[196:199], v[116:119]
	v_mfma_f32_16x16x32_bf16 v[112:115], v[184:187], v[196:199], v[112:115]
	v_mfma_f32_16x16x32_bf16 v[100:103], v[176:179], v[204:207], v[100:103]
	v_mfma_f32_16x16x32_bf16 v[96:99], v[184:187], v[204:207], v[96:99]
	v_mfma_f32_16x16x32_bf16 v[84:87], v[176:179], v[212:215], v[84:87]
	v_mfma_f32_16x16x32_bf16 v[80:83], v[184:187], v[212:215], v[80:83]
	v_mfma_f32_16x16x32_bf16 v[68:71], v[176:179], v[220:223], v[68:71]
	v_mfma_f32_16x16x32_bf16 v[64:67], v[184:187], v[220:223], v[64:67]
	s_setprio 0
	s_barrier
	s_add_i32 s61, s55, s44
	v_lshl_add_u64 v[150:151], s[36:37], 0, v[130:131]
	s_mov_b32 m0, s61
	ds_read_b128 v[188:191], v157 offset:16384
	ds_read_b128 v[196:199], v157 offset:17408
	ds_read_b128 v[200:203], v157 offset:18432
	ds_read_b128 v[204:207], v157 offset:19456
	ds_read_b128 v[208:211], v157 offset:20480
	ds_read_b128 v[212:215], v157 offset:21504
	ds_read_b128 v[216:219], v157 offset:22528
	ds_read_b128 v[220:223], v157 offset:23552
	global_load_lds_dwordx4 v[150:151], off
	s_add_i32 m0, s61, 0x2000
	s_add_u32 s62, s36, 0x40000
	v_lshl_add_u64 v[192:193], s[36:37], 0, v[134:135]
	s_addc_u32 s63, s37, 0
	s_add_i32 s61, s56, s44
	global_load_lds_dwordx4 v[192:193], off
	v_lshl_add_u64 v[224:225], s[62:63], 0, v[130:131]
	s_mov_b32 m0, s61
	v_lshl_add_u64 v[226:227], s[38:39], 0, v[132:133]
	global_load_lds_dwordx4 v[224:225], off
	v_lshl_add_u64 v[224:225], s[62:63], 0, v[134:135]
	s_add_i32 m0, s61, 0x2000
	s_nop 0
	global_load_lds_dwordx4 v[224:225], off
	v_lshl_add_u64 v[224:225], s[38:39], 0, v[128:129]
	s_waitcnt vmcnt(6)
	s_waitcnt lgkmcnt(0)
	s_barrier
	s_setprio 1
	s_waitcnt lgkmcnt(0)
	v_mfma_f32_16x16x32_bf16 v[60:63], v[146:149], v[188:191], v[60:63]
	v_mfma_f32_16x16x32_bf16 v[56:59], v[164:167], v[188:191], v[56:59]
	v_mfma_f32_16x16x32_bf16 v[44:47], v[146:149], v[200:203], v[44:47]
	v_mfma_f32_16x16x32_bf16 v[40:43], v[164:167], v[200:203], v[40:43]
	v_mfma_f32_16x16x32_bf16 v[28:31], v[146:149], v[208:211], v[28:31]
	v_mfma_f32_16x16x32_bf16 v[24:27], v[164:167], v[208:211], v[24:27]
	v_mfma_f32_16x16x32_bf16 v[12:15], v[146:149], v[216:219], v[12:15]
	v_mfma_f32_16x16x32_bf16 v[8:11], v[164:167], v[216:219], v[8:11]
	v_mfma_f32_16x16x32_bf16 v[60:63], v[160:163], v[196:199], v[60:63]
	v_mfma_f32_16x16x32_bf16 v[56:59], v[168:171], v[196:199], v[56:59]
	v_mfma_f32_16x16x32_bf16 v[44:47], v[160:163], v[204:207], v[44:47]
	v_mfma_f32_16x16x32_bf16 v[40:43], v[168:171], v[204:207], v[40:43]
	v_mfma_f32_16x16x32_bf16 v[28:31], v[160:163], v[212:215], v[28:31]
	v_mfma_f32_16x16x32_bf16 v[24:27], v[168:171], v[212:215], v[24:27]
	v_mfma_f32_16x16x32_bf16 v[12:15], v[160:163], v[220:223], v[12:15]
	v_mfma_f32_16x16x32_bf16 v[8:11], v[168:171], v[220:223], v[8:11]
	s_setprio 0
	s_setprio 1
	v_mfma_f32_16x16x32_bf16 v[52:55], v[172:175], v[188:191], v[52:55]
	v_mfma_f32_16x16x32_bf16 v[48:51], v[180:183], v[188:191], v[48:51]
	v_mfma_f32_16x16x32_bf16 v[36:39], v[172:175], v[200:203], v[36:39]
	v_mfma_f32_16x16x32_bf16 v[32:35], v[180:183], v[200:203], v[32:35]
	v_mfma_f32_16x16x32_bf16 v[20:23], v[172:175], v[208:211], v[20:23]
	v_mfma_f32_16x16x32_bf16 v[16:19], v[180:183], v[208:211], v[16:19]
	v_mfma_f32_16x16x32_bf16 v[4:7], v[172:175], v[216:219], v[4:7]
	v_mfma_f32_16x16x32_bf16 v[0:3], v[180:183], v[216:219], v[0:3]
	v_mfma_f32_16x16x32_bf16 v[52:55], v[176:179], v[196:199], v[52:55]
	v_mfma_f32_16x16x32_bf16 v[48:51], v[184:187], v[196:199], v[48:51]
	v_mfma_f32_16x16x32_bf16 v[36:39], v[176:179], v[204:207], v[36:39]
	v_mfma_f32_16x16x32_bf16 v[32:35], v[184:187], v[204:207], v[32:35]
	v_mfma_f32_16x16x32_bf16 v[20:23], v[176:179], v[212:215], v[20:23]
	v_mfma_f32_16x16x32_bf16 v[16:19], v[184:187], v[212:215], v[16:19]
	v_mfma_f32_16x16x32_bf16 v[4:7], v[176:179], v[220:223], v[4:7]
	v_mfma_f32_16x16x32_bf16 v[0:3], v[184:187], v[220:223], v[0:3]
	s_setprio 0
	s_barrier
	s_add_i32 s61, 0, 0x18000
	v_add_u32_e32 v159, s61, v153
	s_add_i32 s62, 0, 0x1c000
	ds_read_b128 v[146:149], v159
	ds_read_b128 v[160:163], v159 offset:1024
	ds_read_b128 v[164:167], v159 offset:2048
	ds_read_b128 v[168:171], v159 offset:3072
	v_add_u32_e32 v159, s62, v153
	ds_read_b128 v[172:175], v159
	ds_read_b128 v[176:179], v159 offset:1024
	ds_read_b128 v[180:183], v159 offset:2048
	ds_read_b128 v[184:187], v159 offset:3072
	s_add_u32 s38, s38, 0x40000
	s_addc_u32 s39, s39, 0
	v_lshl_add_u64 v[228:229], s[38:39], 0, v[128:129]
	ds_read_b128 v[188:191], v157 offset:32768
	ds_read_b128 v[196:199], v157 offset:33792
	ds_read_b128 v[200:203], v157 offset:34816
	ds_read_b128 v[204:207], v157 offset:35840
	ds_read_b128 v[208:211], v157 offset:36864
	ds_read_b128 v[212:215], v157 offset:37888
	ds_read_b128 v[216:219], v157 offset:38912
	ds_read_b128 v[220:223], v157 offset:39936
	s_mov_b32 m0, s35
	s_nop 0
	global_load_lds_dwordx4 v[224:225], off
	s_mov_b32 m0, s45
	s_nop 0
	global_load_lds_dwordx4 v[226:227], off
	s_mov_b32 m0, s48
	s_nop 0
	global_load_lds_dwordx4 v[228:229], off
	v_lshl_add_u64 v[228:229], s[38:39], 0, v[132:133]
	s_mov_b32 m0, s49
	s_nop 0
	global_load_lds_dwordx4 v[228:229], off
	s_waitcnt vmcnt(8)
	s_waitcnt lgkmcnt(0)
	s_barrier
	s_setprio 1
	s_waitcnt lgkmcnt(0)
	v_mfma_f32_16x16x32_bf16 v[124:127], v[146:149], v[188:191], v[124:127]
	v_mfma_f32_16x16x32_bf16 v[120:123], v[164:167], v[188:191], v[120:123]
	v_mfma_f32_16x16x32_bf16 v[108:111], v[146:149], v[200:203], v[108:111]
	v_mfma_f32_16x16x32_bf16 v[104:107], v[164:167], v[200:203], v[104:107]
	v_mfma_f32_16x16x32_bf16 v[92:95], v[146:149], v[208:211], v[92:95]
	v_mfma_f32_16x16x32_bf16 v[88:91], v[164:167], v[208:211], v[88:91]
	v_mfma_f32_16x16x32_bf16 v[76:79], v[146:149], v[216:219], v[76:79]
	v_mfma_f32_16x16x32_bf16 v[72:75], v[164:167], v[216:219], v[72:75]
	v_mfma_f32_16x16x32_bf16 v[124:127], v[160:163], v[196:199], v[124:127]
	v_mfma_f32_16x16x32_bf16 v[120:123], v[168:171], v[196:199], v[120:123]
	v_mfma_f32_16x16x32_bf16 v[108:111], v[160:163], v[204:207], v[108:111]
	v_mfma_f32_16x16x32_bf16 v[104:107], v[168:171], v[204:207], v[104:107]
	v_mfma_f32_16x16x32_bf16 v[92:95], v[160:163], v[212:215], v[92:95]
	v_mfma_f32_16x16x32_bf16 v[88:91], v[168:171], v[212:215], v[88:91]
	v_mfma_f32_16x16x32_bf16 v[76:79], v[160:163], v[220:223], v[76:79]
	v_mfma_f32_16x16x32_bf16 v[72:75], v[168:171], v[220:223], v[72:75]
	s_setprio 0
	s_setprio 1
	v_mfma_f32_16x16x32_bf16 v[116:119], v[172:175], v[188:191], v[116:119]
	v_mfma_f32_16x16x32_bf16 v[112:115], v[180:183], v[188:191], v[112:115]
	v_mfma_f32_16x16x32_bf16 v[100:103], v[172:175], v[200:203], v[100:103]
	v_mfma_f32_16x16x32_bf16 v[96:99], v[180:183], v[200:203], v[96:99]
	v_mfma_f32_16x16x32_bf16 v[84:87], v[172:175], v[208:211], v[84:87]
	v_mfma_f32_16x16x32_bf16 v[80:83], v[180:183], v[208:211], v[80:83]
	v_mfma_f32_16x16x32_bf16 v[68:71], v[172:175], v[216:219], v[68:71]
	v_mfma_f32_16x16x32_bf16 v[64:67], v[180:183], v[216:219], v[64:67]
	v_mfma_f32_16x16x32_bf16 v[116:119], v[176:179], v[196:199], v[116:119]
	v_mfma_f32_16x16x32_bf16 v[112:115], v[184:187], v[196:199], v[112:115]
	v_mfma_f32_16x16x32_bf16 v[100:103], v[176:179], v[204:207], v[100:103]
	v_mfma_f32_16x16x32_bf16 v[96:99], v[184:187], v[204:207], v[96:99]
	v_mfma_f32_16x16x32_bf16 v[84:87], v[176:179], v[212:215], v[84:87]
	v_mfma_f32_16x16x32_bf16 v[80:83], v[184:187], v[212:215], v[80:83]
	v_mfma_f32_16x16x32_bf16 v[68:71], v[176:179], v[220:223], v[68:71]
	v_mfma_f32_16x16x32_bf16 v[64:67], v[184:187], v[220:223], v[64:67]
	s_setprio 0
	s_barrier
	s_add_i32 s38, s61, s44
	v_lshl_add_u64 v[150:151], v[150:151], 0, s[16:17]
	s_mov_b32 m0, s38
	ds_read_b128 v[188:191], v157 offset:49152
	ds_read_b128 v[196:199], v157 offset:50176
	ds_read_b128 v[200:203], v157 offset:51200
	ds_read_b128 v[204:207], v157 offset:52224
	ds_read_b128 v[208:211], v157 offset:53248
	ds_read_b128 v[212:215], v157 offset:54272
	ds_read_b128 v[216:219], v157 offset:55296
	ds_read_b128 v[220:223], v157 offset:56320
	global_load_lds_dwordx4 v[150:151], off
	s_add_i32 m0, s38, 0x2000
	s_add_u32 s36, s36, 0x40080
	v_lshl_add_u64 v[150:151], v[192:193], 0, s[16:17]
	s_addc_u32 s37, s37, 0
	s_add_i32 s38, s62, s44
	global_load_lds_dwordx4 v[150:151], off
	v_lshl_add_u64 v[150:151], s[36:37], 0, v[130:131]
	s_mov_b32 m0, s38
	s_nop 0
	global_load_lds_dwordx4 v[150:151], off
	v_lshl_add_u64 v[150:151], s[36:37], 0, v[134:135]
	s_add_i32 m0, s38, 0x2000
	s_nop 0
	global_load_lds_dwordx4 v[150:151], off
	v_lshl_add_u64 v[150:151], v[224:225], 0, s[16:17]
	s_mov_b32 m0, s50
	s_nop 0
	global_load_lds_dwordx4 v[150:151], off
	v_lshl_add_u64 v[150:151], v[226:227], 0, s[16:17]
	s_mov_b32 m0, s51
	s_nop 0
	global_load_lds_dwordx4 v[150:151], off
	s_waitcnt vmcnt(8)
	s_waitcnt lgkmcnt(0)
	s_barrier
	s_setprio 1
	s_waitcnt lgkmcnt(0)
	v_mfma_f32_16x16x32_bf16 v[60:63], v[146:149], v[188:191], v[60:63]
	v_mfma_f32_16x16x32_bf16 v[56:59], v[164:167], v[188:191], v[56:59]
	v_mfma_f32_16x16x32_bf16 v[44:47], v[146:149], v[200:203], v[44:47]
	v_mfma_f32_16x16x32_bf16 v[40:43], v[164:167], v[200:203], v[40:43]
	v_mfma_f32_16x16x32_bf16 v[28:31], v[146:149], v[208:211], v[28:31]
	v_mfma_f32_16x16x32_bf16 v[24:27], v[164:167], v[208:211], v[24:27]
	v_mfma_f32_16x16x32_bf16 v[12:15], v[146:149], v[216:219], v[12:15]
	v_mfma_f32_16x16x32_bf16 v[8:11], v[164:167], v[216:219], v[8:11]
	v_mfma_f32_16x16x32_bf16 v[60:63], v[160:163], v[196:199], v[60:63]
	v_mfma_f32_16x16x32_bf16 v[56:59], v[168:171], v[196:199], v[56:59]
	v_mfma_f32_16x16x32_bf16 v[44:47], v[160:163], v[204:207], v[44:47]
	v_mfma_f32_16x16x32_bf16 v[40:43], v[168:171], v[204:207], v[40:43]
	v_mfma_f32_16x16x32_bf16 v[28:31], v[160:163], v[212:215], v[28:31]
	v_mfma_f32_16x16x32_bf16 v[24:27], v[168:171], v[212:215], v[24:27]
	v_mfma_f32_16x16x32_bf16 v[12:15], v[160:163], v[220:223], v[12:15]
	v_mfma_f32_16x16x32_bf16 v[8:11], v[168:171], v[220:223], v[8:11]
	s_setprio 0
	s_setprio 1
	v_mfma_f32_16x16x32_bf16 v[52:55], v[172:175], v[188:191], v[52:55]
	v_mfma_f32_16x16x32_bf16 v[48:51], v[180:183], v[188:191], v[48:51]
	v_mfma_f32_16x16x32_bf16 v[36:39], v[172:175], v[200:203], v[36:39]
	v_mfma_f32_16x16x32_bf16 v[32:35], v[180:183], v[200:203], v[32:35]
	v_mfma_f32_16x16x32_bf16 v[20:23], v[172:175], v[208:211], v[20:23]
	v_mfma_f32_16x16x32_bf16 v[16:19], v[180:183], v[208:211], v[16:19]
	v_mfma_f32_16x16x32_bf16 v[4:7], v[172:175], v[216:219], v[4:7]
	v_mfma_f32_16x16x32_bf16 v[0:3], v[180:183], v[216:219], v[0:3]
	v_mfma_f32_16x16x32_bf16 v[52:55], v[176:179], v[196:199], v[52:55]
	v_mfma_f32_16x16x32_bf16 v[48:51], v[184:187], v[196:199], v[48:51]
	v_mfma_f32_16x16x32_bf16 v[36:39], v[176:179], v[204:207], v[36:39]
	v_mfma_f32_16x16x32_bf16 v[32:35], v[184:187], v[204:207], v[32:35]
	v_mfma_f32_16x16x32_bf16 v[20:23], v[176:179], v[212:215], v[20:23]
	v_mfma_f32_16x16x32_bf16 v[16:19], v[184:187], v[212:215], v[16:19]
	v_mfma_f32_16x16x32_bf16 v[4:7], v[176:179], v[220:223], v[4:7]
	v_mfma_f32_16x16x32_bf16 v[0:3], v[184:187], v[220:223], v[0:3]
	s_setprio 0
	s_barrier
	s_add_i32 s60, s60, 2
	s_add_u32 s0, s0, 0x100
	s_addc_u32 s1, s1, 0
	s_add_u32 s25, s25, 0x100
	s_addc_u32 s59, s59, 0
	s_cmp_gt_u32 s60, 13
	s_cbranch_scc0 .LBB0_3031
	s_and_b64 vcc, exec, s[18:19]
	s_cbranch_vccz .LBB0_3034
	s_barrier

.LBB0_3061:
	ds_read_b128 v[144:147], v159
	ds_read_b128 v[148:151], v159 offset:1024
	ds_read_b128 v[152:155], v159 offset:2048
	ds_read_b128 v[162:165], v159 offset:3072
	ds_read_b128 v[166:169], v160
	ds_read_b128 v[170:173], v160 offset:1024
	ds_read_b128 v[174:177], v160 offset:2048
	ds_read_b128 v[178:181], v160 offset:3072
	s_add_u32 s37, s42, 0xfffe0080
	s_addc_u32 s39, s43, -1
	s_cmp_eq_u32 s35, 4
	s_cselect_b32 s51, s1, s39
	s_cselect_b32 s50, s0, s37
	s_cselect_b32 s49, s41, s13
	s_cselect_b32 s48, s40, s11
	v_lshl_add_u64 v[216:217], s[42:43], 0, v[136:137]
	s_add_i32 m0, s60, 0xc000
	ds_read_b128 v[182:185], v161
	ds_read_b128 v[186:189], v161 offset:1024
	ds_read_b128 v[190:193], v161 offset:2048
	ds_read_b128 v[196:199], v161 offset:3072
	ds_read_b128 v[200:203], v161 offset:4096
	ds_read_b128 v[204:207], v161 offset:5120
	ds_read_b128 v[208:211], v161 offset:6144
	ds_read_b128 v[212:215], v161 offset:7168
	global_load_lds_dwordx4 v[216:217], off
	v_lshl_add_u64 v[216:217], s[42:43], 0, v[138:139]
	s_add_i32 m0, s60, 0xe000
	s_nop 0
	global_load_lds_dwordx4 v[216:217], off
	s_waitcnt vmcnt(8)
	s_waitcnt lgkmcnt(0)
	s_barrier
	s_setprio 1
	s_waitcnt lgkmcnt(0)
	v_mfma_f32_16x16x32_bf16 v[124:127], v[144:147], v[182:185], v[124:127]
	v_mfma_f32_16x16x32_bf16 v[120:123], v[152:155], v[182:185], v[120:123]
	v_mfma_f32_16x16x32_bf16 v[108:111], v[144:147], v[190:193], v[108:111]
	v_mfma_f32_16x16x32_bf16 v[104:107], v[152:155], v[190:193], v[104:107]
	v_mfma_f32_16x16x32_bf16 v[92:95], v[144:147], v[200:203], v[92:95]
	v_mfma_f32_16x16x32_bf16 v[88:91], v[152:155], v[200:203], v[88:91]
	v_mfma_f32_16x16x32_bf16 v[76:79], v[144:147], v[208:211], v[76:79]
	v_mfma_f32_16x16x32_bf16 v[72:75], v[152:155], v[208:211], v[72:75]
	v_mfma_f32_16x16x32_bf16 v[124:127], v[148:151], v[186:189], v[124:127]
	v_mfma_f32_16x16x32_bf16 v[120:123], v[162:165], v[186:189], v[120:123]
	v_mfma_f32_16x16x32_bf16 v[108:111], v[148:151], v[196:199], v[108:111]
	v_mfma_f32_16x16x32_bf16 v[104:107], v[162:165], v[196:199], v[104:107]
	v_mfma_f32_16x16x32_bf16 v[92:95], v[148:151], v[204:207], v[92:95]
	v_mfma_f32_16x16x32_bf16 v[88:91], v[162:165], v[204:207], v[88:91]
	v_mfma_f32_16x16x32_bf16 v[76:79], v[148:151], v[212:215], v[76:79]
	v_mfma_f32_16x16x32_bf16 v[72:75], v[162:165], v[212:215], v[72:75]
	s_setprio 0
	s_setprio 1
	v_mfma_f32_16x16x32_bf16 v[116:119], v[166:169], v[182:185], v[116:119]
	v_mfma_f32_16x16x32_bf16 v[112:115], v[174:177], v[182:185], v[112:115]
	v_mfma_f32_16x16x32_bf16 v[100:103], v[166:169], v[190:193], v[100:103]
	v_mfma_f32_16x16x32_bf16 v[96:99], v[174:177], v[190:193], v[96:99]
	v_mfma_f32_16x16x32_bf16 v[84:87], v[166:169], v[200:203], v[84:87]
	v_mfma_f32_16x16x32_bf16 v[80:83], v[174:177], v[200:203], v[80:83]
	v_mfma_f32_16x16x32_bf16 v[68:71], v[166:169], v[208:211], v[68:71]
	v_mfma_f32_16x16x32_bf16 v[64:67], v[174:177], v[208:211], v[64:67]
	v_mfma_f32_16x16x32_bf16 v[116:119], v[170:173], v[186:189], v[116:119]
	v_mfma_f32_16x16x32_bf16 v[112:115], v[178:181], v[186:189], v[112:115]
	v_mfma_f32_16x16x32_bf16 v[100:103], v[170:173], v[196:199], v[100:103]
	v_mfma_f32_16x16x32_bf16 v[96:99], v[178:181], v[196:199], v[96:99]
	v_mfma_f32_16x16x32_bf16 v[84:87], v[170:173], v[204:207], v[84:87]
	v_mfma_f32_16x16x32_bf16 v[80:83], v[178:181], v[204:207], v[80:83]
	v_mfma_f32_16x16x32_bf16 v[68:71], v[170:173], v[212:215], v[68:71]
	v_mfma_f32_16x16x32_bf16 v[64:67], v[178:181], v[212:215], v[64:67]
	s_setprio 0
	s_barrier
	s_add_i32 s37, s73, s57
	v_lshl_add_u64 v[216:217], s[48:49], 0, v[130:131]
	s_mov_b32 m0, s37
	ds_read_b128 v[182:185], v161 offset:16384
	ds_read_b128 v[186:189], v161 offset:17408
	ds_read_b128 v[190:193], v161 offset:18432
	ds_read_b128 v[196:199], v161 offset:19456
	ds_read_b128 v[200:203], v161 offset:20480
	ds_read_b128 v[204:207], v161 offset:21504
	ds_read_b128 v[208:211], v161 offset:22528
	ds_read_b128 v[212:215], v161 offset:23552
	global_load_lds_dwordx4 v[216:217], off
	s_add_i32 m0, s37, 0x2000
	s_add_u32 s80, s48, 0x20000
	v_lshl_add_u64 v[218:219], s[48:49], 0, v[134:135]
	s_addc_u32 s81, s49, 0
	s_add_i32 s37, s77, s57
	global_load_lds_dwordx4 v[218:219], off
	v_lshl_add_u64 v[220:221], s[80:81], 0, v[130:131]
	s_mov_b32 m0, s37
	v_lshl_add_u64 v[222:223], s[50:51], 0, v[132:133]
	global_load_lds_dwordx4 v[220:221], off
	v_lshl_add_u64 v[220:221], s[80:81], 0, v[134:135]
	s_add_i32 m0, s37, 0x2000
	s_nop 0
	global_load_lds_dwordx4 v[220:221], off
	v_lshl_add_u64 v[220:221], s[50:51], 0, v[128:129]
	s_waitcnt vmcnt(6)
	s_waitcnt lgkmcnt(0)
	s_barrier
	s_setprio 1
	s_waitcnt lgkmcnt(0)
	v_mfma_f32_16x16x32_bf16 v[60:63], v[144:147], v[182:185], v[60:63]
	v_mfma_f32_16x16x32_bf16 v[56:59], v[152:155], v[182:185], v[56:59]
	v_mfma_f32_16x16x32_bf16 v[44:47], v[144:147], v[190:193], v[44:47]
	v_mfma_f32_16x16x32_bf16 v[40:43], v[152:155], v[190:193], v[40:43]
	v_mfma_f32_16x16x32_bf16 v[28:31], v[144:147], v[200:203], v[28:31]
	v_mfma_f32_16x16x32_bf16 v[24:27], v[152:155], v[200:203], v[24:27]
	v_mfma_f32_16x16x32_bf16 v[12:15], v[144:147], v[208:211], v[12:15]
	v_mfma_f32_16x16x32_bf16 v[8:11], v[152:155], v[208:211], v[8:11]
	v_mfma_f32_16x16x32_bf16 v[60:63], v[148:151], v[186:189], v[60:63]
	v_mfma_f32_16x16x32_bf16 v[56:59], v[162:165], v[186:189], v[56:59]
	v_mfma_f32_16x16x32_bf16 v[44:47], v[148:151], v[196:199], v[44:47]
	v_mfma_f32_16x16x32_bf16 v[40:43], v[162:165], v[196:199], v[40:43]
	v_mfma_f32_16x16x32_bf16 v[28:31], v[148:151], v[204:207], v[28:31]
	v_mfma_f32_16x16x32_bf16 v[24:27], v[162:165], v[204:207], v[24:27]
	v_mfma_f32_16x16x32_bf16 v[12:15], v[148:151], v[212:215], v[12:15]
	v_mfma_f32_16x16x32_bf16 v[8:11], v[162:165], v[212:215], v[8:11]
	s_setprio 0
	s_setprio 1
	v_mfma_f32_16x16x32_bf16 v[52:55], v[166:169], v[182:185], v[52:55]
	v_mfma_f32_16x16x32_bf16 v[48:51], v[174:177], v[182:185], v[48:51]
	v_mfma_f32_16x16x32_bf16 v[36:39], v[166:169], v[190:193], v[36:39]
	v_mfma_f32_16x16x32_bf16 v[32:35], v[174:177], v[190:193], v[32:35]
	v_mfma_f32_16x16x32_bf16 v[20:23], v[166:169], v[200:203], v[20:23]
	v_mfma_f32_16x16x32_bf16 v[16:19], v[174:177], v[200:203], v[16:19]
	v_mfma_f32_16x16x32_bf16 v[4:7], v[166:169], v[208:211], v[4:7]
	v_mfma_f32_16x16x32_bf16 v[0:3], v[174:177], v[208:211], v[0:3]
	v_mfma_f32_16x16x32_bf16 v[52:55], v[170:173], v[186:189], v[52:55]
	v_mfma_f32_16x16x32_bf16 v[48:51], v[178:181], v[186:189], v[48:51]
	v_mfma_f32_16x16x32_bf16 v[36:39], v[170:173], v[196:199], v[36:39]
	v_mfma_f32_16x16x32_bf16 v[32:35], v[178:181], v[196:199], v[32:35]
	v_mfma_f32_16x16x32_bf16 v[20:23], v[170:173], v[204:207], v[20:23]
	v_mfma_f32_16x16x32_bf16 v[16:19], v[178:181], v[204:207], v[16:19]
	v_mfma_f32_16x16x32_bf16 v[4:7], v[170:173], v[212:215], v[4:7]
	v_mfma_f32_16x16x32_bf16 v[0:3], v[178:181], v[212:215], v[0:3]
	s_setprio 0
	s_barrier
	s_add_i32 s37, 0, 0x18000
	s_add_i32 s39, 0, 0x1c000
	v_add_u32_e32 v162, s37, v157
	v_add_u32_e32 v178, s39, v157
	ds_read_b128 v[144:147], v162
	ds_read_b128 v[148:151], v162 offset:1024
	ds_read_b128 v[152:155], v162 offset:2048
	ds_read_b128 v[162:165], v162 offset:3072
	ds_read_b128 v[166:169], v178
	ds_read_b128 v[170:173], v178 offset:1024
	ds_read_b128 v[174:177], v178 offset:2048
	ds_read_b128 v[178:181], v178 offset:3072
	s_add_u32 s50, s50, 0x20000
	s_addc_u32 s51, s51, 0
	v_lshl_add_u64 v[224:225], s[50:51], 0, v[128:129]
	ds_read_b128 v[182:185], v161 offset:32768
	ds_read_b128 v[186:189], v161 offset:33792
	ds_read_b128 v[190:193], v161 offset:34816
	ds_read_b128 v[196:199], v161 offset:35840
	ds_read_b128 v[200:203], v161 offset:36864
	ds_read_b128 v[204:207], v161 offset:37888
	ds_read_b128 v[208:211], v161 offset:38912
	ds_read_b128 v[212:215], v161 offset:39936
	s_mov_b32 m0, s60
	s_nop 0
	global_load_lds_dwordx4 v[220:221], off
	s_mov_b32 m0, s61
	s_nop 0
	global_load_lds_dwordx4 v[222:223], off
	s_mov_b32 m0, s62
	s_nop 0
	global_load_lds_dwordx4 v[224:225], off
	v_lshl_add_u64 v[224:225], s[50:51], 0, v[132:133]
	s_mov_b32 m0, s63
	s_nop 0
	global_load_lds_dwordx4 v[224:225], off
	s_waitcnt vmcnt(8)
	s_waitcnt lgkmcnt(0)
	s_barrier
	s_setprio 1
	s_waitcnt lgkmcnt(0)
	v_mfma_f32_16x16x32_bf16 v[124:127], v[144:147], v[182:185], v[124:127]
	v_mfma_f32_16x16x32_bf16 v[120:123], v[152:155], v[182:185], v[120:123]
	v_mfma_f32_16x16x32_bf16 v[108:111], v[144:147], v[190:193], v[108:111]
	v_mfma_f32_16x16x32_bf16 v[104:107], v[152:155], v[190:193], v[104:107]
	v_mfma_f32_16x16x32_bf16 v[92:95], v[144:147], v[200:203], v[92:95]
	v_mfma_f32_16x16x32_bf16 v[88:91], v[152:155], v[200:203], v[88:91]
	v_mfma_f32_16x16x32_bf16 v[76:79], v[144:147], v[208:211], v[76:79]
	v_mfma_f32_16x16x32_bf16 v[72:75], v[152:155], v[208:211], v[72:75]
	v_mfma_f32_16x16x32_bf16 v[124:127], v[148:151], v[186:189], v[124:127]
	v_mfma_f32_16x16x32_bf16 v[120:123], v[162:165], v[186:189], v[120:123]
	v_mfma_f32_16x16x32_bf16 v[108:111], v[148:151], v[196:199], v[108:111]
	v_mfma_f32_16x16x32_bf16 v[104:107], v[162:165], v[196:199], v[104:107]
	v_mfma_f32_16x16x32_bf16 v[92:95], v[148:151], v[204:207], v[92:95]
	v_mfma_f32_16x16x32_bf16 v[88:91], v[162:165], v[204:207], v[88:91]
	v_mfma_f32_16x16x32_bf16 v[76:79], v[148:151], v[212:215], v[76:79]
	v_mfma_f32_16x16x32_bf16 v[72:75], v[162:165], v[212:215], v[72:75]
	s_setprio 0
	s_setprio 1
	v_mfma_f32_16x16x32_bf16 v[116:119], v[166:169], v[182:185], v[116:119]
	v_mfma_f32_16x16x32_bf16 v[112:115], v[174:177], v[182:185], v[112:115]
	v_mfma_f32_16x16x32_bf16 v[100:103], v[166:169], v[190:193], v[100:103]
	v_mfma_f32_16x16x32_bf16 v[96:99], v[174:177], v[190:193], v[96:99]
	v_mfma_f32_16x16x32_bf16 v[84:87], v[166:169], v[200:203], v[84:87]
	v_mfma_f32_16x16x32_bf16 v[80:83], v[174:177], v[200:203], v[80:83]
	v_mfma_f32_16x16x32_bf16 v[68:71], v[166:169], v[208:211], v[68:71]
	v_mfma_f32_16x16x32_bf16 v[64:67], v[174:177], v[208:211], v[64:67]
	v_mfma_f32_16x16x32_bf16 v[116:119], v[170:173], v[186:189], v[116:119]
	v_mfma_f32_16x16x32_bf16 v[112:115], v[178:181], v[186:189], v[112:115]
	v_mfma_f32_16x16x32_bf16 v[100:103], v[170:173], v[196:199], v[100:103]
	v_mfma_f32_16x16x32_bf16 v[96:99], v[178:181], v[196:199], v[96:99]
	v_mfma_f32_16x16x32_bf16 v[84:87], v[170:173], v[204:207], v[84:87]
	v_mfma_f32_16x16x32_bf16 v[80:83], v[178:181], v[204:207], v[80:83]
	v_mfma_f32_16x16x32_bf16 v[68:71], v[170:173], v[212:215], v[68:71]
	v_mfma_f32_16x16x32_bf16 v[64:67], v[178:181], v[212:215], v[64:67]
	s_setprio 0
	s_barrier
	s_add_i32 s37, s37, s57
	v_lshl_add_u64 v[216:217], v[216:217], 0, s[22:23]
	s_mov_b32 m0, s37
	ds_read_b128 v[182:185], v161 offset:49152
	ds_read_b128 v[186:189], v161 offset:50176
	ds_read_b128 v[190:193], v161 offset:51200
	ds_read_b128 v[196:199], v161 offset:52224
	ds_read_b128 v[200:203], v161 offset:53248
	ds_read_b128 v[204:207], v161 offset:54272
	ds_read_b128 v[208:211], v161 offset:55296
	ds_read_b128 v[212:215], v161 offset:56320
	global_load_lds_dwordx4 v[216:217], off
	s_add_i32 m0, s37, 0x2000
	s_add_u32 s48, s48, 0x20080
	v_lshl_add_u64 v[216:217], v[218:219], 0, s[22:23]
	s_addc_u32 s49, s49, 0
	s_add_i32 s37, s39, s57
	global_load_lds_dwordx4 v[216:217], off
	v_lshl_add_u64 v[216:217], s[48:49], 0, v[130:131]
	s_mov_b32 m0, s37
	s_nop 0
	global_load_lds_dwordx4 v[216:217], off
	v_lshl_add_u64 v[216:217], s[48:49], 0, v[134:135]
	s_add_i32 m0, s37, 0x2000
	s_nop 0
	global_load_lds_dwordx4 v[216:217], off
	v_lshl_add_u64 v[216:217], v[220:221], 0, s[22:23]
	s_mov_b32 m0, s70
	s_nop 0
	global_load_lds_dwordx4 v[216:217], off
	v_lshl_add_u64 v[216:217], v[222:223], 0, s[22:23]
	s_mov_b32 m0, s71
	s_nop 0
	global_load_lds_dwordx4 v[216:217], off
	s_waitcnt vmcnt(8)
	s_waitcnt lgkmcnt(0)
	s_barrier
	s_setprio 1
	s_waitcnt lgkmcnt(0)
	v_mfma_f32_16x16x32_bf16 v[60:63], v[144:147], v[182:185], v[60:63]
	v_mfma_f32_16x16x32_bf16 v[56:59], v[152:155], v[182:185], v[56:59]
	v_mfma_f32_16x16x32_bf16 v[44:47], v[144:147], v[190:193], v[44:47]
	v_mfma_f32_16x16x32_bf16 v[40:43], v[152:155], v[190:193], v[40:43]
	v_mfma_f32_16x16x32_bf16 v[28:31], v[144:147], v[200:203], v[28:31]
	v_mfma_f32_16x16x32_bf16 v[24:27], v[152:155], v[200:203], v[24:27]
	v_mfma_f32_16x16x32_bf16 v[12:15], v[144:147], v[208:211], v[12:15]
	v_mfma_f32_16x16x32_bf16 v[8:11], v[152:155], v[208:211], v[8:11]
	v_mfma_f32_16x16x32_bf16 v[60:63], v[148:151], v[186:189], v[60:63]
	v_mfma_f32_16x16x32_bf16 v[56:59], v[162:165], v[186:189], v[56:59]
	v_mfma_f32_16x16x32_bf16 v[44:47], v[148:151], v[196:199], v[44:47]
	v_mfma_f32_16x16x32_bf16 v[40:43], v[162:165], v[196:199], v[40:43]
	v_mfma_f32_16x16x32_bf16 v[28:31], v[148:151], v[204:207], v[28:31]
	v_mfma_f32_16x16x32_bf16 v[24:27], v[162:165], v[204:207], v[24:27]
	v_mfma_f32_16x16x32_bf16 v[12:15], v[148:151], v[212:215], v[12:15]
	v_mfma_f32_16x16x32_bf16 v[8:11], v[162:165], v[212:215], v[8:11]
	s_setprio 0
	s_setprio 1
	v_mfma_f32_16x16x32_bf16 v[52:55], v[166:169], v[182:185], v[52:55]
	v_mfma_f32_16x16x32_bf16 v[48:51], v[174:177], v[182:185], v[48:51]
	v_mfma_f32_16x16x32_bf16 v[36:39], v[166:169], v[190:193], v[36:39]
	v_mfma_f32_16x16x32_bf16 v[32:35], v[174:177], v[190:193], v[32:35]
	v_mfma_f32_16x16x32_bf16 v[20:23], v[166:169], v[200:203], v[20:23]
	v_mfma_f32_16x16x32_bf16 v[16:19], v[174:177], v[200:203], v[16:19]
	v_mfma_f32_16x16x32_bf16 v[4:7], v[166:169], v[208:211], v[4:7]
	v_mfma_f32_16x16x32_bf16 v[0:3], v[174:177], v[208:211], v[0:3]
	v_mfma_f32_16x16x32_bf16 v[52:55], v[170:173], v[186:189], v[52:55]
	v_mfma_f32_16x16x32_bf16 v[48:51], v[178:181], v[186:189], v[48:51]
	v_mfma_f32_16x16x32_bf16 v[36:39], v[170:173], v[196:199], v[36:39]
	v_mfma_f32_16x16x32_bf16 v[32:35], v[178:181], v[196:199], v[32:35]
	v_mfma_f32_16x16x32_bf16 v[20:23], v[170:173], v[204:207], v[20:23]
	v_mfma_f32_16x16x32_bf16 v[16:19], v[178:181], v[204:207], v[16:19]
	v_mfma_f32_16x16x32_bf16 v[4:7], v[170:173], v[212:215], v[4:7]
	v_mfma_f32_16x16x32_bf16 v[0:3], v[178:181], v[212:215], v[0:3]
	s_setprio 0
	s_barrier
	s_add_i32 s35, s35, 2
	s_add_u32 s42, s42, 0x100
	s_addc_u32 s43, s43, 0
	s_add_u32 s11, s11, 0x100
	s_addc_u32 s13, s13, 0
	s_cmp_gt_u32 s35, 5
	s_cbranch_scc0 .LBB0_3061
	s_and_b64 vcc, exec, s[24:25]
	s_cbranch_vccz .LBB0_3064
	s_barrier

.LBB0_3235:
	ds_read_b128 v[144:147], v151
	ds_read_b128 v[156:159], v151 offset:1024
	ds_read_b128 v[160:163], v151 offset:2048
	ds_read_b128 v[164:167], v151 offset:3072
	ds_read_b128 v[168:171], v152
	ds_read_b128 v[172:175], v152 offset:1024
	ds_read_b128 v[176:179], v152 offset:2048
	ds_read_b128 v[180:183], v152 offset:3072
	s_add_u32 s38, s36, 0xfffc0080
	s_addc_u32 s39, s37, -1
	s_cmp_eq_u32 s70, 12
	s_cselect_b32 s41, s27, s39
	s_cselect_b32 s40, s35, s38
	s_cselect_b32 s39, s25, s63
	s_cselect_b32 s38, s61, s62
	v_lshl_add_u64 v[192:193], s[36:37], 0, v[136:137]
	s_add_i32 m0, s50, 0xc000
	ds_read_b128 v[184:187], v153
	ds_read_b128 v[188:191], v153 offset:1024
	ds_read_b128 v[196:199], v153 offset:2048
	ds_read_b128 v[200:203], v153 offset:3072
	ds_read_b128 v[204:207], v153 offset:4096
	ds_read_b128 v[208:211], v153 offset:5120
	ds_read_b128 v[212:215], v153 offset:6144
	ds_read_b128 v[216:219], v153 offset:7168
	global_load_lds_dwordx4 v[192:193], off
	v_lshl_add_u64 v[192:193], s[36:37], 0, v[138:139]
	s_add_i32 m0, s50, 0xe000
	s_nop 0
	global_load_lds_dwordx4 v[192:193], off
	s_waitcnt vmcnt(8)
	s_waitcnt lgkmcnt(0)
	s_barrier
	s_setprio 1
	s_waitcnt lgkmcnt(0)
	v_mfma_f32_16x16x32_bf16 v[124:127], v[144:147], v[184:187], v[124:127]
	v_mfma_f32_16x16x32_bf16 v[120:123], v[160:163], v[184:187], v[120:123]
	v_mfma_f32_16x16x32_bf16 v[108:111], v[144:147], v[196:199], v[108:111]
	v_mfma_f32_16x16x32_bf16 v[104:107], v[160:163], v[196:199], v[104:107]
	v_mfma_f32_16x16x32_bf16 v[92:95], v[144:147], v[204:207], v[92:95]
	v_mfma_f32_16x16x32_bf16 v[88:91], v[160:163], v[204:207], v[88:91]
	v_mfma_f32_16x16x32_bf16 v[76:79], v[144:147], v[212:215], v[76:79]
	v_mfma_f32_16x16x32_bf16 v[72:75], v[160:163], v[212:215], v[72:75]
	v_mfma_f32_16x16x32_bf16 v[124:127], v[156:159], v[188:191], v[124:127]
	v_mfma_f32_16x16x32_bf16 v[120:123], v[164:167], v[188:191], v[120:123]
	v_mfma_f32_16x16x32_bf16 v[108:111], v[156:159], v[200:203], v[108:111]
	v_mfma_f32_16x16x32_bf16 v[104:107], v[164:167], v[200:203], v[104:107]
	v_mfma_f32_16x16x32_bf16 v[92:95], v[156:159], v[208:211], v[92:95]
	v_mfma_f32_16x16x32_bf16 v[88:91], v[164:167], v[208:211], v[88:91]
	v_mfma_f32_16x16x32_bf16 v[76:79], v[156:159], v[216:219], v[76:79]
	v_mfma_f32_16x16x32_bf16 v[72:75], v[164:167], v[216:219], v[72:75]
	s_setprio 0
	s_setprio 1
	v_mfma_f32_16x16x32_bf16 v[116:119], v[168:171], v[184:187], v[116:119]
	v_mfma_f32_16x16x32_bf16 v[112:115], v[176:179], v[184:187], v[112:115]
	v_mfma_f32_16x16x32_bf16 v[100:103], v[168:171], v[196:199], v[100:103]
	v_mfma_f32_16x16x32_bf16 v[96:99], v[176:179], v[196:199], v[96:99]
	v_mfma_f32_16x16x32_bf16 v[84:87], v[168:171], v[204:207], v[84:87]
	v_mfma_f32_16x16x32_bf16 v[80:83], v[176:179], v[204:207], v[80:83]
	v_mfma_f32_16x16x32_bf16 v[68:71], v[168:171], v[212:215], v[68:71]
	v_mfma_f32_16x16x32_bf16 v[64:67], v[176:179], v[212:215], v[64:67]
	v_mfma_f32_16x16x32_bf16 v[116:119], v[172:175], v[188:191], v[116:119]
	v_mfma_f32_16x16x32_bf16 v[112:115], v[180:183], v[188:191], v[112:115]
	v_mfma_f32_16x16x32_bf16 v[100:103], v[172:175], v[200:203], v[100:103]
	v_mfma_f32_16x16x32_bf16 v[96:99], v[180:183], v[200:203], v[96:99]
	v_mfma_f32_16x16x32_bf16 v[84:87], v[172:175], v[208:211], v[84:87]
	v_mfma_f32_16x16x32_bf16 v[80:83], v[180:183], v[208:211], v[80:83]
	v_mfma_f32_16x16x32_bf16 v[68:71], v[172:175], v[216:219], v[68:71]
	v_mfma_f32_16x16x32_bf16 v[64:67], v[180:183], v[216:219], v[64:67]
	s_setprio 0
	s_barrier
	s_add_i32 s71, s58, s49
	v_lshl_add_u64 v[192:193], s[38:39], 0, v[130:131]
	s_mov_b32 m0, s71
	ds_read_b128 v[184:187], v153 offset:16384
	ds_read_b128 v[188:191], v153 offset:17408
	ds_read_b128 v[196:199], v153 offset:18432
	ds_read_b128 v[200:203], v153 offset:19456
	ds_read_b128 v[204:207], v153 offset:20480
	ds_read_b128 v[208:211], v153 offset:21504
	ds_read_b128 v[212:215], v153 offset:22528
	ds_read_b128 v[216:219], v153 offset:23552
	global_load_lds_dwordx4 v[192:193], off
	s_add_i32 m0, s71, 0x2000
	s_add_u32 s72, s38, 0x40000
	v_lshl_add_u64 v[220:221], s[38:39], 0, v[134:135]
	s_addc_u32 s73, s39, 0
	s_add_i32 s71, s59, s49
	global_load_lds_dwordx4 v[220:221], off
	v_lshl_add_u64 v[222:223], s[72:73], 0, v[130:131]
	s_mov_b32 m0, s71
	v_lshl_add_u64 v[224:225], s[40:41], 0, v[132:133]
	global_load_lds_dwordx4 v[222:223], off
	v_lshl_add_u64 v[222:223], s[72:73], 0, v[134:135]
	s_add_i32 m0, s71, 0x2000
	s_nop 0
	global_load_lds_dwordx4 v[222:223], off
	v_lshl_add_u64 v[222:223], s[40:41], 0, v[128:129]
	s_waitcnt vmcnt(6)
	s_waitcnt lgkmcnt(0)
	s_barrier
	s_setprio 1
	s_waitcnt lgkmcnt(0)
	v_mfma_f32_16x16x32_bf16 v[60:63], v[144:147], v[184:187], v[60:63]
	v_mfma_f32_16x16x32_bf16 v[56:59], v[160:163], v[184:187], v[56:59]
	v_mfma_f32_16x16x32_bf16 v[44:47], v[144:147], v[196:199], v[44:47]
	v_mfma_f32_16x16x32_bf16 v[40:43], v[160:163], v[196:199], v[40:43]
	v_mfma_f32_16x16x32_bf16 v[28:31], v[144:147], v[204:207], v[28:31]
	v_mfma_f32_16x16x32_bf16 v[24:27], v[160:163], v[204:207], v[24:27]
	v_mfma_f32_16x16x32_bf16 v[12:15], v[144:147], v[212:215], v[12:15]
	v_mfma_f32_16x16x32_bf16 v[8:11], v[160:163], v[212:215], v[8:11]
	v_mfma_f32_16x16x32_bf16 v[60:63], v[156:159], v[188:191], v[60:63]
	v_mfma_f32_16x16x32_bf16 v[56:59], v[164:167], v[188:191], v[56:59]
	v_mfma_f32_16x16x32_bf16 v[44:47], v[156:159], v[200:203], v[44:47]
	v_mfma_f32_16x16x32_bf16 v[40:43], v[164:167], v[200:203], v[40:43]
	v_mfma_f32_16x16x32_bf16 v[28:31], v[156:159], v[208:211], v[28:31]
	v_mfma_f32_16x16x32_bf16 v[24:27], v[164:167], v[208:211], v[24:27]
	v_mfma_f32_16x16x32_bf16 v[12:15], v[156:159], v[216:219], v[12:15]
	v_mfma_f32_16x16x32_bf16 v[8:11], v[164:167], v[216:219], v[8:11]
	s_setprio 0
	s_setprio 1
	v_mfma_f32_16x16x32_bf16 v[52:55], v[168:171], v[184:187], v[52:55]
	v_mfma_f32_16x16x32_bf16 v[48:51], v[176:179], v[184:187], v[48:51]
	v_mfma_f32_16x16x32_bf16 v[36:39], v[168:171], v[196:199], v[36:39]
	v_mfma_f32_16x16x32_bf16 v[32:35], v[176:179], v[196:199], v[32:35]
	v_mfma_f32_16x16x32_bf16 v[20:23], v[168:171], v[204:207], v[20:23]
	v_mfma_f32_16x16x32_bf16 v[16:19], v[176:179], v[204:207], v[16:19]
	v_mfma_f32_16x16x32_bf16 v[4:7], v[168:171], v[212:215], v[4:7]
	v_mfma_f32_16x16x32_bf16 v[0:3], v[176:179], v[212:215], v[0:3]
	v_mfma_f32_16x16x32_bf16 v[52:55], v[172:175], v[188:191], v[52:55]
	v_mfma_f32_16x16x32_bf16 v[48:51], v[180:183], v[188:191], v[48:51]
	v_mfma_f32_16x16x32_bf16 v[36:39], v[172:175], v[200:203], v[36:39]
	v_mfma_f32_16x16x32_bf16 v[32:35], v[180:183], v[200:203], v[32:35]
	v_mfma_f32_16x16x32_bf16 v[20:23], v[172:175], v[208:211], v[20:23]
	v_mfma_f32_16x16x32_bf16 v[16:19], v[180:183], v[208:211], v[16:19]
	v_mfma_f32_16x16x32_bf16 v[4:7], v[172:175], v[216:219], v[4:7]
	v_mfma_f32_16x16x32_bf16 v[0:3], v[180:183], v[216:219], v[0:3]
	s_setprio 0
	s_barrier
	s_add_i32 s71, 0, 0x18000
	v_add_u32_e32 v155, s71, v149
	s_add_i32 s72, 0, 0x1c000
	ds_read_b128 v[144:147], v155
	ds_read_b128 v[156:159], v155 offset:1024
	ds_read_b128 v[160:163], v155 offset:2048
	ds_read_b128 v[164:167], v155 offset:3072
	v_add_u32_e32 v155, s72, v149
	ds_read_b128 v[168:171], v155
	ds_read_b128 v[172:175], v155 offset:1024
	ds_read_b128 v[176:179], v155 offset:2048
	ds_read_b128 v[180:183], v155 offset:3072
	s_add_u32 s40, s40, 0x40000
	s_addc_u32 s41, s41, 0
	v_lshl_add_u64 v[226:227], s[40:41], 0, v[128:129]
	ds_read_b128 v[184:187], v153 offset:32768
	ds_read_b128 v[188:191], v153 offset:33792
	ds_read_b128 v[196:199], v153 offset:34816
	ds_read_b128 v[200:203], v153 offset:35840
	ds_read_b128 v[204:207], v153 offset:36864
	ds_read_b128 v[208:211], v153 offset:37888
	ds_read_b128 v[212:215], v153 offset:38912
	ds_read_b128 v[216:219], v153 offset:39936
	s_mov_b32 m0, s50
	s_nop 0
	global_load_lds_dwordx4 v[222:223], off
	s_mov_b32 m0, s51
	s_nop 0
	global_load_lds_dwordx4 v[224:225], off
	s_mov_b32 m0, s52
	s_nop 0
	global_load_lds_dwordx4 v[226:227], off
	v_lshl_add_u64 v[226:227], s[40:41], 0, v[132:133]
	s_mov_b32 m0, s53
	s_nop 0
	global_load_lds_dwordx4 v[226:227], off
	s_waitcnt vmcnt(8)
	s_waitcnt lgkmcnt(0)
	s_barrier
	s_setprio 1
	s_waitcnt lgkmcnt(0)
	v_mfma_f32_16x16x32_bf16 v[124:127], v[144:147], v[184:187], v[124:127]
	v_mfma_f32_16x16x32_bf16 v[120:123], v[160:163], v[184:187], v[120:123]
	v_mfma_f32_16x16x32_bf16 v[108:111], v[144:147], v[196:199], v[108:111]
	v_mfma_f32_16x16x32_bf16 v[104:107], v[160:163], v[196:199], v[104:107]
	v_mfma_f32_16x16x32_bf16 v[92:95], v[144:147], v[204:207], v[92:95]
	v_mfma_f32_16x16x32_bf16 v[88:91], v[160:163], v[204:207], v[88:91]
	v_mfma_f32_16x16x32_bf16 v[76:79], v[144:147], v[212:215], v[76:79]
	v_mfma_f32_16x16x32_bf16 v[72:75], v[160:163], v[212:215], v[72:75]
	v_mfma_f32_16x16x32_bf16 v[124:127], v[156:159], v[188:191], v[124:127]
	v_mfma_f32_16x16x32_bf16 v[120:123], v[164:167], v[188:191], v[120:123]
	v_mfma_f32_16x16x32_bf16 v[108:111], v[156:159], v[200:203], v[108:111]
	v_mfma_f32_16x16x32_bf16 v[104:107], v[164:167], v[200:203], v[104:107]
	v_mfma_f32_16x16x32_bf16 v[92:95], v[156:159], v[208:211], v[92:95]
	v_mfma_f32_16x16x32_bf16 v[88:91], v[164:167], v[208:211], v[88:91]
	v_mfma_f32_16x16x32_bf16 v[76:79], v[156:159], v[216:219], v[76:79]
	v_mfma_f32_16x16x32_bf16 v[72:75], v[164:167], v[216:219], v[72:75]
	s_setprio 0
	s_setprio 1
	v_mfma_f32_16x16x32_bf16 v[116:119], v[168:171], v[184:187], v[116:119]
	v_mfma_f32_16x16x32_bf16 v[112:115], v[176:179], v[184:187], v[112:115]
	v_mfma_f32_16x16x32_bf16 v[100:103], v[168:171], v[196:199], v[100:103]
	v_mfma_f32_16x16x32_bf16 v[96:99], v[176:179], v[196:199], v[96:99]
	v_mfma_f32_16x16x32_bf16 v[84:87], v[168:171], v[204:207], v[84:87]
	v_mfma_f32_16x16x32_bf16 v[80:83], v[176:179], v[204:207], v[80:83]
	v_mfma_f32_16x16x32_bf16 v[68:71], v[168:171], v[212:215], v[68:71]
	v_mfma_f32_16x16x32_bf16 v[64:67], v[176:179], v[212:215], v[64:67]
	v_mfma_f32_16x16x32_bf16 v[116:119], v[172:175], v[188:191], v[116:119]
	v_mfma_f32_16x16x32_bf16 v[112:115], v[180:183], v[188:191], v[112:115]
	v_mfma_f32_16x16x32_bf16 v[100:103], v[172:175], v[200:203], v[100:103]
	v_mfma_f32_16x16x32_bf16 v[96:99], v[180:183], v[200:203], v[96:99]
	v_mfma_f32_16x16x32_bf16 v[84:87], v[172:175], v[208:211], v[84:87]
	v_mfma_f32_16x16x32_bf16 v[80:83], v[180:183], v[208:211], v[80:83]
	v_mfma_f32_16x16x32_bf16 v[68:71], v[172:175], v[216:219], v[68:71]
	v_mfma_f32_16x16x32_bf16 v[64:67], v[180:183], v[216:219], v[64:67]
	s_setprio 0
	s_barrier
	s_add_i32 s40, s71, s49
	v_lshl_add_u64 v[192:193], v[192:193], 0, s[20:21]
	s_mov_b32 m0, s40
	ds_read_b128 v[184:187], v153 offset:49152
	ds_read_b128 v[188:191], v153 offset:50176
	ds_read_b128 v[196:199], v153 offset:51200
	ds_read_b128 v[200:203], v153 offset:52224
	ds_read_b128 v[204:207], v153 offset:53248
	ds_read_b128 v[208:211], v153 offset:54272
	ds_read_b128 v[212:215], v153 offset:55296
	ds_read_b128 v[216:219], v153 offset:56320
	global_load_lds_dwordx4 v[192:193], off
	s_add_i32 m0, s40, 0x2000
	s_add_u32 s38, s38, 0x40080
	v_lshl_add_u64 v[192:193], v[220:221], 0, s[20:21]
	s_addc_u32 s39, s39, 0
	s_add_i32 s40, s72, s49
	global_load_lds_dwordx4 v[192:193], off
	v_lshl_add_u64 v[192:193], s[38:39], 0, v[130:131]
	s_mov_b32 m0, s40
	s_nop 0
	global_load_lds_dwordx4 v[192:193], off
	v_lshl_add_u64 v[192:193], s[38:39], 0, v[134:135]
	s_add_i32 m0, s40, 0x2000
	s_nop 0
	global_load_lds_dwordx4 v[192:193], off
	v_lshl_add_u64 v[192:193], v[222:223], 0, s[20:21]
	s_mov_b32 m0, s55
	s_nop 0
	global_load_lds_dwordx4 v[192:193], off
	v_lshl_add_u64 v[192:193], v[224:225], 0, s[20:21]
	s_mov_b32 m0, s56
	s_nop 0
	global_load_lds_dwordx4 v[192:193], off
	s_waitcnt vmcnt(8)
	s_waitcnt lgkmcnt(0)
	s_barrier
	s_setprio 1
	s_waitcnt lgkmcnt(0)
	v_mfma_f32_16x16x32_bf16 v[60:63], v[144:147], v[184:187], v[60:63]
	v_mfma_f32_16x16x32_bf16 v[56:59], v[160:163], v[184:187], v[56:59]
	v_mfma_f32_16x16x32_bf16 v[44:47], v[144:147], v[196:199], v[44:47]
	v_mfma_f32_16x16x32_bf16 v[40:43], v[160:163], v[196:199], v[40:43]
	v_mfma_f32_16x16x32_bf16 v[28:31], v[144:147], v[204:207], v[28:31]
	v_mfma_f32_16x16x32_bf16 v[24:27], v[160:163], v[204:207], v[24:27]
	v_mfma_f32_16x16x32_bf16 v[12:15], v[144:147], v[212:215], v[12:15]
	v_mfma_f32_16x16x32_bf16 v[8:11], v[160:163], v[212:215], v[8:11]
	v_mfma_f32_16x16x32_bf16 v[60:63], v[156:159], v[188:191], v[60:63]
	v_mfma_f32_16x16x32_bf16 v[56:59], v[164:167], v[188:191], v[56:59]
	v_mfma_f32_16x16x32_bf16 v[44:47], v[156:159], v[200:203], v[44:47]
	v_mfma_f32_16x16x32_bf16 v[40:43], v[164:167], v[200:203], v[40:43]
	v_mfma_f32_16x16x32_bf16 v[28:31], v[156:159], v[208:211], v[28:31]
	v_mfma_f32_16x16x32_bf16 v[24:27], v[164:167], v[208:211], v[24:27]
	v_mfma_f32_16x16x32_bf16 v[12:15], v[156:159], v[216:219], v[12:15]
	v_mfma_f32_16x16x32_bf16 v[8:11], v[164:167], v[216:219], v[8:11]
	s_setprio 0
	s_setprio 1
	v_mfma_f32_16x16x32_bf16 v[52:55], v[168:171], v[184:187], v[52:55]
	v_mfma_f32_16x16x32_bf16 v[48:51], v[176:179], v[184:187], v[48:51]
	v_mfma_f32_16x16x32_bf16 v[36:39], v[168:171], v[196:199], v[36:39]
	v_mfma_f32_16x16x32_bf16 v[32:35], v[176:179], v[196:199], v[32:35]
	v_mfma_f32_16x16x32_bf16 v[20:23], v[168:171], v[204:207], v[20:23]
	v_mfma_f32_16x16x32_bf16 v[16:19], v[176:179], v[204:207], v[16:19]
	v_mfma_f32_16x16x32_bf16 v[4:7], v[168:171], v[212:215], v[4:7]
	v_mfma_f32_16x16x32_bf16 v[0:3], v[176:179], v[212:215], v[0:3]
	v_mfma_f32_16x16x32_bf16 v[52:55], v[172:175], v[188:191], v[52:55]
	v_mfma_f32_16x16x32_bf16 v[48:51], v[180:183], v[188:191], v[48:51]
	v_mfma_f32_16x16x32_bf16 v[36:39], v[172:175], v[200:203], v[36:39]
	v_mfma_f32_16x16x32_bf16 v[32:35], v[180:183], v[200:203], v[32:35]
	v_mfma_f32_16x16x32_bf16 v[20:23], v[172:175], v[208:211], v[20:23]
	v_mfma_f32_16x16x32_bf16 v[16:19], v[180:183], v[208:211], v[16:19]
	v_mfma_f32_16x16x32_bf16 v[4:7], v[172:175], v[216:219], v[4:7]
	v_mfma_f32_16x16x32_bf16 v[0:3], v[180:183], v[216:219], v[0:3]
	s_setprio 0
	s_barrier
	s_add_i32 s70, s70, 2
	s_add_u32 s36, s36, 0x100
	s_addc_u32 s37, s37, 0
	s_add_u32 s62, s62, 0x100
	s_addc_u32 s63, s63, 0
	s_cmp_gt_u32 s70, 13
	s_cbranch_scc0 .LBB0_3235
	s_and_b64 vcc, exec, s[22:23]
	s_cbranch_vccz .LBB0_3238
	s_barrier

.LBB0_3319:
	ds_read_b128 v[154:157], v149
	ds_read_b128 v[158:161], v149 offset:1024
	ds_read_b128 v[162:165], v149 offset:2048
	ds_read_b128 v[166:169], v149 offset:3072
	ds_read_b128 v[170:173], v150
	ds_read_b128 v[174:177], v150 offset:1024
	ds_read_b128 v[178:181], v150 offset:2048
	ds_read_b128 v[182:185], v150 offset:3072
	s_add_u32 s28, s26, 0xfffc0080
	s_addc_u32 s29, s27, -1
	s_cmp_eq_u32 s59, 12
	s_cselect_b32 s31, s19, s29
	s_cselect_b32 s30, s55, s28
	s_cselect_b32 s29, s17, s58
	s_cselect_b32 s28, s56, s57
	v_lshl_add_u64 v[144:145], s[26:27], 0, v[136:137]
	s_add_i32 m0, s25, 0xc000
	ds_read_b128 v[186:189], v151
	ds_read_b128 v[190:193], v151 offset:1024
	ds_read_b128 v[196:199], v151 offset:2048
	ds_read_b128 v[200:203], v151 offset:3072
	ds_read_b128 v[204:207], v151 offset:4096
	ds_read_b128 v[208:211], v151 offset:5120
	ds_read_b128 v[212:215], v151 offset:6144
	ds_read_b128 v[216:219], v151 offset:7168
	global_load_lds_dwordx4 v[144:145], off
	v_lshl_add_u64 v[144:145], s[26:27], 0, v[138:139]
	s_add_i32 m0, s25, 0xe000
	s_nop 0
	global_load_lds_dwordx4 v[144:145], off
	s_waitcnt vmcnt(8)
	s_waitcnt lgkmcnt(0)
	s_barrier
	s_setprio 1
	s_waitcnt lgkmcnt(0)
	v_mfma_f32_16x16x32_bf16 v[116:119], v[154:157], v[186:189], v[116:119]
	v_mfma_f32_16x16x32_bf16 v[112:115], v[162:165], v[186:189], v[112:115]
	v_mfma_f32_16x16x32_bf16 v[100:103], v[154:157], v[196:199], v[100:103]
	v_mfma_f32_16x16x32_bf16 v[96:99], v[162:165], v[196:199], v[96:99]
	v_mfma_f32_16x16x32_bf16 v[84:87], v[154:157], v[204:207], v[84:87]
	v_mfma_f32_16x16x32_bf16 v[80:83], v[162:165], v[204:207], v[80:83]
	v_mfma_f32_16x16x32_bf16 v[68:71], v[154:157], v[212:215], v[68:71]
	v_mfma_f32_16x16x32_bf16 v[64:67], v[162:165], v[212:215], v[64:67]
	v_mfma_f32_16x16x32_bf16 v[116:119], v[158:161], v[190:193], v[116:119]
	v_mfma_f32_16x16x32_bf16 v[112:115], v[166:169], v[190:193], v[112:115]
	v_mfma_f32_16x16x32_bf16 v[100:103], v[158:161], v[200:203], v[100:103]
	v_mfma_f32_16x16x32_bf16 v[96:99], v[166:169], v[200:203], v[96:99]
	v_mfma_f32_16x16x32_bf16 v[84:87], v[158:161], v[208:211], v[84:87]
	v_mfma_f32_16x16x32_bf16 v[80:83], v[166:169], v[208:211], v[80:83]
	v_mfma_f32_16x16x32_bf16 v[68:71], v[158:161], v[216:219], v[68:71]
	v_mfma_f32_16x16x32_bf16 v[64:67], v[166:169], v[216:219], v[64:67]
	s_setprio 0
	s_setprio 1
	v_mfma_f32_16x16x32_bf16 v[124:127], v[170:173], v[186:189], v[124:127]
	v_mfma_f32_16x16x32_bf16 v[120:123], v[178:181], v[186:189], v[120:123]
	v_mfma_f32_16x16x32_bf16 v[108:111], v[170:173], v[196:199], v[108:111]
	v_mfma_f32_16x16x32_bf16 v[104:107], v[178:181], v[196:199], v[104:107]
	v_mfma_f32_16x16x32_bf16 v[92:95], v[170:173], v[204:207], v[92:95]
	v_mfma_f32_16x16x32_bf16 v[88:91], v[178:181], v[204:207], v[88:91]
	v_mfma_f32_16x16x32_bf16 v[76:79], v[170:173], v[212:215], v[76:79]
	v_mfma_f32_16x16x32_bf16 v[72:75], v[178:181], v[212:215], v[72:75]
	v_mfma_f32_16x16x32_bf16 v[124:127], v[174:177], v[190:193], v[124:127]
	v_mfma_f32_16x16x32_bf16 v[120:123], v[182:185], v[190:193], v[120:123]
	v_mfma_f32_16x16x32_bf16 v[108:111], v[174:177], v[200:203], v[108:111]
	v_mfma_f32_16x16x32_bf16 v[104:107], v[182:185], v[200:203], v[104:107]
	v_mfma_f32_16x16x32_bf16 v[92:95], v[174:177], v[208:211], v[92:95]
	v_mfma_f32_16x16x32_bf16 v[88:91], v[182:185], v[208:211], v[88:91]
	v_mfma_f32_16x16x32_bf16 v[76:79], v[174:177], v[216:219], v[76:79]
	v_mfma_f32_16x16x32_bf16 v[72:75], v[182:185], v[216:219], v[72:75]
	s_setprio 0
	s_barrier
	s_add_i32 s60, s50, s39
	v_lshl_add_u64 v[144:145], s[28:29], 0, v[132:133]
	s_mov_b32 m0, s60
	ds_read_b128 v[186:189], v151 offset:16384
	ds_read_b128 v[190:193], v151 offset:17408
	ds_read_b128 v[196:199], v151 offset:18432
	ds_read_b128 v[200:203], v151 offset:19456
	ds_read_b128 v[204:207], v151 offset:20480
	ds_read_b128 v[208:211], v151 offset:21504
	ds_read_b128 v[212:215], v151 offset:22528
	ds_read_b128 v[216:219], v151 offset:23552
	global_load_lds_dwordx4 v[144:145], off
	s_add_i32 m0, s60, 0x2000
	s_add_u32 s60, s28, 0x40000
	v_lshl_add_u64 v[220:221], s[28:29], 0, v[128:129]
	s_addc_u32 s61, s29, 0
	s_add_i32 s62, s51, s39
	global_load_lds_dwordx4 v[220:221], off
	v_lshl_add_u64 v[222:223], s[60:61], 0, v[132:133]
	s_mov_b32 m0, s62
	v_lshl_add_u64 v[224:225], s[30:31], 0, v[130:131]
	global_load_lds_dwordx4 v[222:223], off
	v_lshl_add_u64 v[222:223], s[60:61], 0, v[128:129]
	s_add_i32 m0, s62, 0x2000
	s_nop 0
	global_load_lds_dwordx4 v[222:223], off
	v_lshl_add_u64 v[222:223], s[30:31], 0, v[134:135]
	s_waitcnt vmcnt(6)
	s_waitcnt lgkmcnt(0)
	s_barrier
	s_setprio 1
	s_waitcnt lgkmcnt(0)
	v_mfma_f32_16x16x32_bf16 v[52:55], v[154:157], v[186:189], v[52:55]
	v_mfma_f32_16x16x32_bf16 v[48:51], v[162:165], v[186:189], v[48:51]
	v_mfma_f32_16x16x32_bf16 v[36:39], v[154:157], v[196:199], v[36:39]
	v_mfma_f32_16x16x32_bf16 v[32:35], v[162:165], v[196:199], v[32:35]
	v_mfma_f32_16x16x32_bf16 v[20:23], v[154:157], v[204:207], v[20:23]
	v_mfma_f32_16x16x32_bf16 v[16:19], v[162:165], v[204:207], v[16:19]
	v_mfma_f32_16x16x32_bf16 v[4:7], v[154:157], v[212:215], v[4:7]
	v_mfma_f32_16x16x32_bf16 v[0:3], v[162:165], v[212:215], v[0:3]
	v_mfma_f32_16x16x32_bf16 v[52:55], v[158:161], v[190:193], v[52:55]
	v_mfma_f32_16x16x32_bf16 v[48:51], v[166:169], v[190:193], v[48:51]
	v_mfma_f32_16x16x32_bf16 v[36:39], v[158:161], v[200:203], v[36:39]
	v_mfma_f32_16x16x32_bf16 v[32:35], v[166:169], v[200:203], v[32:35]
	v_mfma_f32_16x16x32_bf16 v[20:23], v[158:161], v[208:211], v[20:23]
	v_mfma_f32_16x16x32_bf16 v[16:19], v[166:169], v[208:211], v[16:19]
	v_mfma_f32_16x16x32_bf16 v[4:7], v[158:161], v[216:219], v[4:7]
	v_mfma_f32_16x16x32_bf16 v[0:3], v[166:169], v[216:219], v[0:3]
	s_setprio 0
	s_setprio 1
	v_mfma_f32_16x16x32_bf16 v[60:63], v[170:173], v[186:189], v[60:63]
	v_mfma_f32_16x16x32_bf16 v[56:59], v[178:181], v[186:189], v[56:59]
	v_mfma_f32_16x16x32_bf16 v[44:47], v[170:173], v[196:199], v[44:47]
	v_mfma_f32_16x16x32_bf16 v[40:43], v[178:181], v[196:199], v[40:43]
	v_mfma_f32_16x16x32_bf16 v[28:31], v[170:173], v[204:207], v[28:31]
	v_mfma_f32_16x16x32_bf16 v[24:27], v[178:181], v[204:207], v[24:27]
	v_mfma_f32_16x16x32_bf16 v[12:15], v[170:173], v[212:215], v[12:15]
	v_mfma_f32_16x16x32_bf16 v[8:11], v[178:181], v[212:215], v[8:11]
	v_mfma_f32_16x16x32_bf16 v[60:63], v[174:177], v[190:193], v[60:63]
	v_mfma_f32_16x16x32_bf16 v[56:59], v[182:185], v[190:193], v[56:59]
	v_mfma_f32_16x16x32_bf16 v[44:47], v[174:177], v[200:203], v[44:47]
	v_mfma_f32_16x16x32_bf16 v[40:43], v[182:185], v[200:203], v[40:43]
	v_mfma_f32_16x16x32_bf16 v[28:31], v[174:177], v[208:211], v[28:31]
	v_mfma_f32_16x16x32_bf16 v[24:27], v[182:185], v[208:211], v[24:27]
	v_mfma_f32_16x16x32_bf16 v[12:15], v[174:177], v[216:219], v[12:15]
	v_mfma_f32_16x16x32_bf16 v[8:11], v[182:185], v[216:219], v[8:11]
	s_setprio 0
	s_barrier
	s_add_i32 s60, 0, 0x18000
	v_add_u32_e32 v153, s60, v147
	s_add_i32 s61, 0, 0x1c000
	ds_read_b128 v[154:157], v153
	ds_read_b128 v[158:161], v153 offset:1024
	ds_read_b128 v[162:165], v153 offset:2048
	ds_read_b128 v[166:169], v153 offset:3072
	v_add_u32_e32 v153, s61, v147
	ds_read_b128 v[170:173], v153
	ds_read_b128 v[174:177], v153 offset:1024
	ds_read_b128 v[178:181], v153 offset:2048
	ds_read_b128 v[182:185], v153 offset:3072
	s_add_u32 s30, s30, 0x40000
	s_addc_u32 s31, s31, 0
	v_lshl_add_u64 v[226:227], s[30:31], 0, v[134:135]
	ds_read_b128 v[186:189], v151 offset:32768
	ds_read_b128 v[190:193], v151 offset:33792
	ds_read_b128 v[196:199], v151 offset:34816
	ds_read_b128 v[200:203], v151 offset:35840
	ds_read_b128 v[204:207], v151 offset:36864
	ds_read_b128 v[208:211], v151 offset:37888
	ds_read_b128 v[212:215], v151 offset:38912
	ds_read_b128 v[216:219], v151 offset:39936
	s_mov_b32 m0, s25
	s_nop 0
	global_load_lds_dwordx4 v[222:223], off
	s_mov_b32 m0, s41
	s_nop 0
	global_load_lds_dwordx4 v[224:225], off
	s_mov_b32 m0, s42
	s_nop 0
	global_load_lds_dwordx4 v[226:227], off
	v_lshl_add_u64 v[226:227], s[30:31], 0, v[130:131]
	s_mov_b32 m0, s43
	s_nop 0
	global_load_lds_dwordx4 v[226:227], off
	s_waitcnt vmcnt(8)
	s_waitcnt lgkmcnt(0)
	s_barrier
	s_setprio 1
	s_waitcnt lgkmcnt(0)
	v_mfma_f32_16x16x32_bf16 v[116:119], v[154:157], v[186:189], v[116:119]
	v_mfma_f32_16x16x32_bf16 v[112:115], v[162:165], v[186:189], v[112:115]
	v_mfma_f32_16x16x32_bf16 v[100:103], v[154:157], v[196:199], v[100:103]
	v_mfma_f32_16x16x32_bf16 v[96:99], v[162:165], v[196:199], v[96:99]
	v_mfma_f32_16x16x32_bf16 v[84:87], v[154:157], v[204:207], v[84:87]
	v_mfma_f32_16x16x32_bf16 v[80:83], v[162:165], v[204:207], v[80:83]
	v_mfma_f32_16x16x32_bf16 v[68:71], v[154:157], v[212:215], v[68:71]
	v_mfma_f32_16x16x32_bf16 v[64:67], v[162:165], v[212:215], v[64:67]
	v_mfma_f32_16x16x32_bf16 v[116:119], v[158:161], v[190:193], v[116:119]
	v_mfma_f32_16x16x32_bf16 v[112:115], v[166:169], v[190:193], v[112:115]
	v_mfma_f32_16x16x32_bf16 v[100:103], v[158:161], v[200:203], v[100:103]
	v_mfma_f32_16x16x32_bf16 v[96:99], v[166:169], v[200:203], v[96:99]
	v_mfma_f32_16x16x32_bf16 v[84:87], v[158:161], v[208:211], v[84:87]
	v_mfma_f32_16x16x32_bf16 v[80:83], v[166:169], v[208:211], v[80:83]
	v_mfma_f32_16x16x32_bf16 v[68:71], v[158:161], v[216:219], v[68:71]
	v_mfma_f32_16x16x32_bf16 v[64:67], v[166:169], v[216:219], v[64:67]
	s_setprio 0
	s_setprio 1
	v_mfma_f32_16x16x32_bf16 v[124:127], v[170:173], v[186:189], v[124:127]
	v_mfma_f32_16x16x32_bf16 v[120:123], v[178:181], v[186:189], v[120:123]
	v_mfma_f32_16x16x32_bf16 v[108:111], v[170:173], v[196:199], v[108:111]
	v_mfma_f32_16x16x32_bf16 v[104:107], v[178:181], v[196:199], v[104:107]
	v_mfma_f32_16x16x32_bf16 v[92:95], v[170:173], v[204:207], v[92:95]
	v_mfma_f32_16x16x32_bf16 v[88:91], v[178:181], v[204:207], v[88:91]
	v_mfma_f32_16x16x32_bf16 v[76:79], v[170:173], v[212:215], v[76:79]
	v_mfma_f32_16x16x32_bf16 v[72:75], v[178:181], v[212:215], v[72:75]
	v_mfma_f32_16x16x32_bf16 v[124:127], v[174:177], v[190:193], v[124:127]
	v_mfma_f32_16x16x32_bf16 v[120:123], v[182:185], v[190:193], v[120:123]
	v_mfma_f32_16x16x32_bf16 v[108:111], v[174:177], v[200:203], v[108:111]
	v_mfma_f32_16x16x32_bf16 v[104:107], v[182:185], v[200:203], v[104:107]
	v_mfma_f32_16x16x32_bf16 v[92:95], v[174:177], v[208:211], v[92:95]
	v_mfma_f32_16x16x32_bf16 v[88:91], v[182:185], v[208:211], v[88:91]
	v_mfma_f32_16x16x32_bf16 v[76:79], v[174:177], v[216:219], v[76:79]
	v_mfma_f32_16x16x32_bf16 v[72:75], v[182:185], v[216:219], v[72:75]
	s_setprio 0
	s_barrier
	s_add_i32 s30, s60, s39
	v_lshl_add_u64 v[144:145], v[144:145], 0, s[12:13]
	s_mov_b32 m0, s30
	ds_read_b128 v[186:189], v151 offset:49152
	ds_read_b128 v[190:193], v151 offset:50176
	ds_read_b128 v[196:199], v151 offset:51200
	ds_read_b128 v[200:203], v151 offset:52224
	ds_read_b128 v[204:207], v151 offset:53248
	ds_read_b128 v[208:211], v151 offset:54272
	ds_read_b128 v[212:215], v151 offset:55296
	ds_read_b128 v[216:219], v151 offset:56320
	global_load_lds_dwordx4 v[144:145], off
	s_add_i32 m0, s30, 0x2000
	s_add_u32 s28, s28, 0x40080
	v_lshl_add_u64 v[144:145], v[220:221], 0, s[12:13]
	s_addc_u32 s29, s29, 0
	s_add_i32 s30, s61, s39
	global_load_lds_dwordx4 v[144:145], off
	v_lshl_add_u64 v[144:145], s[28:29], 0, v[132:133]
	s_mov_b32 m0, s30
	s_nop 0
	global_load_lds_dwordx4 v[144:145], off
	v_lshl_add_u64 v[144:145], s[28:29], 0, v[128:129]
	s_add_i32 m0, s30, 0x2000
	s_nop 0
	global_load_lds_dwordx4 v[144:145], off
	v_lshl_add_u64 v[144:145], v[222:223], 0, s[12:13]
	s_mov_b32 m0, s45
	s_nop 0
	global_load_lds_dwordx4 v[144:145], off
	v_lshl_add_u64 v[144:145], v[224:225], 0, s[12:13]
	s_mov_b32 m0, s48
	s_nop 0
	global_load_lds_dwordx4 v[144:145], off
	s_waitcnt vmcnt(8)
	s_waitcnt lgkmcnt(0)
	s_barrier
	s_setprio 1
	s_waitcnt lgkmcnt(0)
	v_mfma_f32_16x16x32_bf16 v[52:55], v[154:157], v[186:189], v[52:55]
	v_mfma_f32_16x16x32_bf16 v[48:51], v[162:165], v[186:189], v[48:51]
	v_mfma_f32_16x16x32_bf16 v[36:39], v[154:157], v[196:199], v[36:39]
	v_mfma_f32_16x16x32_bf16 v[32:35], v[162:165], v[196:199], v[32:35]
	v_mfma_f32_16x16x32_bf16 v[20:23], v[154:157], v[204:207], v[20:23]
	v_mfma_f32_16x16x32_bf16 v[16:19], v[162:165], v[204:207], v[16:19]
	v_mfma_f32_16x16x32_bf16 v[4:7], v[154:157], v[212:215], v[4:7]
	v_mfma_f32_16x16x32_bf16 v[0:3], v[162:165], v[212:215], v[0:3]
	v_mfma_f32_16x16x32_bf16 v[52:55], v[158:161], v[190:193], v[52:55]
	v_mfma_f32_16x16x32_bf16 v[48:51], v[166:169], v[190:193], v[48:51]
	v_mfma_f32_16x16x32_bf16 v[36:39], v[158:161], v[200:203], v[36:39]
	v_mfma_f32_16x16x32_bf16 v[32:35], v[166:169], v[200:203], v[32:35]
	v_mfma_f32_16x16x32_bf16 v[20:23], v[158:161], v[208:211], v[20:23]
	v_mfma_f32_16x16x32_bf16 v[16:19], v[166:169], v[208:211], v[16:19]
	v_mfma_f32_16x16x32_bf16 v[4:7], v[158:161], v[216:219], v[4:7]
	v_mfma_f32_16x16x32_bf16 v[0:3], v[166:169], v[216:219], v[0:3]
	s_setprio 0
	s_setprio 1
	v_mfma_f32_16x16x32_bf16 v[60:63], v[170:173], v[186:189], v[60:63]
	v_mfma_f32_16x16x32_bf16 v[56:59], v[178:181], v[186:189], v[56:59]
	v_mfma_f32_16x16x32_bf16 v[44:47], v[170:173], v[196:199], v[44:47]
	v_mfma_f32_16x16x32_bf16 v[40:43], v[178:181], v[196:199], v[40:43]
	v_mfma_f32_16x16x32_bf16 v[28:31], v[170:173], v[204:207], v[28:31]
	v_mfma_f32_16x16x32_bf16 v[24:27], v[178:181], v[204:207], v[24:27]
	v_mfma_f32_16x16x32_bf16 v[12:15], v[170:173], v[212:215], v[12:15]
	v_mfma_f32_16x16x32_bf16 v[8:11], v[178:181], v[212:215], v[8:11]
	v_mfma_f32_16x16x32_bf16 v[60:63], v[174:177], v[190:193], v[60:63]
	v_mfma_f32_16x16x32_bf16 v[56:59], v[182:185], v[190:193], v[56:59]
	v_mfma_f32_16x16x32_bf16 v[44:47], v[174:177], v[200:203], v[44:47]
	v_mfma_f32_16x16x32_bf16 v[40:43], v[182:185], v[200:203], v[40:43]
	v_mfma_f32_16x16x32_bf16 v[28:31], v[174:177], v[208:211], v[28:31]
	v_mfma_f32_16x16x32_bf16 v[24:27], v[182:185], v[208:211], v[24:27]
	v_mfma_f32_16x16x32_bf16 v[12:15], v[174:177], v[216:219], v[12:15]
	v_mfma_f32_16x16x32_bf16 v[8:11], v[182:185], v[216:219], v[8:11]
	s_setprio 0
	s_barrier
	s_add_i32 s59, s59, 2
	s_add_u32 s26, s26, 0x100
	s_addc_u32 s27, s27, 0
	s_add_u32 s57, s57, 0x100
	s_addc_u32 s58, s58, 0
	s_cmp_gt_u32 s59, 13
	s_cbranch_scc0 .LBB0_3319
	s_and_b64 vcc, exec, s[14:15]
	s_cbranch_vccz .LBB0_3322
	s_barrier

.LBB0_3401:
	ds_read_b128 v[144:147], v151
	ds_read_b128 v[156:159], v151 offset:1024
	ds_read_b128 v[160:163], v151 offset:2048
	ds_read_b128 v[164:167], v151 offset:3072
	ds_read_b128 v[168:171], v152
	ds_read_b128 v[172:175], v152 offset:1024
	ds_read_b128 v[176:179], v152 offset:2048
	ds_read_b128 v[180:183], v152 offset:3072
	s_add_u32 s24, s22, 0x100
	s_addc_u32 s25, s23, 0
	s_cmp_eq_u32 s56, 40
	s_cselect_b32 s29, s1, s25
	s_cselect_b32 s28, s0, s24
	s_cselect_b32 s27, s21, s55
	s_cselect_b32 s26, s20, s54
	v_lshl_add_u64 v[192:193], s[22:23], 0, v[136:137]
	s_add_i32 m0, s38, 0xc000
	ds_read_b128 v[184:187], v153
	ds_read_b128 v[188:191], v153 offset:1024
	ds_read_b128 v[196:199], v153 offset:2048
	ds_read_b128 v[200:203], v153 offset:3072
	ds_read_b128 v[204:207], v153 offset:4096
	ds_read_b128 v[208:211], v153 offset:5120
	ds_read_b128 v[212:215], v153 offset:6144
	ds_read_b128 v[216:219], v153 offset:7168
	global_load_lds_dwordx4 v[192:193], off
	v_lshl_add_u64 v[192:193], s[22:23], 0, v[138:139]
	s_add_i32 m0, s38, 0xe000
	s_nop 0
	global_load_lds_dwordx4 v[192:193], off
	s_waitcnt vmcnt(8)
	s_waitcnt lgkmcnt(0)
	s_barrier
	s_setprio 1
	s_waitcnt lgkmcnt(0)
	v_mfma_f32_16x16x32_bf16 v[124:127], v[144:147], v[184:187], v[124:127]
	v_mfma_f32_16x16x32_bf16 v[120:123], v[160:163], v[184:187], v[120:123]
	v_mfma_f32_16x16x32_bf16 v[108:111], v[144:147], v[196:199], v[108:111]
	v_mfma_f32_16x16x32_bf16 v[104:107], v[160:163], v[196:199], v[104:107]
	v_mfma_f32_16x16x32_bf16 v[92:95], v[144:147], v[204:207], v[92:95]
	v_mfma_f32_16x16x32_bf16 v[88:91], v[160:163], v[204:207], v[88:91]
	v_mfma_f32_16x16x32_bf16 v[76:79], v[144:147], v[212:215], v[76:79]
	v_mfma_f32_16x16x32_bf16 v[72:75], v[160:163], v[212:215], v[72:75]
	v_mfma_f32_16x16x32_bf16 v[124:127], v[156:159], v[188:191], v[124:127]
	v_mfma_f32_16x16x32_bf16 v[120:123], v[164:167], v[188:191], v[120:123]
	v_mfma_f32_16x16x32_bf16 v[108:111], v[156:159], v[200:203], v[108:111]
	v_mfma_f32_16x16x32_bf16 v[104:107], v[164:167], v[200:203], v[104:107]
	v_mfma_f32_16x16x32_bf16 v[92:95], v[156:159], v[208:211], v[92:95]
	v_mfma_f32_16x16x32_bf16 v[88:91], v[164:167], v[208:211], v[88:91]
	v_mfma_f32_16x16x32_bf16 v[76:79], v[156:159], v[216:219], v[76:79]
	v_mfma_f32_16x16x32_bf16 v[72:75], v[164:167], v[216:219], v[72:75]
	s_setprio 0
	s_setprio 1
	v_mfma_f32_16x16x32_bf16 v[116:119], v[168:171], v[184:187], v[116:119]
	v_mfma_f32_16x16x32_bf16 v[112:115], v[176:179], v[184:187], v[112:115]
	v_mfma_f32_16x16x32_bf16 v[100:103], v[168:171], v[196:199], v[100:103]
	v_mfma_f32_16x16x32_bf16 v[96:99], v[176:179], v[196:199], v[96:99]
	v_mfma_f32_16x16x32_bf16 v[84:87], v[168:171], v[204:207], v[84:87]
	v_mfma_f32_16x16x32_bf16 v[80:83], v[176:179], v[204:207], v[80:83]
	v_mfma_f32_16x16x32_bf16 v[68:71], v[168:171], v[212:215], v[68:71]
	v_mfma_f32_16x16x32_bf16 v[64:67], v[176:179], v[212:215], v[64:67]
	v_mfma_f32_16x16x32_bf16 v[116:119], v[172:175], v[188:191], v[116:119]
	v_mfma_f32_16x16x32_bf16 v[112:115], v[180:183], v[188:191], v[112:115]
	v_mfma_f32_16x16x32_bf16 v[100:103], v[172:175], v[200:203], v[100:103]
	v_mfma_f32_16x16x32_bf16 v[96:99], v[180:183], v[200:203], v[96:99]
	v_mfma_f32_16x16x32_bf16 v[84:87], v[172:175], v[208:211], v[84:87]
	v_mfma_f32_16x16x32_bf16 v[80:83], v[180:183], v[208:211], v[80:83]
	v_mfma_f32_16x16x32_bf16 v[68:71], v[172:175], v[216:219], v[68:71]
	v_mfma_f32_16x16x32_bf16 v[64:67], v[180:183], v[216:219], v[64:67]
	s_setprio 0
	s_barrier
	s_add_i32 s22, s48, s37
	v_lshl_add_u64 v[192:193], s[26:27], 0, v[130:131]
	s_mov_b32 m0, s22
	ds_read_b128 v[184:187], v153 offset:16384
	ds_read_b128 v[188:191], v153 offset:17408
	ds_read_b128 v[196:199], v153 offset:18432
	ds_read_b128 v[200:203], v153 offset:19456
	ds_read_b128 v[204:207], v153 offset:20480
	ds_read_b128 v[208:211], v153 offset:21504
	ds_read_b128 v[212:215], v153 offset:22528
	ds_read_b128 v[216:219], v153 offset:23552
	global_load_lds_dwordx4 v[192:193], off
	s_add_i32 m0, s22, 0x2000
	s_add_u32 s22, s26, 0xb0000
	v_lshl_add_u64 v[220:221], s[26:27], 0, v[134:135]
	s_addc_u32 s23, s27, 0
	s_add_i32 s57, s49, s37
	global_load_lds_dwordx4 v[220:221], off
	v_lshl_add_u64 v[222:223], s[22:23], 0, v[130:131]
	s_mov_b32 m0, s57
	v_lshl_add_u64 v[224:225], s[28:29], 0, v[132:133]
	global_load_lds_dwordx4 v[222:223], off
	v_lshl_add_u64 v[222:223], s[22:23], 0, v[134:135]
	s_add_i32 m0, s57, 0x2000
	s_nop 0
	global_load_lds_dwordx4 v[222:223], off
	v_lshl_add_u64 v[222:223], s[28:29], 0, v[128:129]
	s_waitcnt vmcnt(6)
	s_waitcnt lgkmcnt(0)
	s_barrier
	s_setprio 1
	s_waitcnt lgkmcnt(0)
	v_mfma_f32_16x16x32_bf16 v[60:63], v[144:147], v[184:187], v[60:63]
	v_mfma_f32_16x16x32_bf16 v[56:59], v[160:163], v[184:187], v[56:59]
	v_mfma_f32_16x16x32_bf16 v[44:47], v[144:147], v[196:199], v[44:47]
	v_mfma_f32_16x16x32_bf16 v[40:43], v[160:163], v[196:199], v[40:43]
	v_mfma_f32_16x16x32_bf16 v[28:31], v[144:147], v[204:207], v[28:31]
	v_mfma_f32_16x16x32_bf16 v[24:27], v[160:163], v[204:207], v[24:27]
	v_mfma_f32_16x16x32_bf16 v[12:15], v[144:147], v[212:215], v[12:15]
	v_mfma_f32_16x16x32_bf16 v[8:11], v[160:163], v[212:215], v[8:11]
	v_mfma_f32_16x16x32_bf16 v[60:63], v[156:159], v[188:191], v[60:63]
	v_mfma_f32_16x16x32_bf16 v[56:59], v[164:167], v[188:191], v[56:59]
	v_mfma_f32_16x16x32_bf16 v[44:47], v[156:159], v[200:203], v[44:47]
	v_mfma_f32_16x16x32_bf16 v[40:43], v[164:167], v[200:203], v[40:43]
	v_mfma_f32_16x16x32_bf16 v[28:31], v[156:159], v[208:211], v[28:31]
	v_mfma_f32_16x16x32_bf16 v[24:27], v[164:167], v[208:211], v[24:27]
	v_mfma_f32_16x16x32_bf16 v[12:15], v[156:159], v[216:219], v[12:15]
	v_mfma_f32_16x16x32_bf16 v[8:11], v[164:167], v[216:219], v[8:11]
	s_setprio 0
	s_setprio 1
	v_mfma_f32_16x16x32_bf16 v[52:55], v[168:171], v[184:187], v[52:55]
	v_mfma_f32_16x16x32_bf16 v[48:51], v[176:179], v[184:187], v[48:51]
	v_mfma_f32_16x16x32_bf16 v[36:39], v[168:171], v[196:199], v[36:39]
	v_mfma_f32_16x16x32_bf16 v[32:35], v[176:179], v[196:199], v[32:35]
	v_mfma_f32_16x16x32_bf16 v[20:23], v[168:171], v[204:207], v[20:23]
	v_mfma_f32_16x16x32_bf16 v[16:19], v[176:179], v[204:207], v[16:19]
	v_mfma_f32_16x16x32_bf16 v[4:7], v[168:171], v[212:215], v[4:7]
	v_mfma_f32_16x16x32_bf16 v[0:3], v[176:179], v[212:215], v[0:3]
	v_mfma_f32_16x16x32_bf16 v[52:55], v[172:175], v[188:191], v[52:55]
	v_mfma_f32_16x16x32_bf16 v[48:51], v[180:183], v[188:191], v[48:51]
	v_mfma_f32_16x16x32_bf16 v[36:39], v[172:175], v[200:203], v[36:39]
	v_mfma_f32_16x16x32_bf16 v[32:35], v[180:183], v[200:203], v[32:35]
	v_mfma_f32_16x16x32_bf16 v[20:23], v[172:175], v[208:211], v[20:23]
	v_mfma_f32_16x16x32_bf16 v[16:19], v[180:183], v[208:211], v[16:19]
	v_mfma_f32_16x16x32_bf16 v[4:7], v[172:175], v[216:219], v[4:7]
	v_mfma_f32_16x16x32_bf16 v[0:3], v[180:183], v[216:219], v[0:3]
	s_setprio 0
	s_barrier
	s_add_i32 s57, 0, 0x18000
	v_add_u32_e32 v155, s57, v149
	s_add_i32 s58, 0, 0x1c000
	ds_read_b128 v[144:147], v155
	ds_read_b128 v[156:159], v155 offset:1024
	ds_read_b128 v[160:163], v155 offset:2048
	ds_read_b128 v[164:167], v155 offset:3072
	v_add_u32_e32 v155, s58, v149
	ds_read_b128 v[168:171], v155
	ds_read_b128 v[172:175], v155 offset:1024
	ds_read_b128 v[176:179], v155 offset:2048
	ds_read_b128 v[180:183], v155 offset:3072
	s_add_u32 s22, s28, 0xb0000
	s_addc_u32 s23, s29, 0
	v_lshl_add_u64 v[226:227], s[22:23], 0, v[128:129]
	ds_read_b128 v[184:187], v153 offset:32768
	ds_read_b128 v[188:191], v153 offset:33792
	ds_read_b128 v[196:199], v153 offset:34816
	ds_read_b128 v[200:203], v153 offset:35840
	ds_read_b128 v[204:207], v153 offset:36864
	ds_read_b128 v[208:211], v153 offset:37888
	ds_read_b128 v[212:215], v153 offset:38912
	ds_read_b128 v[216:219], v153 offset:39936
	s_mov_b32 m0, s38
	s_nop 0
	global_load_lds_dwordx4 v[222:223], off
	s_mov_b32 m0, s39
	s_nop 0
	global_load_lds_dwordx4 v[224:225], off
	s_mov_b32 m0, s40
	s_nop 0
	global_load_lds_dwordx4 v[226:227], off
	v_lshl_add_u64 v[226:227], s[22:23], 0, v[132:133]
	s_mov_b32 m0, s41
	s_nop 0
	global_load_lds_dwordx4 v[226:227], off
	s_waitcnt vmcnt(8)
	s_waitcnt lgkmcnt(0)
	s_barrier
	s_setprio 1
	s_waitcnt lgkmcnt(0)
	v_mfma_f32_16x16x32_bf16 v[124:127], v[144:147], v[184:187], v[124:127]
	v_mfma_f32_16x16x32_bf16 v[120:123], v[160:163], v[184:187], v[120:123]
	v_mfma_f32_16x16x32_bf16 v[108:111], v[144:147], v[196:199], v[108:111]
	v_mfma_f32_16x16x32_bf16 v[104:107], v[160:163], v[196:199], v[104:107]
	v_mfma_f32_16x16x32_bf16 v[92:95], v[144:147], v[204:207], v[92:95]
	v_mfma_f32_16x16x32_bf16 v[88:91], v[160:163], v[204:207], v[88:91]
	v_mfma_f32_16x16x32_bf16 v[76:79], v[144:147], v[212:215], v[76:79]
	v_mfma_f32_16x16x32_bf16 v[72:75], v[160:163], v[212:215], v[72:75]
	v_mfma_f32_16x16x32_bf16 v[124:127], v[156:159], v[188:191], v[124:127]
	v_mfma_f32_16x16x32_bf16 v[120:123], v[164:167], v[188:191], v[120:123]
	v_mfma_f32_16x16x32_bf16 v[108:111], v[156:159], v[200:203], v[108:111]
	v_mfma_f32_16x16x32_bf16 v[104:107], v[164:167], v[200:203], v[104:107]
	v_mfma_f32_16x16x32_bf16 v[92:95], v[156:159], v[208:211], v[92:95]
	v_mfma_f32_16x16x32_bf16 v[88:91], v[164:167], v[208:211], v[88:91]
	v_mfma_f32_16x16x32_bf16 v[76:79], v[156:159], v[216:219], v[76:79]
	v_mfma_f32_16x16x32_bf16 v[72:75], v[164:167], v[216:219], v[72:75]
	s_setprio 0
	s_setprio 1
	v_mfma_f32_16x16x32_bf16 v[116:119], v[168:171], v[184:187], v[116:119]
	v_mfma_f32_16x16x32_bf16 v[112:115], v[176:179], v[184:187], v[112:115]
	v_mfma_f32_16x16x32_bf16 v[100:103], v[168:171], v[196:199], v[100:103]
	v_mfma_f32_16x16x32_bf16 v[96:99], v[176:179], v[196:199], v[96:99]
	v_mfma_f32_16x16x32_bf16 v[84:87], v[168:171], v[204:207], v[84:87]
	v_mfma_f32_16x16x32_bf16 v[80:83], v[176:179], v[204:207], v[80:83]
	v_mfma_f32_16x16x32_bf16 v[68:71], v[168:171], v[212:215], v[68:71]
	v_mfma_f32_16x16x32_bf16 v[64:67], v[176:179], v[212:215], v[64:67]
	v_mfma_f32_16x16x32_bf16 v[116:119], v[172:175], v[188:191], v[116:119]
	v_mfma_f32_16x16x32_bf16 v[112:115], v[180:183], v[188:191], v[112:115]
	v_mfma_f32_16x16x32_bf16 v[100:103], v[172:175], v[200:203], v[100:103]
	v_mfma_f32_16x16x32_bf16 v[96:99], v[180:183], v[200:203], v[96:99]
	v_mfma_f32_16x16x32_bf16 v[84:87], v[172:175], v[208:211], v[84:87]
	v_mfma_f32_16x16x32_bf16 v[80:83], v[180:183], v[208:211], v[80:83]
	v_mfma_f32_16x16x32_bf16 v[68:71], v[172:175], v[216:219], v[68:71]
	v_mfma_f32_16x16x32_bf16 v[64:67], v[180:183], v[216:219], v[64:67]
	s_setprio 0
	s_barrier
	s_add_i32 s22, s57, s37
	v_lshl_add_u64 v[192:193], v[192:193], 0, s[16:17]
	s_mov_b32 m0, s22
	ds_read_b128 v[184:187], v153 offset:49152
	ds_read_b128 v[188:191], v153 offset:50176
	ds_read_b128 v[196:199], v153 offset:51200
	ds_read_b128 v[200:203], v153 offset:52224
	ds_read_b128 v[204:207], v153 offset:53248
	ds_read_b128 v[208:211], v153 offset:54272
	ds_read_b128 v[212:215], v153 offset:55296
	ds_read_b128 v[216:219], v153 offset:56320
	global_load_lds_dwordx4 v[192:193], off
	s_add_i32 m0, s22, 0x2000
	s_add_u32 s22, s26, 0xb0080
	v_lshl_add_u64 v[192:193], v[220:221], 0, s[16:17]
	s_addc_u32 s23, s27, 0
	s_add_i32 s26, s58, s37
	global_load_lds_dwordx4 v[192:193], off
	v_lshl_add_u64 v[192:193], s[22:23], 0, v[130:131]
	s_mov_b32 m0, s26
	s_nop 0
	global_load_lds_dwordx4 v[192:193], off
	v_lshl_add_u64 v[192:193], s[22:23], 0, v[134:135]
	s_add_i32 m0, s26, 0x2000
	s_nop 0
	global_load_lds_dwordx4 v[192:193], off
	v_lshl_add_u64 v[192:193], v[222:223], 0, s[16:17]
	s_mov_b32 m0, s43
	s_nop 0
	global_load_lds_dwordx4 v[192:193], off
	v_lshl_add_u64 v[192:193], v[224:225], 0, s[16:17]
	s_mov_b32 m0, s44
	s_nop 0
	global_load_lds_dwordx4 v[192:193], off
	s_waitcnt vmcnt(8)
	s_waitcnt lgkmcnt(0)
	s_barrier
	s_setprio 1
	s_waitcnt lgkmcnt(0)
	v_mfma_f32_16x16x32_bf16 v[60:63], v[144:147], v[184:187], v[60:63]
	v_mfma_f32_16x16x32_bf16 v[56:59], v[160:163], v[184:187], v[56:59]
	v_mfma_f32_16x16x32_bf16 v[44:47], v[144:147], v[196:199], v[44:47]
	v_mfma_f32_16x16x32_bf16 v[40:43], v[160:163], v[196:199], v[40:43]
	v_mfma_f32_16x16x32_bf16 v[28:31], v[144:147], v[204:207], v[28:31]
	v_mfma_f32_16x16x32_bf16 v[24:27], v[160:163], v[204:207], v[24:27]
	v_mfma_f32_16x16x32_bf16 v[12:15], v[144:147], v[212:215], v[12:15]
	v_mfma_f32_16x16x32_bf16 v[8:11], v[160:163], v[212:215], v[8:11]
	v_mfma_f32_16x16x32_bf16 v[60:63], v[156:159], v[188:191], v[60:63]
	v_mfma_f32_16x16x32_bf16 v[56:59], v[164:167], v[188:191], v[56:59]
	v_mfma_f32_16x16x32_bf16 v[44:47], v[156:159], v[200:203], v[44:47]
	v_mfma_f32_16x16x32_bf16 v[40:43], v[164:167], v[200:203], v[40:43]
	v_mfma_f32_16x16x32_bf16 v[28:31], v[156:159], v[208:211], v[28:31]
	v_mfma_f32_16x16x32_bf16 v[24:27], v[164:167], v[208:211], v[24:27]
	v_mfma_f32_16x16x32_bf16 v[12:15], v[156:159], v[216:219], v[12:15]
	v_mfma_f32_16x16x32_bf16 v[8:11], v[164:167], v[216:219], v[8:11]
	s_setprio 0
	s_setprio 1
	v_mfma_f32_16x16x32_bf16 v[52:55], v[168:171], v[184:187], v[52:55]
	v_mfma_f32_16x16x32_bf16 v[48:51], v[176:179], v[184:187], v[48:51]
	v_mfma_f32_16x16x32_bf16 v[36:39], v[168:171], v[196:199], v[36:39]
	v_mfma_f32_16x16x32_bf16 v[32:35], v[176:179], v[196:199], v[32:35]
	v_mfma_f32_16x16x32_bf16 v[20:23], v[168:171], v[204:207], v[20:23]
	v_mfma_f32_16x16x32_bf16 v[16:19], v[176:179], v[204:207], v[16:19]
	v_mfma_f32_16x16x32_bf16 v[4:7], v[168:171], v[212:215], v[4:7]
	v_mfma_f32_16x16x32_bf16 v[0:3], v[176:179], v[212:215], v[0:3]
	v_mfma_f32_16x16x32_bf16 v[52:55], v[172:175], v[188:191], v[52:55]
	v_mfma_f32_16x16x32_bf16 v[48:51], v[180:183], v[188:191], v[48:51]
	v_mfma_f32_16x16x32_bf16 v[36:39], v[172:175], v[200:203], v[36:39]
	v_mfma_f32_16x16x32_bf16 v[32:35], v[180:183], v[200:203], v[32:35]
	v_mfma_f32_16x16x32_bf16 v[20:23], v[172:175], v[208:211], v[20:23]
	v_mfma_f32_16x16x32_bf16 v[16:19], v[180:183], v[208:211], v[16:19]
	v_mfma_f32_16x16x32_bf16 v[4:7], v[172:175], v[216:219], v[4:7]
	v_mfma_f32_16x16x32_bf16 v[0:3], v[180:183], v[216:219], v[0:3]
	s_setprio 0
	s_barrier
	s_add_i32 s56, s56, 2
	s_add_u32 s54, s54, 0x100
	s_addc_u32 s55, s55, 0
	s_cmp_gt_u32 s56, 41
	s_mov_b64 s[22:23], s[24:25]
	s_cbranch_scc0 .LBB0_3401
	s_and_b64 vcc, exec, s[18:19]
	s_cbranch_vccz .LBB0_3404
	s_barrier
